# E2 prompt attention as workgroup task with K/V^T in LDS; final RMSNorm loads batched; wave reductions via DPP; sample gate item moved to idle wave
# speedup vs baseline: 1.0925x; 1.0238x over previous
; __device__ __forceinline__ float bf_lo(unsigned w) { return __uint_as_float(w << 16); }
; __device__ __forceinline__ float bf_hi(unsigned w) { return __uint_as_float(w & 0xffff0000u); }
; __global__ void __launch_bounds__(NTHREADS, 2) hybrid_fwd(Params P) {
;     ...
;                 for (int it0 = gw; it0 < T_ALL * 8; it0 += 4 * NGW) {
;                     u32x4 av[4], gv[4];
; #pragma unroll
;                     for (int r = 0; r < 4; ++r) {
;                         int it = it0 + r * NGW; it = it < T_ALL * 8 ? it : gw;
;                         const int h = it & 7; const size_t tok = it >> 3;
;                         av[r] = *(const u32x4*)(OB + tok * 4096 + h * 512 + 8 * lane); gv[r] = *(const u32x4*)(Z + tok * RIN + 8192 + h * 512 + 8 * lane);
;                     }
; #pragma unroll
;                     for (int r = 0; r < 4; ++r) {
;                         const int it = it0 + r * NGW;
;                         const int h = it & 7; const size_t tok = it >> 3;
;                         const u32x4 a = av[r], gq = gv[r];
;                         float v[8] = {bf_lo(a.x), bf_hi(a.x), bf_lo(a.y), bf_hi(a.y), bf_lo(a.z), bf_hi(a.z), bf_lo(a.w), bf_hi(a.w)};
;                         float s = 0.f;
; #pragma unroll
;                         for (int e = 0; e < 8; ++e) s += v[e];
;                         const float mean = wave_sum(s) * (1.0f / 512.0f);
.LBB0_478:
	s_ashr_i32 s28, s40, 3
	s_ashr_i32 s29, s28, 31
	s_lshl_b64 s[18:19], s[28:29], 13
	s_add_u32 s10, s37, s18
	s_addc_u32 s11, s38, s19
	s_and_b32 s12, s39, 0xe00
	s_lshl_b32 s80, s12, 1
	s_add_u32 s10, s10, s80
	s_addc_u32 s11, s11, 0
	s_add_i32 s43, s92, s40
	s_cmp_lt_i32 s43, 0x10800
	s_cselect_b32 s20, s43, s36
	global_load_dwordx4 v[26:29], v0, s[10:11]
	s_ashr_i32 s10, s20, 3
	s_ashr_i32 s11, s10, 31
	s_lshl_b64 s[12:13], s[10:11], 13
	s_add_u32 s11, s37, s12
	s_addc_u32 s12, s38, s13
	s_lshl_b32 s13, s20, 10
	s_and_b32 s13, s13, 0x1c00
	s_add_u32 s20, s11, s13
	s_addc_u32 s21, s12, 0
	s_mul_hi_i32 s11, s10, 0x6000
	s_mulk_i32 s10, 0x6000
	s_add_u32 s10, s8, s10
	s_addc_u32 s11, s9, s11
	s_add_u32 s22, s10, s13
	v_readlane_b32 s10, v254, 15
	s_addc_u32 s23, s11, 0
	s_add_i32 s42, s10, s40
	s_cmp_lt_i32 s42, 0x10800
	s_cselect_b64 s[12:13], -1, 0
	s_and_b64 s[10:11], s[12:13], exec
	s_cselect_b32 s26, s42, s36
	s_ashr_i32 s10, s26, 3
	s_ashr_i32 s11, s10, 31
	s_lshl_b64 s[24:25], s[10:11], 13
	s_add_u32 s11, s37, s24
	s_addc_u32 s25, s38, s25
	s_lshl_b32 s24, s26, 10
	s_and_b32 s26, s24, 0x1c00
	s_add_u32 s24, s11, s26
	s_addc_u32 s25, s25, 0
	s_mul_hi_i32 s11, s10, 0x6000
	s_mulk_i32 s10, 0x6000
	s_add_u32 s10, s8, s10
	s_addc_u32 s11, s9, s11
	s_add_u32 s26, s10, s26
	s_mul_i32 s41, s88, 24
	s_addc_u32 s27, s11, 0
	s_add_i32 s41, s41, s40
	s_cmp_lt_i32 s41, 0x10800
	s_cselect_b64 s[10:11], -1, 0
	s_and_b64 s[30:31], s[10:11], exec
	s_cselect_b32 s29, s41, s36
	s_ashr_i32 s34, s29, 3
	s_ashr_i32 s35, s34, 31
	s_lshl_b64 s[30:31], s[34:35], 13
	s_add_u32 s30, s37, s30
	s_addc_u32 s31, s38, s31
	s_lshl_b32 s29, s29, 10
	s_and_b32 s29, s29, 0x1c00
	s_add_u32 s30, s30, s29
	s_addc_u32 s31, s31, 0
	s_mul_hi_i32 s35, s34, 0x6000
	s_mulk_i32 s34, 0x6000
	s_add_u32 s34, s8, s34
	global_load_dwordx4 v[22:25], v0, s[20:21]
	v_lshl_add_u64 v[2:3], s[22:23], 0, v[0:1]
	s_mov_b32 s20, 0x13e0c000
	s_addc_u32 s35, s9, s35
	v_add_co_u32_e32 v2, vcc, s20, v2
	s_add_u32 s34, s34, s29
	s_nop 0
	v_addc_co_u32_e32 v3, vcc, 0, v3, vcc
	s_addc_u32 s35, s35, 0
	s_mul_hi_i32 s29, s28, 0x6000
	s_mulk_i32 s28, 0x6000
	global_load_dwordx4 v[18:21], v[2:3], off
	s_waitcnt lgkmcnt(0)
	global_load_dwordx4 v[14:17], v0, s[24:25]
	v_lshl_add_u64 v[2:3], s[26:27], 0, v[0:1]
	s_add_u32 s28, s8, s28
	v_add_co_u32_e32 v2, vcc, s20, v2
	s_addc_u32 s29, s9, s29
	s_nop 0
	v_addc_co_u32_e32 v3, vcc, 0, v3, vcc
	s_add_u32 s28, s28, s80
	global_load_dwordx4 v[10:13], v[2:3], off
	global_load_dwordx4 v[6:9], v0, s[30:31]
	v_lshl_add_u64 v[2:3], s[34:35], 0, v[0:1]
	s_addc_u32 s29, s29, 0
	v_add_co_u32_e32 v2, vcc, s20, v2
	v_lshl_add_u64 v[30:31], s[28:29], 0, v[0:1]
	s_nop 0
	v_addc_co_u32_e32 v3, vcc, 0, v3, vcc
	v_add_co_u32_e32 v30, vcc, s20, v30
	global_load_dwordx4 v[2:5], v[2:3], off
	s_nop 0
	v_addc_co_u32_e32 v31, vcc, 0, v31, vcc
	global_load_dwordx4 v[30:33], v[30:31], off
	s_waitcnt vmcnt(7)
	v_lshlrev_b32_e32 v54, 16, v26
	v_and_b32_e32 v55, 0xffff0000, v26
	v_add_f32_e32 v26, 0, v54
	v_lshlrev_b32_e32 v50, 16, v27
	v_and_b32_e32 v51, 0xffff0000, v27
	v_lshlrev_b32_e32 v48, 16, v28
	v_and_b32_e32 v49, 0xffff0000, v28
	v_lshlrev_b32_e32 v46, 16, v29
	v_and_b32_e32 v47, 0xffff0000, v29
	v_lshl_add_u64 v[36:37], v[34:35], 0, s[80:81]
	v_lshl_add_u64 v[38:39], v[36:37], 0, s[18:19]
	s_cmp_gt_i32 s43, 0x107ff
	s_waitcnt vmcnt(0)
	v_lshlrev_b32_e32 v52, 16, v31
	v_and_b32_e32 v53, 0xffff0000, v31
	v_add_f32_e32 v31, v26, v55
	v_lshlrev_b32_e32 v26, 16, v30
	v_and_b32_e32 v27, 0xffff0000, v30
	v_add_f32_e32 v30, v31, v50
	v_add_f32_e32 v30, v30, v51
	v_add_f32_e32 v30, v30, v48
	v_add_f32_e32 v30, v30, v49
	v_add_f32_e32 v30, v30, v46
	v_add_f32_e32 v30, v30, v47
	v_lshlrev_b32_e32 v28, 16, v32
	v_and_b32_e32 v29, 0xffff0000, v32
	s_waitcnt lgkmcnt(0)
	s_nop 1
	v_add_f32_dpp v30, v30, v30 quad_perm:[1,0,3,2] row_mask:0xf bank_mask:0xf
	s_nop 1
	v_add_f32_dpp v30, v30, v30 quad_perm:[2,3,0,1] row_mask:0xf bank_mask:0xf
	s_nop 1
	v_add_f32_dpp v30, v30, v30 row_half_mirror row_mask:0xf bank_mask:0xf
	s_nop 1
	v_add_f32_dpp v30, v30, v30 row_mirror row_mask:0xf bank_mask:0xf
	s_nop 1
	v_add_f32_dpp v30, v30, v30 row_bcast:15 row_mask:0xa bank_mask:0xf
	s_nop 1
	v_add_f32_dpp v30, v30, v30 row_bcast:31 row_mask:0xc bank_mask:0xf
	s_nop 1
	v_readlane_b32 s100, v30, 63
	s_nop 1
	v_mov_b32_e32 v30, s100
	v_mul_f32_e32 v30, 0x3b000000, v30
	v_pk_add_f32 v[54:55], v[54:55], v[30:31] op_sel_hi:[1,0] neg_lo:[0,1] neg_hi:[0,1]
	v_pk_add_f32 v[50:51], v[50:51], v[30:31] op_sel_hi:[1,0] neg_lo:[0,1] neg_hi:[0,1]
	v_pk_mul_f32 v[56:57], v[54:55], v[54:55]
	v_pk_mul_f32 v[58:59], v[50:51], v[50:51]
	v_add_f32_e32 v32, v56, v57
	v_pk_add_f32 v[48:49], v[48:49], v[30:31] op_sel_hi:[1,0] neg_lo:[0,1] neg_hi:[0,1]
	v_add_f32_e32 v32, v32, v58
	v_pk_mul_f32 v[60:61], v[48:49], v[48:49]
	v_add_f32_e32 v32, v32, v59
	v_pk_add_f32 v[30:31], v[46:47], v[30:31] op_sel_hi:[1,0] neg_lo:[0,1] neg_hi:[0,1]
	v_add_f32_e32 v32, v32, v60
	v_pk_mul_f32 v[46:47], v[30:31], v[30:31]
	v_add_f32_e32 v32, v32, v61
	v_add_f32_e32 v32, v32, v46
	v_add_f32_e32 v32, v32, v47
	s_waitcnt lgkmcnt(0)
; __device__ __forceinline__ float bf_lo(unsigned w) { return __uint_as_float(w << 16); }
; __device__ __forceinline__ float bf_hi(unsigned w) { return __uint_as_float(w & 0xffff0000u); }
; __device__ __forceinline__ unsigned pk2(float lo, float hi) { return pg8::cvt_pk_bf16(lo, hi); }
; __global__ void __launch_bounds__(NTHREADS, 2) hybrid_fwd(Params P) {
;     ...
;                         const float mean = wave_sum(s) * (1.0f / 512.0f);
;                         float q = 0.f;
; #pragma unroll
;                         for (int e = 0; e < 8; ++e) { v[e] -= mean; q += v[e] * v[e]; }
;                         const float rstd = rsqrtf(wave_sum(q) * (1.0f / 512.0f) + EPSN);
;                         u32x4 w; w.x = pk2(v[0] * rstd * bf_lo(gq.x), v[1] * rstd * bf_hi(gq.x)); w.y = pk2(v[2] * rstd * bf_lo(gq.y), v[3] * rstd * bf_hi(gq.y));
;                         w.z = pk2(v[4] * rstd * bf_lo(gq.z), v[5] * rstd * bf_hi(gq.z)); w.w = pk2(v[6] * rstd * bf_lo(gq.w), v[7] * rstd * bf_hi(gq.w));
;                         if (it < T_ALL * 8) *(u32x4*)(MIX + tok * 4096 + h * 512 + 8 * lane) = w;
	s_nop 1
	v_add_f32_dpp v32, v32, v32 quad_perm:[1,0,3,2] row_mask:0xf bank_mask:0xf
	s_nop 1
	v_add_f32_dpp v32, v32, v32 quad_perm:[2,3,0,1] row_mask:0xf bank_mask:0xf
	s_nop 1
	v_add_f32_dpp v32, v32, v32 row_half_mirror row_mask:0xf bank_mask:0xf
	s_nop 1
	v_add_f32_dpp v32, v32, v32 row_mirror row_mask:0xf bank_mask:0xf
	s_nop 1
	v_add_f32_dpp v32, v32, v32 row_bcast:15 row_mask:0xa bank_mask:0xf
	s_nop 1
	v_add_f32_dpp v32, v32, v32 row_bcast:31 row_mask:0xc bank_mask:0xf
	s_nop 1
	v_readlane_b32 s100, v32, 63
	s_nop 1
	v_mov_b32_e32 v32, s100
	v_fmamk_f32 v32, v32, 0x3b000000, v138
	v_cmp_gt_f32_e32 vcc, s59, v32
	v_mul_f32_e32 v46, 0x4b800000, v32
	s_nop 0
	v_cndmask_b32_e32 v32, v32, v46, vcc
	v_rsq_f32_e32 v32, v32
	s_nop 0
	v_mul_f32_e32 v46, 0x45800000, v32
	v_cndmask_b32_e32 v32, v32, v46, vcc
	v_pk_mul_f32 v[46:47], v[54:55], v[32:33] op_sel_hi:[1,0]
	v_pk_mul_f32 v[30:31], v[30:31], v[32:33] op_sel_hi:[1,0]
	v_pk_mul_f32 v[26:27], v[46:47], v[26:27]
	v_pk_mul_f32 v[46:47], v[50:51], v[32:33] op_sel_hi:[1,0]
	v_cvt_pk_bf16_f32 v26, v26, v27
	v_pk_mul_f32 v[46:47], v[46:47], v[52:53]
	s_nop 0
	v_cvt_pk_bf16_f32 v27, v46, v47
	v_pk_mul_f32 v[46:47], v[48:49], v[32:33] op_sel_hi:[1,0]
	v_lshlrev_b32_e32 v32, 16, v33
	v_and_b32_e32 v33, 0xffff0000, v33
	v_pk_mul_f32 v[28:29], v[46:47], v[28:29]
	v_pk_mul_f32 v[30:31], v[30:31], v[32:33]
	v_cvt_pk_bf16_f32 v28, v28, v29
	v_cvt_pk_bf16_f32 v29, v30, v31
	global_store_dwordx4 v[38:39], v[26:29], off
	v_lshlrev_b32_e32 v32, 16, v24
	v_and_b32_e32 v33, 0xffff0000, v24
	v_lshlrev_b32_e32 v26, 16, v22
	v_and_b32_e32 v27, 0xffff0000, v22
	v_add_f32_e32 v22, 0, v26
	v_lshlrev_b32_e32 v24, 16, v23
	v_add_f32_e32 v22, v22, v27
	v_lshlrev_b32_e32 v30, 16, v25
	v_and_b32_e32 v31, 0xffff0000, v25
	v_and_b32_e32 v25, 0xffff0000, v23
	v_add_f32_e32 v22, v22, v24
	v_add_f32_e32 v22, v22, v25
	v_add_f32_e32 v22, v22, v32
	v_add_f32_e32 v22, v22, v33
	v_add_f32_e32 v22, v22, v30
	v_add_f32_e32 v22, v22, v31
	s_waitcnt lgkmcnt(0)
	s_nop 1
	v_add_f32_dpp v22, v22, v22 quad_perm:[1,0,3,2] row_mask:0xf bank_mask:0xf
	s_nop 1
	v_add_f32_dpp v22, v22, v22 quad_perm:[2,3,0,1] row_mask:0xf bank_mask:0xf
	s_nop 1
	v_add_f32_dpp v22, v22, v22 row_half_mirror row_mask:0xf bank_mask:0xf
	s_nop 1
	v_add_f32_dpp v22, v22, v22 row_mirror row_mask:0xf bank_mask:0xf
	s_nop 1
	v_add_f32_dpp v22, v22, v22 row_bcast:15 row_mask:0xa bank_mask:0xf
	s_nop 1
	v_add_f32_dpp v22, v22, v22 row_bcast:31 row_mask:0xc bank_mask:0xf
	s_nop 1
	v_readlane_b32 s100, v22, 63
	s_nop 1
	v_mov_b32_e32 v22, s100
	v_mul_f32_e32 v22, 0x3b000000, v22
	v_pk_add_f32 v[28:29], v[26:27], v[22:23] op_sel_hi:[1,0] neg_lo:[0,1] neg_hi:[0,1]
	v_pk_add_f32 v[26:27], v[24:25], v[22:23] op_sel_hi:[1,0] neg_lo:[0,1] neg_hi:[0,1]
	v_pk_mul_f32 v[38:39], v[28:29], v[28:29]
	v_pk_mul_f32 v[46:47], v[26:27], v[26:27]
	v_add_f32_e32 v38, v38, v39
	v_pk_add_f32 v[24:25], v[32:33], v[22:23] op_sel_hi:[1,0] neg_lo:[0,1] neg_hi:[0,1]
	v_add_f32_e32 v38, v38, v46
	v_pk_mul_f32 v[32:33], v[24:25], v[24:25]
	v_add_f32_e32 v38, v38, v47
	v_pk_add_f32 v[22:23], v[30:31], v[22:23] op_sel_hi:[1,0] neg_lo:[0,1] neg_hi:[0,1]
	v_add_f32_e32 v32, v38, v32
	v_pk_mul_f32 v[30:31], v[22:23], v[22:23]
	v_add_f32_e32 v32, v32, v33
	v_add_f32_e32 v30, v32, v30
	v_add_f32_e32 v30, v30, v31
	ds_bpermute_b32 v31, v40, v30
	s_waitcnt lgkmcnt(0)
	v_add_f32_e32 v30, v30, v31
	ds_bpermute_b32 v31, v41, v30
	s_waitcnt lgkmcnt(0)
	v_add_f32_e32 v30, v30, v31
	ds_bpermute_b32 v31, v42, v30
	s_waitcnt lgkmcnt(0)
	v_add_f32_e32 v30, v30, v31
	ds_bpermute_b32 v31, v43, v30
	s_waitcnt lgkmcnt(0)
	v_add_f32_e32 v30, v30, v31
	ds_bpermute_b32 v31, v44, v30
	s_waitcnt lgkmcnt(0)
	v_add_f32_e32 v30, v30, v31
	ds_bpermute_b32 v31, v45, v30
	s_cbranch_scc1 .LBB0_480
	s_waitcnt lgkmcnt(0)
	v_add_f32_e32 v30, v30, v31
	v_fmamk_f32 v30, v30, 0x3b000000, v138
	v_cmp_gt_f32_e32 vcc, s59, v30
	v_mul_f32_e32 v31, 0x4b800000, v30
	v_lshlrev_b32_e32 v38, 16, v18
	v_cndmask_b32_e32 v30, v30, v31, vcc
	v_rsq_f32_e32 v30, v30
	v_and_b32_e32 v39, 0xffff0000, v18
	s_ashr_i32 s18, s43, 3
	s_ashr_i32 s19, s18, 31
	v_mul_f32_e32 v31, 0x45800000, v30
	v_cndmask_b32_e32 v30, v30, v31, vcc
	v_pk_mul_f32 v[28:29], v[28:29], v[30:31] op_sel_hi:[1,0]
	v_pk_mul_f32 v[26:27], v[26:27], v[30:31] op_sel_hi:[1,0]
	v_pk_mul_f32 v[28:29], v[28:29], v[38:39]
	v_pk_mul_f32 v[24:25], v[24:25], v[30:31] op_sel_hi:[1,0]
	v_cvt_pk_bf16_f32 v18, v28, v29
	v_lshlrev_b32_e32 v28, 16, v19
	v_and_b32_e32 v29, 0xffff0000, v19
	v_pk_mul_f32 v[26:27], v[26:27], v[28:29]
	v_pk_mul_f32 v[22:23], v[22:23], v[30:31] op_sel_hi:[1,0]
	v_cvt_pk_bf16_f32 v19, v26, v27
	v_lshlrev_b32_e32 v26, 16, v20
	v_and_b32_e32 v27, 0xffff0000, v20
	v_pk_mul_f32 v[24:25], v[24:25], v[26:27]
	s_lshl_b64 s[18:19], s[18:19], 13
	v_cvt_pk_bf16_f32 v20, v24, v25
	v_lshlrev_b32_e32 v24, 16, v21
	v_and_b32_e32 v25, 0xffff0000, v21
	v_pk_mul_f32 v[22:23], v[22:23], v[24:25]
	v_lshl_add_u64 v[32:33], v[36:37], 0, s[18:19]
	v_cvt_pk_bf16_f32 v21, v22, v23
	global_store_dwordx4 v[32:33], v[18:21], off
; __device__ __forceinline__ float bf_lo(unsigned w) { return __uint_as_float(w << 16); }
; __device__ __forceinline__ float bf_hi(unsigned w) { return __uint_as_float(w & 0xffff0000u); }
; __device__ __forceinline__ unsigned pk2(float lo, float hi) { return pg8::cvt_pk_bf16(lo, hi); }
; __global__ void __launch_bounds__(NTHREADS, 2) hybrid_fwd(Params P) {
;     ...
;                     for (int r = 0; r < 4; ++r) {
;                         const int it = it0 + r * NGW;
;                         const int h = it & 7; const size_t tok = it >> 3;
;                         const u32x4 a = av[r], gq = gv[r];
;                         float v[8] = {bf_lo(a.x), bf_hi(a.x), bf_lo(a.y), bf_hi(a.y), bf_lo(a.z), bf_hi(a.z), bf_lo(a.w), bf_hi(a.w)};
;                         float s = 0.f;
; #pragma unroll
;                         for (int e = 0; e < 8; ++e) s += v[e];
;                         const float mean = wave_sum(s) * (1.0f / 512.0f);
;                         float q = 0.f;
; #pragma unroll
;                         for (int e = 0; e < 8; ++e) { v[e] -= mean; q += v[e] * v[e]; }
;                         const float rstd = rsqrtf(wave_sum(q) * (1.0f / 512.0f) + EPSN);
;                         u32x4 w; w.x = pk2(v[0] * rstd * bf_lo(gq.x), v[1] * rstd * bf_hi(gq.x)); w.y = pk2(v[2] * rstd * bf_lo(gq.y), v[3] * rstd * bf_hi(gq.y));
;                         w.z = pk2(v[4] * rstd * bf_lo(gq.z), v[5] * rstd * bf_hi(gq.z)); w.w = pk2(v[6] * rstd * bf_lo(gq.w), v[7] * rstd * bf_hi(gq.w));
;                         if (it < T_ALL * 8) *(u32x4*)(MIX + tok * 4096 + h * 512 + 8 * lane) = w;
.LBB0_480:
	s_nop 1
	v_lshlrev_b32_e32 v18, 16, v14
	v_and_b32_e32 v19, 0xffff0000, v14
	v_lshlrev_b32_e32 v22, 16, v16
	v_and_b32_e32 v23, 0xffff0000, v16
	v_add_f32_e32 v16, 0, v18
	v_lshlrev_b32_e32 v14, 16, v15
	v_add_f32_e32 v16, v16, v19
	v_and_b32_e32 v15, 0xffff0000, v15
	v_add_f32_e32 v16, v16, v14
	v_add_f32_e32 v16, v16, v15
	v_add_f32_e32 v16, v16, v22
	v_lshlrev_b32_e32 v24, 16, v17
	v_add_f32_e32 v16, v16, v23
	v_and_b32_e32 v25, 0xffff0000, v17
	v_add_f32_e32 v16, v16, v24
	v_add_f32_e32 v16, v16, v25
	s_andn2_b64 vcc, exec, s[12:13]
	s_waitcnt lgkmcnt(0)
	s_nop 1
	v_add_f32_dpp v16, v16, v16 quad_perm:[1,0,3,2] row_mask:0xf bank_mask:0xf
	s_nop 1
	v_add_f32_dpp v16, v16, v16 quad_perm:[2,3,0,1] row_mask:0xf bank_mask:0xf
	s_nop 1
	v_add_f32_dpp v16, v16, v16 row_half_mirror row_mask:0xf bank_mask:0xf
	s_nop 1
	v_add_f32_dpp v16, v16, v16 row_mirror row_mask:0xf bank_mask:0xf
	s_nop 1
	v_add_f32_dpp v16, v16, v16 row_bcast:15 row_mask:0xa bank_mask:0xf
	s_nop 1
	v_add_f32_dpp v16, v16, v16 row_bcast:31 row_mask:0xc bank_mask:0xf
	s_nop 1
	v_readlane_b32 s100, v16, 63
	s_nop 1
	v_mov_b32_e32 v16, s100
	v_mul_f32_e32 v26, 0x3b000000, v16
	v_pk_add_f32 v[20:21], v[18:19], v[26:27] op_sel_hi:[1,0] neg_lo:[0,1] neg_hi:[0,1]
	v_pk_add_f32 v[18:19], v[14:15], v[26:27] op_sel_hi:[1,0] neg_lo:[0,1] neg_hi:[0,1]
	v_pk_add_f32 v[16:17], v[22:23], v[26:27] op_sel_hi:[1,0] neg_lo:[0,1] neg_hi:[0,1]
	v_pk_mul_f32 v[22:23], v[20:21], v[20:21]
	v_pk_add_f32 v[14:15], v[24:25], v[26:27] op_sel_hi:[1,0] neg_lo:[0,1] neg_hi:[0,1]
	v_pk_mul_f32 v[24:25], v[18:19], v[18:19]
	v_add_f32_e32 v22, v22, v23
	v_add_f32_e32 v22, v22, v24
	v_pk_mul_f32 v[26:27], v[16:17], v[16:17]
	v_add_f32_e32 v22, v22, v25
	v_add_f32_e32 v22, v22, v26
	v_pk_mul_f32 v[28:29], v[14:15], v[14:15]
	v_add_f32_e32 v22, v22, v27
	v_add_f32_e32 v22, v22, v28
	v_add_f32_e32 v22, v22, v29
	ds_bpermute_b32 v23, v40, v22
	s_waitcnt lgkmcnt(0)
	v_add_f32_e32 v22, v22, v23
	ds_bpermute_b32 v23, v41, v22
	s_waitcnt lgkmcnt(0)
	v_add_f32_e32 v22, v22, v23
	ds_bpermute_b32 v23, v42, v22
	s_waitcnt lgkmcnt(0)
	v_add_f32_e32 v22, v22, v23
	ds_bpermute_b32 v23, v43, v22
	s_waitcnt lgkmcnt(0)
	v_add_f32_e32 v22, v22, v23
	ds_bpermute_b32 v23, v44, v22
	s_waitcnt lgkmcnt(0)
	v_add_f32_e32 v22, v22, v23
	ds_bpermute_b32 v23, v45, v22
	s_cbranch_vccnz .LBB0_482
	s_waitcnt lgkmcnt(0)
	v_add_f32_e32 v22, v22, v23
	v_fmamk_f32 v22, v22, 0x3b000000, v138
	v_cmp_gt_f32_e32 vcc, s59, v22
	v_mul_f32_e32 v23, 0x4b800000, v22
	v_lshlrev_b32_e32 v26, 16, v10
	v_cndmask_b32_e32 v22, v22, v23, vcc
	v_rsq_f32_e32 v22, v22
	v_and_b32_e32 v27, 0xffff0000, v10
	s_ashr_i32 s12, s42, 3
	s_ashr_i32 s13, s12, 31
	v_mul_f32_e32 v23, 0x45800000, v22
	v_cndmask_b32_e32 v22, v22, v23, vcc
	v_pk_mul_f32 v[20:21], v[20:21], v[22:23] op_sel_hi:[1,0]
	v_pk_mul_f32 v[18:19], v[18:19], v[22:23] op_sel_hi:[1,0]
	v_pk_mul_f32 v[20:21], v[20:21], v[26:27]
	v_pk_mul_f32 v[16:17], v[16:17], v[22:23] op_sel_hi:[1,0]
	v_cvt_pk_bf16_f32 v10, v20, v21
	v_lshlrev_b32_e32 v20, 16, v11
	v_and_b32_e32 v21, 0xffff0000, v11
	v_pk_mul_f32 v[18:19], v[18:19], v[20:21]
	v_pk_mul_f32 v[14:15], v[14:15], v[22:23] op_sel_hi:[1,0]
	v_cvt_pk_bf16_f32 v11, v18, v19
	v_lshlrev_b32_e32 v18, 16, v12
	v_and_b32_e32 v19, 0xffff0000, v12
	v_pk_mul_f32 v[16:17], v[16:17], v[18:19]
	s_lshl_b64 s[12:13], s[12:13], 13
	v_cvt_pk_bf16_f32 v12, v16, v17
	v_lshlrev_b32_e32 v16, 16, v13
	v_and_b32_e32 v17, 0xffff0000, v13
	v_pk_mul_f32 v[14:15], v[14:15], v[16:17]
	v_lshl_add_u64 v[24:25], v[36:37], 0, s[12:13]
	v_cvt_pk_bf16_f32 v13, v14, v15
	global_store_dwordx4 v[24:25], v[10:13], off
; __device__ __forceinline__ float bf_lo(unsigned w) { return __uint_as_float(w << 16); }
; __device__ __forceinline__ float bf_hi(unsigned w) { return __uint_as_float(w & 0xffff0000u); }
; __device__ __forceinline__ unsigned pk2(float lo, float hi) { return pg8::cvt_pk_bf16(lo, hi); }
; __global__ void __launch_bounds__(NTHREADS, 2) hybrid_fwd(Params P) {
;     ...
;                     for (int r = 0; r < 4; ++r) {
;                         const int it = it0 + r * NGW;
;                         const int h = it & 7; const size_t tok = it >> 3;
;                         const u32x4 a = av[r], gq = gv[r];
;                         float v[8] = {bf_lo(a.x), bf_hi(a.x), bf_lo(a.y), bf_hi(a.y), bf_lo(a.z), bf_hi(a.z), bf_lo(a.w), bf_hi(a.w)};
;                         float s = 0.f;
; #pragma unroll
;                         for (int e = 0; e < 8; ++e) s += v[e];
;                         const float mean = wave_sum(s) * (1.0f / 512.0f);
;                         float q = 0.f;
; #pragma unroll
;                         for (int e = 0; e < 8; ++e) { v[e] -= mean; q += v[e] * v[e]; }
;                         const float rstd = rsqrtf(wave_sum(q) * (1.0f / 512.0f) + EPSN);
;                         u32x4 w; w.x = pk2(v[0] * rstd * bf_lo(gq.x), v[1] * rstd * bf_hi(gq.x)); w.y = pk2(v[2] * rstd * bf_lo(gq.y), v[3] * rstd * bf_hi(gq.y));
;                         w.z = pk2(v[4] * rstd * bf_lo(gq.z), v[5] * rstd * bf_hi(gq.z)); w.w = pk2(v[6] * rstd * bf_lo(gq.w), v[7] * rstd * bf_hi(gq.w));
;                         if (it < T_ALL * 8) *(u32x4*)(MIX + tok * 4096 + h * 512 + 8 * lane) = w;
.LBB0_482:
	s_nop 1
	v_lshlrev_b32_e32 v10, 16, v6
	v_and_b32_e32 v11, 0xffff0000, v6
	v_lshlrev_b32_e32 v14, 16, v8
	v_and_b32_e32 v15, 0xffff0000, v8
	v_add_f32_e32 v8, 0, v10
	v_lshlrev_b32_e32 v6, 16, v7
	v_add_f32_e32 v8, v8, v11
	v_and_b32_e32 v7, 0xffff0000, v7
	v_add_f32_e32 v8, v8, v6
	v_add_f32_e32 v8, v8, v7
	v_add_f32_e32 v8, v8, v14
	v_lshlrev_b32_e32 v16, 16, v9
	v_add_f32_e32 v8, v8, v15
	v_and_b32_e32 v17, 0xffff0000, v9
	v_add_f32_e32 v8, v8, v16
	v_add_f32_e32 v8, v8, v17
	s_andn2_b64 vcc, exec, s[10:11]
	s_waitcnt lgkmcnt(0)
	s_nop 1
	v_add_f32_dpp v8, v8, v8 quad_perm:[1,0,3,2] row_mask:0xf bank_mask:0xf
	s_nop 1
	v_add_f32_dpp v8, v8, v8 quad_perm:[2,3,0,1] row_mask:0xf bank_mask:0xf
	s_nop 1
	v_add_f32_dpp v8, v8, v8 row_half_mirror row_mask:0xf bank_mask:0xf
	s_nop 1
	v_add_f32_dpp v8, v8, v8 row_mirror row_mask:0xf bank_mask:0xf
	s_nop 1
	v_add_f32_dpp v8, v8, v8 row_bcast:15 row_mask:0xa bank_mask:0xf
	s_nop 1
	v_add_f32_dpp v8, v8, v8 row_bcast:31 row_mask:0xc bank_mask:0xf
	s_nop 1
	v_readlane_b32 s100, v8, 63
	s_nop 1
	v_mov_b32_e32 v8, s100
	v_mul_f32_e32 v18, 0x3b000000, v8
	v_pk_add_f32 v[12:13], v[10:11], v[18:19] op_sel_hi:[1,0] neg_lo:[0,1] neg_hi:[0,1]
	v_pk_add_f32 v[10:11], v[6:7], v[18:19] op_sel_hi:[1,0] neg_lo:[0,1] neg_hi:[0,1]
	v_pk_add_f32 v[8:9], v[14:15], v[18:19] op_sel_hi:[1,0] neg_lo:[0,1] neg_hi:[0,1]
	v_pk_mul_f32 v[14:15], v[12:13], v[12:13]
	v_pk_add_f32 v[6:7], v[16:17], v[18:19] op_sel_hi:[1,0] neg_lo:[0,1] neg_hi:[0,1]
	v_pk_mul_f32 v[16:17], v[10:11], v[10:11]
	v_add_f32_e32 v14, v14, v15
	v_add_f32_e32 v14, v14, v16
	v_pk_mul_f32 v[18:19], v[8:9], v[8:9]
	v_add_f32_e32 v14, v14, v17
	v_add_f32_e32 v14, v14, v18
	v_pk_mul_f32 v[20:21], v[6:7], v[6:7]
	v_add_f32_e32 v14, v14, v19
	v_add_f32_e32 v14, v14, v20
	v_add_f32_e32 v14, v14, v21
	ds_bpermute_b32 v15, v40, v14
	s_waitcnt lgkmcnt(0)
	v_add_f32_e32 v14, v14, v15
	ds_bpermute_b32 v15, v41, v14
	s_waitcnt lgkmcnt(0)
	v_add_f32_e32 v14, v14, v15
	ds_bpermute_b32 v15, v42, v14
	s_waitcnt lgkmcnt(0)
	v_add_f32_e32 v14, v14, v15
	ds_bpermute_b32 v15, v43, v14
	s_waitcnt lgkmcnt(0)
	v_add_f32_e32 v14, v14, v15
	ds_bpermute_b32 v15, v44, v14
	s_waitcnt lgkmcnt(0)
	v_add_f32_e32 v14, v14, v15
	ds_bpermute_b32 v15, v45, v14
	s_cbranch_vccnz .LBB0_477
	s_waitcnt lgkmcnt(0)
	v_add_f32_e32 v14, v14, v15
	v_fmamk_f32 v14, v14, 0x3b000000, v138
	v_cmp_gt_f32_e32 vcc, s59, v14
	v_mul_f32_e32 v15, 0x4b800000, v14
	v_lshlrev_b32_e32 v18, 16, v2
	v_cndmask_b32_e32 v14, v14, v15, vcc
	v_rsq_f32_e32 v14, v14
	v_and_b32_e32 v19, 0xffff0000, v2
	s_ashr_i32 s10, s41, 3
	s_ashr_i32 s11, s10, 31
	v_mul_f32_e32 v15, 0x45800000, v14
	v_cndmask_b32_e32 v14, v14, v15, vcc
	v_pk_mul_f32 v[12:13], v[12:13], v[14:15] op_sel_hi:[1,0]
	v_pk_mul_f32 v[10:11], v[10:11], v[14:15] op_sel_hi:[1,0]
	v_pk_mul_f32 v[12:13], v[12:13], v[18:19]
	v_pk_mul_f32 v[8:9], v[8:9], v[14:15] op_sel_hi:[1,0]
	v_cvt_pk_bf16_f32 v2, v12, v13
	v_lshlrev_b32_e32 v12, 16, v3
	v_and_b32_e32 v13, 0xffff0000, v3
	v_pk_mul_f32 v[10:11], v[10:11], v[12:13]
	v_pk_mul_f32 v[6:7], v[6:7], v[14:15] op_sel_hi:[1,0]
	v_cvt_pk_bf16_f32 v3, v10, v11
	v_lshlrev_b32_e32 v10, 16, v4
	v_and_b32_e32 v11, 0xffff0000, v4
	v_pk_mul_f32 v[8:9], v[8:9], v[10:11]
	s_lshl_b64 s[10:11], s[10:11], 13
	v_cvt_pk_bf16_f32 v4, v8, v9
	v_lshlrev_b32_e32 v8, 16, v5
	v_and_b32_e32 v9, 0xffff0000, v5
	v_pk_mul_f32 v[6:7], v[6:7], v[8:9]
	v_lshl_add_u64 v[16:17], v[36:37], 0, s[10:11]
	v_cvt_pk_bf16_f32 v5, v6, v7
	global_store_dwordx4 v[16:17], v[2:5], off
	s_branch .LBB0_477

; __device__ __forceinline__ float bf_lo(unsigned w) { return __uint_as_float(w << 16); }
; __device__ __forceinline__ float bf_hi(unsigned w) { return __uint_as_float(w & 0xffff0000u); }
; __device__ __forceinline__ void gate_prompt_item(LAS unsigned char* lds, const bf16_t* z, bf16_t* mix, const float* w_s, const float* b_s,
;                                                  const float* lnv_g, const float* lnv_b, int item, int tid) {
;     ...
;     for (int r = 0; r < 16; ++r) {
;         const int row = 16 * wave + r;
;         const bf16_t* vp = z + (tok0 + row) * EIN + 3328 + lane * 16;
;         const u32x4 a = *(const u32x4*)vp, c = *(const u32x4*)(vp + 8);
;         float v[16] = {bf_lo(a.x), bf_hi(a.x), bf_lo(a.y), bf_hi(a.y), bf_lo(a.z), bf_hi(a.z), bf_lo(a.w), bf_hi(a.w),
;                        bf_lo(c.x), bf_hi(c.x), bf_lo(c.y), bf_hi(c.y), bf_lo(c.z), bf_hi(c.z), bf_lo(c.w), bf_hi(c.w)};
;         float s = 0.f;
; #pragma unroll
;         for (int e = 0; e < 16; ++e) s += v[e];
;         const float mean = wave_sum(s) * (1.0f / 1024.0f);
;         float q = 0.f;
; #pragma unroll
;         for (int e = 0; e < 16; ++e) { const float d = v[e] - mean; q += d * d; }
;         const float rstd = rsqrtf(wave_sum(q) * (1.0f / 1024.0f) + EPSN);
;         if (lane == 0) { stat[row * 2] = mean; stat[row * 2 + 1] = rstd; }
;     }
.LBB0_909:
	v_lshl_add_u64 v[4:5], v[2:3], 0, s[84:85]
	s_waitcnt lgkmcnt(0)
	v_add_co_u32_e32 v6, vcc, 0x13e09000, v4
	s_mov_b64 s[8:9], 0x13e09a00
	s_nop 0
	v_addc_co_u32_e32 v7, vcc, 0, v5, vcc
	global_load_dwordx4 v[6:9], v[6:7], off offset:2560
	v_lshl_add_u64 v[10:11], v[4:5], 0, s[8:9]
	global_load_dwordx4 v[10:13], v[10:11], off offset:16
	s_waitcnt vmcnt(1)
	v_lshlrev_b32_e32 v14, 16, v6
	v_and_b32_e32 v15, 0xffff0000, v6
	v_add_f32_e32 v6, 0, v14
	v_lshlrev_b32_e32 v16, 16, v7
	v_add_f32_e32 v6, v6, v15
	v_and_b32_e32 v7, 0xffff0000, v7
	v_add_f32_e32 v6, v6, v16
	v_lshlrev_b32_e32 v17, 16, v8
	v_add_f32_e32 v6, v6, v7
	v_and_b32_e32 v8, 0xffff0000, v8
	v_add_f32_e32 v6, v6, v17
	v_lshlrev_b32_e32 v18, 16, v9
	v_add_f32_e32 v6, v6, v8
	v_and_b32_e32 v9, 0xffff0000, v9
	v_add_f32_e32 v6, v6, v18
	s_waitcnt vmcnt(0)
	v_lshlrev_b32_e32 v19, 16, v10
	v_add_f32_e32 v6, v6, v9
	v_and_b32_e32 v10, 0xffff0000, v10
	v_add_f32_e32 v6, v6, v19
	v_lshlrev_b32_e32 v20, 16, v11
	v_add_f32_e32 v6, v6, v10
	v_and_b32_e32 v11, 0xffff0000, v11
	v_add_f32_e32 v6, v6, v20
	v_lshlrev_b32_e32 v21, 16, v12
	v_add_f32_e32 v6, v6, v11
	v_and_b32_e32 v12, 0xffff0000, v12
	v_add_f32_e32 v6, v6, v21
	v_lshlrev_b32_e32 v22, 16, v13
	v_add_f32_e32 v6, v6, v12
	v_and_b32_e32 v13, 0xffff0000, v13
	v_add_f32_e32 v6, v6, v22
	v_add_f32_e32 v6, v6, v13
	s_waitcnt lgkmcnt(0)
	s_nop 1
	v_add_f32_dpp v6, v6, v6 quad_perm:[1,0,3,2] row_mask:0xf bank_mask:0xf
	s_nop 1
	v_add_f32_dpp v6, v6, v6 quad_perm:[2,3,0,1] row_mask:0xf bank_mask:0xf
	s_nop 1
	v_add_f32_dpp v6, v6, v6 row_half_mirror row_mask:0xf bank_mask:0xf
	s_nop 1
	v_add_f32_dpp v6, v6, v6 row_mirror row_mask:0xf bank_mask:0xf
	s_nop 1
	v_add_f32_dpp v6, v6, v6 row_bcast:15 row_mask:0xa bank_mask:0xf
	s_nop 1
	v_add_f32_dpp v6, v6, v6 row_bcast:31 row_mask:0xc bank_mask:0xf
	s_nop 1
	v_readlane_b32 s100, v6, 63
	s_nop 1
	v_mov_b32_e32 v6, s100
	v_fmac_f32_e32 v15, 0xba800000, v6
	v_fmac_f32_e32 v14, 0xba800000, v6
	v_mul_f32_e32 v15, v15, v15
	v_fmac_f32_e32 v16, 0xba800000, v6
	v_fmac_f32_e32 v15, v14, v14
	v_fmac_f32_e32 v7, 0xba800000, v6
	v_fmac_f32_e32 v15, v16, v16
	v_fmac_f32_e32 v17, 0xba800000, v6
	v_fmac_f32_e32 v15, v7, v7
	v_fmac_f32_e32 v8, 0xba800000, v6
	v_fmac_f32_e32 v15, v17, v17
	v_fmac_f32_e32 v18, 0xba800000, v6
	v_fmac_f32_e32 v15, v8, v8
	v_fmac_f32_e32 v9, 0xba800000, v6
	v_fmac_f32_e32 v15, v18, v18
	v_fmac_f32_e32 v19, 0xba800000, v6
	v_fmac_f32_e32 v15, v9, v9
	v_fmac_f32_e32 v10, 0xba800000, v6
	v_fmac_f32_e32 v15, v19, v19
	v_fmac_f32_e32 v20, 0xba800000, v6
	v_fmac_f32_e32 v15, v10, v10
	v_fmac_f32_e32 v11, 0xba800000, v6
	v_fmac_f32_e32 v15, v20, v20
	v_fmac_f32_e32 v21, 0xba800000, v6
	v_fmac_f32_e32 v15, v11, v11
	v_fmac_f32_e32 v12, 0xba800000, v6
	v_fmac_f32_e32 v15, v21, v21
	v_fmac_f32_e32 v22, 0xba800000, v6
	v_fmac_f32_e32 v15, v12, v12
	v_fmac_f32_e32 v15, v22, v22
	v_fmac_f32_e32 v13, 0xba800000, v6
	v_fmac_f32_e32 v15, v13, v13
	ds_bpermute_b32 v7, v47, v15
	s_waitcnt lgkmcnt(0)
	v_add_f32_e32 v7, v15, v7
	ds_bpermute_b32 v8, v120, v7
	s_waitcnt lgkmcnt(0)
	v_add_f32_e32 v7, v7, v8
	ds_bpermute_b32 v8, v121, v7
	s_waitcnt lgkmcnt(0)
	v_add_f32_e32 v7, v7, v8
	ds_bpermute_b32 v8, v122, v7
	s_waitcnt lgkmcnt(0)
	v_add_f32_e32 v7, v7, v8
	ds_bpermute_b32 v8, v123, v7
	s_waitcnt lgkmcnt(0)
	v_add_f32_e32 v7, v7, v8
	ds_bpermute_b32 v8, v124, v7
	s_and_saveexec_b64 s[8:9], s[4:5]
	s_cbranch_execz .LBB0_911
	s_waitcnt lgkmcnt(0)
	v_add_f32_e32 v7, v7, v8
	v_fmamk_f32 v7, v7, 0x3a800000, v138
	v_mul_f32_e32 v8, 0x4b800000, v7
	v_cmp_gt_f32_e32 vcc, s59, v7
	v_mul_f32_e32 v6, 0x3a800000, v6
	s_nop 0
	v_cndmask_b32_e32 v7, v7, v8, vcc
	v_rsq_f32_e32 v7, v7
	s_nop 0
	v_mul_f32_e32 v8, 0x45800000, v7
	v_cndmask_b32_e32 v7, v7, v8, vcc
	ds_write_b64 v0, v[6:7]
; __device__ __forceinline__ float bf_lo(unsigned w) { return __uint_as_float(w << 16); }
; __device__ __forceinline__ float bf_hi(unsigned w) { return __uint_as_float(w & 0xffff0000u); }
; __device__ __forceinline__ void gate_prompt_item(LAS unsigned char* lds, const bf16_t* z, bf16_t* mix, const float* w_s, const float* b_s,
;                                                  const float* lnv_g, const float* lnv_b, int item, int tid) {
;     ...
;     for (int r = 0; r < 16; ++r) {
;         const int row = 16 * wave + r;
;         const bf16_t* vp = z + (tok0 + row) * EIN + 3328 + lane * 16;
;         const u32x4 a = *(const u32x4*)vp, c = *(const u32x4*)(vp + 8);
;         float v[16] = {bf_lo(a.x), bf_hi(a.x), bf_lo(a.y), bf_hi(a.y), bf_lo(a.z), bf_hi(a.z), bf_lo(a.w), bf_hi(a.w),
;                        bf_lo(c.x), bf_hi(c.x), bf_lo(c.y), bf_hi(c.y), bf_lo(c.z), bf_hi(c.z), bf_lo(c.w), bf_hi(c.w)};
;         float s = 0.f;
; #pragma unroll
;         for (int e = 0; e < 16; ++e) s += v[e];
;         const float mean = wave_sum(s) * (1.0f / 1024.0f);
;         float q = 0.f;
; #pragma unroll
;         for (int e = 0; e < 16; ++e) { const float d = v[e] - mean; q += d * d; }
;         const float rstd = rsqrtf(wave_sum(q) * (1.0f / 1024.0f) + EPSN);
;         if (lane == 0) { stat[row * 2] = mean; stat[row * 2 + 1] = rstd; }
;     }
.LBB0_911:
	s_or_b64 exec, exec, s[8:9]
	v_add_co_u32_e32 v6, vcc, 0x13e0c000, v4
	s_mov_b64 s[8:9], 0x13e0c400
	s_nop 0
	v_addc_co_u32_e32 v7, vcc, 0, v5, vcc
	s_waitcnt lgkmcnt(0)
	global_load_dwordx4 v[6:9], v[6:7], off offset:1024
	v_lshl_add_u64 v[4:5], v[4:5], 0, s[8:9]
	global_load_dwordx4 v[10:13], v[4:5], off offset:16
	s_waitcnt vmcnt(1)
	v_lshlrev_b32_e32 v5, 16, v6
	v_and_b32_e32 v6, 0xffff0000, v6
	v_add_f32_e32 v4, 0, v5
	v_lshlrev_b32_e32 v14, 16, v7
	v_add_f32_e32 v4, v4, v6
	v_and_b32_e32 v7, 0xffff0000, v7
	v_add_f32_e32 v4, v4, v14
	v_lshlrev_b32_e32 v15, 16, v8
	v_add_f32_e32 v4, v4, v7
	v_and_b32_e32 v8, 0xffff0000, v8
	v_add_f32_e32 v4, v4, v15
	v_lshlrev_b32_e32 v16, 16, v9
	v_add_f32_e32 v4, v4, v8
	v_and_b32_e32 v9, 0xffff0000, v9
	v_add_f32_e32 v4, v4, v16
	s_waitcnt vmcnt(0)
	v_lshlrev_b32_e32 v17, 16, v10
	v_add_f32_e32 v4, v4, v9
	v_and_b32_e32 v10, 0xffff0000, v10
	v_add_f32_e32 v4, v4, v17
	v_lshlrev_b32_e32 v18, 16, v11
	v_add_f32_e32 v4, v4, v10
	v_and_b32_e32 v11, 0xffff0000, v11
	v_add_f32_e32 v4, v4, v18
	v_lshlrev_b32_e32 v19, 16, v12
	v_add_f32_e32 v4, v4, v11
	v_and_b32_e32 v12, 0xffff0000, v12
	v_add_f32_e32 v4, v4, v19
	v_lshlrev_b32_e32 v20, 16, v13
	v_add_f32_e32 v4, v4, v12
	v_and_b32_e32 v13, 0xffff0000, v13
	v_add_f32_e32 v4, v4, v20
	v_add_f32_e32 v4, v4, v13
	s_waitcnt lgkmcnt(0)
	s_nop 1
	v_add_f32_dpp v4, v4, v4 quad_perm:[1,0,3,2] row_mask:0xf bank_mask:0xf
	s_nop 1
	v_add_f32_dpp v4, v4, v4 quad_perm:[2,3,0,1] row_mask:0xf bank_mask:0xf
	s_nop 1
	v_add_f32_dpp v4, v4, v4 row_half_mirror row_mask:0xf bank_mask:0xf
	s_nop 1
	v_add_f32_dpp v4, v4, v4 row_mirror row_mask:0xf bank_mask:0xf
	s_nop 1
	v_add_f32_dpp v4, v4, v4 row_bcast:15 row_mask:0xa bank_mask:0xf
	s_nop 1
	v_add_f32_dpp v4, v4, v4 row_bcast:31 row_mask:0xc bank_mask:0xf
	s_nop 1
	v_readlane_b32 s100, v4, 63
	s_nop 1
	v_mov_b32_e32 v4, s100
	v_fmac_f32_e32 v6, 0xba800000, v4
	v_fmac_f32_e32 v5, 0xba800000, v4
	v_mul_f32_e32 v6, v6, v6
	v_fmac_f32_e32 v14, 0xba800000, v4
	v_fmac_f32_e32 v6, v5, v5
	v_fmac_f32_e32 v7, 0xba800000, v4
	v_fmac_f32_e32 v6, v14, v14
	v_fmac_f32_e32 v15, 0xba800000, v4
	v_fmac_f32_e32 v6, v7, v7
	v_fmac_f32_e32 v8, 0xba800000, v4
	v_fmac_f32_e32 v6, v15, v15
	v_fmac_f32_e32 v16, 0xba800000, v4
	v_fmac_f32_e32 v6, v8, v8
	v_fmac_f32_e32 v9, 0xba800000, v4
	v_fmac_f32_e32 v6, v16, v16
	v_fmac_f32_e32 v17, 0xba800000, v4
	v_fmac_f32_e32 v6, v9, v9
	v_fmac_f32_e32 v10, 0xba800000, v4
	v_fmac_f32_e32 v6, v17, v17
	v_fmac_f32_e32 v18, 0xba800000, v4
	v_fmac_f32_e32 v6, v10, v10
	v_fmac_f32_e32 v11, 0xba800000, v4
	v_fmac_f32_e32 v6, v18, v18
	v_fmac_f32_e32 v19, 0xba800000, v4
	v_fmac_f32_e32 v6, v11, v11
	v_fmac_f32_e32 v12, 0xba800000, v4
	v_fmac_f32_e32 v6, v19, v19
	v_fmac_f32_e32 v20, 0xba800000, v4
	v_fmac_f32_e32 v6, v12, v12
	v_fmac_f32_e32 v6, v20, v20
	v_fmac_f32_e32 v13, 0xba800000, v4
	v_fmac_f32_e32 v6, v13, v13
	ds_bpermute_b32 v5, v47, v6
	s_waitcnt lgkmcnt(0)
	v_add_f32_e32 v5, v6, v5
	ds_bpermute_b32 v6, v120, v5
	s_waitcnt lgkmcnt(0)
	v_add_f32_e32 v5, v5, v6
	ds_bpermute_b32 v6, v121, v5
	s_waitcnt lgkmcnt(0)
	v_add_f32_e32 v5, v5, v6
	ds_bpermute_b32 v6, v122, v5
	s_waitcnt lgkmcnt(0)
	v_add_f32_e32 v5, v5, v6
	ds_bpermute_b32 v6, v123, v5
	s_waitcnt lgkmcnt(0)
	v_add_f32_e32 v5, v5, v6
	ds_bpermute_b32 v6, v124, v5
	s_and_saveexec_b64 s[8:9], s[4:5]
	s_cbranch_execz .LBB0_908
	s_waitcnt lgkmcnt(0)
	v_add_f32_e32 v5, v5, v6
	v_fmamk_f32 v5, v5, 0x3a800000, v138
	v_mul_f32_e32 v6, 0x4b800000, v5
	v_cmp_gt_f32_e32 vcc, s59, v5
	v_mul_f32_e32 v4, 0x3a800000, v4
	s_nop 0
	v_cndmask_b32_e32 v5, v5, v6, vcc
	v_rsq_f32_e32 v5, v5
	s_nop 0
	v_mul_f32_e32 v6, 0x45800000, v5
	v_cndmask_b32_e32 v5, v5, v6, vcc
	ds_write_b64 v0, v[4:5] offset:8
	s_branch .LBB0_908

; #define MFMA16(a, b, c) __builtin_amdgcn_mfma_f32_16x16x32_bf16((a), (b), (c), 0, 0, 0)
; __device__ __forceinline__ void attn_prompt_item(const bf16_t* z, const bf16_t* vt, bf16_t* mix, const float* sinks, int it, int lane) {
;     const int h = it & 15, qt = it >> 4, b = qt >> 8, s0 = (qt & 255) << 4, kv = h >> 3;
;     const int l15 = lane & 15, g = lane >> 4;
;     const size_t tokq = (size_t)b * SEQL + s0 + l15;
;     const bf16_t* qp = z + tokq * EIN + h * 64 + 8 * g;
;     const bf16x8 qf0 = *(const bf16x8*)qp, qf1 = *(const bf16x8*)(qp + 32);
;     const float slope = exp2f(-0.5f * (float)(h + 1));
;     const float sink = sinks[h];
;     f32x4 sc[9];
;     float mx = -1e30f;
; #pragma unroll
;     for (int kt = 0; kt < 9; ++kt) {
;         const int p0 = s0 - 128 + 16 * kt;
;         const int key = p0 + l15, keyc = key < 0 ? 0 : key;
;         const bf16_t* kp = z + ((size_t)b * SEQL + keyc) * EIN + 1024 + kv * 64 + 8 * g;
;         const bf16x8 k0 = *(const bf16x8*)kp, k1 = *(const bf16x8*)(kp + 32);
;         f32x4 a = {0.f, 0.f, 0.f, 0.f};
;         a = MFMA16(k0, qf0, a); a = MFMA16(k1, qf1, a);
; #pragma unroll
;         for (int j = 0; j < 4; ++j) {
;             const int kpos = p0 + 4 * g + j, dist = s0 + l15 - kpos;
;             const bool valid = (dist >= 0) && (dist < 128) && (kpos >= 0);
;             const float v = valid ? a[j] * 0.125f - slope * (float)dist : -1e30f;
;             sc[kt][j] = v; mx = fmaxf(mx, v);
;         }
;     }
;     s16x4 vq[5][4][2];
; #pragma unroll
;     for (int u = 0; u < 5; ++u) {
;         int pos0 = s0 - 128 + 32 * u + 4 * g, pos1 = pos0 + 16;
;         pos0 = pos0 < 0 ? 0 : pos0; pos1 = pos1 < 0 ? 0 : pos1;
; #pragma unroll
;         for (int mi = 0; mi < 4; ++mi) {
;             const bf16_t* vp = vt + (size_t)(kv * 64 + mi * 16 + l15) * T_ALL + (size_t)b * SEQL;
;             vq[u][mi][0] = *(const s16x4*)(vp + pos0); vq[u][mi][1] = *(const s16x4*)(vp + pos1);
;         }
;     }
; __global__ void __launch_bounds__(NTHREADS, 2) hybrid_fwd(Params P) {
;     ...
;                 if (PHS(13)) {
;                     if (NGW == 2048) {
;                         if ((gw & 3) == 0) attn_prompt_item(Z, VT, MIX, sinks, 7680 + (gw >> 2), lane);
;                         else { const int hw = (gw >> 2) * 3 + (gw & 3) - 1; for (int j = 0; j < 5; ++j) attn_prompt_item(Z, VT, MIX, sinks, j * 1536 + hw, lane); }
.LBB0_1054:
	s_andn2_b64 vcc, exec, s[4:5]
	v_and_b32_e32 v124, 15, v152
	s_cbranch_vccnz .LBB0_1060
	v_readlane_b32 s10, v254, 42
	v_readlane_b32 s11, v254, 43
	s_lshr_b32 s4, s74, 7
	s_bfe_u32 s5, s74, 0x10006
	s_and_b32 s6, s74, 63
	s_lshl_b32 s6, s6, 6
	s_add_u32 s12, s10, 0x13e08000
	s_addc_u32 s13, s11, 0
	s_add_u32 s14, s10, 0x20408000
	s_addc_u32 s15, s11, 0
	s_and_b32 s8, s44, 3
	s_lshr_b32 s9, s44, 2
	s_lshl_b32 s9, s9, 2
	s_lshl_b32 s7, s5, 3
	s_add_i32 s9, s9, s7
	s_lshl_b32 s21, s9, 2
	s_add_u32 s22, s40, s21
	s_addc_u32 s23, s41, 0
	s_load_dwordx4 s[28:31], s[22:23], 0x0
	v_lshrrev_b32_e32 v145, 3, v139
	v_and_b32_e32 v146, 7, v139
	v_lshlrev_b32_e32 v146, 4, v146
	v_mul_u32_u24_e32 v147, 144, v145
	v_add_u32_e32 v147, v147, v146
	s_lshl_b32 s21, s5, 7
	s_addk_i32 s21, 0x800
	v_add_u32_e32 v146, s21, v146
	s_lshl_b32 s7, s4, 12
	s_sub_i32 s21, s6, 0x80
	s_add_i32 s22, s21, 0
	v_add_u32_e32 v148, s22, v145
	v_max_i32_e32 v148, 0, v148
	v_add_u32_e32 v148, s7, v148
	v_mul_u32_u24_e32 v148, 0x2a00, v148
	v_add_u32_e32 v148, v148, v146
	global_load_dwordx4 v[20:23], v148, s[12:13]
	s_add_i32 s22, s21, 64
	v_add_u32_e32 v148, s22, v145
	v_max_i32_e32 v148, 0, v148
	v_add_u32_e32 v148, s7, v148
	v_mul_u32_u24_e32 v148, 0x2a00, v148
	v_add_u32_e32 v148, v148, v146
	global_load_dwordx4 v[24:27], v148, s[12:13]
	s_add_i32 s22, s21, 128
	v_add_u32_e32 v148, s22, v145
	v_max_i32_e32 v148, 0, v148
	v_add_u32_e32 v148, s7, v148
	v_mul_u32_u24_e32 v148, 0x2a00, v148
	v_add_u32_e32 v148, v148, v146
	global_load_dwordx4 v[28:31], v148, s[12:13]
	s_add_i32 s22, s21, 192
	v_add_u32_e32 v148, s22, v145
	v_max_i32_e32 v148, 0, v148
	v_add_u32_e32 v148, s7, v148
	v_mul_u32_u24_e32 v148, 0x2a00, v148
	v_add_u32_e32 v148, v148, v146
	global_load_dwordx4 v[32:35], v148, s[12:13]
	v_lshrrev_b32_e32 v145, 5, v139
	v_and_b32_e32 v146, 31, v139
	v_mul_u32_u24_e32 v149, 528, v145
	v_lshl_add_u32 v149, v146, 4, v149
	v_add_u32_e32 v149, 0x9000, v149
	v_lshl_add_u32 v146, v146, 3, s21
	v_max_i32_e32 v146, 0, v146
	v_add_u32_e32 v146, s7, v146
	v_lshlrev_b32_e32 v146, 1, v146
	s_lshl_b32 s22, s5, 6
	v_add_u32_e32 v145, s22, v145
	v_mul_u32_u24_e32 v145, 0x4200, v145
	v_add_u32_e32 v145, v145, v146
	s_mov_b64 s[16:17], s[24:25]
	global_load_dwordx4 v[36:39], v145, s[16:17]
	s_add_u32 s16, s16, 0x42000
	s_addc_u32 s17, s17, 0
	global_load_dwordx4 v[72:75], v145, s[16:17]
	s_add_u32 s16, s16, 0x42000
	s_addc_u32 s17, s17, 0
	global_load_dwordx4 v[76:79], v145, s[16:17]
	s_add_u32 s16, s16, 0x42000
	s_addc_u32 s17, s17, 0
	global_load_dwordx4 v[126:129], v145, s[16:17]
	v_and_b32_e32 v2, 15, v215
	v_lshrrev_b32_e32 v3, 4, v215
	s_lshl_b32 s18, s8, 4
	s_add_i32 s18, s18, s6
	s_add_i32 s19, s18, s7
	v_add_u32_e32 v150, s19, v2
	v_mul_u32_u24_e32 v151, 0x2a00, v150
	v_lshl_add_u32 v155, v3, 4, v151
	v_lshl_add_u32 v156, v3, 3, v151
	v_lshlrev_b32_e32 v157, 12, v150
	v_lshl_add_u32 v157, v3, 3, v157
	s_lshl_b32 s21, s9, 7
	s_add_u32 s22, s12, s21
	s_addc_u32 s23, s13, 0
	global_load_dwordx4 v[40:43], v155, s[22:23] offset:0
	global_load_dwordx4 v[44:47], v155, s[22:23] offset:64
	global_load_dwordx4 v[48:51], v155, s[22:23] offset:128
	global_load_dwordx4 v[52:55], v155, s[22:23] offset:192
	global_load_dwordx4 v[56:59], v155, s[22:23] offset:256
	global_load_dwordx4 v[60:63], v155, s[22:23] offset:320
	global_load_dwordx4 v[64:67], v155, s[22:23] offset:384
	global_load_dwordx4 v[68:71], v155, s[22:23] offset:448
	s_add_u32 s26, s22, 0xa00
	s_addc_u32 s27, s23, 0
	s_add_u32 s14, s14, s21
	s_addc_u32 s15, s15, 0
	v_mul_u32_u24_e32 v158, 144, v2
	v_lshl_add_u32 v158, v3, 4, v158
	s_mul_i32 s21, s8, 2304
	v_add_u32_e32 v158, s21, v158
	v_mul_u32_u24_e32 v159, 528, v2
	v_lshl_add_u32 v159, v3, 3, v159
	s_lshl_b32 s21, s8, 5
	s_add_i32 s21, s21, 0x9000
	v_add_u32_e32 v159, s21, v159
	v_lshlrev_b32_e32 v160, 2, v3
	v_sub_u32_e32 v160, v2, v160
	v_add_u32_e32 v160, 0x80, v160
	v_add_u32_e32 v161, s18, v2
	v_min_u32_e32 v161, 0x7f, v161
	v_xor_b32_e32 v162, 16, v215
	v_lshlrev_b32_e32 v162, 2, v162
	v_xor_b32_e32 v163, 32, v215
	v_lshlrev_b32_e32 v163, 2, v163
	s_add_i32 s21, s9, 1
	v_cvt_f32_i32_e32 v164, s21
	v_mul_f32_e32 v164, -0.5, v164
	v_exp_f32_e32 v164, v164
	s_add_i32 s21, s9, 2
	v_cvt_f32_i32_e32 v165, s21
	v_mul_f32_e32 v165, -0.5, v165
	v_exp_f32_e32 v165, v165
	s_add_i32 s21, s9, 3
	v_cvt_f32_i32_e32 v166, s21
	v_mul_f32_e32 v166, -0.5, v166
	v_exp_f32_e32 v166, v166
	s_add_i32 s21, s9, 4
	v_cvt_f32_i32_e32 v167, s21
	v_mul_f32_e32 v167, -0.5, v167
	v_exp_f32_e32 v167, v167
	s_waitcnt vmcnt(15)
	ds_write_b128 v147, v[20:23] offset:0
	s_waitcnt vmcnt(14)
	ds_write_b128 v147, v[24:27] offset:9216
	s_waitcnt vmcnt(13)
	ds_write_b128 v147, v[28:31] offset:18432
	s_waitcnt vmcnt(12)
	ds_write_b128 v147, v[32:35] offset:27648
	s_waitcnt vmcnt(11)
	ds_write_b128 v149, v[36:39] offset:0
	s_waitcnt vmcnt(10)
	ds_write_b128 v149, v[72:75] offset:8448
	s_waitcnt vmcnt(9)
	ds_write_b128 v149, v[76:79] offset:16896
	s_waitcnt vmcnt(8)
	ds_write_b128 v149, v[126:129] offset:25344
	s_waitcnt lgkmcnt(0)
	s_barrier
; #define MFMA16(a, b, c) __builtin_amdgcn_mfma_f32_16x16x32_bf16((a), (b), (c), 0, 0, 0)
; __device__ __forceinline__ void attn_prompt_item(const bf16_t* z, const bf16_t* vt, bf16_t* mix, const float* sinks, int it, int lane) {
;     ...
; #pragma unroll
;     for (int kt = 0; kt < 9; ++kt) {
;         const int p0 = s0 - 128 + 16 * kt;
;         const int key = p0 + l15, keyc = key < 0 ? 0 : key;
;         const bf16_t* kp = z + ((size_t)b * SEQL + keyc) * EIN + 1024 + kv * 64 + 8 * g;
;         const bf16x8 k0 = *(const bf16x8*)kp, k1 = *(const bf16x8*)(kp + 32);
;         f32x4 a = {0.f, 0.f, 0.f, 0.f};
;         a = MFMA16(k0, qf0, a); a = MFMA16(k1, qf1, a);
; #pragma unroll
;         for (int j = 0; j < 4; ++j) {
;             const int kpos = p0 + 4 * g + j, dist = s0 + l15 - kpos;
;             const bool valid = (dist >= 0) && (dist < 128) && (kpos >= 0);
;             const float v = valid ? a[j] * 0.125f - slope * (float)dist : -1e30f;
;             sc[kt][j] = v; mx = fmaxf(mx, v);
;         }
;     }
;     ...
;         const u32x2 gw = *(const u32x2*)(z + tokq * EIN + 1280 + col);
	global_load_dwordx2 v[130:131], v156, s[26:27] offset:0
	global_load_dwordx2 v[132:133], v156, s[26:27] offset:32
	global_load_dwordx2 v[134:135], v156, s[26:27] offset:64
	global_load_dwordx2 v[136:137], v156, s[26:27] offset:96
	s_waitcnt vmcnt(4)
	ds_read_b128 v[20:23], v158 offset:0
	ds_read_b128 v[24:27], v158 offset:64
	ds_read_b128 v[28:31], v158 offset:2304
	ds_read_b128 v[32:35], v158 offset:2368
	ds_read_b128 v[36:39], v158 offset:4608
	ds_read_b128 v[72:75], v158 offset:4672
	ds_read_b128 v[76:79], v158 offset:6912
	ds_read_b128 v[126:129], v158 offset:6976
	s_waitcnt lgkmcnt(7)
	v_mfma_f32_16x16x32_bf16 v[84:87], v[20:23], v[40:43], 0
	ds_read_b128 v[20:23], v158 offset:9216
	s_waitcnt lgkmcnt(7)
	v_mfma_f32_16x16x32_bf16 v[84:87], v[24:27], v[44:47], v[84:87]
	ds_read_b128 v[24:27], v158 offset:9280
	s_waitcnt lgkmcnt(7)
	v_mfma_f32_16x16x32_bf16 v[88:91], v[28:31], v[40:43], 0
	ds_read_b128 v[28:31], v158 offset:11520
	s_waitcnt lgkmcnt(7)
	v_mfma_f32_16x16x32_bf16 v[88:91], v[32:35], v[44:47], v[88:91]
	ds_read_b128 v[32:35], v158 offset:11584
	s_waitcnt lgkmcnt(7)
	v_mfma_f32_16x16x32_bf16 v[92:95], v[36:39], v[40:43], 0
	ds_read_b128 v[36:39], v158 offset:13824
	s_waitcnt lgkmcnt(7)
	v_mfma_f32_16x16x32_bf16 v[92:95], v[72:75], v[44:47], v[92:95]
	ds_read_b128 v[72:75], v158 offset:13888
	s_waitcnt lgkmcnt(7)
	v_mfma_f32_16x16x32_bf16 v[96:99], v[76:79], v[40:43], 0
	ds_read_b128 v[76:79], v158 offset:16128
	s_waitcnt lgkmcnt(7)
	v_mfma_f32_16x16x32_bf16 v[96:99], v[126:129], v[44:47], v[96:99]
	ds_read_b128 v[126:129], v158 offset:16192
	s_waitcnt lgkmcnt(7)
	v_mfma_f32_16x16x32_bf16 v[100:103], v[20:23], v[40:43], 0
	ds_read_b128 v[20:23], v158 offset:18432
	s_waitcnt lgkmcnt(7)
	v_mfma_f32_16x16x32_bf16 v[100:103], v[24:27], v[44:47], v[100:103]
	ds_read_b128 v[24:27], v158 offset:18496
	s_waitcnt lgkmcnt(7)
	v_mfma_f32_16x16x32_bf16 v[104:107], v[28:31], v[40:43], 0
	s_waitcnt lgkmcnt(6)
	v_mfma_f32_16x16x32_bf16 v[104:107], v[32:35], v[44:47], v[104:107]
	s_waitcnt lgkmcnt(5)
	v_mfma_f32_16x16x32_bf16 v[108:111], v[36:39], v[40:43], 0
	s_waitcnt lgkmcnt(4)
	v_mfma_f32_16x16x32_bf16 v[108:111], v[72:75], v[44:47], v[108:111]
	s_waitcnt lgkmcnt(3)
	v_mfma_f32_16x16x32_bf16 v[112:115], v[76:79], v[40:43], 0
	s_waitcnt lgkmcnt(2)
	v_mfma_f32_16x16x32_bf16 v[112:115], v[126:129], v[44:47], v[112:115]
	s_waitcnt lgkmcnt(1)
	v_mfma_f32_16x16x32_bf16 v[116:119], v[20:23], v[40:43], 0
	s_waitcnt lgkmcnt(0)
	v_mfma_f32_16x16x32_bf16 v[116:119], v[24:27], v[44:47], v[116:119]
	ds_read_b64 v[20:21], v159 offset:0
	ds_read_b64 v[22:23], v159 offset:32
	ds_read_b64 v[24:25], v159 offset:8448
	ds_read_b64 v[26:27], v159 offset:8480
	ds_read_b64 v[28:29], v159 offset:16896
	ds_read_b64 v[30:31], v159 offset:16928
	ds_read_b64 v[32:33], v159 offset:25344
	ds_read_b64 v[34:35], v159 offset:25376
	ds_read_b64 v[36:37], v159 offset:64
	ds_read_b64 v[38:39], v159 offset:96
	ds_read_b64 v[72:73], v159 offset:8512
	ds_read_b64 v[74:75], v159 offset:8544
	ds_read_b64 v[76:77], v159 offset:16960
	ds_read_b64 v[78:79], v159 offset:16992
	s_nop 4
	v_mov_b32_e32 v168, 0xf149f2ca
	v_mov_b32_e32 v169, v160
	v_cvt_f32_i32_e32 v170, v169
	v_mul_f32_e32 v170, v164, v170
	v_fma_f32 v84, v84, v144, -v170
	v_cmp_ge_u32_e64 vcc, v161, v169
	v_subrev_u32_e32 v169, 1, v160
	v_cvt_f32_i32_e32 v170, v169
	v_mul_f32_e32 v170, v164, v170
	v_fma_f32 v85, v85, v144, -v170
	v_cmp_ge_u32_e64 s[22:23], v161, v169
	v_cndmask_b32_e64 v84, v221, v84, vcc
	v_subrev_u32_e32 v169, 2, v160
	v_cvt_f32_i32_e32 v170, v169
	v_mul_f32_e32 v170, v164, v170
	v_fma_f32 v86, v86, v144, -v170
	v_cmp_ge_u32_e64 vcc, v161, v169
	v_cndmask_b32_e64 v85, v221, v85, s[22:23]
	v_subrev_u32_e32 v169, 3, v160
	v_cvt_f32_i32_e32 v170, v169
	v_mul_f32_e32 v170, v164, v170
	v_fma_f32 v87, v87, v144, -v170
	v_cmp_ge_u32_e64 s[22:23], v161, v169
	v_cndmask_b32_e64 v86, v221, v86, vcc
	v_subrev_u32_e32 v169, 16, v160
	v_cvt_f32_i32_e32 v170, v169
	v_mul_f32_e32 v170, v164, v170
	v_fma_f32 v88, v88, v144, -v170
	v_cmp_ge_u32_e64 vcc, v161, v169
	v_cndmask_b32_e64 v87, v221, v87, s[22:23]
	v_subrev_u32_e32 v169, 17, v160
	v_cvt_f32_i32_e32 v170, v169
	v_mul_f32_e32 v170, v164, v170
	v_fma_f32 v89, v89, v144, -v170
	v_cmp_ge_u32_e64 s[22:23], v161, v169
	v_cndmask_b32_e64 v88, v221, v88, vcc
	v_subrev_u32_e32 v169, 18, v160
	v_cvt_f32_i32_e32 v170, v169
	v_mul_f32_e32 v170, v164, v170
	v_fma_f32 v90, v90, v144, -v170
	v_cmp_ge_u32_e64 vcc, v161, v169
	v_cndmask_b32_e64 v89, v221, v89, s[22:23]
	v_subrev_u32_e32 v169, 19, v160
	v_cvt_f32_i32_e32 v170, v169
	v_mul_f32_e32 v170, v164, v170
	v_fma_f32 v91, v91, v144, -v170
	v_cmp_ge_u32_e64 s[22:23], v161, v169
	v_cndmask_b32_e64 v90, v221, v90, vcc
	v_max3_f32 v168, v168, v84, v85
	v_max3_f32 v168, v168, v86, v87
	v_subrev_u32_e32 v169, 32, v160
	v_cvt_f32_i32_e32 v170, v169
	v_mul_f32_e32 v170, v164, v170
	v_fma_f32 v92, v92, v144, -v170
	v_cmp_ge_u32_e64 vcc, v161, v169
	v_cndmask_b32_e64 v91, v221, v91, s[22:23]
	v_subrev_u32_e32 v169, 33, v160
	v_cvt_f32_i32_e32 v170, v169
	v_mul_f32_e32 v170, v164, v170
	v_fma_f32 v93, v93, v144, -v170
	v_cmp_ge_u32_e64 s[22:23], v161, v169
	v_cndmask_b32_e64 v92, v221, v92, vcc
	v_subrev_u32_e32 v169, 34, v160
	v_cvt_f32_i32_e32 v170, v169
	v_mul_f32_e32 v170, v164, v170
	v_fma_f32 v94, v94, v144, -v170
	v_cmp_ge_u32_e64 vcc, v161, v169
	v_cndmask_b32_e64 v93, v221, v93, s[22:23]
	v_subrev_u32_e32 v169, 35, v160
	v_cvt_f32_i32_e32 v170, v169
	v_mul_f32_e32 v170, v164, v170
	v_fma_f32 v95, v95, v144, -v170
	v_cmp_ge_u32_e64 s[22:23], v161, v169
	v_cndmask_b32_e64 v94, v221, v94, vcc
	v_max3_f32 v168, v168, v88, v89
; __device__ __forceinline__ void attn_prompt_item(const bf16_t* z, const bf16_t* vt, bf16_t* mix, const float* sinks, int it, int lane) {
;     ...
; #pragma unroll
;         for (int j = 0; j < 4; ++j) {
;             const int kpos = p0 + 4 * g + j, dist = s0 + l15 - kpos;
;             const bool valid = (dist >= 0) && (dist < 128) && (kpos >= 0);
;             const float v = valid ? a[j] * 0.125f - slope * (float)dist : -1e30f;
;             sc[kt][j] = v; mx = fmaxf(mx, v);
;         }
;     }
;     ...
;     mx = fmaxf(mx, __shfl_xor(mx, 16)); mx = fmaxf(mx, __shfl_xor(mx, 32)); mx = fmaxf(mx, sink);
	v_max3_f32 v168, v168, v90, v91
	v_subrev_u32_e32 v169, 48, v160
	v_cvt_f32_i32_e32 v170, v169
	v_mul_f32_e32 v170, v164, v170
	v_fma_f32 v96, v96, v144, -v170
	v_cmp_ge_u32_e64 vcc, v161, v169
	v_cndmask_b32_e64 v95, v221, v95, s[22:23]
	v_subrev_u32_e32 v169, 49, v160
	v_cvt_f32_i32_e32 v170, v169
	v_mul_f32_e32 v170, v164, v170
	v_fma_f32 v97, v97, v144, -v170
	v_cmp_ge_u32_e64 s[22:23], v161, v169
	v_cndmask_b32_e64 v96, v221, v96, vcc
	v_subrev_u32_e32 v169, 50, v160
	v_cvt_f32_i32_e32 v170, v169
	v_mul_f32_e32 v170, v164, v170
	v_fma_f32 v98, v98, v144, -v170
	v_cmp_ge_u32_e64 vcc, v161, v169
	v_cndmask_b32_e64 v97, v221, v97, s[22:23]
	v_subrev_u32_e32 v169, 51, v160
	v_cvt_f32_i32_e32 v170, v169
	v_mul_f32_e32 v170, v164, v170
	v_fma_f32 v99, v99, v144, -v170
	v_cmp_ge_u32_e64 s[22:23], v161, v169
	v_cndmask_b32_e64 v98, v221, v98, vcc
	v_max3_f32 v168, v168, v92, v93
	v_max3_f32 v168, v168, v94, v95
	v_subrev_u32_e32 v169, 64, v160
	v_cvt_f32_i32_e32 v170, v169
	v_mul_f32_e32 v170, v164, v170
	v_fma_f32 v100, v100, v144, -v170
	v_cmp_ge_u32_e64 vcc, v161, v169
	v_cndmask_b32_e64 v99, v221, v99, s[22:23]
	v_subrev_u32_e32 v169, 65, v160
	v_cvt_f32_i32_e32 v170, v169
	v_mul_f32_e32 v170, v164, v170
	v_fma_f32 v101, v101, v144, -v170
	v_cmp_ge_u32_e64 s[22:23], v161, v169
	v_cndmask_b32_e64 v100, v221, v100, vcc
	v_subrev_u32_e32 v169, 66, v160
	v_cvt_f32_i32_e32 v170, v169
	v_mul_f32_e32 v170, v164, v170
	v_fma_f32 v102, v102, v144, -v170
	v_cmp_ge_u32_e64 vcc, v161, v169
	v_cndmask_b32_e64 v101, v221, v101, s[22:23]
	v_subrev_u32_e32 v169, 67, v160
	v_cvt_f32_i32_e32 v170, v169
	v_mul_f32_e32 v170, v164, v170
	v_fma_f32 v103, v103, v144, -v170
	v_cmp_ge_u32_e64 s[22:23], v161, v169
	v_cndmask_b32_e64 v102, v221, v102, vcc
	v_max3_f32 v168, v168, v96, v97
	v_max3_f32 v168, v168, v98, v99
	v_subrev_u32_e32 v169, 80, v160
	v_cvt_f32_i32_e32 v170, v169
	v_mul_f32_e32 v170, v164, v170
	v_fma_f32 v104, v104, v144, -v170
	v_cmp_ge_u32_e64 vcc, v161, v169
	v_cndmask_b32_e64 v103, v221, v103, s[22:23]
	v_subrev_u32_e32 v169, 81, v160
	v_cvt_f32_i32_e32 v170, v169
	v_mul_f32_e32 v170, v164, v170
	v_fma_f32 v105, v105, v144, -v170
	v_cmp_ge_u32_e64 s[22:23], v161, v169
	v_cndmask_b32_e64 v104, v221, v104, vcc
	v_subrev_u32_e32 v169, 82, v160
	v_cvt_f32_i32_e32 v170, v169
	v_mul_f32_e32 v170, v164, v170
	v_fma_f32 v106, v106, v144, -v170
	v_cmp_ge_u32_e64 vcc, v161, v169
	v_cndmask_b32_e64 v105, v221, v105, s[22:23]
	v_subrev_u32_e32 v169, 83, v160
	v_cvt_f32_i32_e32 v170, v169
	v_mul_f32_e32 v170, v164, v170
	v_fma_f32 v107, v107, v144, -v170
	v_cmp_ge_u32_e64 s[22:23], v161, v169
	v_cndmask_b32_e64 v106, v221, v106, vcc
	v_max3_f32 v168, v168, v100, v101
	v_max3_f32 v168, v168, v102, v103
	v_subrev_u32_e32 v169, 96, v160
	v_cvt_f32_i32_e32 v170, v169
	v_mul_f32_e32 v170, v164, v170
	v_fma_f32 v108, v108, v144, -v170
	v_cmp_ge_u32_e64 vcc, v161, v169
	v_cndmask_b32_e64 v107, v221, v107, s[22:23]
	v_subrev_u32_e32 v169, 97, v160
	v_cvt_f32_i32_e32 v170, v169
	v_mul_f32_e32 v170, v164, v170
	v_fma_f32 v109, v109, v144, -v170
	v_cmp_ge_u32_e64 s[22:23], v161, v169
	v_cndmask_b32_e64 v108, v221, v108, vcc
	v_subrev_u32_e32 v169, 98, v160
	v_cvt_f32_i32_e32 v170, v169
	v_mul_f32_e32 v170, v164, v170
	v_fma_f32 v110, v110, v144, -v170
	v_cmp_ge_u32_e64 vcc, v161, v169
	v_cndmask_b32_e64 v109, v221, v109, s[22:23]
	v_subrev_u32_e32 v169, 99, v160
	v_cvt_f32_i32_e32 v170, v169
	v_mul_f32_e32 v170, v164, v170
	v_fma_f32 v111, v111, v144, -v170
	v_cmp_ge_u32_e64 s[22:23], v161, v169
	v_cndmask_b32_e64 v110, v221, v110, vcc
	v_max3_f32 v168, v168, v104, v105
	v_max3_f32 v168, v168, v106, v107
	v_subrev_u32_e32 v169, 112, v160
	v_cvt_f32_i32_e32 v170, v169
	v_mul_f32_e32 v170, v164, v170
	v_fma_f32 v112, v112, v144, -v170
	v_cmp_ge_u32_e64 vcc, v161, v169
	v_cndmask_b32_e64 v111, v221, v111, s[22:23]
	v_subrev_u32_e32 v169, 113, v160
	v_cvt_f32_i32_e32 v170, v169
	v_mul_f32_e32 v170, v164, v170
	v_fma_f32 v113, v113, v144, -v170
	v_cmp_ge_u32_e64 s[22:23], v161, v169
	v_cndmask_b32_e64 v112, v221, v112, vcc
	v_subrev_u32_e32 v169, 114, v160
	v_cvt_f32_i32_e32 v170, v169
	v_mul_f32_e32 v170, v164, v170
	v_fma_f32 v114, v114, v144, -v170
	v_cmp_ge_u32_e64 vcc, v161, v169
	v_cndmask_b32_e64 v113, v221, v113, s[22:23]
	v_subrev_u32_e32 v169, 115, v160
	v_cvt_f32_i32_e32 v170, v169
	v_mul_f32_e32 v170, v164, v170
	v_fma_f32 v115, v115, v144, -v170
	v_cmp_ge_u32_e64 s[22:23], v161, v169
	v_cndmask_b32_e64 v114, v221, v114, vcc
	v_max3_f32 v168, v168, v108, v109
	v_max3_f32 v168, v168, v110, v111
	v_subrev_u32_e32 v169, 128, v160
	v_cvt_f32_i32_e32 v170, v169
	v_mul_f32_e32 v170, v164, v170
	v_fma_f32 v116, v116, v144, -v170
	v_cmp_ge_u32_e64 vcc, v161, v169
	v_cndmask_b32_e64 v115, v221, v115, s[22:23]
	v_subrev_u32_e32 v169, 129, v160
	v_cvt_f32_i32_e32 v170, v169
	v_mul_f32_e32 v170, v164, v170
	v_fma_f32 v117, v117, v144, -v170
	v_cmp_ge_u32_e64 s[22:23], v161, v169
	v_cndmask_b32_e64 v116, v221, v116, vcc
	v_subrev_u32_e32 v169, 130, v160
	v_cvt_f32_i32_e32 v170, v169
	v_mul_f32_e32 v170, v164, v170
	v_fma_f32 v118, v118, v144, -v170
	v_cmp_ge_u32_e64 vcc, v161, v169
	v_cndmask_b32_e64 v117, v221, v117, s[22:23]
	v_subrev_u32_e32 v169, 131, v160
	v_cvt_f32_i32_e32 v170, v169
	v_mul_f32_e32 v170, v164, v170
	v_fma_f32 v119, v119, v144, -v170
	v_cmp_ge_u32_e64 s[22:23], v161, v169
	v_cndmask_b32_e64 v118, v221, v118, vcc
	v_max3_f32 v168, v168, v112, v113
	v_max3_f32 v168, v168, v114, v115
	s_nop 1
	v_cndmask_b32_e64 v119, v221, v119, s[22:23]
	v_max3_f32 v168, v168, v116, v117
	v_max3_f32 v168, v168, v118, v119
	ds_bpermute_b32 v169, v162, v168
	s_waitcnt lgkmcnt(0)
; __device__ __forceinline__ void attn_prompt_item(const bf16_t* z, const bf16_t* vt, bf16_t* mix, const float* sinks, int it, int lane) {
;     ...
;     mx = fmaxf(mx, __shfl_xor(mx, 16)); mx = fmaxf(mx, __shfl_xor(mx, 32)); mx = fmaxf(mx, sink);
;     float sum = 0.f;
; #pragma unroll
;     for (int kt = 0; kt < 9; ++kt)
; #pragma unroll
;         for (int j = 0; j < 4; ++j) { const float p = __expf(sc[kt][j] - mx); sc[kt][j] = p; sum += p; }
;     sum += __shfl_xor(sum, 16); sum += __shfl_xor(sum, 32);
;     const float inv = 1.0f / (sum + __expf(sink - mx));
	v_max_f32_e32 v169, v169, v169
	v_max_f32_e32 v168, v168, v169
	ds_bpermute_b32 v169, v163, v168
	s_waitcnt lgkmcnt(0)
	v_max_f32_e32 v169, v169, v169
	v_max_f32_e32 v168, v168, v169
	v_max_f32_e32 v168, s28, v168
	v_mov_b32_e32 v171, 0
	v_sub_f32_e32 v84, v84, v168
	v_mul_f32_e32 v84, 0x3fb8aa3b, v84
	v_exp_f32_e32 v84, v84
	v_sub_f32_e32 v85, v85, v168
	v_mul_f32_e32 v85, 0x3fb8aa3b, v85
	v_exp_f32_e32 v85, v85
	v_add_f32_e32 v171, v84, v171
	v_sub_f32_e32 v86, v86, v168
	v_mul_f32_e32 v86, 0x3fb8aa3b, v86
	v_exp_f32_e32 v86, v86
	v_add_f32_e32 v171, v85, v171
	v_sub_f32_e32 v87, v87, v168
	v_mul_f32_e32 v87, 0x3fb8aa3b, v87
	v_exp_f32_e32 v87, v87
	v_add_f32_e32 v171, v86, v171
	v_sub_f32_e32 v88, v88, v168
	v_mul_f32_e32 v88, 0x3fb8aa3b, v88
	v_exp_f32_e32 v88, v88
	v_add_f32_e32 v171, v87, v171
	v_sub_f32_e32 v89, v89, v168
	v_mul_f32_e32 v89, 0x3fb8aa3b, v89
	v_exp_f32_e32 v89, v89
	v_add_f32_e32 v171, v88, v171
	v_sub_f32_e32 v90, v90, v168
	v_mul_f32_e32 v90, 0x3fb8aa3b, v90
	v_exp_f32_e32 v90, v90
	v_add_f32_e32 v171, v89, v171
	v_sub_f32_e32 v91, v91, v168
	v_mul_f32_e32 v91, 0x3fb8aa3b, v91
	v_exp_f32_e32 v91, v91
	v_add_f32_e32 v171, v90, v171
	v_sub_f32_e32 v92, v92, v168
	v_mul_f32_e32 v92, 0x3fb8aa3b, v92
	v_exp_f32_e32 v92, v92
	v_add_f32_e32 v171, v91, v171
	v_sub_f32_e32 v93, v93, v168
	v_mul_f32_e32 v93, 0x3fb8aa3b, v93
	v_exp_f32_e32 v93, v93
	v_add_f32_e32 v171, v92, v171
	v_sub_f32_e32 v94, v94, v168
	v_mul_f32_e32 v94, 0x3fb8aa3b, v94
	v_exp_f32_e32 v94, v94
	v_add_f32_e32 v171, v93, v171
	v_sub_f32_e32 v95, v95, v168
	v_mul_f32_e32 v95, 0x3fb8aa3b, v95
	v_exp_f32_e32 v95, v95
	v_add_f32_e32 v171, v94, v171
	v_sub_f32_e32 v96, v96, v168
	v_mul_f32_e32 v96, 0x3fb8aa3b, v96
	v_exp_f32_e32 v96, v96
	v_add_f32_e32 v171, v95, v171
	v_sub_f32_e32 v97, v97, v168
	v_mul_f32_e32 v97, 0x3fb8aa3b, v97
	v_exp_f32_e32 v97, v97
	v_add_f32_e32 v171, v96, v171
	v_sub_f32_e32 v98, v98, v168
	v_mul_f32_e32 v98, 0x3fb8aa3b, v98
	v_exp_f32_e32 v98, v98
	v_add_f32_e32 v171, v97, v171
	v_sub_f32_e32 v99, v99, v168
	v_mul_f32_e32 v99, 0x3fb8aa3b, v99
	v_exp_f32_e32 v99, v99
	v_add_f32_e32 v171, v98, v171
	v_sub_f32_e32 v100, v100, v168
	v_mul_f32_e32 v100, 0x3fb8aa3b, v100
	v_exp_f32_e32 v100, v100
	v_add_f32_e32 v171, v99, v171
	v_sub_f32_e32 v101, v101, v168
	v_mul_f32_e32 v101, 0x3fb8aa3b, v101
	v_exp_f32_e32 v101, v101
	v_add_f32_e32 v171, v100, v171
	v_sub_f32_e32 v102, v102, v168
	v_mul_f32_e32 v102, 0x3fb8aa3b, v102
	v_exp_f32_e32 v102, v102
	v_add_f32_e32 v171, v101, v171
	v_sub_f32_e32 v103, v103, v168
	v_mul_f32_e32 v103, 0x3fb8aa3b, v103
	v_exp_f32_e32 v103, v103
	v_add_f32_e32 v171, v102, v171
	v_sub_f32_e32 v104, v104, v168
	v_mul_f32_e32 v104, 0x3fb8aa3b, v104
	v_exp_f32_e32 v104, v104
	v_add_f32_e32 v171, v103, v171
	v_sub_f32_e32 v105, v105, v168
	v_mul_f32_e32 v105, 0x3fb8aa3b, v105
	v_exp_f32_e32 v105, v105
	v_add_f32_e32 v171, v104, v171
	v_sub_f32_e32 v106, v106, v168
	v_mul_f32_e32 v106, 0x3fb8aa3b, v106
	v_exp_f32_e32 v106, v106
	v_add_f32_e32 v171, v105, v171
	v_sub_f32_e32 v107, v107, v168
	v_mul_f32_e32 v107, 0x3fb8aa3b, v107
	v_exp_f32_e32 v107, v107
	v_add_f32_e32 v171, v106, v171
	v_sub_f32_e32 v108, v108, v168
	v_mul_f32_e32 v108, 0x3fb8aa3b, v108
	v_exp_f32_e32 v108, v108
	v_add_f32_e32 v171, v107, v171
	v_sub_f32_e32 v109, v109, v168
	v_mul_f32_e32 v109, 0x3fb8aa3b, v109
	v_exp_f32_e32 v109, v109
	v_add_f32_e32 v171, v108, v171
	v_sub_f32_e32 v110, v110, v168
	v_mul_f32_e32 v110, 0x3fb8aa3b, v110
	v_exp_f32_e32 v110, v110
	v_add_f32_e32 v171, v109, v171
	v_sub_f32_e32 v111, v111, v168
	v_mul_f32_e32 v111, 0x3fb8aa3b, v111
	v_exp_f32_e32 v111, v111
	v_add_f32_e32 v171, v110, v171
	v_sub_f32_e32 v112, v112, v168
	v_mul_f32_e32 v112, 0x3fb8aa3b, v112
	v_exp_f32_e32 v112, v112
	v_add_f32_e32 v171, v111, v171
	v_sub_f32_e32 v113, v113, v168
	v_mul_f32_e32 v113, 0x3fb8aa3b, v113
	v_exp_f32_e32 v113, v113
	v_add_f32_e32 v171, v112, v171
	v_sub_f32_e32 v114, v114, v168
	v_mul_f32_e32 v114, 0x3fb8aa3b, v114
	v_exp_f32_e32 v114, v114
	v_add_f32_e32 v171, v113, v171
	v_sub_f32_e32 v115, v115, v168
	v_mul_f32_e32 v115, 0x3fb8aa3b, v115
	v_exp_f32_e32 v115, v115
	v_add_f32_e32 v171, v114, v171
	v_sub_f32_e32 v116, v116, v168
	v_mul_f32_e32 v116, 0x3fb8aa3b, v116
	v_exp_f32_e32 v116, v116
	v_add_f32_e32 v171, v115, v171
	v_sub_f32_e32 v117, v117, v168
	v_mul_f32_e32 v117, 0x3fb8aa3b, v117
	v_exp_f32_e32 v117, v117
	v_add_f32_e32 v171, v116, v171
	v_sub_f32_e32 v118, v118, v168
	v_mul_f32_e32 v118, 0x3fb8aa3b, v118
	v_exp_f32_e32 v118, v118
	v_add_f32_e32 v171, v117, v171
	v_sub_f32_e32 v119, v119, v168
	v_mul_f32_e32 v119, 0x3fb8aa3b, v119
	v_exp_f32_e32 v119, v119
	v_add_f32_e32 v171, v118, v171
	v_sub_f32_e32 v172, s28, v168
	v_add_f32_e32 v171, v119, v171
	v_mul_f32_e32 v172, 0x3fb8aa3b, v172
	v_exp_f32_e32 v172, v172
	ds_bpermute_b32 v169, v162, v171
	s_waitcnt lgkmcnt(0)
	v_add_f32_e32 v171, v171, v169
	ds_bpermute_b32 v169, v163, v171
	s_waitcnt lgkmcnt(0)
; #define MFMA16(a, b, c) __builtin_amdgcn_mfma_f32_16x16x32_bf16((a), (b), (c), 0, 0, 0)
; __device__ __forceinline__ unsigned pk2(float lo, float hi) { return pg8::cvt_pk_bf16(lo, hi); }
; __device__ __forceinline__ void attn_prompt_item(const bf16_t* z, const bf16_t* vt, bf16_t* mix, const float* sinks, int it, int lane) {
;     ...
;     sum += __shfl_xor(sum, 16); sum += __shfl_xor(sum, 32);
;     const float inv = 1.0f / (sum + __expf(sink - mx));
;     f32x4 o[4];
; #pragma unroll
;     for (int mi = 0; mi < 4; ++mi) o[mi] = (f32x4){0.f, 0.f, 0.f, 0.f};
; #pragma unroll
;     for (int u = 0; u < 5; ++u) {
;         u32x4 pw; pw.x = pk2(sc[2 * u][0] * inv, sc[2 * u][1] * inv); pw.y = pk2(sc[2 * u][2] * inv, sc[2 * u][3] * inv);
;         if (2 * u + 1 < 9) { pw.z = pk2(sc[(2 * u + 1) % 9][0] * inv, sc[(2 * u + 1) % 9][1] * inv); pw.w = pk2(sc[(2 * u + 1) % 9][2] * inv, sc[(2 * u + 1) % 9][3] * inv); }
;         else { pw.z = 0u; pw.w = 0u; }
;         const bf16x8 pb = as_bf16x8(pw);
; #pragma unroll
;         for (int mi = 0; mi < 4; ++mi) {
;             const s16x4 v0 = vq[u][mi][0], v1 = vq[u][mi][1];
;             const bf16x8 va = (bf16x8){v0[0], v0[1], v0[2], v0[3], v1[0], v1[1], v1[2], v1[3]};
;             o[mi] = MFMA16(va, pb, o[mi]);
;         }
;     }
	v_add_f32_e32 v171, v171, v169
	v_add_f32_e32 v171, v171, v172
	v_div_scale_f32 v169, s[22:23], v171, v171, 1.0
	v_rcp_f32_e32 v170, v169
	s_nop 0
	v_fma_f32 v172, -v169, v170, 1.0
	v_fmac_f32_e32 v170, v172, v170
	v_div_scale_f32 v172, vcc, 1.0, v171, 1.0
	v_mul_f32_e32 v173, v172, v170
	v_fma_f32 v174, -v169, v173, v172
	v_fmac_f32_e32 v173, v174, v170
	v_fma_f32 v169, -v169, v173, v172
	v_div_fmas_f32 v169, v169, v170, v173
	v_div_fixup_f32 v174, v169, v171, 1.0
	v_pk_mul_f32 v[170:171], v[84:85], v[174:175] op_sel_hi:[1,0]
	v_cvt_pk_bf16_f32 v84, v170, v171
	v_pk_mul_f32 v[170:171], v[86:87], v[174:175] op_sel_hi:[1,0]
	v_cvt_pk_bf16_f32 v85, v170, v171
	v_pk_mul_f32 v[170:171], v[88:89], v[174:175] op_sel_hi:[1,0]
	v_cvt_pk_bf16_f32 v86, v170, v171
	v_pk_mul_f32 v[170:171], v[90:91], v[174:175] op_sel_hi:[1,0]
	v_cvt_pk_bf16_f32 v87, v170, v171
	v_pk_mul_f32 v[170:171], v[92:93], v[174:175] op_sel_hi:[1,0]
	v_cvt_pk_bf16_f32 v88, v170, v171
	v_pk_mul_f32 v[170:171], v[94:95], v[174:175] op_sel_hi:[1,0]
	v_cvt_pk_bf16_f32 v89, v170, v171
	v_pk_mul_f32 v[170:171], v[96:97], v[174:175] op_sel_hi:[1,0]
	v_cvt_pk_bf16_f32 v90, v170, v171
	v_pk_mul_f32 v[170:171], v[98:99], v[174:175] op_sel_hi:[1,0]
	v_cvt_pk_bf16_f32 v91, v170, v171
	v_pk_mul_f32 v[170:171], v[100:101], v[174:175] op_sel_hi:[1,0]
	v_cvt_pk_bf16_f32 v92, v170, v171
	v_pk_mul_f32 v[170:171], v[102:103], v[174:175] op_sel_hi:[1,0]
	v_cvt_pk_bf16_f32 v93, v170, v171
	v_pk_mul_f32 v[170:171], v[104:105], v[174:175] op_sel_hi:[1,0]
	v_cvt_pk_bf16_f32 v94, v170, v171
	v_pk_mul_f32 v[170:171], v[106:107], v[174:175] op_sel_hi:[1,0]
	v_cvt_pk_bf16_f32 v95, v170, v171
	v_pk_mul_f32 v[170:171], v[108:109], v[174:175] op_sel_hi:[1,0]
	v_cvt_pk_bf16_f32 v96, v170, v171
	v_pk_mul_f32 v[170:171], v[110:111], v[174:175] op_sel_hi:[1,0]
	v_cvt_pk_bf16_f32 v97, v170, v171
	v_pk_mul_f32 v[170:171], v[112:113], v[174:175] op_sel_hi:[1,0]
	v_cvt_pk_bf16_f32 v98, v170, v171
	v_pk_mul_f32 v[170:171], v[114:115], v[174:175] op_sel_hi:[1,0]
	v_cvt_pk_bf16_f32 v99, v170, v171
	v_pk_mul_f32 v[170:171], v[116:117], v[174:175] op_sel_hi:[1,0]
	v_cvt_pk_bf16_f32 v100, v170, v171
	v_pk_mul_f32 v[170:171], v[118:119], v[174:175] op_sel_hi:[1,0]
	v_cvt_pk_bf16_f32 v101, v170, v171
	v_mov_b32_e32 v102, 0
	v_mov_b32_e32 v103, 0
	s_nop 1
	s_waitcnt lgkmcnt(12)
	v_mfma_f32_16x16x32_bf16 v[4:7], v[20:23], v[84:87], 0
	ds_read_b64 v[20:21], v159 offset:25408
	ds_read_b64 v[22:23], v159 offset:25440
	s_waitcnt lgkmcnt(12)
	v_mfma_f32_16x16x32_bf16 v[8:11], v[24:27], v[84:87], 0
	ds_read_b64 v[24:25], v159 offset:128
	ds_read_b64 v[26:27], v159 offset:160
	s_waitcnt lgkmcnt(12)
	v_mfma_f32_16x16x32_bf16 v[12:15], v[28:31], v[84:87], 0
	ds_read_b64 v[28:29], v159 offset:8576
	ds_read_b64 v[30:31], v159 offset:8608
	s_waitcnt lgkmcnt(12)
	v_mfma_f32_16x16x32_bf16 v[16:19], v[32:35], v[84:87], 0
	ds_read_b64 v[32:33], v159 offset:17024
	ds_read_b64 v[34:35], v159 offset:17056
	s_waitcnt lgkmcnt(12)
	v_mfma_f32_16x16x32_bf16 v[4:7], v[36:39], v[88:91], v[4:7]
	ds_read_b64 v[36:37], v159 offset:25472
	ds_read_b64 v[38:39], v159 offset:25504
	s_waitcnt lgkmcnt(12)
	v_mfma_f32_16x16x32_bf16 v[8:11], v[72:75], v[88:91], v[8:11]
	ds_read_b64 v[72:73], v159 offset:192
	ds_read_b64 v[74:75], v159 offset:224
	s_waitcnt lgkmcnt(12)
	v_mfma_f32_16x16x32_bf16 v[12:15], v[76:79], v[88:91], v[12:15]
	ds_read_b64 v[76:77], v159 offset:8640
	ds_read_b64 v[78:79], v159 offset:8672
	s_waitcnt lgkmcnt(12)
	v_mfma_f32_16x16x32_bf16 v[16:19], v[20:23], v[88:91], v[16:19]
	ds_read_b64 v[20:21], v159 offset:17088
	ds_read_b64 v[22:23], v159 offset:17120
	s_waitcnt lgkmcnt(12)
	v_mfma_f32_16x16x32_bf16 v[4:7], v[24:27], v[92:95], v[4:7]
	ds_read_b64 v[24:25], v159 offset:25536
	ds_read_b64 v[26:27], v159 offset:25568
	s_waitcnt lgkmcnt(12)
	v_mfma_f32_16x16x32_bf16 v[8:11], v[28:31], v[92:95], v[8:11]
	ds_read_b64 v[28:29], v159 offset:256
	ds_read_b64 v[30:31], v159 offset:288
	s_waitcnt lgkmcnt(12)
	v_mfma_f32_16x16x32_bf16 v[12:15], v[32:35], v[92:95], v[12:15]
	ds_read_b64 v[32:33], v159 offset:8704
	ds_read_b64 v[34:35], v159 offset:8736
	s_waitcnt lgkmcnt(12)
	v_mfma_f32_16x16x32_bf16 v[16:19], v[36:39], v[92:95], v[16:19]
	ds_read_b64 v[36:37], v159 offset:17152
	ds_read_b64 v[38:39], v159 offset:17184
	s_waitcnt lgkmcnt(12)
	v_mfma_f32_16x16x32_bf16 v[4:7], v[72:75], v[96:99], v[4:7]
	ds_read_b64 v[72:73], v159 offset:25600
	ds_read_b64 v[74:75], v159 offset:25632
	s_waitcnt lgkmcnt(12)
	v_mfma_f32_16x16x32_bf16 v[8:11], v[76:79], v[96:99], v[8:11]
	s_waitcnt lgkmcnt(10)
	v_mfma_f32_16x16x32_bf16 v[12:15], v[20:23], v[96:99], v[12:15]
	s_waitcnt lgkmcnt(8)
	v_mfma_f32_16x16x32_bf16 v[16:19], v[24:27], v[96:99], v[16:19]
	s_waitcnt lgkmcnt(6)
	v_mfma_f32_16x16x32_bf16 v[4:7], v[28:31], v[100:103], v[4:7]
	s_waitcnt lgkmcnt(4)
	v_mfma_f32_16x16x32_bf16 v[8:11], v[32:35], v[100:103], v[8:11]
	s_waitcnt lgkmcnt(2)
	v_mfma_f32_16x16x32_bf16 v[12:15], v[36:39], v[100:103], v[12:15]
	s_waitcnt lgkmcnt(0)
	v_mfma_f32_16x16x32_bf16 v[16:19], v[72:75], v[100:103], v[16:19]
	s_nop 7
	s_waitcnt vmcnt(0)
; #define MFMA16(a, b, c) __builtin_amdgcn_mfma_f32_16x16x32_bf16((a), (b), (c), 0, 0, 0)
; __device__ __forceinline__ float bf_lo(unsigned w) { return __uint_as_float(w << 16); }
; __device__ __forceinline__ float bf_hi(unsigned w) { return __uint_as_float(w & 0xffff0000u); }
; __device__ __forceinline__ unsigned pk2(float lo, float hi) { return pg8::cvt_pk_bf16(lo, hi); }
; __device__ __forceinline__ void attn_prompt_item(const bf16_t* z, const bf16_t* vt, bf16_t* mix, const float* sinks, int it, int lane) {
;     ...
; #pragma unroll
;     for (int kt = 0; kt < 9; ++kt) {
;         const int p0 = s0 - 128 + 16 * kt;
;         const int key = p0 + l15, keyc = key < 0 ? 0 : key;
;         const bf16_t* kp = z + ((size_t)b * SEQL + keyc) * EIN + 1024 + kv * 64 + 8 * g;
;         const bf16x8 k0 = *(const bf16x8*)kp, k1 = *(const bf16x8*)(kp + 32);
;         f32x4 a = {0.f, 0.f, 0.f, 0.f};
;         a = MFMA16(k0, qf0, a); a = MFMA16(k1, qf1, a);
; #pragma unroll
;         for (int j = 0; j < 4; ++j) {
;             const int kpos = p0 + 4 * g + j, dist = s0 + l15 - kpos;
;             const bool valid = (dist >= 0) && (dist < 128) && (kpos >= 0);
;             const float v = valid ? a[j] * 0.125f - slope * (float)dist : -1e30f;
;             sc[kt][j] = v; mx = fmaxf(mx, v);
;         }
;     }
;     ...
; #pragma unroll
;     for (int mi = 0; mi < 4; ++mi) {
;         const int col = h * 64 + mi * 16 + 4 * g;
;         const u32x2 gw = *(const u32x2*)(z + tokq * EIN + 1280 + col);
;         u32x2 w; w.x = pk2(o[mi][0] * bf_lo(gw.x), o[mi][1] * bf_hi(gw.x)); w.y = pk2(o[mi][2] * bf_lo(gw.y), o[mi][3] * bf_hi(gw.y));
;         *(u32x2*)(mix + tokq * 2048 + col) = w;
;     }
	v_lshlrev_b32_e32 v172, 16, v130
	v_and_b32_e32 v173, 0xffff0000, v130
	v_lshlrev_b32_e32 v174, 16, v131
	v_and_b32_e32 v175, 0xffff0000, v131
	v_mul_f32_e32 v172, v4, v172
	v_mul_f32_e32 v173, v5, v173
	v_mul_f32_e32 v174, v6, v174
	v_mul_f32_e32 v175, v7, v175
	v_cvt_pk_bf16_f32 v170, v172, v173
	v_cvt_pk_bf16_f32 v171, v174, v175
	global_store_dwordx2 v157, v[170:171], s[14:15] offset:0
	v_lshlrev_b32_e32 v172, 16, v132
	v_and_b32_e32 v173, 0xffff0000, v132
	v_lshlrev_b32_e32 v174, 16, v133
	v_and_b32_e32 v175, 0xffff0000, v133
	v_mul_f32_e32 v172, v8, v172
	v_mul_f32_e32 v173, v9, v173
	v_mul_f32_e32 v174, v10, v174
	v_mul_f32_e32 v175, v11, v175
	v_cvt_pk_bf16_f32 v170, v172, v173
	v_cvt_pk_bf16_f32 v171, v174, v175
	global_store_dwordx2 v157, v[170:171], s[14:15] offset:32
	v_lshlrev_b32_e32 v172, 16, v134
	v_and_b32_e32 v173, 0xffff0000, v134
	v_lshlrev_b32_e32 v174, 16, v135
	v_and_b32_e32 v175, 0xffff0000, v135
	v_mul_f32_e32 v172, v12, v172
	v_mul_f32_e32 v173, v13, v173
	v_mul_f32_e32 v174, v14, v174
	v_mul_f32_e32 v175, v15, v175
	v_cvt_pk_bf16_f32 v170, v172, v173
	v_cvt_pk_bf16_f32 v171, v174, v175
	global_store_dwordx2 v157, v[170:171], s[14:15] offset:64
	v_lshlrev_b32_e32 v172, 16, v136
	v_and_b32_e32 v173, 0xffff0000, v136
	v_lshlrev_b32_e32 v174, 16, v137
	v_and_b32_e32 v175, 0xffff0000, v137
	v_mul_f32_e32 v172, v16, v172
	v_mul_f32_e32 v173, v17, v173
	v_mul_f32_e32 v174, v18, v174
	v_mul_f32_e32 v175, v19, v175
	v_cvt_pk_bf16_f32 v170, v172, v173
	v_cvt_pk_bf16_f32 v171, v174, v175
	global_store_dwordx2 v157, v[170:171], s[14:15] offset:96
	global_load_dwordx2 v[130:131], v156, s[26:27] offset:128
	global_load_dwordx2 v[132:133], v156, s[26:27] offset:160
	global_load_dwordx2 v[134:135], v156, s[26:27] offset:192
	global_load_dwordx2 v[136:137], v156, s[26:27] offset:224
	ds_read_b128 v[20:23], v158 offset:0
	ds_read_b128 v[24:27], v158 offset:64
	ds_read_b128 v[28:31], v158 offset:2304
	ds_read_b128 v[32:35], v158 offset:2368
	ds_read_b128 v[36:39], v158 offset:4608
	ds_read_b128 v[72:75], v158 offset:4672
	ds_read_b128 v[76:79], v158 offset:6912
	ds_read_b128 v[126:129], v158 offset:6976
	s_waitcnt lgkmcnt(7)
	v_mfma_f32_16x16x32_bf16 v[84:87], v[20:23], v[48:51], 0
	ds_read_b128 v[20:23], v158 offset:9216
	s_waitcnt lgkmcnt(7)
	v_mfma_f32_16x16x32_bf16 v[84:87], v[24:27], v[52:55], v[84:87]
	ds_read_b128 v[24:27], v158 offset:9280
	s_waitcnt lgkmcnt(7)
	v_mfma_f32_16x16x32_bf16 v[88:91], v[28:31], v[48:51], 0
	ds_read_b128 v[28:31], v158 offset:11520
	s_waitcnt lgkmcnt(7)
	v_mfma_f32_16x16x32_bf16 v[88:91], v[32:35], v[52:55], v[88:91]
	ds_read_b128 v[32:35], v158 offset:11584
	s_waitcnt lgkmcnt(7)
	v_mfma_f32_16x16x32_bf16 v[92:95], v[36:39], v[48:51], 0
	ds_read_b128 v[36:39], v158 offset:13824
	s_waitcnt lgkmcnt(7)
	v_mfma_f32_16x16x32_bf16 v[92:95], v[72:75], v[52:55], v[92:95]
	ds_read_b128 v[72:75], v158 offset:13888
	s_waitcnt lgkmcnt(7)
	v_mfma_f32_16x16x32_bf16 v[96:99], v[76:79], v[48:51], 0
	ds_read_b128 v[76:79], v158 offset:16128
	s_waitcnt lgkmcnt(7)
	v_mfma_f32_16x16x32_bf16 v[96:99], v[126:129], v[52:55], v[96:99]
	ds_read_b128 v[126:129], v158 offset:16192
	s_waitcnt lgkmcnt(7)
	v_mfma_f32_16x16x32_bf16 v[100:103], v[20:23], v[48:51], 0
	ds_read_b128 v[20:23], v158 offset:18432
	s_waitcnt lgkmcnt(7)
	v_mfma_f32_16x16x32_bf16 v[100:103], v[24:27], v[52:55], v[100:103]
	ds_read_b128 v[24:27], v158 offset:18496
	s_waitcnt lgkmcnt(7)
	v_mfma_f32_16x16x32_bf16 v[104:107], v[28:31], v[48:51], 0
	s_waitcnt lgkmcnt(6)
	v_mfma_f32_16x16x32_bf16 v[104:107], v[32:35], v[52:55], v[104:107]
	s_waitcnt lgkmcnt(5)
	v_mfma_f32_16x16x32_bf16 v[108:111], v[36:39], v[48:51], 0
	s_waitcnt lgkmcnt(4)
	v_mfma_f32_16x16x32_bf16 v[108:111], v[72:75], v[52:55], v[108:111]
	s_waitcnt lgkmcnt(3)
	v_mfma_f32_16x16x32_bf16 v[112:115], v[76:79], v[48:51], 0
	s_waitcnt lgkmcnt(2)
	v_mfma_f32_16x16x32_bf16 v[112:115], v[126:129], v[52:55], v[112:115]
	s_waitcnt lgkmcnt(1)
	v_mfma_f32_16x16x32_bf16 v[116:119], v[20:23], v[48:51], 0
	s_waitcnt lgkmcnt(0)
	v_mfma_f32_16x16x32_bf16 v[116:119], v[24:27], v[52:55], v[116:119]
	ds_read_b64 v[20:21], v159 offset:0
	ds_read_b64 v[22:23], v159 offset:32
	ds_read_b64 v[24:25], v159 offset:8448
	ds_read_b64 v[26:27], v159 offset:8480
	ds_read_b64 v[28:29], v159 offset:16896
	ds_read_b64 v[30:31], v159 offset:16928
	ds_read_b64 v[32:33], v159 offset:25344
	ds_read_b64 v[34:35], v159 offset:25376
	ds_read_b64 v[36:37], v159 offset:64
	ds_read_b64 v[38:39], v159 offset:96
	ds_read_b64 v[72:73], v159 offset:8512
	ds_read_b64 v[74:75], v159 offset:8544
	ds_read_b64 v[76:77], v159 offset:16960
	ds_read_b64 v[78:79], v159 offset:16992
	s_nop 4
	v_mov_b32_e32 v168, 0xf149f2ca
	v_mov_b32_e32 v169, v160
	v_cvt_f32_i32_e32 v170, v169
	v_mul_f32_e32 v170, v165, v170
	v_fma_f32 v84, v84, v144, -v170
	v_cmp_ge_u32_e64 vcc, v161, v169
	v_subrev_u32_e32 v169, 1, v160
	v_cvt_f32_i32_e32 v170, v169
	v_mul_f32_e32 v170, v165, v170
	v_fma_f32 v85, v85, v144, -v170
	v_cmp_ge_u32_e64 s[22:23], v161, v169
	v_cndmask_b32_e64 v84, v221, v84, vcc
	v_subrev_u32_e32 v169, 2, v160
	v_cvt_f32_i32_e32 v170, v169
	v_mul_f32_e32 v170, v165, v170
	v_fma_f32 v86, v86, v144, -v170
	v_cmp_ge_u32_e64 vcc, v161, v169
	v_cndmask_b32_e64 v85, v221, v85, s[22:23]
	v_subrev_u32_e32 v169, 3, v160
	v_cvt_f32_i32_e32 v170, v169
	v_mul_f32_e32 v170, v165, v170
	v_fma_f32 v87, v87, v144, -v170
	v_cmp_ge_u32_e64 s[22:23], v161, v169
	v_cndmask_b32_e64 v86, v221, v86, vcc
	v_subrev_u32_e32 v169, 16, v160
	v_cvt_f32_i32_e32 v170, v169
	v_mul_f32_e32 v170, v165, v170
	v_fma_f32 v88, v88, v144, -v170
	v_cmp_ge_u32_e64 vcc, v161, v169
; __device__ __forceinline__ void attn_prompt_item(const bf16_t* z, const bf16_t* vt, bf16_t* mix, const float* sinks, int it, int lane) {
;     ...
; #pragma unroll
;         for (int j = 0; j < 4; ++j) {
;             const int kpos = p0 + 4 * g + j, dist = s0 + l15 - kpos;
;             const bool valid = (dist >= 0) && (dist < 128) && (kpos >= 0);
;             const float v = valid ? a[j] * 0.125f - slope * (float)dist : -1e30f;
;             sc[kt][j] = v; mx = fmaxf(mx, v);
;         }
	v_cndmask_b32_e64 v87, v221, v87, s[22:23]
	v_subrev_u32_e32 v169, 17, v160
	v_cvt_f32_i32_e32 v170, v169
	v_mul_f32_e32 v170, v165, v170
	v_fma_f32 v89, v89, v144, -v170
	v_cmp_ge_u32_e64 s[22:23], v161, v169
	v_cndmask_b32_e64 v88, v221, v88, vcc
	v_subrev_u32_e32 v169, 18, v160
	v_cvt_f32_i32_e32 v170, v169
	v_mul_f32_e32 v170, v165, v170
	v_fma_f32 v90, v90, v144, -v170
	v_cmp_ge_u32_e64 vcc, v161, v169
	v_cndmask_b32_e64 v89, v221, v89, s[22:23]
	v_subrev_u32_e32 v169, 19, v160
	v_cvt_f32_i32_e32 v170, v169
	v_mul_f32_e32 v170, v165, v170
	v_fma_f32 v91, v91, v144, -v170
	v_cmp_ge_u32_e64 s[22:23], v161, v169
	v_cndmask_b32_e64 v90, v221, v90, vcc
	v_max3_f32 v168, v168, v84, v85
	v_max3_f32 v168, v168, v86, v87
	v_subrev_u32_e32 v169, 32, v160
	v_cvt_f32_i32_e32 v170, v169
	v_mul_f32_e32 v170, v165, v170
	v_fma_f32 v92, v92, v144, -v170
	v_cmp_ge_u32_e64 vcc, v161, v169
	v_cndmask_b32_e64 v91, v221, v91, s[22:23]
	v_subrev_u32_e32 v169, 33, v160
	v_cvt_f32_i32_e32 v170, v169
	v_mul_f32_e32 v170, v165, v170
	v_fma_f32 v93, v93, v144, -v170
	v_cmp_ge_u32_e64 s[22:23], v161, v169
	v_cndmask_b32_e64 v92, v221, v92, vcc
	v_subrev_u32_e32 v169, 34, v160
	v_cvt_f32_i32_e32 v170, v169
	v_mul_f32_e32 v170, v165, v170
	v_fma_f32 v94, v94, v144, -v170
	v_cmp_ge_u32_e64 vcc, v161, v169
	v_cndmask_b32_e64 v93, v221, v93, s[22:23]
	v_subrev_u32_e32 v169, 35, v160
	v_cvt_f32_i32_e32 v170, v169
	v_mul_f32_e32 v170, v165, v170
	v_fma_f32 v95, v95, v144, -v170
	v_cmp_ge_u32_e64 s[22:23], v161, v169
	v_cndmask_b32_e64 v94, v221, v94, vcc
	v_max3_f32 v168, v168, v88, v89
	v_max3_f32 v168, v168, v90, v91
	v_subrev_u32_e32 v169, 48, v160
	v_cvt_f32_i32_e32 v170, v169
	v_mul_f32_e32 v170, v165, v170
	v_fma_f32 v96, v96, v144, -v170
	v_cmp_ge_u32_e64 vcc, v161, v169
	v_cndmask_b32_e64 v95, v221, v95, s[22:23]
	v_subrev_u32_e32 v169, 49, v160
	v_cvt_f32_i32_e32 v170, v169
	v_mul_f32_e32 v170, v165, v170
	v_fma_f32 v97, v97, v144, -v170
	v_cmp_ge_u32_e64 s[22:23], v161, v169
	v_cndmask_b32_e64 v96, v221, v96, vcc
	v_subrev_u32_e32 v169, 50, v160
	v_cvt_f32_i32_e32 v170, v169
	v_mul_f32_e32 v170, v165, v170
	v_fma_f32 v98, v98, v144, -v170
	v_cmp_ge_u32_e64 vcc, v161, v169
	v_cndmask_b32_e64 v97, v221, v97, s[22:23]
	v_subrev_u32_e32 v169, 51, v160
	v_cvt_f32_i32_e32 v170, v169
	v_mul_f32_e32 v170, v165, v170
	v_fma_f32 v99, v99, v144, -v170
	v_cmp_ge_u32_e64 s[22:23], v161, v169
	v_cndmask_b32_e64 v98, v221, v98, vcc
	v_max3_f32 v168, v168, v92, v93
	v_max3_f32 v168, v168, v94, v95
	v_subrev_u32_e32 v169, 64, v160
	v_cvt_f32_i32_e32 v170, v169
	v_mul_f32_e32 v170, v165, v170
	v_fma_f32 v100, v100, v144, -v170
	v_cmp_ge_u32_e64 vcc, v161, v169
	v_cndmask_b32_e64 v99, v221, v99, s[22:23]
	v_subrev_u32_e32 v169, 65, v160
	v_cvt_f32_i32_e32 v170, v169
	v_mul_f32_e32 v170, v165, v170
	v_fma_f32 v101, v101, v144, -v170
	v_cmp_ge_u32_e64 s[22:23], v161, v169
	v_cndmask_b32_e64 v100, v221, v100, vcc
	v_subrev_u32_e32 v169, 66, v160
	v_cvt_f32_i32_e32 v170, v169
	v_mul_f32_e32 v170, v165, v170
	v_fma_f32 v102, v102, v144, -v170
	v_cmp_ge_u32_e64 vcc, v161, v169
	v_cndmask_b32_e64 v101, v221, v101, s[22:23]
	v_subrev_u32_e32 v169, 67, v160
	v_cvt_f32_i32_e32 v170, v169
	v_mul_f32_e32 v170, v165, v170
	v_fma_f32 v103, v103, v144, -v170
	v_cmp_ge_u32_e64 s[22:23], v161, v169
	v_cndmask_b32_e64 v102, v221, v102, vcc
	v_max3_f32 v168, v168, v96, v97
	v_max3_f32 v168, v168, v98, v99
	v_subrev_u32_e32 v169, 80, v160
	v_cvt_f32_i32_e32 v170, v169
	v_mul_f32_e32 v170, v165, v170
	v_fma_f32 v104, v104, v144, -v170
	v_cmp_ge_u32_e64 vcc, v161, v169
	v_cndmask_b32_e64 v103, v221, v103, s[22:23]
	v_subrev_u32_e32 v169, 81, v160
	v_cvt_f32_i32_e32 v170, v169
	v_mul_f32_e32 v170, v165, v170
	v_fma_f32 v105, v105, v144, -v170
	v_cmp_ge_u32_e64 s[22:23], v161, v169
	v_cndmask_b32_e64 v104, v221, v104, vcc
	v_subrev_u32_e32 v169, 82, v160
	v_cvt_f32_i32_e32 v170, v169
	v_mul_f32_e32 v170, v165, v170
	v_fma_f32 v106, v106, v144, -v170
	v_cmp_ge_u32_e64 vcc, v161, v169
	v_cndmask_b32_e64 v105, v221, v105, s[22:23]
	v_subrev_u32_e32 v169, 83, v160
	v_cvt_f32_i32_e32 v170, v169
	v_mul_f32_e32 v170, v165, v170
	v_fma_f32 v107, v107, v144, -v170
	v_cmp_ge_u32_e64 s[22:23], v161, v169
	v_cndmask_b32_e64 v106, v221, v106, vcc
	v_max3_f32 v168, v168, v100, v101
	v_max3_f32 v168, v168, v102, v103
	v_subrev_u32_e32 v169, 96, v160
	v_cvt_f32_i32_e32 v170, v169
	v_mul_f32_e32 v170, v165, v170
	v_fma_f32 v108, v108, v144, -v170
	v_cmp_ge_u32_e64 vcc, v161, v169
	v_cndmask_b32_e64 v107, v221, v107, s[22:23]
	v_subrev_u32_e32 v169, 97, v160
	v_cvt_f32_i32_e32 v170, v169
	v_mul_f32_e32 v170, v165, v170
	v_fma_f32 v109, v109, v144, -v170
	v_cmp_ge_u32_e64 s[22:23], v161, v169
	v_cndmask_b32_e64 v108, v221, v108, vcc
	v_subrev_u32_e32 v169, 98, v160
	v_cvt_f32_i32_e32 v170, v169
	v_mul_f32_e32 v170, v165, v170
	v_fma_f32 v110, v110, v144, -v170
	v_cmp_ge_u32_e64 vcc, v161, v169
	v_cndmask_b32_e64 v109, v221, v109, s[22:23]
	v_subrev_u32_e32 v169, 99, v160
	v_cvt_f32_i32_e32 v170, v169
	v_mul_f32_e32 v170, v165, v170
	v_fma_f32 v111, v111, v144, -v170
	v_cmp_ge_u32_e64 s[22:23], v161, v169
	v_cndmask_b32_e64 v110, v221, v110, vcc
	v_max3_f32 v168, v168, v104, v105
	v_max3_f32 v168, v168, v106, v107
	v_subrev_u32_e32 v169, 112, v160
	v_cvt_f32_i32_e32 v170, v169
	v_mul_f32_e32 v170, v165, v170
	v_fma_f32 v112, v112, v144, -v170
	v_cmp_ge_u32_e64 vcc, v161, v169
	v_cndmask_b32_e64 v111, v221, v111, s[22:23]
	v_subrev_u32_e32 v169, 113, v160
	v_cvt_f32_i32_e32 v170, v169
	v_mul_f32_e32 v170, v165, v170
	v_fma_f32 v113, v113, v144, -v170
	v_cmp_ge_u32_e64 s[22:23], v161, v169
	v_cndmask_b32_e64 v112, v221, v112, vcc
; __device__ __forceinline__ void attn_prompt_item(const bf16_t* z, const bf16_t* vt, bf16_t* mix, const float* sinks, int it, int lane) {
;     ...
; #pragma unroll
;         for (int j = 0; j < 4; ++j) {
;             const int kpos = p0 + 4 * g + j, dist = s0 + l15 - kpos;
;             const bool valid = (dist >= 0) && (dist < 128) && (kpos >= 0);
;             const float v = valid ? a[j] * 0.125f - slope * (float)dist : -1e30f;
;             sc[kt][j] = v; mx = fmaxf(mx, v);
;         }
;     }
;     s16x4 vq[5][4][2];
; #pragma unroll
;     for (int u = 0; u < 5; ++u) {
;         int pos0 = s0 - 128 + 32 * u + 4 * g, pos1 = pos0 + 16;
;         pos0 = pos0 < 0 ? 0 : pos0; pos1 = pos1 < 0 ? 0 : pos1;
; #pragma unroll
;         for (int mi = 0; mi < 4; ++mi) {
;             const bf16_t* vp = vt + (size_t)(kv * 64 + mi * 16 + l15) * T_ALL + (size_t)b * SEQL;
;             vq[u][mi][0] = *(const s16x4*)(vp + pos0); vq[u][mi][1] = *(const s16x4*)(vp + pos1);
;         }
;     }
;     mx = fmaxf(mx, __shfl_xor(mx, 16)); mx = fmaxf(mx, __shfl_xor(mx, 32)); mx = fmaxf(mx, sink);
;     float sum = 0.f;
; #pragma unroll
;     for (int kt = 0; kt < 9; ++kt)
; #pragma unroll
;         for (int j = 0; j < 4; ++j) { const float p = __expf(sc[kt][j] - mx); sc[kt][j] = p; sum += p; }
	v_subrev_u32_e32 v169, 114, v160
	v_cvt_f32_i32_e32 v170, v169
	v_mul_f32_e32 v170, v165, v170
	v_fma_f32 v114, v114, v144, -v170
	v_cmp_ge_u32_e64 vcc, v161, v169
	v_cndmask_b32_e64 v113, v221, v113, s[22:23]
	v_subrev_u32_e32 v169, 115, v160
	v_cvt_f32_i32_e32 v170, v169
	v_mul_f32_e32 v170, v165, v170
	v_fma_f32 v115, v115, v144, -v170
	v_cmp_ge_u32_e64 s[22:23], v161, v169
	v_cndmask_b32_e64 v114, v221, v114, vcc
	v_max3_f32 v168, v168, v108, v109
	v_max3_f32 v168, v168, v110, v111
	v_subrev_u32_e32 v169, 128, v160
	v_cvt_f32_i32_e32 v170, v169
	v_mul_f32_e32 v170, v165, v170
	v_fma_f32 v116, v116, v144, -v170
	v_cmp_ge_u32_e64 vcc, v161, v169
	v_cndmask_b32_e64 v115, v221, v115, s[22:23]
	v_subrev_u32_e32 v169, 129, v160
	v_cvt_f32_i32_e32 v170, v169
	v_mul_f32_e32 v170, v165, v170
	v_fma_f32 v117, v117, v144, -v170
	v_cmp_ge_u32_e64 s[22:23], v161, v169
	v_cndmask_b32_e64 v116, v221, v116, vcc
	v_subrev_u32_e32 v169, 130, v160
	v_cvt_f32_i32_e32 v170, v169
	v_mul_f32_e32 v170, v165, v170
	v_fma_f32 v118, v118, v144, -v170
	v_cmp_ge_u32_e64 vcc, v161, v169
	v_cndmask_b32_e64 v117, v221, v117, s[22:23]
	v_subrev_u32_e32 v169, 131, v160
	v_cvt_f32_i32_e32 v170, v169
	v_mul_f32_e32 v170, v165, v170
	v_fma_f32 v119, v119, v144, -v170
	v_cmp_ge_u32_e64 s[22:23], v161, v169
	v_cndmask_b32_e64 v118, v221, v118, vcc
	v_max3_f32 v168, v168, v112, v113
	v_max3_f32 v168, v168, v114, v115
	s_nop 1
	v_cndmask_b32_e64 v119, v221, v119, s[22:23]
	v_max3_f32 v168, v168, v116, v117
	v_max3_f32 v168, v168, v118, v119
	ds_bpermute_b32 v169, v162, v168
	s_waitcnt lgkmcnt(0)
	v_max_f32_e32 v169, v169, v169
	v_max_f32_e32 v168, v168, v169
	ds_bpermute_b32 v169, v163, v168
	s_waitcnt lgkmcnt(0)
	v_max_f32_e32 v169, v169, v169
	v_max_f32_e32 v168, v168, v169
	v_max_f32_e32 v168, s29, v168
	v_mov_b32_e32 v171, 0
	v_sub_f32_e32 v84, v84, v168
	v_mul_f32_e32 v84, 0x3fb8aa3b, v84
	v_exp_f32_e32 v84, v84
	v_sub_f32_e32 v85, v85, v168
	v_mul_f32_e32 v85, 0x3fb8aa3b, v85
	v_exp_f32_e32 v85, v85
	v_add_f32_e32 v171, v84, v171
	v_sub_f32_e32 v86, v86, v168
	v_mul_f32_e32 v86, 0x3fb8aa3b, v86
	v_exp_f32_e32 v86, v86
	v_add_f32_e32 v171, v85, v171
	v_sub_f32_e32 v87, v87, v168
	v_mul_f32_e32 v87, 0x3fb8aa3b, v87
	v_exp_f32_e32 v87, v87
	v_add_f32_e32 v171, v86, v171
	v_sub_f32_e32 v88, v88, v168
	v_mul_f32_e32 v88, 0x3fb8aa3b, v88
	v_exp_f32_e32 v88, v88
	v_add_f32_e32 v171, v87, v171
	v_sub_f32_e32 v89, v89, v168
	v_mul_f32_e32 v89, 0x3fb8aa3b, v89
	v_exp_f32_e32 v89, v89
	v_add_f32_e32 v171, v88, v171
	v_sub_f32_e32 v90, v90, v168
	v_mul_f32_e32 v90, 0x3fb8aa3b, v90
	v_exp_f32_e32 v90, v90
	v_add_f32_e32 v171, v89, v171
	v_sub_f32_e32 v91, v91, v168
	v_mul_f32_e32 v91, 0x3fb8aa3b, v91
	v_exp_f32_e32 v91, v91
	v_add_f32_e32 v171, v90, v171
	v_sub_f32_e32 v92, v92, v168
	v_mul_f32_e32 v92, 0x3fb8aa3b, v92
	v_exp_f32_e32 v92, v92
	v_add_f32_e32 v171, v91, v171
	v_sub_f32_e32 v93, v93, v168
	v_mul_f32_e32 v93, 0x3fb8aa3b, v93
	v_exp_f32_e32 v93, v93
	v_add_f32_e32 v171, v92, v171
	v_sub_f32_e32 v94, v94, v168
	v_mul_f32_e32 v94, 0x3fb8aa3b, v94
	v_exp_f32_e32 v94, v94
	v_add_f32_e32 v171, v93, v171
	v_sub_f32_e32 v95, v95, v168
	v_mul_f32_e32 v95, 0x3fb8aa3b, v95
	v_exp_f32_e32 v95, v95
	v_add_f32_e32 v171, v94, v171
	v_sub_f32_e32 v96, v96, v168
	v_mul_f32_e32 v96, 0x3fb8aa3b, v96
	v_exp_f32_e32 v96, v96
	v_add_f32_e32 v171, v95, v171
	v_sub_f32_e32 v97, v97, v168
	v_mul_f32_e32 v97, 0x3fb8aa3b, v97
	v_exp_f32_e32 v97, v97
	v_add_f32_e32 v171, v96, v171
	v_sub_f32_e32 v98, v98, v168
	v_mul_f32_e32 v98, 0x3fb8aa3b, v98
	v_exp_f32_e32 v98, v98
	v_add_f32_e32 v171, v97, v171
	v_sub_f32_e32 v99, v99, v168
	v_mul_f32_e32 v99, 0x3fb8aa3b, v99
	v_exp_f32_e32 v99, v99
	v_add_f32_e32 v171, v98, v171
	v_sub_f32_e32 v100, v100, v168
	v_mul_f32_e32 v100, 0x3fb8aa3b, v100
	v_exp_f32_e32 v100, v100
	v_add_f32_e32 v171, v99, v171
	v_sub_f32_e32 v101, v101, v168
	v_mul_f32_e32 v101, 0x3fb8aa3b, v101
	v_exp_f32_e32 v101, v101
	v_add_f32_e32 v171, v100, v171
	v_sub_f32_e32 v102, v102, v168
	v_mul_f32_e32 v102, 0x3fb8aa3b, v102
	v_exp_f32_e32 v102, v102
	v_add_f32_e32 v171, v101, v171
	v_sub_f32_e32 v103, v103, v168
	v_mul_f32_e32 v103, 0x3fb8aa3b, v103
	v_exp_f32_e32 v103, v103
	v_add_f32_e32 v171, v102, v171
	v_sub_f32_e32 v104, v104, v168
	v_mul_f32_e32 v104, 0x3fb8aa3b, v104
	v_exp_f32_e32 v104, v104
	v_add_f32_e32 v171, v103, v171
	v_sub_f32_e32 v105, v105, v168
	v_mul_f32_e32 v105, 0x3fb8aa3b, v105
	v_exp_f32_e32 v105, v105
	v_add_f32_e32 v171, v104, v171
	v_sub_f32_e32 v106, v106, v168
	v_mul_f32_e32 v106, 0x3fb8aa3b, v106
	v_exp_f32_e32 v106, v106
	v_add_f32_e32 v171, v105, v171
	v_sub_f32_e32 v107, v107, v168
	v_mul_f32_e32 v107, 0x3fb8aa3b, v107
	v_exp_f32_e32 v107, v107
	v_add_f32_e32 v171, v106, v171
	v_sub_f32_e32 v108, v108, v168
	v_mul_f32_e32 v108, 0x3fb8aa3b, v108
	v_exp_f32_e32 v108, v108
	v_add_f32_e32 v171, v107, v171
	v_sub_f32_e32 v109, v109, v168
	v_mul_f32_e32 v109, 0x3fb8aa3b, v109
	v_exp_f32_e32 v109, v109
	v_add_f32_e32 v171, v108, v171
	v_sub_f32_e32 v110, v110, v168
	v_mul_f32_e32 v110, 0x3fb8aa3b, v110
	v_exp_f32_e32 v110, v110
	v_add_f32_e32 v171, v109, v171
	v_sub_f32_e32 v111, v111, v168
	v_mul_f32_e32 v111, 0x3fb8aa3b, v111
	v_exp_f32_e32 v111, v111
	v_add_f32_e32 v171, v110, v171
	v_sub_f32_e32 v112, v112, v168
	v_mul_f32_e32 v112, 0x3fb8aa3b, v112
	v_exp_f32_e32 v112, v112
	v_add_f32_e32 v171, v111, v171
	v_sub_f32_e32 v113, v113, v168
	v_mul_f32_e32 v113, 0x3fb8aa3b, v113
	v_exp_f32_e32 v113, v113
	v_add_f32_e32 v171, v112, v171
	v_sub_f32_e32 v114, v114, v168
	v_mul_f32_e32 v114, 0x3fb8aa3b, v114
	v_exp_f32_e32 v114, v114
	v_add_f32_e32 v171, v113, v171
	v_sub_f32_e32 v115, v115, v168
	v_mul_f32_e32 v115, 0x3fb8aa3b, v115
	v_exp_f32_e32 v115, v115
	v_add_f32_e32 v171, v114, v171
	v_sub_f32_e32 v116, v116, v168
	v_mul_f32_e32 v116, 0x3fb8aa3b, v116
	v_exp_f32_e32 v116, v116
	v_add_f32_e32 v171, v115, v171
	v_sub_f32_e32 v117, v117, v168
	v_mul_f32_e32 v117, 0x3fb8aa3b, v117
	v_exp_f32_e32 v117, v117
	v_add_f32_e32 v171, v116, v171
	v_sub_f32_e32 v118, v118, v168
	v_mul_f32_e32 v118, 0x3fb8aa3b, v118
	v_exp_f32_e32 v118, v118
	v_add_f32_e32 v171, v117, v171
	v_sub_f32_e32 v119, v119, v168
	v_mul_f32_e32 v119, 0x3fb8aa3b, v119
	v_exp_f32_e32 v119, v119
	v_add_f32_e32 v171, v118, v171
	v_sub_f32_e32 v172, s29, v168
	v_add_f32_e32 v171, v119, v171
	v_mul_f32_e32 v172, 0x3fb8aa3b, v172
	v_exp_f32_e32 v172, v172
	ds_bpermute_b32 v169, v162, v171
	s_waitcnt lgkmcnt(0)
; #define MFMA16(a, b, c) __builtin_amdgcn_mfma_f32_16x16x32_bf16((a), (b), (c), 0, 0, 0)
; __device__ __forceinline__ unsigned pk2(float lo, float hi) { return pg8::cvt_pk_bf16(lo, hi); }
; __device__ __forceinline__ void attn_prompt_item(const bf16_t* z, const bf16_t* vt, bf16_t* mix, const float* sinks, int it, int lane) {
;     ...
;     sum += __shfl_xor(sum, 16); sum += __shfl_xor(sum, 32);
;     const float inv = 1.0f / (sum + __expf(sink - mx));
;     f32x4 o[4];
; #pragma unroll
;     for (int mi = 0; mi < 4; ++mi) o[mi] = (f32x4){0.f, 0.f, 0.f, 0.f};
; #pragma unroll
;     for (int u = 0; u < 5; ++u) {
;         u32x4 pw; pw.x = pk2(sc[2 * u][0] * inv, sc[2 * u][1] * inv); pw.y = pk2(sc[2 * u][2] * inv, sc[2 * u][3] * inv);
;         if (2 * u + 1 < 9) { pw.z = pk2(sc[(2 * u + 1) % 9][0] * inv, sc[(2 * u + 1) % 9][1] * inv); pw.w = pk2(sc[(2 * u + 1) % 9][2] * inv, sc[(2 * u + 1) % 9][3] * inv); }
;         else { pw.z = 0u; pw.w = 0u; }
;         const bf16x8 pb = as_bf16x8(pw);
; #pragma unroll
;         for (int mi = 0; mi < 4; ++mi) {
;             const s16x4 v0 = vq[u][mi][0], v1 = vq[u][mi][1];
;             const bf16x8 va = (bf16x8){v0[0], v0[1], v0[2], v0[3], v1[0], v1[1], v1[2], v1[3]};
;             o[mi] = MFMA16(va, pb, o[mi]);
;         }
;     }
	v_add_f32_e32 v171, v171, v169
	ds_bpermute_b32 v169, v163, v171
	s_waitcnt lgkmcnt(0)
	v_add_f32_e32 v171, v171, v169
	v_add_f32_e32 v171, v171, v172
	v_div_scale_f32 v169, s[22:23], v171, v171, 1.0
	v_rcp_f32_e32 v170, v169
	s_nop 0
	v_fma_f32 v172, -v169, v170, 1.0
	v_fmac_f32_e32 v170, v172, v170
	v_div_scale_f32 v172, vcc, 1.0, v171, 1.0
	v_mul_f32_e32 v173, v172, v170
	v_fma_f32 v174, -v169, v173, v172
	v_fmac_f32_e32 v173, v174, v170
	v_fma_f32 v169, -v169, v173, v172
	v_div_fmas_f32 v169, v169, v170, v173
	v_div_fixup_f32 v174, v169, v171, 1.0
	v_pk_mul_f32 v[170:171], v[84:85], v[174:175] op_sel_hi:[1,0]
	v_cvt_pk_bf16_f32 v84, v170, v171
	v_pk_mul_f32 v[170:171], v[86:87], v[174:175] op_sel_hi:[1,0]
	v_cvt_pk_bf16_f32 v85, v170, v171
	v_pk_mul_f32 v[170:171], v[88:89], v[174:175] op_sel_hi:[1,0]
	v_cvt_pk_bf16_f32 v86, v170, v171
	v_pk_mul_f32 v[170:171], v[90:91], v[174:175] op_sel_hi:[1,0]
	v_cvt_pk_bf16_f32 v87, v170, v171
	v_pk_mul_f32 v[170:171], v[92:93], v[174:175] op_sel_hi:[1,0]
	v_cvt_pk_bf16_f32 v88, v170, v171
	v_pk_mul_f32 v[170:171], v[94:95], v[174:175] op_sel_hi:[1,0]
	v_cvt_pk_bf16_f32 v89, v170, v171
	v_pk_mul_f32 v[170:171], v[96:97], v[174:175] op_sel_hi:[1,0]
	v_cvt_pk_bf16_f32 v90, v170, v171
	v_pk_mul_f32 v[170:171], v[98:99], v[174:175] op_sel_hi:[1,0]
	v_cvt_pk_bf16_f32 v91, v170, v171
	v_pk_mul_f32 v[170:171], v[100:101], v[174:175] op_sel_hi:[1,0]
	v_cvt_pk_bf16_f32 v92, v170, v171
	v_pk_mul_f32 v[170:171], v[102:103], v[174:175] op_sel_hi:[1,0]
	v_cvt_pk_bf16_f32 v93, v170, v171
	v_pk_mul_f32 v[170:171], v[104:105], v[174:175] op_sel_hi:[1,0]
	v_cvt_pk_bf16_f32 v94, v170, v171
	v_pk_mul_f32 v[170:171], v[106:107], v[174:175] op_sel_hi:[1,0]
	v_cvt_pk_bf16_f32 v95, v170, v171
	v_pk_mul_f32 v[170:171], v[108:109], v[174:175] op_sel_hi:[1,0]
	v_cvt_pk_bf16_f32 v96, v170, v171
	v_pk_mul_f32 v[170:171], v[110:111], v[174:175] op_sel_hi:[1,0]
	v_cvt_pk_bf16_f32 v97, v170, v171
	v_pk_mul_f32 v[170:171], v[112:113], v[174:175] op_sel_hi:[1,0]
	v_cvt_pk_bf16_f32 v98, v170, v171
	v_pk_mul_f32 v[170:171], v[114:115], v[174:175] op_sel_hi:[1,0]
	v_cvt_pk_bf16_f32 v99, v170, v171
	v_pk_mul_f32 v[170:171], v[116:117], v[174:175] op_sel_hi:[1,0]
	v_cvt_pk_bf16_f32 v100, v170, v171
	v_pk_mul_f32 v[170:171], v[118:119], v[174:175] op_sel_hi:[1,0]
	v_cvt_pk_bf16_f32 v101, v170, v171
	v_mov_b32_e32 v102, 0
	v_mov_b32_e32 v103, 0
	s_nop 1
	s_waitcnt lgkmcnt(12)
	v_mfma_f32_16x16x32_bf16 v[4:7], v[20:23], v[84:87], 0
	ds_read_b64 v[20:21], v159 offset:25408
	ds_read_b64 v[22:23], v159 offset:25440
	s_waitcnt lgkmcnt(12)
	v_mfma_f32_16x16x32_bf16 v[8:11], v[24:27], v[84:87], 0
	ds_read_b64 v[24:25], v159 offset:128
	ds_read_b64 v[26:27], v159 offset:160
	s_waitcnt lgkmcnt(12)
	v_mfma_f32_16x16x32_bf16 v[12:15], v[28:31], v[84:87], 0
	ds_read_b64 v[28:29], v159 offset:8576
	ds_read_b64 v[30:31], v159 offset:8608
	s_waitcnt lgkmcnt(12)
	v_mfma_f32_16x16x32_bf16 v[16:19], v[32:35], v[84:87], 0
	ds_read_b64 v[32:33], v159 offset:17024
	ds_read_b64 v[34:35], v159 offset:17056
	s_waitcnt lgkmcnt(12)
	v_mfma_f32_16x16x32_bf16 v[4:7], v[36:39], v[88:91], v[4:7]
	ds_read_b64 v[36:37], v159 offset:25472
	ds_read_b64 v[38:39], v159 offset:25504
	s_waitcnt lgkmcnt(12)
	v_mfma_f32_16x16x32_bf16 v[8:11], v[72:75], v[88:91], v[8:11]
	ds_read_b64 v[72:73], v159 offset:192
	ds_read_b64 v[74:75], v159 offset:224
	s_waitcnt lgkmcnt(12)
	v_mfma_f32_16x16x32_bf16 v[12:15], v[76:79], v[88:91], v[12:15]
	ds_read_b64 v[76:77], v159 offset:8640
	ds_read_b64 v[78:79], v159 offset:8672
	s_waitcnt lgkmcnt(12)
	v_mfma_f32_16x16x32_bf16 v[16:19], v[20:23], v[88:91], v[16:19]
	ds_read_b64 v[20:21], v159 offset:17088
	ds_read_b64 v[22:23], v159 offset:17120
	s_waitcnt lgkmcnt(12)
	v_mfma_f32_16x16x32_bf16 v[4:7], v[24:27], v[92:95], v[4:7]
	ds_read_b64 v[24:25], v159 offset:25536
	ds_read_b64 v[26:27], v159 offset:25568
	s_waitcnt lgkmcnt(12)
	v_mfma_f32_16x16x32_bf16 v[8:11], v[28:31], v[92:95], v[8:11]
	ds_read_b64 v[28:29], v159 offset:256
	ds_read_b64 v[30:31], v159 offset:288
	s_waitcnt lgkmcnt(12)
	v_mfma_f32_16x16x32_bf16 v[12:15], v[32:35], v[92:95], v[12:15]
	ds_read_b64 v[32:33], v159 offset:8704
	ds_read_b64 v[34:35], v159 offset:8736
	s_waitcnt lgkmcnt(12)
	v_mfma_f32_16x16x32_bf16 v[16:19], v[36:39], v[92:95], v[16:19]
	ds_read_b64 v[36:37], v159 offset:17152
	ds_read_b64 v[38:39], v159 offset:17184
	s_waitcnt lgkmcnt(12)
	v_mfma_f32_16x16x32_bf16 v[4:7], v[72:75], v[96:99], v[4:7]
	ds_read_b64 v[72:73], v159 offset:25600
	ds_read_b64 v[74:75], v159 offset:25632
	s_waitcnt lgkmcnt(12)
	v_mfma_f32_16x16x32_bf16 v[8:11], v[76:79], v[96:99], v[8:11]
	s_waitcnt lgkmcnt(10)
	v_mfma_f32_16x16x32_bf16 v[12:15], v[20:23], v[96:99], v[12:15]
	s_waitcnt lgkmcnt(8)
	v_mfma_f32_16x16x32_bf16 v[16:19], v[24:27], v[96:99], v[16:19]
	s_waitcnt lgkmcnt(6)
	v_mfma_f32_16x16x32_bf16 v[4:7], v[28:31], v[100:103], v[4:7]
	s_waitcnt lgkmcnt(4)
	v_mfma_f32_16x16x32_bf16 v[8:11], v[32:35], v[100:103], v[8:11]
	s_waitcnt lgkmcnt(2)
	v_mfma_f32_16x16x32_bf16 v[12:15], v[36:39], v[100:103], v[12:15]
	s_waitcnt lgkmcnt(0)
	v_mfma_f32_16x16x32_bf16 v[16:19], v[72:75], v[100:103], v[16:19]
	s_nop 7
	s_waitcnt vmcnt(0)
; #define MFMA16(a, b, c) __builtin_amdgcn_mfma_f32_16x16x32_bf16((a), (b), (c), 0, 0, 0)
; __device__ __forceinline__ float bf_lo(unsigned w) { return __uint_as_float(w << 16); }
; __device__ __forceinline__ float bf_hi(unsigned w) { return __uint_as_float(w & 0xffff0000u); }
; __device__ __forceinline__ unsigned pk2(float lo, float hi) { return pg8::cvt_pk_bf16(lo, hi); }
; __device__ __forceinline__ void attn_prompt_item(const bf16_t* z, const bf16_t* vt, bf16_t* mix, const float* sinks, int it, int lane) {
;     ...
; #pragma unroll
;     for (int kt = 0; kt < 9; ++kt) {
;         const int p0 = s0 - 128 + 16 * kt;
;         const int key = p0 + l15, keyc = key < 0 ? 0 : key;
;         const bf16_t* kp = z + ((size_t)b * SEQL + keyc) * EIN + 1024 + kv * 64 + 8 * g;
;         const bf16x8 k0 = *(const bf16x8*)kp, k1 = *(const bf16x8*)(kp + 32);
;         f32x4 a = {0.f, 0.f, 0.f, 0.f};
;         a = MFMA16(k0, qf0, a); a = MFMA16(k1, qf1, a);
; #pragma unroll
;         for (int j = 0; j < 4; ++j) {
;             const int kpos = p0 + 4 * g + j, dist = s0 + l15 - kpos;
;             const bool valid = (dist >= 0) && (dist < 128) && (kpos >= 0);
;             const float v = valid ? a[j] * 0.125f - slope * (float)dist : -1e30f;
;             sc[kt][j] = v; mx = fmaxf(mx, v);
;         }
;     ...
; #pragma unroll
;     for (int mi = 0; mi < 4; ++mi) {
;         const int col = h * 64 + mi * 16 + 4 * g;
;         const u32x2 gw = *(const u32x2*)(z + tokq * EIN + 1280 + col);
;         u32x2 w; w.x = pk2(o[mi][0] * bf_lo(gw.x), o[mi][1] * bf_hi(gw.x)); w.y = pk2(o[mi][2] * bf_lo(gw.y), o[mi][3] * bf_hi(gw.y));
;         *(u32x2*)(mix + tokq * 2048 + col) = w;
;     }
	v_lshlrev_b32_e32 v172, 16, v130
	v_and_b32_e32 v173, 0xffff0000, v130
	v_lshlrev_b32_e32 v174, 16, v131
	v_and_b32_e32 v175, 0xffff0000, v131
	v_mul_f32_e32 v172, v4, v172
	v_mul_f32_e32 v173, v5, v173
	v_mul_f32_e32 v174, v6, v174
	v_mul_f32_e32 v175, v7, v175
	v_cvt_pk_bf16_f32 v170, v172, v173
	v_cvt_pk_bf16_f32 v171, v174, v175
	global_store_dwordx2 v157, v[170:171], s[14:15] offset:128
	v_lshlrev_b32_e32 v172, 16, v132
	v_and_b32_e32 v173, 0xffff0000, v132
	v_lshlrev_b32_e32 v174, 16, v133
	v_and_b32_e32 v175, 0xffff0000, v133
	v_mul_f32_e32 v172, v8, v172
	v_mul_f32_e32 v173, v9, v173
	v_mul_f32_e32 v174, v10, v174
	v_mul_f32_e32 v175, v11, v175
	v_cvt_pk_bf16_f32 v170, v172, v173
	v_cvt_pk_bf16_f32 v171, v174, v175
	global_store_dwordx2 v157, v[170:171], s[14:15] offset:160
	v_lshlrev_b32_e32 v172, 16, v134
	v_and_b32_e32 v173, 0xffff0000, v134
	v_lshlrev_b32_e32 v174, 16, v135
	v_and_b32_e32 v175, 0xffff0000, v135
	v_mul_f32_e32 v172, v12, v172
	v_mul_f32_e32 v173, v13, v173
	v_mul_f32_e32 v174, v14, v174
	v_mul_f32_e32 v175, v15, v175
	v_cvt_pk_bf16_f32 v170, v172, v173
	v_cvt_pk_bf16_f32 v171, v174, v175
	global_store_dwordx2 v157, v[170:171], s[14:15] offset:192
	v_lshlrev_b32_e32 v172, 16, v136
	v_and_b32_e32 v173, 0xffff0000, v136
	v_lshlrev_b32_e32 v174, 16, v137
	v_and_b32_e32 v175, 0xffff0000, v137
	v_mul_f32_e32 v172, v16, v172
	v_mul_f32_e32 v173, v17, v173
	v_mul_f32_e32 v174, v18, v174
	v_mul_f32_e32 v175, v19, v175
	v_cvt_pk_bf16_f32 v170, v172, v173
	v_cvt_pk_bf16_f32 v171, v174, v175
	global_store_dwordx2 v157, v[170:171], s[14:15] offset:224
	global_load_dwordx2 v[130:131], v156, s[26:27] offset:256
	global_load_dwordx2 v[132:133], v156, s[26:27] offset:288
	global_load_dwordx2 v[134:135], v156, s[26:27] offset:320
	global_load_dwordx2 v[136:137], v156, s[26:27] offset:352
	ds_read_b128 v[20:23], v158 offset:0
	ds_read_b128 v[24:27], v158 offset:64
	ds_read_b128 v[28:31], v158 offset:2304
	ds_read_b128 v[32:35], v158 offset:2368
	ds_read_b128 v[36:39], v158 offset:4608
	ds_read_b128 v[72:75], v158 offset:4672
	ds_read_b128 v[76:79], v158 offset:6912
	ds_read_b128 v[126:129], v158 offset:6976
	s_waitcnt lgkmcnt(7)
	v_mfma_f32_16x16x32_bf16 v[84:87], v[20:23], v[56:59], 0
	ds_read_b128 v[20:23], v158 offset:9216
	s_waitcnt lgkmcnt(7)
	v_mfma_f32_16x16x32_bf16 v[84:87], v[24:27], v[60:63], v[84:87]
	ds_read_b128 v[24:27], v158 offset:9280
	s_waitcnt lgkmcnt(7)
	v_mfma_f32_16x16x32_bf16 v[88:91], v[28:31], v[56:59], 0
	ds_read_b128 v[28:31], v158 offset:11520
	s_waitcnt lgkmcnt(7)
	v_mfma_f32_16x16x32_bf16 v[88:91], v[32:35], v[60:63], v[88:91]
	ds_read_b128 v[32:35], v158 offset:11584
	s_waitcnt lgkmcnt(7)
	v_mfma_f32_16x16x32_bf16 v[92:95], v[36:39], v[56:59], 0
	ds_read_b128 v[36:39], v158 offset:13824
	s_waitcnt lgkmcnt(7)
	v_mfma_f32_16x16x32_bf16 v[92:95], v[72:75], v[60:63], v[92:95]
	ds_read_b128 v[72:75], v158 offset:13888
	s_waitcnt lgkmcnt(7)
	v_mfma_f32_16x16x32_bf16 v[96:99], v[76:79], v[56:59], 0
	ds_read_b128 v[76:79], v158 offset:16128
	s_waitcnt lgkmcnt(7)
	v_mfma_f32_16x16x32_bf16 v[96:99], v[126:129], v[60:63], v[96:99]
	ds_read_b128 v[126:129], v158 offset:16192
	s_waitcnt lgkmcnt(7)
	v_mfma_f32_16x16x32_bf16 v[100:103], v[20:23], v[56:59], 0
	ds_read_b128 v[20:23], v158 offset:18432
	s_waitcnt lgkmcnt(7)
	v_mfma_f32_16x16x32_bf16 v[100:103], v[24:27], v[60:63], v[100:103]
	ds_read_b128 v[24:27], v158 offset:18496
	s_waitcnt lgkmcnt(7)
	v_mfma_f32_16x16x32_bf16 v[104:107], v[28:31], v[56:59], 0
	s_waitcnt lgkmcnt(6)
	v_mfma_f32_16x16x32_bf16 v[104:107], v[32:35], v[60:63], v[104:107]
	s_waitcnt lgkmcnt(5)
	v_mfma_f32_16x16x32_bf16 v[108:111], v[36:39], v[56:59], 0
	s_waitcnt lgkmcnt(4)
	v_mfma_f32_16x16x32_bf16 v[108:111], v[72:75], v[60:63], v[108:111]
	s_waitcnt lgkmcnt(3)
	v_mfma_f32_16x16x32_bf16 v[112:115], v[76:79], v[56:59], 0
	s_waitcnt lgkmcnt(2)
	v_mfma_f32_16x16x32_bf16 v[112:115], v[126:129], v[60:63], v[112:115]
	s_waitcnt lgkmcnt(1)
	v_mfma_f32_16x16x32_bf16 v[116:119], v[20:23], v[56:59], 0
	s_waitcnt lgkmcnt(0)
	v_mfma_f32_16x16x32_bf16 v[116:119], v[24:27], v[60:63], v[116:119]
	ds_read_b64 v[20:21], v159 offset:0
	ds_read_b64 v[22:23], v159 offset:32
	ds_read_b64 v[24:25], v159 offset:8448
	ds_read_b64 v[26:27], v159 offset:8480
	ds_read_b64 v[28:29], v159 offset:16896
	ds_read_b64 v[30:31], v159 offset:16928
	ds_read_b64 v[32:33], v159 offset:25344
	ds_read_b64 v[34:35], v159 offset:25376
	ds_read_b64 v[36:37], v159 offset:64
	ds_read_b64 v[38:39], v159 offset:96
	ds_read_b64 v[72:73], v159 offset:8512
	ds_read_b64 v[74:75], v159 offset:8544
	ds_read_b64 v[76:77], v159 offset:16960
	ds_read_b64 v[78:79], v159 offset:16992
	s_nop 4
	v_mov_b32_e32 v168, 0xf149f2ca
	v_mov_b32_e32 v169, v160
	v_cvt_f32_i32_e32 v170, v169
	v_mul_f32_e32 v170, v166, v170
	v_fma_f32 v84, v84, v144, -v170
	v_cmp_ge_u32_e64 vcc, v161, v169
	v_subrev_u32_e32 v169, 1, v160
	v_cvt_f32_i32_e32 v170, v169
	v_mul_f32_e32 v170, v166, v170
	v_fma_f32 v85, v85, v144, -v170
	v_cmp_ge_u32_e64 s[22:23], v161, v169
	v_cndmask_b32_e64 v84, v221, v84, vcc
	v_subrev_u32_e32 v169, 2, v160
	v_cvt_f32_i32_e32 v170, v169
	v_mul_f32_e32 v170, v166, v170
	v_fma_f32 v86, v86, v144, -v170
	v_cmp_ge_u32_e64 vcc, v161, v169
	v_cndmask_b32_e64 v85, v221, v85, s[22:23]
	v_subrev_u32_e32 v169, 3, v160
	v_cvt_f32_i32_e32 v170, v169
	v_mul_f32_e32 v170, v166, v170
	v_fma_f32 v87, v87, v144, -v170
	v_cmp_ge_u32_e64 s[22:23], v161, v169
	v_cndmask_b32_e64 v86, v221, v86, vcc
	v_subrev_u32_e32 v169, 16, v160
	v_cvt_f32_i32_e32 v170, v169
	v_mul_f32_e32 v170, v166, v170
	v_fma_f32 v88, v88, v144, -v170
	v_cmp_ge_u32_e64 vcc, v161, v169
; __device__ __forceinline__ void attn_prompt_item(const bf16_t* z, const bf16_t* vt, bf16_t* mix, const float* sinks, int it, int lane) {
;     ...
; #pragma unroll
;         for (int j = 0; j < 4; ++j) {
;             const int kpos = p0 + 4 * g + j, dist = s0 + l15 - kpos;
;             const bool valid = (dist >= 0) && (dist < 128) && (kpos >= 0);
;             const float v = valid ? a[j] * 0.125f - slope * (float)dist : -1e30f;
;             sc[kt][j] = v; mx = fmaxf(mx, v);
;         }
	v_cndmask_b32_e64 v87, v221, v87, s[22:23]
	v_subrev_u32_e32 v169, 17, v160
	v_cvt_f32_i32_e32 v170, v169
	v_mul_f32_e32 v170, v166, v170
	v_fma_f32 v89, v89, v144, -v170
	v_cmp_ge_u32_e64 s[22:23], v161, v169
	v_cndmask_b32_e64 v88, v221, v88, vcc
	v_subrev_u32_e32 v169, 18, v160
	v_cvt_f32_i32_e32 v170, v169
	v_mul_f32_e32 v170, v166, v170
	v_fma_f32 v90, v90, v144, -v170
	v_cmp_ge_u32_e64 vcc, v161, v169
	v_cndmask_b32_e64 v89, v221, v89, s[22:23]
	v_subrev_u32_e32 v169, 19, v160
	v_cvt_f32_i32_e32 v170, v169
	v_mul_f32_e32 v170, v166, v170
	v_fma_f32 v91, v91, v144, -v170
	v_cmp_ge_u32_e64 s[22:23], v161, v169
	v_cndmask_b32_e64 v90, v221, v90, vcc
	v_max3_f32 v168, v168, v84, v85
	v_max3_f32 v168, v168, v86, v87
	v_subrev_u32_e32 v169, 32, v160
	v_cvt_f32_i32_e32 v170, v169
	v_mul_f32_e32 v170, v166, v170
	v_fma_f32 v92, v92, v144, -v170
	v_cmp_ge_u32_e64 vcc, v161, v169
	v_cndmask_b32_e64 v91, v221, v91, s[22:23]
	v_subrev_u32_e32 v169, 33, v160
	v_cvt_f32_i32_e32 v170, v169
	v_mul_f32_e32 v170, v166, v170
	v_fma_f32 v93, v93, v144, -v170
	v_cmp_ge_u32_e64 s[22:23], v161, v169
	v_cndmask_b32_e64 v92, v221, v92, vcc
	v_subrev_u32_e32 v169, 34, v160
	v_cvt_f32_i32_e32 v170, v169
	v_mul_f32_e32 v170, v166, v170
	v_fma_f32 v94, v94, v144, -v170
	v_cmp_ge_u32_e64 vcc, v161, v169
	v_cndmask_b32_e64 v93, v221, v93, s[22:23]
	v_subrev_u32_e32 v169, 35, v160
	v_cvt_f32_i32_e32 v170, v169
	v_mul_f32_e32 v170, v166, v170
	v_fma_f32 v95, v95, v144, -v170
	v_cmp_ge_u32_e64 s[22:23], v161, v169
	v_cndmask_b32_e64 v94, v221, v94, vcc
	v_max3_f32 v168, v168, v88, v89
	v_max3_f32 v168, v168, v90, v91
	v_subrev_u32_e32 v169, 48, v160
	v_cvt_f32_i32_e32 v170, v169
	v_mul_f32_e32 v170, v166, v170
	v_fma_f32 v96, v96, v144, -v170
	v_cmp_ge_u32_e64 vcc, v161, v169
	v_cndmask_b32_e64 v95, v221, v95, s[22:23]
	v_subrev_u32_e32 v169, 49, v160
	v_cvt_f32_i32_e32 v170, v169
	v_mul_f32_e32 v170, v166, v170
	v_fma_f32 v97, v97, v144, -v170
	v_cmp_ge_u32_e64 s[22:23], v161, v169
	v_cndmask_b32_e64 v96, v221, v96, vcc
	v_subrev_u32_e32 v169, 50, v160
	v_cvt_f32_i32_e32 v170, v169
	v_mul_f32_e32 v170, v166, v170
	v_fma_f32 v98, v98, v144, -v170
	v_cmp_ge_u32_e64 vcc, v161, v169
	v_cndmask_b32_e64 v97, v221, v97, s[22:23]
	v_subrev_u32_e32 v169, 51, v160
	v_cvt_f32_i32_e32 v170, v169
	v_mul_f32_e32 v170, v166, v170
	v_fma_f32 v99, v99, v144, -v170
	v_cmp_ge_u32_e64 s[22:23], v161, v169
	v_cndmask_b32_e64 v98, v221, v98, vcc
	v_max3_f32 v168, v168, v92, v93
	v_max3_f32 v168, v168, v94, v95
	v_subrev_u32_e32 v169, 64, v160
	v_cvt_f32_i32_e32 v170, v169
	v_mul_f32_e32 v170, v166, v170
	v_fma_f32 v100, v100, v144, -v170
	v_cmp_ge_u32_e64 vcc, v161, v169
	v_cndmask_b32_e64 v99, v221, v99, s[22:23]
	v_subrev_u32_e32 v169, 65, v160
	v_cvt_f32_i32_e32 v170, v169
	v_mul_f32_e32 v170, v166, v170
	v_fma_f32 v101, v101, v144, -v170
	v_cmp_ge_u32_e64 s[22:23], v161, v169
	v_cndmask_b32_e64 v100, v221, v100, vcc
	v_subrev_u32_e32 v169, 66, v160
	v_cvt_f32_i32_e32 v170, v169
	v_mul_f32_e32 v170, v166, v170
	v_fma_f32 v102, v102, v144, -v170
	v_cmp_ge_u32_e64 vcc, v161, v169
	v_cndmask_b32_e64 v101, v221, v101, s[22:23]
	v_subrev_u32_e32 v169, 67, v160
	v_cvt_f32_i32_e32 v170, v169
	v_mul_f32_e32 v170, v166, v170
	v_fma_f32 v103, v103, v144, -v170
	v_cmp_ge_u32_e64 s[22:23], v161, v169
	v_cndmask_b32_e64 v102, v221, v102, vcc
	v_max3_f32 v168, v168, v96, v97
	v_max3_f32 v168, v168, v98, v99
	v_subrev_u32_e32 v169, 80, v160
	v_cvt_f32_i32_e32 v170, v169
	v_mul_f32_e32 v170, v166, v170
	v_fma_f32 v104, v104, v144, -v170
	v_cmp_ge_u32_e64 vcc, v161, v169
	v_cndmask_b32_e64 v103, v221, v103, s[22:23]
	v_subrev_u32_e32 v169, 81, v160
	v_cvt_f32_i32_e32 v170, v169
	v_mul_f32_e32 v170, v166, v170
	v_fma_f32 v105, v105, v144, -v170
	v_cmp_ge_u32_e64 s[22:23], v161, v169
	v_cndmask_b32_e64 v104, v221, v104, vcc
	v_subrev_u32_e32 v169, 82, v160
	v_cvt_f32_i32_e32 v170, v169
	v_mul_f32_e32 v170, v166, v170
	v_fma_f32 v106, v106, v144, -v170
	v_cmp_ge_u32_e64 vcc, v161, v169
	v_cndmask_b32_e64 v105, v221, v105, s[22:23]
	v_subrev_u32_e32 v169, 83, v160
	v_cvt_f32_i32_e32 v170, v169
	v_mul_f32_e32 v170, v166, v170
	v_fma_f32 v107, v107, v144, -v170
	v_cmp_ge_u32_e64 s[22:23], v161, v169
	v_cndmask_b32_e64 v106, v221, v106, vcc
	v_max3_f32 v168, v168, v100, v101
	v_max3_f32 v168, v168, v102, v103
	v_subrev_u32_e32 v169, 96, v160
	v_cvt_f32_i32_e32 v170, v169
	v_mul_f32_e32 v170, v166, v170
	v_fma_f32 v108, v108, v144, -v170
	v_cmp_ge_u32_e64 vcc, v161, v169
	v_cndmask_b32_e64 v107, v221, v107, s[22:23]
	v_subrev_u32_e32 v169, 97, v160
	v_cvt_f32_i32_e32 v170, v169
	v_mul_f32_e32 v170, v166, v170
	v_fma_f32 v109, v109, v144, -v170
	v_cmp_ge_u32_e64 s[22:23], v161, v169
	v_cndmask_b32_e64 v108, v221, v108, vcc
	v_subrev_u32_e32 v169, 98, v160
	v_cvt_f32_i32_e32 v170, v169
	v_mul_f32_e32 v170, v166, v170
	v_fma_f32 v110, v110, v144, -v170
	v_cmp_ge_u32_e64 vcc, v161, v169
	v_cndmask_b32_e64 v109, v221, v109, s[22:23]
	v_subrev_u32_e32 v169, 99, v160
	v_cvt_f32_i32_e32 v170, v169
	v_mul_f32_e32 v170, v166, v170
	v_fma_f32 v111, v111, v144, -v170
	v_cmp_ge_u32_e64 s[22:23], v161, v169
	v_cndmask_b32_e64 v110, v221, v110, vcc
	v_max3_f32 v168, v168, v104, v105
	v_max3_f32 v168, v168, v106, v107
	v_subrev_u32_e32 v169, 112, v160
	v_cvt_f32_i32_e32 v170, v169
	v_mul_f32_e32 v170, v166, v170
	v_fma_f32 v112, v112, v144, -v170
	v_cmp_ge_u32_e64 vcc, v161, v169
	v_cndmask_b32_e64 v111, v221, v111, s[22:23]
	v_subrev_u32_e32 v169, 113, v160
	v_cvt_f32_i32_e32 v170, v169
	v_mul_f32_e32 v170, v166, v170
	v_fma_f32 v113, v113, v144, -v170
	v_cmp_ge_u32_e64 s[22:23], v161, v169
	v_cndmask_b32_e64 v112, v221, v112, vcc
; __device__ __forceinline__ void attn_prompt_item(const bf16_t* z, const bf16_t* vt, bf16_t* mix, const float* sinks, int it, int lane) {
;     ...
; #pragma unroll
;         for (int j = 0; j < 4; ++j) {
;             const int kpos = p0 + 4 * g + j, dist = s0 + l15 - kpos;
;             const bool valid = (dist >= 0) && (dist < 128) && (kpos >= 0);
;             const float v = valid ? a[j] * 0.125f - slope * (float)dist : -1e30f;
;             sc[kt][j] = v; mx = fmaxf(mx, v);
;         }
;     }
;     s16x4 vq[5][4][2];
; #pragma unroll
;     for (int u = 0; u < 5; ++u) {
;         int pos0 = s0 - 128 + 32 * u + 4 * g, pos1 = pos0 + 16;
;         pos0 = pos0 < 0 ? 0 : pos0; pos1 = pos1 < 0 ? 0 : pos1;
; #pragma unroll
;         for (int mi = 0; mi < 4; ++mi) {
;             const bf16_t* vp = vt + (size_t)(kv * 64 + mi * 16 + l15) * T_ALL + (size_t)b * SEQL;
;             vq[u][mi][0] = *(const s16x4*)(vp + pos0); vq[u][mi][1] = *(const s16x4*)(vp + pos1);
;         }
;     }
;     mx = fmaxf(mx, __shfl_xor(mx, 16)); mx = fmaxf(mx, __shfl_xor(mx, 32)); mx = fmaxf(mx, sink);
;     float sum = 0.f;
; #pragma unroll
;     for (int kt = 0; kt < 9; ++kt)
; #pragma unroll
;         for (int j = 0; j < 4; ++j) { const float p = __expf(sc[kt][j] - mx); sc[kt][j] = p; sum += p; }
;     sum += __shfl_xor(sum, 16); sum += __shfl_xor(sum, 32);
	v_subrev_u32_e32 v169, 114, v160
	v_cvt_f32_i32_e32 v170, v169
	v_mul_f32_e32 v170, v166, v170
	v_fma_f32 v114, v114, v144, -v170
	v_cmp_ge_u32_e64 vcc, v161, v169
	v_cndmask_b32_e64 v113, v221, v113, s[22:23]
	v_subrev_u32_e32 v169, 115, v160
	v_cvt_f32_i32_e32 v170, v169
	v_mul_f32_e32 v170, v166, v170
	v_fma_f32 v115, v115, v144, -v170
	v_cmp_ge_u32_e64 s[22:23], v161, v169
	v_cndmask_b32_e64 v114, v221, v114, vcc
	v_max3_f32 v168, v168, v108, v109
	v_max3_f32 v168, v168, v110, v111
	v_subrev_u32_e32 v169, 128, v160
	v_cvt_f32_i32_e32 v170, v169
	v_mul_f32_e32 v170, v166, v170
	v_fma_f32 v116, v116, v144, -v170
	v_cmp_ge_u32_e64 vcc, v161, v169
	v_cndmask_b32_e64 v115, v221, v115, s[22:23]
	v_subrev_u32_e32 v169, 129, v160
	v_cvt_f32_i32_e32 v170, v169
	v_mul_f32_e32 v170, v166, v170
	v_fma_f32 v117, v117, v144, -v170
	v_cmp_ge_u32_e64 s[22:23], v161, v169
	v_cndmask_b32_e64 v116, v221, v116, vcc
	v_subrev_u32_e32 v169, 130, v160
	v_cvt_f32_i32_e32 v170, v169
	v_mul_f32_e32 v170, v166, v170
	v_fma_f32 v118, v118, v144, -v170
	v_cmp_ge_u32_e64 vcc, v161, v169
	v_cndmask_b32_e64 v117, v221, v117, s[22:23]
	v_subrev_u32_e32 v169, 131, v160
	v_cvt_f32_i32_e32 v170, v169
	v_mul_f32_e32 v170, v166, v170
	v_fma_f32 v119, v119, v144, -v170
	v_cmp_ge_u32_e64 s[22:23], v161, v169
	v_cndmask_b32_e64 v118, v221, v118, vcc
	v_max3_f32 v168, v168, v112, v113
	v_max3_f32 v168, v168, v114, v115
	s_nop 1
	v_cndmask_b32_e64 v119, v221, v119, s[22:23]
	v_max3_f32 v168, v168, v116, v117
	v_max3_f32 v168, v168, v118, v119
	ds_bpermute_b32 v169, v162, v168
	s_waitcnt lgkmcnt(0)
	v_max_f32_e32 v169, v169, v169
	v_max_f32_e32 v168, v168, v169
	ds_bpermute_b32 v169, v163, v168
	s_waitcnt lgkmcnt(0)
	v_max_f32_e32 v169, v169, v169
	v_max_f32_e32 v168, v168, v169
	v_max_f32_e32 v168, s30, v168
	v_mov_b32_e32 v171, 0
	v_sub_f32_e32 v84, v84, v168
	v_mul_f32_e32 v84, 0x3fb8aa3b, v84
	v_exp_f32_e32 v84, v84
	v_sub_f32_e32 v85, v85, v168
	v_mul_f32_e32 v85, 0x3fb8aa3b, v85
	v_exp_f32_e32 v85, v85
	v_add_f32_e32 v171, v84, v171
	v_sub_f32_e32 v86, v86, v168
	v_mul_f32_e32 v86, 0x3fb8aa3b, v86
	v_exp_f32_e32 v86, v86
	v_add_f32_e32 v171, v85, v171
	v_sub_f32_e32 v87, v87, v168
	v_mul_f32_e32 v87, 0x3fb8aa3b, v87
	v_exp_f32_e32 v87, v87
	v_add_f32_e32 v171, v86, v171
	v_sub_f32_e32 v88, v88, v168
	v_mul_f32_e32 v88, 0x3fb8aa3b, v88
	v_exp_f32_e32 v88, v88
	v_add_f32_e32 v171, v87, v171
	v_sub_f32_e32 v89, v89, v168
	v_mul_f32_e32 v89, 0x3fb8aa3b, v89
	v_exp_f32_e32 v89, v89
	v_add_f32_e32 v171, v88, v171
	v_sub_f32_e32 v90, v90, v168
	v_mul_f32_e32 v90, 0x3fb8aa3b, v90
	v_exp_f32_e32 v90, v90
	v_add_f32_e32 v171, v89, v171
	v_sub_f32_e32 v91, v91, v168
	v_mul_f32_e32 v91, 0x3fb8aa3b, v91
	v_exp_f32_e32 v91, v91
	v_add_f32_e32 v171, v90, v171
	v_sub_f32_e32 v92, v92, v168
	v_mul_f32_e32 v92, 0x3fb8aa3b, v92
	v_exp_f32_e32 v92, v92
	v_add_f32_e32 v171, v91, v171
	v_sub_f32_e32 v93, v93, v168
	v_mul_f32_e32 v93, 0x3fb8aa3b, v93
	v_exp_f32_e32 v93, v93
	v_add_f32_e32 v171, v92, v171
	v_sub_f32_e32 v94, v94, v168
	v_mul_f32_e32 v94, 0x3fb8aa3b, v94
	v_exp_f32_e32 v94, v94
	v_add_f32_e32 v171, v93, v171
	v_sub_f32_e32 v95, v95, v168
	v_mul_f32_e32 v95, 0x3fb8aa3b, v95
	v_exp_f32_e32 v95, v95
	v_add_f32_e32 v171, v94, v171
	v_sub_f32_e32 v96, v96, v168
	v_mul_f32_e32 v96, 0x3fb8aa3b, v96
	v_exp_f32_e32 v96, v96
	v_add_f32_e32 v171, v95, v171
	v_sub_f32_e32 v97, v97, v168
	v_mul_f32_e32 v97, 0x3fb8aa3b, v97
	v_exp_f32_e32 v97, v97
	v_add_f32_e32 v171, v96, v171
	v_sub_f32_e32 v98, v98, v168
	v_mul_f32_e32 v98, 0x3fb8aa3b, v98
	v_exp_f32_e32 v98, v98
	v_add_f32_e32 v171, v97, v171
	v_sub_f32_e32 v99, v99, v168
	v_mul_f32_e32 v99, 0x3fb8aa3b, v99
	v_exp_f32_e32 v99, v99
	v_add_f32_e32 v171, v98, v171
	v_sub_f32_e32 v100, v100, v168
	v_mul_f32_e32 v100, 0x3fb8aa3b, v100
	v_exp_f32_e32 v100, v100
	v_add_f32_e32 v171, v99, v171
	v_sub_f32_e32 v101, v101, v168
	v_mul_f32_e32 v101, 0x3fb8aa3b, v101
	v_exp_f32_e32 v101, v101
	v_add_f32_e32 v171, v100, v171
	v_sub_f32_e32 v102, v102, v168
	v_mul_f32_e32 v102, 0x3fb8aa3b, v102
	v_exp_f32_e32 v102, v102
	v_add_f32_e32 v171, v101, v171
	v_sub_f32_e32 v103, v103, v168
	v_mul_f32_e32 v103, 0x3fb8aa3b, v103
	v_exp_f32_e32 v103, v103
	v_add_f32_e32 v171, v102, v171
	v_sub_f32_e32 v104, v104, v168
	v_mul_f32_e32 v104, 0x3fb8aa3b, v104
	v_exp_f32_e32 v104, v104
	v_add_f32_e32 v171, v103, v171
	v_sub_f32_e32 v105, v105, v168
	v_mul_f32_e32 v105, 0x3fb8aa3b, v105
	v_exp_f32_e32 v105, v105
	v_add_f32_e32 v171, v104, v171
	v_sub_f32_e32 v106, v106, v168
	v_mul_f32_e32 v106, 0x3fb8aa3b, v106
	v_exp_f32_e32 v106, v106
	v_add_f32_e32 v171, v105, v171
	v_sub_f32_e32 v107, v107, v168
	v_mul_f32_e32 v107, 0x3fb8aa3b, v107
	v_exp_f32_e32 v107, v107
	v_add_f32_e32 v171, v106, v171
	v_sub_f32_e32 v108, v108, v168
	v_mul_f32_e32 v108, 0x3fb8aa3b, v108
	v_exp_f32_e32 v108, v108
	v_add_f32_e32 v171, v107, v171
	v_sub_f32_e32 v109, v109, v168
	v_mul_f32_e32 v109, 0x3fb8aa3b, v109
	v_exp_f32_e32 v109, v109
	v_add_f32_e32 v171, v108, v171
	v_sub_f32_e32 v110, v110, v168
	v_mul_f32_e32 v110, 0x3fb8aa3b, v110
	v_exp_f32_e32 v110, v110
	v_add_f32_e32 v171, v109, v171
	v_sub_f32_e32 v111, v111, v168
	v_mul_f32_e32 v111, 0x3fb8aa3b, v111
	v_exp_f32_e32 v111, v111
	v_add_f32_e32 v171, v110, v171
	v_sub_f32_e32 v112, v112, v168
	v_mul_f32_e32 v112, 0x3fb8aa3b, v112
	v_exp_f32_e32 v112, v112
	v_add_f32_e32 v171, v111, v171
	v_sub_f32_e32 v113, v113, v168
	v_mul_f32_e32 v113, 0x3fb8aa3b, v113
	v_exp_f32_e32 v113, v113
	v_add_f32_e32 v171, v112, v171
	v_sub_f32_e32 v114, v114, v168
	v_mul_f32_e32 v114, 0x3fb8aa3b, v114
	v_exp_f32_e32 v114, v114
	v_add_f32_e32 v171, v113, v171
	v_sub_f32_e32 v115, v115, v168
	v_mul_f32_e32 v115, 0x3fb8aa3b, v115
	v_exp_f32_e32 v115, v115
	v_add_f32_e32 v171, v114, v171
	v_sub_f32_e32 v116, v116, v168
	v_mul_f32_e32 v116, 0x3fb8aa3b, v116
	v_exp_f32_e32 v116, v116
	v_add_f32_e32 v171, v115, v171
	v_sub_f32_e32 v117, v117, v168
	v_mul_f32_e32 v117, 0x3fb8aa3b, v117
	v_exp_f32_e32 v117, v117
	v_add_f32_e32 v171, v116, v171
	v_sub_f32_e32 v118, v118, v168
	v_mul_f32_e32 v118, 0x3fb8aa3b, v118
	v_exp_f32_e32 v118, v118
	v_add_f32_e32 v171, v117, v171
	v_sub_f32_e32 v119, v119, v168
	v_mul_f32_e32 v119, 0x3fb8aa3b, v119
	v_exp_f32_e32 v119, v119
	v_add_f32_e32 v171, v118, v171
	v_sub_f32_e32 v172, s30, v168
	v_add_f32_e32 v171, v119, v171
	v_mul_f32_e32 v172, 0x3fb8aa3b, v172
	v_exp_f32_e32 v172, v172
	ds_bpermute_b32 v169, v162, v171
	s_waitcnt lgkmcnt(0)
; #define MFMA16(a, b, c) __builtin_amdgcn_mfma_f32_16x16x32_bf16((a), (b), (c), 0, 0, 0)
; __device__ __forceinline__ unsigned pk2(float lo, float hi) { return pg8::cvt_pk_bf16(lo, hi); }
; __device__ __forceinline__ void attn_prompt_item(const bf16_t* z, const bf16_t* vt, bf16_t* mix, const float* sinks, int it, int lane) {
;     ...
;     sum += __shfl_xor(sum, 16); sum += __shfl_xor(sum, 32);
;     const float inv = 1.0f / (sum + __expf(sink - mx));
;     f32x4 o[4];
; #pragma unroll
;     for (int mi = 0; mi < 4; ++mi) o[mi] = (f32x4){0.f, 0.f, 0.f, 0.f};
; #pragma unroll
;     for (int u = 0; u < 5; ++u) {
;         u32x4 pw; pw.x = pk2(sc[2 * u][0] * inv, sc[2 * u][1] * inv); pw.y = pk2(sc[2 * u][2] * inv, sc[2 * u][3] * inv);
;         if (2 * u + 1 < 9) { pw.z = pk2(sc[(2 * u + 1) % 9][0] * inv, sc[(2 * u + 1) % 9][1] * inv); pw.w = pk2(sc[(2 * u + 1) % 9][2] * inv, sc[(2 * u + 1) % 9][3] * inv); }
;         else { pw.z = 0u; pw.w = 0u; }
;         const bf16x8 pb = as_bf16x8(pw);
; #pragma unroll
;         for (int mi = 0; mi < 4; ++mi) {
;             const s16x4 v0 = vq[u][mi][0], v1 = vq[u][mi][1];
;             const bf16x8 va = (bf16x8){v0[0], v0[1], v0[2], v0[3], v1[0], v1[1], v1[2], v1[3]};
;             o[mi] = MFMA16(va, pb, o[mi]);
;         }
;     }
	v_add_f32_e32 v171, v171, v169
	ds_bpermute_b32 v169, v163, v171
	s_waitcnt lgkmcnt(0)
	v_add_f32_e32 v171, v171, v169
	v_add_f32_e32 v171, v171, v172
	v_div_scale_f32 v169, s[22:23], v171, v171, 1.0
	v_rcp_f32_e32 v170, v169
	s_nop 0
	v_fma_f32 v172, -v169, v170, 1.0
	v_fmac_f32_e32 v170, v172, v170
	v_div_scale_f32 v172, vcc, 1.0, v171, 1.0
	v_mul_f32_e32 v173, v172, v170
	v_fma_f32 v174, -v169, v173, v172
	v_fmac_f32_e32 v173, v174, v170
	v_fma_f32 v169, -v169, v173, v172
	v_div_fmas_f32 v169, v169, v170, v173
	v_div_fixup_f32 v174, v169, v171, 1.0
	v_pk_mul_f32 v[170:171], v[84:85], v[174:175] op_sel_hi:[1,0]
	v_cvt_pk_bf16_f32 v84, v170, v171
	v_pk_mul_f32 v[170:171], v[86:87], v[174:175] op_sel_hi:[1,0]
	v_cvt_pk_bf16_f32 v85, v170, v171
	v_pk_mul_f32 v[170:171], v[88:89], v[174:175] op_sel_hi:[1,0]
	v_cvt_pk_bf16_f32 v86, v170, v171
	v_pk_mul_f32 v[170:171], v[90:91], v[174:175] op_sel_hi:[1,0]
	v_cvt_pk_bf16_f32 v87, v170, v171
	v_pk_mul_f32 v[170:171], v[92:93], v[174:175] op_sel_hi:[1,0]
	v_cvt_pk_bf16_f32 v88, v170, v171
	v_pk_mul_f32 v[170:171], v[94:95], v[174:175] op_sel_hi:[1,0]
	v_cvt_pk_bf16_f32 v89, v170, v171
	v_pk_mul_f32 v[170:171], v[96:97], v[174:175] op_sel_hi:[1,0]
	v_cvt_pk_bf16_f32 v90, v170, v171
	v_pk_mul_f32 v[170:171], v[98:99], v[174:175] op_sel_hi:[1,0]
	v_cvt_pk_bf16_f32 v91, v170, v171
	v_pk_mul_f32 v[170:171], v[100:101], v[174:175] op_sel_hi:[1,0]
	v_cvt_pk_bf16_f32 v92, v170, v171
	v_pk_mul_f32 v[170:171], v[102:103], v[174:175] op_sel_hi:[1,0]
	v_cvt_pk_bf16_f32 v93, v170, v171
	v_pk_mul_f32 v[170:171], v[104:105], v[174:175] op_sel_hi:[1,0]
	v_cvt_pk_bf16_f32 v94, v170, v171
	v_pk_mul_f32 v[170:171], v[106:107], v[174:175] op_sel_hi:[1,0]
	v_cvt_pk_bf16_f32 v95, v170, v171
	v_pk_mul_f32 v[170:171], v[108:109], v[174:175] op_sel_hi:[1,0]
	v_cvt_pk_bf16_f32 v96, v170, v171
	v_pk_mul_f32 v[170:171], v[110:111], v[174:175] op_sel_hi:[1,0]
	v_cvt_pk_bf16_f32 v97, v170, v171
	v_pk_mul_f32 v[170:171], v[112:113], v[174:175] op_sel_hi:[1,0]
	v_cvt_pk_bf16_f32 v98, v170, v171
	v_pk_mul_f32 v[170:171], v[114:115], v[174:175] op_sel_hi:[1,0]
	v_cvt_pk_bf16_f32 v99, v170, v171
	v_pk_mul_f32 v[170:171], v[116:117], v[174:175] op_sel_hi:[1,0]
	v_cvt_pk_bf16_f32 v100, v170, v171
	v_pk_mul_f32 v[170:171], v[118:119], v[174:175] op_sel_hi:[1,0]
	v_cvt_pk_bf16_f32 v101, v170, v171
	v_mov_b32_e32 v102, 0
	v_mov_b32_e32 v103, 0
	s_nop 1
	s_waitcnt lgkmcnt(12)
	v_mfma_f32_16x16x32_bf16 v[4:7], v[20:23], v[84:87], 0
	ds_read_b64 v[20:21], v159 offset:25408
	ds_read_b64 v[22:23], v159 offset:25440
	s_waitcnt lgkmcnt(12)
	v_mfma_f32_16x16x32_bf16 v[8:11], v[24:27], v[84:87], 0
	ds_read_b64 v[24:25], v159 offset:128
	ds_read_b64 v[26:27], v159 offset:160
	s_waitcnt lgkmcnt(12)
	v_mfma_f32_16x16x32_bf16 v[12:15], v[28:31], v[84:87], 0
	ds_read_b64 v[28:29], v159 offset:8576
	ds_read_b64 v[30:31], v159 offset:8608
	s_waitcnt lgkmcnt(12)
	v_mfma_f32_16x16x32_bf16 v[16:19], v[32:35], v[84:87], 0
	ds_read_b64 v[32:33], v159 offset:17024
	ds_read_b64 v[34:35], v159 offset:17056
	s_waitcnt lgkmcnt(12)
	v_mfma_f32_16x16x32_bf16 v[4:7], v[36:39], v[88:91], v[4:7]
	ds_read_b64 v[36:37], v159 offset:25472
	ds_read_b64 v[38:39], v159 offset:25504
	s_waitcnt lgkmcnt(12)
	v_mfma_f32_16x16x32_bf16 v[8:11], v[72:75], v[88:91], v[8:11]
	ds_read_b64 v[72:73], v159 offset:192
	ds_read_b64 v[74:75], v159 offset:224
	s_waitcnt lgkmcnt(12)
	v_mfma_f32_16x16x32_bf16 v[12:15], v[76:79], v[88:91], v[12:15]
	ds_read_b64 v[76:77], v159 offset:8640
	ds_read_b64 v[78:79], v159 offset:8672
	s_waitcnt lgkmcnt(12)
	v_mfma_f32_16x16x32_bf16 v[16:19], v[20:23], v[88:91], v[16:19]
	ds_read_b64 v[20:21], v159 offset:17088
	ds_read_b64 v[22:23], v159 offset:17120
	s_waitcnt lgkmcnt(12)
	v_mfma_f32_16x16x32_bf16 v[4:7], v[24:27], v[92:95], v[4:7]
	ds_read_b64 v[24:25], v159 offset:25536
	ds_read_b64 v[26:27], v159 offset:25568
	s_waitcnt lgkmcnt(12)
	v_mfma_f32_16x16x32_bf16 v[8:11], v[28:31], v[92:95], v[8:11]
	ds_read_b64 v[28:29], v159 offset:256
	ds_read_b64 v[30:31], v159 offset:288
	s_waitcnt lgkmcnt(12)
	v_mfma_f32_16x16x32_bf16 v[12:15], v[32:35], v[92:95], v[12:15]
	ds_read_b64 v[32:33], v159 offset:8704
	ds_read_b64 v[34:35], v159 offset:8736
	s_waitcnt lgkmcnt(12)
	v_mfma_f32_16x16x32_bf16 v[16:19], v[36:39], v[92:95], v[16:19]
	ds_read_b64 v[36:37], v159 offset:17152
	ds_read_b64 v[38:39], v159 offset:17184
	s_waitcnt lgkmcnt(12)
	v_mfma_f32_16x16x32_bf16 v[4:7], v[72:75], v[96:99], v[4:7]
	ds_read_b64 v[72:73], v159 offset:25600
	ds_read_b64 v[74:75], v159 offset:25632
	s_waitcnt lgkmcnt(12)
	v_mfma_f32_16x16x32_bf16 v[8:11], v[76:79], v[96:99], v[8:11]
	s_waitcnt lgkmcnt(10)
	v_mfma_f32_16x16x32_bf16 v[12:15], v[20:23], v[96:99], v[12:15]
	s_waitcnt lgkmcnt(8)
	v_mfma_f32_16x16x32_bf16 v[16:19], v[24:27], v[96:99], v[16:19]
	s_waitcnt lgkmcnt(6)
	v_mfma_f32_16x16x32_bf16 v[4:7], v[28:31], v[100:103], v[4:7]
	s_waitcnt lgkmcnt(4)
	v_mfma_f32_16x16x32_bf16 v[8:11], v[32:35], v[100:103], v[8:11]
	s_waitcnt lgkmcnt(2)
	v_mfma_f32_16x16x32_bf16 v[12:15], v[36:39], v[100:103], v[12:15]
	s_waitcnt lgkmcnt(0)
	v_mfma_f32_16x16x32_bf16 v[16:19], v[72:75], v[100:103], v[16:19]
	s_nop 7
	s_waitcnt vmcnt(0)
; #define MFMA16(a, b, c) __builtin_amdgcn_mfma_f32_16x16x32_bf16((a), (b), (c), 0, 0, 0)
; __device__ __forceinline__ float bf_lo(unsigned w) { return __uint_as_float(w << 16); }
; __device__ __forceinline__ float bf_hi(unsigned w) { return __uint_as_float(w & 0xffff0000u); }
; __device__ __forceinline__ unsigned pk2(float lo, float hi) { return pg8::cvt_pk_bf16(lo, hi); }
; __device__ __forceinline__ void attn_prompt_item(const bf16_t* z, const bf16_t* vt, bf16_t* mix, const float* sinks, int it, int lane) {
;     ...
; #pragma unroll
;     for (int kt = 0; kt < 9; ++kt) {
;         const int p0 = s0 - 128 + 16 * kt;
;         const int key = p0 + l15, keyc = key < 0 ? 0 : key;
;         const bf16_t* kp = z + ((size_t)b * SEQL + keyc) * EIN + 1024 + kv * 64 + 8 * g;
;         const bf16x8 k0 = *(const bf16x8*)kp, k1 = *(const bf16x8*)(kp + 32);
;         f32x4 a = {0.f, 0.f, 0.f, 0.f};
;         a = MFMA16(k0, qf0, a); a = MFMA16(k1, qf1, a);
; #pragma unroll
;         for (int j = 0; j < 4; ++j) {
;             const int kpos = p0 + 4 * g + j, dist = s0 + l15 - kpos;
;             const bool valid = (dist >= 0) && (dist < 128) && (kpos >= 0);
;             const float v = valid ? a[j] * 0.125f - slope * (float)dist : -1e30f;
;             sc[kt][j] = v; mx = fmaxf(mx, v);
;         }
;     ...
; #pragma unroll
;     for (int mi = 0; mi < 4; ++mi) {
;         const int col = h * 64 + mi * 16 + 4 * g;
;         const u32x2 gw = *(const u32x2*)(z + tokq * EIN + 1280 + col);
;         u32x2 w; w.x = pk2(o[mi][0] * bf_lo(gw.x), o[mi][1] * bf_hi(gw.x)); w.y = pk2(o[mi][2] * bf_lo(gw.y), o[mi][3] * bf_hi(gw.y));
;         *(u32x2*)(mix + tokq * 2048 + col) = w;
;     }
	v_lshlrev_b32_e32 v172, 16, v130
	v_and_b32_e32 v173, 0xffff0000, v130
	v_lshlrev_b32_e32 v174, 16, v131
	v_and_b32_e32 v175, 0xffff0000, v131
	v_mul_f32_e32 v172, v4, v172
	v_mul_f32_e32 v173, v5, v173
	v_mul_f32_e32 v174, v6, v174
	v_mul_f32_e32 v175, v7, v175
	v_cvt_pk_bf16_f32 v170, v172, v173
	v_cvt_pk_bf16_f32 v171, v174, v175
	global_store_dwordx2 v157, v[170:171], s[14:15] offset:256
	v_lshlrev_b32_e32 v172, 16, v132
	v_and_b32_e32 v173, 0xffff0000, v132
	v_lshlrev_b32_e32 v174, 16, v133
	v_and_b32_e32 v175, 0xffff0000, v133
	v_mul_f32_e32 v172, v8, v172
	v_mul_f32_e32 v173, v9, v173
	v_mul_f32_e32 v174, v10, v174
	v_mul_f32_e32 v175, v11, v175
	v_cvt_pk_bf16_f32 v170, v172, v173
	v_cvt_pk_bf16_f32 v171, v174, v175
	global_store_dwordx2 v157, v[170:171], s[14:15] offset:288
	v_lshlrev_b32_e32 v172, 16, v134
	v_and_b32_e32 v173, 0xffff0000, v134
	v_lshlrev_b32_e32 v174, 16, v135
	v_and_b32_e32 v175, 0xffff0000, v135
	v_mul_f32_e32 v172, v12, v172
	v_mul_f32_e32 v173, v13, v173
	v_mul_f32_e32 v174, v14, v174
	v_mul_f32_e32 v175, v15, v175
	v_cvt_pk_bf16_f32 v170, v172, v173
	v_cvt_pk_bf16_f32 v171, v174, v175
	global_store_dwordx2 v157, v[170:171], s[14:15] offset:320
	v_lshlrev_b32_e32 v172, 16, v136
	v_and_b32_e32 v173, 0xffff0000, v136
	v_lshlrev_b32_e32 v174, 16, v137
	v_and_b32_e32 v175, 0xffff0000, v137
	v_mul_f32_e32 v172, v16, v172
	v_mul_f32_e32 v173, v17, v173
	v_mul_f32_e32 v174, v18, v174
	v_mul_f32_e32 v175, v19, v175
	v_cvt_pk_bf16_f32 v170, v172, v173
	v_cvt_pk_bf16_f32 v171, v174, v175
	global_store_dwordx2 v157, v[170:171], s[14:15] offset:352
	global_load_dwordx2 v[130:131], v156, s[26:27] offset:384
	global_load_dwordx2 v[132:133], v156, s[26:27] offset:416
	global_load_dwordx2 v[134:135], v156, s[26:27] offset:448
	global_load_dwordx2 v[136:137], v156, s[26:27] offset:480
	ds_read_b128 v[20:23], v158 offset:0
	ds_read_b128 v[24:27], v158 offset:64
	ds_read_b128 v[28:31], v158 offset:2304
	ds_read_b128 v[32:35], v158 offset:2368
	ds_read_b128 v[36:39], v158 offset:4608
	ds_read_b128 v[72:75], v158 offset:4672
	ds_read_b128 v[76:79], v158 offset:6912
	ds_read_b128 v[126:129], v158 offset:6976
	s_waitcnt lgkmcnt(7)
	v_mfma_f32_16x16x32_bf16 v[84:87], v[20:23], v[64:67], 0
	ds_read_b128 v[20:23], v158 offset:9216
	s_waitcnt lgkmcnt(7)
	v_mfma_f32_16x16x32_bf16 v[84:87], v[24:27], v[68:71], v[84:87]
	ds_read_b128 v[24:27], v158 offset:9280
	s_waitcnt lgkmcnt(7)
	v_mfma_f32_16x16x32_bf16 v[88:91], v[28:31], v[64:67], 0
	ds_read_b128 v[28:31], v158 offset:11520
	s_waitcnt lgkmcnt(7)
	v_mfma_f32_16x16x32_bf16 v[88:91], v[32:35], v[68:71], v[88:91]
	ds_read_b128 v[32:35], v158 offset:11584
	s_waitcnt lgkmcnt(7)
	v_mfma_f32_16x16x32_bf16 v[92:95], v[36:39], v[64:67], 0
	ds_read_b128 v[36:39], v158 offset:13824
	s_waitcnt lgkmcnt(7)
	v_mfma_f32_16x16x32_bf16 v[92:95], v[72:75], v[68:71], v[92:95]
	ds_read_b128 v[72:75], v158 offset:13888
	s_waitcnt lgkmcnt(7)
	v_mfma_f32_16x16x32_bf16 v[96:99], v[76:79], v[64:67], 0
	ds_read_b128 v[76:79], v158 offset:16128
	s_waitcnt lgkmcnt(7)
	v_mfma_f32_16x16x32_bf16 v[96:99], v[126:129], v[68:71], v[96:99]
	ds_read_b128 v[126:129], v158 offset:16192
	s_waitcnt lgkmcnt(7)
	v_mfma_f32_16x16x32_bf16 v[100:103], v[20:23], v[64:67], 0
	ds_read_b128 v[20:23], v158 offset:18432
	s_waitcnt lgkmcnt(7)
	v_mfma_f32_16x16x32_bf16 v[100:103], v[24:27], v[68:71], v[100:103]
	ds_read_b128 v[24:27], v158 offset:18496
	s_waitcnt lgkmcnt(7)
	v_mfma_f32_16x16x32_bf16 v[104:107], v[28:31], v[64:67], 0
	s_waitcnt lgkmcnt(6)
	v_mfma_f32_16x16x32_bf16 v[104:107], v[32:35], v[68:71], v[104:107]
	s_waitcnt lgkmcnt(5)
	v_mfma_f32_16x16x32_bf16 v[108:111], v[36:39], v[64:67], 0
	s_waitcnt lgkmcnt(4)
	v_mfma_f32_16x16x32_bf16 v[108:111], v[72:75], v[68:71], v[108:111]
	s_waitcnt lgkmcnt(3)
	v_mfma_f32_16x16x32_bf16 v[112:115], v[76:79], v[64:67], 0
	s_waitcnt lgkmcnt(2)
	v_mfma_f32_16x16x32_bf16 v[112:115], v[126:129], v[68:71], v[112:115]
	s_waitcnt lgkmcnt(1)
	v_mfma_f32_16x16x32_bf16 v[116:119], v[20:23], v[64:67], 0
	s_waitcnt lgkmcnt(0)
	v_mfma_f32_16x16x32_bf16 v[116:119], v[24:27], v[68:71], v[116:119]
	ds_read_b64 v[20:21], v159 offset:0
	ds_read_b64 v[22:23], v159 offset:32
	ds_read_b64 v[24:25], v159 offset:8448
	ds_read_b64 v[26:27], v159 offset:8480
	ds_read_b64 v[28:29], v159 offset:16896
	ds_read_b64 v[30:31], v159 offset:16928
	ds_read_b64 v[32:33], v159 offset:25344
	ds_read_b64 v[34:35], v159 offset:25376
	ds_read_b64 v[36:37], v159 offset:64
	ds_read_b64 v[38:39], v159 offset:96
	ds_read_b64 v[72:73], v159 offset:8512
	ds_read_b64 v[74:75], v159 offset:8544
	ds_read_b64 v[76:77], v159 offset:16960
	ds_read_b64 v[78:79], v159 offset:16992
	s_nop 4
	v_mov_b32_e32 v168, 0xf149f2ca
	v_mov_b32_e32 v169, v160
	v_cvt_f32_i32_e32 v170, v169
	v_mul_f32_e32 v170, v167, v170
	v_fma_f32 v84, v84, v144, -v170
	v_cmp_ge_u32_e64 vcc, v161, v169
	v_subrev_u32_e32 v169, 1, v160
	v_cvt_f32_i32_e32 v170, v169
	v_mul_f32_e32 v170, v167, v170
	v_fma_f32 v85, v85, v144, -v170
	v_cmp_ge_u32_e64 s[22:23], v161, v169
	v_cndmask_b32_e64 v84, v221, v84, vcc
	v_subrev_u32_e32 v169, 2, v160
	v_cvt_f32_i32_e32 v170, v169
	v_mul_f32_e32 v170, v167, v170
	v_fma_f32 v86, v86, v144, -v170
	v_cmp_ge_u32_e64 vcc, v161, v169
	v_cndmask_b32_e64 v85, v221, v85, s[22:23]
	v_subrev_u32_e32 v169, 3, v160
	v_cvt_f32_i32_e32 v170, v169
	v_mul_f32_e32 v170, v167, v170
	v_fma_f32 v87, v87, v144, -v170
	v_cmp_ge_u32_e64 s[22:23], v161, v169
	v_cndmask_b32_e64 v86, v221, v86, vcc
	v_subrev_u32_e32 v169, 16, v160
	v_cvt_f32_i32_e32 v170, v169
	v_mul_f32_e32 v170, v167, v170
	v_fma_f32 v88, v88, v144, -v170
	v_cmp_ge_u32_e64 vcc, v161, v169
; __device__ __forceinline__ void attn_prompt_item(const bf16_t* z, const bf16_t* vt, bf16_t* mix, const float* sinks, int it, int lane) {
;     ...
; #pragma unroll
;         for (int j = 0; j < 4; ++j) {
;             const int kpos = p0 + 4 * g + j, dist = s0 + l15 - kpos;
;             const bool valid = (dist >= 0) && (dist < 128) && (kpos >= 0);
;             const float v = valid ? a[j] * 0.125f - slope * (float)dist : -1e30f;
;             sc[kt][j] = v; mx = fmaxf(mx, v);
;         }
	v_cndmask_b32_e64 v87, v221, v87, s[22:23]
	v_subrev_u32_e32 v169, 17, v160
	v_cvt_f32_i32_e32 v170, v169
	v_mul_f32_e32 v170, v167, v170
	v_fma_f32 v89, v89, v144, -v170
	v_cmp_ge_u32_e64 s[22:23], v161, v169
	v_cndmask_b32_e64 v88, v221, v88, vcc
	v_subrev_u32_e32 v169, 18, v160
	v_cvt_f32_i32_e32 v170, v169
	v_mul_f32_e32 v170, v167, v170
	v_fma_f32 v90, v90, v144, -v170
	v_cmp_ge_u32_e64 vcc, v161, v169
	v_cndmask_b32_e64 v89, v221, v89, s[22:23]
	v_subrev_u32_e32 v169, 19, v160
	v_cvt_f32_i32_e32 v170, v169
	v_mul_f32_e32 v170, v167, v170
	v_fma_f32 v91, v91, v144, -v170
	v_cmp_ge_u32_e64 s[22:23], v161, v169
	v_cndmask_b32_e64 v90, v221, v90, vcc
	v_max3_f32 v168, v168, v84, v85
	v_max3_f32 v168, v168, v86, v87
	v_subrev_u32_e32 v169, 32, v160
	v_cvt_f32_i32_e32 v170, v169
	v_mul_f32_e32 v170, v167, v170
	v_fma_f32 v92, v92, v144, -v170
	v_cmp_ge_u32_e64 vcc, v161, v169
	v_cndmask_b32_e64 v91, v221, v91, s[22:23]
	v_subrev_u32_e32 v169, 33, v160
	v_cvt_f32_i32_e32 v170, v169
	v_mul_f32_e32 v170, v167, v170
	v_fma_f32 v93, v93, v144, -v170
	v_cmp_ge_u32_e64 s[22:23], v161, v169
	v_cndmask_b32_e64 v92, v221, v92, vcc
	v_subrev_u32_e32 v169, 34, v160
	v_cvt_f32_i32_e32 v170, v169
	v_mul_f32_e32 v170, v167, v170
	v_fma_f32 v94, v94, v144, -v170
	v_cmp_ge_u32_e64 vcc, v161, v169
	v_cndmask_b32_e64 v93, v221, v93, s[22:23]
	v_subrev_u32_e32 v169, 35, v160
	v_cvt_f32_i32_e32 v170, v169
	v_mul_f32_e32 v170, v167, v170
	v_fma_f32 v95, v95, v144, -v170
	v_cmp_ge_u32_e64 s[22:23], v161, v169
	v_cndmask_b32_e64 v94, v221, v94, vcc
	v_max3_f32 v168, v168, v88, v89
	v_max3_f32 v168, v168, v90, v91
	v_subrev_u32_e32 v169, 48, v160
	v_cvt_f32_i32_e32 v170, v169
	v_mul_f32_e32 v170, v167, v170
	v_fma_f32 v96, v96, v144, -v170
	v_cmp_ge_u32_e64 vcc, v161, v169
	v_cndmask_b32_e64 v95, v221, v95, s[22:23]
	v_subrev_u32_e32 v169, 49, v160
	v_cvt_f32_i32_e32 v170, v169
	v_mul_f32_e32 v170, v167, v170
	v_fma_f32 v97, v97, v144, -v170
	v_cmp_ge_u32_e64 s[22:23], v161, v169
	v_cndmask_b32_e64 v96, v221, v96, vcc
	v_subrev_u32_e32 v169, 50, v160
	v_cvt_f32_i32_e32 v170, v169
	v_mul_f32_e32 v170, v167, v170
	v_fma_f32 v98, v98, v144, -v170
	v_cmp_ge_u32_e64 vcc, v161, v169
	v_cndmask_b32_e64 v97, v221, v97, s[22:23]
	v_subrev_u32_e32 v169, 51, v160
	v_cvt_f32_i32_e32 v170, v169
	v_mul_f32_e32 v170, v167, v170
	v_fma_f32 v99, v99, v144, -v170
	v_cmp_ge_u32_e64 s[22:23], v161, v169
	v_cndmask_b32_e64 v98, v221, v98, vcc
	v_max3_f32 v168, v168, v92, v93
	v_max3_f32 v168, v168, v94, v95
	v_subrev_u32_e32 v169, 64, v160
	v_cvt_f32_i32_e32 v170, v169
	v_mul_f32_e32 v170, v167, v170
	v_fma_f32 v100, v100, v144, -v170
	v_cmp_ge_u32_e64 vcc, v161, v169
	v_cndmask_b32_e64 v99, v221, v99, s[22:23]
	v_subrev_u32_e32 v169, 65, v160
	v_cvt_f32_i32_e32 v170, v169
	v_mul_f32_e32 v170, v167, v170
	v_fma_f32 v101, v101, v144, -v170
	v_cmp_ge_u32_e64 s[22:23], v161, v169
	v_cndmask_b32_e64 v100, v221, v100, vcc
	v_subrev_u32_e32 v169, 66, v160
	v_cvt_f32_i32_e32 v170, v169
	v_mul_f32_e32 v170, v167, v170
	v_fma_f32 v102, v102, v144, -v170
	v_cmp_ge_u32_e64 vcc, v161, v169
	v_cndmask_b32_e64 v101, v221, v101, s[22:23]
	v_subrev_u32_e32 v169, 67, v160
	v_cvt_f32_i32_e32 v170, v169
	v_mul_f32_e32 v170, v167, v170
	v_fma_f32 v103, v103, v144, -v170
	v_cmp_ge_u32_e64 s[22:23], v161, v169
	v_cndmask_b32_e64 v102, v221, v102, vcc
	v_max3_f32 v168, v168, v96, v97
	v_max3_f32 v168, v168, v98, v99
	v_subrev_u32_e32 v169, 80, v160
	v_cvt_f32_i32_e32 v170, v169
	v_mul_f32_e32 v170, v167, v170
	v_fma_f32 v104, v104, v144, -v170
	v_cmp_ge_u32_e64 vcc, v161, v169
	v_cndmask_b32_e64 v103, v221, v103, s[22:23]
	v_subrev_u32_e32 v169, 81, v160
	v_cvt_f32_i32_e32 v170, v169
	v_mul_f32_e32 v170, v167, v170
	v_fma_f32 v105, v105, v144, -v170
	v_cmp_ge_u32_e64 s[22:23], v161, v169
	v_cndmask_b32_e64 v104, v221, v104, vcc
	v_subrev_u32_e32 v169, 82, v160
	v_cvt_f32_i32_e32 v170, v169
	v_mul_f32_e32 v170, v167, v170
	v_fma_f32 v106, v106, v144, -v170
	v_cmp_ge_u32_e64 vcc, v161, v169
	v_cndmask_b32_e64 v105, v221, v105, s[22:23]
	v_subrev_u32_e32 v169, 83, v160
	v_cvt_f32_i32_e32 v170, v169
	v_mul_f32_e32 v170, v167, v170
	v_fma_f32 v107, v107, v144, -v170
	v_cmp_ge_u32_e64 s[22:23], v161, v169
	v_cndmask_b32_e64 v106, v221, v106, vcc
	v_max3_f32 v168, v168, v100, v101
	v_max3_f32 v168, v168, v102, v103
	v_subrev_u32_e32 v169, 96, v160
	v_cvt_f32_i32_e32 v170, v169
	v_mul_f32_e32 v170, v167, v170
	v_fma_f32 v108, v108, v144, -v170
	v_cmp_ge_u32_e64 vcc, v161, v169
	v_cndmask_b32_e64 v107, v221, v107, s[22:23]
	v_subrev_u32_e32 v169, 97, v160
	v_cvt_f32_i32_e32 v170, v169
	v_mul_f32_e32 v170, v167, v170
	v_fma_f32 v109, v109, v144, -v170
	v_cmp_ge_u32_e64 s[22:23], v161, v169
	v_cndmask_b32_e64 v108, v221, v108, vcc
	v_subrev_u32_e32 v169, 98, v160
	v_cvt_f32_i32_e32 v170, v169
	v_mul_f32_e32 v170, v167, v170
	v_fma_f32 v110, v110, v144, -v170
	v_cmp_ge_u32_e64 vcc, v161, v169
	v_cndmask_b32_e64 v109, v221, v109, s[22:23]
	v_subrev_u32_e32 v169, 99, v160
	v_cvt_f32_i32_e32 v170, v169
	v_mul_f32_e32 v170, v167, v170
	v_fma_f32 v111, v111, v144, -v170
	v_cmp_ge_u32_e64 s[22:23], v161, v169
	v_cndmask_b32_e64 v110, v221, v110, vcc
	v_max3_f32 v168, v168, v104, v105
	v_max3_f32 v168, v168, v106, v107
	v_subrev_u32_e32 v169, 112, v160
	v_cvt_f32_i32_e32 v170, v169
	v_mul_f32_e32 v170, v167, v170
	v_fma_f32 v112, v112, v144, -v170
	v_cmp_ge_u32_e64 vcc, v161, v169
	v_cndmask_b32_e64 v111, v221, v111, s[22:23]
	v_subrev_u32_e32 v169, 113, v160
	v_cvt_f32_i32_e32 v170, v169
	v_mul_f32_e32 v170, v167, v170
	v_fma_f32 v113, v113, v144, -v170
	v_cmp_ge_u32_e64 s[22:23], v161, v169
	v_cndmask_b32_e64 v112, v221, v112, vcc
; __device__ __forceinline__ void attn_prompt_item(const bf16_t* z, const bf16_t* vt, bf16_t* mix, const float* sinks, int it, int lane) {
;     ...
; #pragma unroll
;         for (int j = 0; j < 4; ++j) {
;             const int kpos = p0 + 4 * g + j, dist = s0 + l15 - kpos;
;             const bool valid = (dist >= 0) && (dist < 128) && (kpos >= 0);
;             const float v = valid ? a[j] * 0.125f - slope * (float)dist : -1e30f;
;             sc[kt][j] = v; mx = fmaxf(mx, v);
;         }
;     }
;     s16x4 vq[5][4][2];
; #pragma unroll
;     for (int u = 0; u < 5; ++u) {
;         int pos0 = s0 - 128 + 32 * u + 4 * g, pos1 = pos0 + 16;
;         pos0 = pos0 < 0 ? 0 : pos0; pos1 = pos1 < 0 ? 0 : pos1;
; #pragma unroll
;         for (int mi = 0; mi < 4; ++mi) {
;             const bf16_t* vp = vt + (size_t)(kv * 64 + mi * 16 + l15) * T_ALL + (size_t)b * SEQL;
;             vq[u][mi][0] = *(const s16x4*)(vp + pos0); vq[u][mi][1] = *(const s16x4*)(vp + pos1);
;         }
;     }
;     mx = fmaxf(mx, __shfl_xor(mx, 16)); mx = fmaxf(mx, __shfl_xor(mx, 32)); mx = fmaxf(mx, sink);
;     float sum = 0.f;
; #pragma unroll
;     for (int kt = 0; kt < 9; ++kt)
; #pragma unroll
;         for (int j = 0; j < 4; ++j) { const float p = __expf(sc[kt][j] - mx); sc[kt][j] = p; sum += p; }
;     sum += __shfl_xor(sum, 16); sum += __shfl_xor(sum, 32);
	v_subrev_u32_e32 v169, 114, v160
	v_cvt_f32_i32_e32 v170, v169
	v_mul_f32_e32 v170, v167, v170
	v_fma_f32 v114, v114, v144, -v170
	v_cmp_ge_u32_e64 vcc, v161, v169
	v_cndmask_b32_e64 v113, v221, v113, s[22:23]
	v_subrev_u32_e32 v169, 115, v160
	v_cvt_f32_i32_e32 v170, v169
	v_mul_f32_e32 v170, v167, v170
	v_fma_f32 v115, v115, v144, -v170
	v_cmp_ge_u32_e64 s[22:23], v161, v169
	v_cndmask_b32_e64 v114, v221, v114, vcc
	v_max3_f32 v168, v168, v108, v109
	v_max3_f32 v168, v168, v110, v111
	v_subrev_u32_e32 v169, 128, v160
	v_cvt_f32_i32_e32 v170, v169
	v_mul_f32_e32 v170, v167, v170
	v_fma_f32 v116, v116, v144, -v170
	v_cmp_ge_u32_e64 vcc, v161, v169
	v_cndmask_b32_e64 v115, v221, v115, s[22:23]
	v_subrev_u32_e32 v169, 129, v160
	v_cvt_f32_i32_e32 v170, v169
	v_mul_f32_e32 v170, v167, v170
	v_fma_f32 v117, v117, v144, -v170
	v_cmp_ge_u32_e64 s[22:23], v161, v169
	v_cndmask_b32_e64 v116, v221, v116, vcc
	v_subrev_u32_e32 v169, 130, v160
	v_cvt_f32_i32_e32 v170, v169
	v_mul_f32_e32 v170, v167, v170
	v_fma_f32 v118, v118, v144, -v170
	v_cmp_ge_u32_e64 vcc, v161, v169
	v_cndmask_b32_e64 v117, v221, v117, s[22:23]
	v_subrev_u32_e32 v169, 131, v160
	v_cvt_f32_i32_e32 v170, v169
	v_mul_f32_e32 v170, v167, v170
	v_fma_f32 v119, v119, v144, -v170
	v_cmp_ge_u32_e64 s[22:23], v161, v169
	v_cndmask_b32_e64 v118, v221, v118, vcc
	v_max3_f32 v168, v168, v112, v113
	v_max3_f32 v168, v168, v114, v115
	s_nop 1
	v_cndmask_b32_e64 v119, v221, v119, s[22:23]
	v_max3_f32 v168, v168, v116, v117
	v_max3_f32 v168, v168, v118, v119
	ds_bpermute_b32 v169, v162, v168
	s_waitcnt lgkmcnt(0)
	v_max_f32_e32 v169, v169, v169
	v_max_f32_e32 v168, v168, v169
	ds_bpermute_b32 v169, v163, v168
	s_waitcnt lgkmcnt(0)
	v_max_f32_e32 v169, v169, v169
	v_max_f32_e32 v168, v168, v169
	v_max_f32_e32 v168, s31, v168
	v_mov_b32_e32 v171, 0
	v_sub_f32_e32 v84, v84, v168
	v_mul_f32_e32 v84, 0x3fb8aa3b, v84
	v_exp_f32_e32 v84, v84
	v_sub_f32_e32 v85, v85, v168
	v_mul_f32_e32 v85, 0x3fb8aa3b, v85
	v_exp_f32_e32 v85, v85
	v_add_f32_e32 v171, v84, v171
	v_sub_f32_e32 v86, v86, v168
	v_mul_f32_e32 v86, 0x3fb8aa3b, v86
	v_exp_f32_e32 v86, v86
	v_add_f32_e32 v171, v85, v171
	v_sub_f32_e32 v87, v87, v168
	v_mul_f32_e32 v87, 0x3fb8aa3b, v87
	v_exp_f32_e32 v87, v87
	v_add_f32_e32 v171, v86, v171
	v_sub_f32_e32 v88, v88, v168
	v_mul_f32_e32 v88, 0x3fb8aa3b, v88
	v_exp_f32_e32 v88, v88
	v_add_f32_e32 v171, v87, v171
	v_sub_f32_e32 v89, v89, v168
	v_mul_f32_e32 v89, 0x3fb8aa3b, v89
	v_exp_f32_e32 v89, v89
	v_add_f32_e32 v171, v88, v171
	v_sub_f32_e32 v90, v90, v168
	v_mul_f32_e32 v90, 0x3fb8aa3b, v90
	v_exp_f32_e32 v90, v90
	v_add_f32_e32 v171, v89, v171
	v_sub_f32_e32 v91, v91, v168
	v_mul_f32_e32 v91, 0x3fb8aa3b, v91
	v_exp_f32_e32 v91, v91
	v_add_f32_e32 v171, v90, v171
	v_sub_f32_e32 v92, v92, v168
	v_mul_f32_e32 v92, 0x3fb8aa3b, v92
	v_exp_f32_e32 v92, v92
	v_add_f32_e32 v171, v91, v171
	v_sub_f32_e32 v93, v93, v168
	v_mul_f32_e32 v93, 0x3fb8aa3b, v93
	v_exp_f32_e32 v93, v93
	v_add_f32_e32 v171, v92, v171
	v_sub_f32_e32 v94, v94, v168
	v_mul_f32_e32 v94, 0x3fb8aa3b, v94
	v_exp_f32_e32 v94, v94
	v_add_f32_e32 v171, v93, v171
	v_sub_f32_e32 v95, v95, v168
	v_mul_f32_e32 v95, 0x3fb8aa3b, v95
	v_exp_f32_e32 v95, v95
	v_add_f32_e32 v171, v94, v171
	v_sub_f32_e32 v96, v96, v168
	v_mul_f32_e32 v96, 0x3fb8aa3b, v96
	v_exp_f32_e32 v96, v96
	v_add_f32_e32 v171, v95, v171
	v_sub_f32_e32 v97, v97, v168
	v_mul_f32_e32 v97, 0x3fb8aa3b, v97
	v_exp_f32_e32 v97, v97
	v_add_f32_e32 v171, v96, v171
	v_sub_f32_e32 v98, v98, v168
	v_mul_f32_e32 v98, 0x3fb8aa3b, v98
	v_exp_f32_e32 v98, v98
	v_add_f32_e32 v171, v97, v171
	v_sub_f32_e32 v99, v99, v168
	v_mul_f32_e32 v99, 0x3fb8aa3b, v99
	v_exp_f32_e32 v99, v99
	v_add_f32_e32 v171, v98, v171
	v_sub_f32_e32 v100, v100, v168
	v_mul_f32_e32 v100, 0x3fb8aa3b, v100
	v_exp_f32_e32 v100, v100
	v_add_f32_e32 v171, v99, v171
	v_sub_f32_e32 v101, v101, v168
	v_mul_f32_e32 v101, 0x3fb8aa3b, v101
	v_exp_f32_e32 v101, v101
	v_add_f32_e32 v171, v100, v171
	v_sub_f32_e32 v102, v102, v168
	v_mul_f32_e32 v102, 0x3fb8aa3b, v102
	v_exp_f32_e32 v102, v102
	v_add_f32_e32 v171, v101, v171
	v_sub_f32_e32 v103, v103, v168
	v_mul_f32_e32 v103, 0x3fb8aa3b, v103
	v_exp_f32_e32 v103, v103
	v_add_f32_e32 v171, v102, v171
	v_sub_f32_e32 v104, v104, v168
	v_mul_f32_e32 v104, 0x3fb8aa3b, v104
	v_exp_f32_e32 v104, v104
	v_add_f32_e32 v171, v103, v171
	v_sub_f32_e32 v105, v105, v168
	v_mul_f32_e32 v105, 0x3fb8aa3b, v105
	v_exp_f32_e32 v105, v105
	v_add_f32_e32 v171, v104, v171
	v_sub_f32_e32 v106, v106, v168
	v_mul_f32_e32 v106, 0x3fb8aa3b, v106
	v_exp_f32_e32 v106, v106
	v_add_f32_e32 v171, v105, v171
	v_sub_f32_e32 v107, v107, v168
	v_mul_f32_e32 v107, 0x3fb8aa3b, v107
	v_exp_f32_e32 v107, v107
	v_add_f32_e32 v171, v106, v171
	v_sub_f32_e32 v108, v108, v168
	v_mul_f32_e32 v108, 0x3fb8aa3b, v108
	v_exp_f32_e32 v108, v108
	v_add_f32_e32 v171, v107, v171
	v_sub_f32_e32 v109, v109, v168
	v_mul_f32_e32 v109, 0x3fb8aa3b, v109
	v_exp_f32_e32 v109, v109
	v_add_f32_e32 v171, v108, v171
	v_sub_f32_e32 v110, v110, v168
	v_mul_f32_e32 v110, 0x3fb8aa3b, v110
	v_exp_f32_e32 v110, v110
	v_add_f32_e32 v171, v109, v171
	v_sub_f32_e32 v111, v111, v168
	v_mul_f32_e32 v111, 0x3fb8aa3b, v111
	v_exp_f32_e32 v111, v111
	v_add_f32_e32 v171, v110, v171
	v_sub_f32_e32 v112, v112, v168
	v_mul_f32_e32 v112, 0x3fb8aa3b, v112
	v_exp_f32_e32 v112, v112
	v_add_f32_e32 v171, v111, v171
	v_sub_f32_e32 v113, v113, v168
	v_mul_f32_e32 v113, 0x3fb8aa3b, v113
	v_exp_f32_e32 v113, v113
	v_add_f32_e32 v171, v112, v171
	v_sub_f32_e32 v114, v114, v168
	v_mul_f32_e32 v114, 0x3fb8aa3b, v114
	v_exp_f32_e32 v114, v114
	v_add_f32_e32 v171, v113, v171
	v_sub_f32_e32 v115, v115, v168
	v_mul_f32_e32 v115, 0x3fb8aa3b, v115
	v_exp_f32_e32 v115, v115
	v_add_f32_e32 v171, v114, v171
	v_sub_f32_e32 v116, v116, v168
	v_mul_f32_e32 v116, 0x3fb8aa3b, v116
	v_exp_f32_e32 v116, v116
	v_add_f32_e32 v171, v115, v171
	v_sub_f32_e32 v117, v117, v168
	v_mul_f32_e32 v117, 0x3fb8aa3b, v117
	v_exp_f32_e32 v117, v117
	v_add_f32_e32 v171, v116, v171
	v_sub_f32_e32 v118, v118, v168
	v_mul_f32_e32 v118, 0x3fb8aa3b, v118
	v_exp_f32_e32 v118, v118
	v_add_f32_e32 v171, v117, v171
	v_sub_f32_e32 v119, v119, v168
	v_mul_f32_e32 v119, 0x3fb8aa3b, v119
	v_exp_f32_e32 v119, v119
	v_add_f32_e32 v171, v118, v171
	v_sub_f32_e32 v172, s31, v168
	v_add_f32_e32 v171, v119, v171
	v_mul_f32_e32 v172, 0x3fb8aa3b, v172
	v_exp_f32_e32 v172, v172
	ds_bpermute_b32 v169, v162, v171
	s_waitcnt lgkmcnt(0)
; #define MFMA16(a, b, c) __builtin_amdgcn_mfma_f32_16x16x32_bf16((a), (b), (c), 0, 0, 0)
; __device__ __forceinline__ float bf_lo(unsigned w) { return __uint_as_float(w << 16); }
; __device__ __forceinline__ float bf_hi(unsigned w) { return __uint_as_float(w & 0xffff0000u); }
; __device__ __forceinline__ unsigned pk2(float lo, float hi) { return pg8::cvt_pk_bf16(lo, hi); }
; __device__ __forceinline__ void attn_prompt_item(const bf16_t* z, const bf16_t* vt, bf16_t* mix, const float* sinks, int it, int lane) {
;     ...
;     sum += __shfl_xor(sum, 16); sum += __shfl_xor(sum, 32);
;     const float inv = 1.0f / (sum + __expf(sink - mx));
;     f32x4 o[4];
; #pragma unroll
;     for (int mi = 0; mi < 4; ++mi) o[mi] = (f32x4){0.f, 0.f, 0.f, 0.f};
; #pragma unroll
;     for (int u = 0; u < 5; ++u) {
;         u32x4 pw; pw.x = pk2(sc[2 * u][0] * inv, sc[2 * u][1] * inv); pw.y = pk2(sc[2 * u][2] * inv, sc[2 * u][3] * inv);
;         if (2 * u + 1 < 9) { pw.z = pk2(sc[(2 * u + 1) % 9][0] * inv, sc[(2 * u + 1) % 9][1] * inv); pw.w = pk2(sc[(2 * u + 1) % 9][2] * inv, sc[(2 * u + 1) % 9][3] * inv); }
;         else { pw.z = 0u; pw.w = 0u; }
;         const bf16x8 pb = as_bf16x8(pw);
; #pragma unroll
;         for (int mi = 0; mi < 4; ++mi) {
;             const s16x4 v0 = vq[u][mi][0], v1 = vq[u][mi][1];
;             const bf16x8 va = (bf16x8){v0[0], v0[1], v0[2], v0[3], v1[0], v1[1], v1[2], v1[3]};
;             o[mi] = MFMA16(va, pb, o[mi]);
;         }
;     }
; #pragma unroll
;     for (int mi = 0; mi < 4; ++mi) {
;         const int col = h * 64 + mi * 16 + 4 * g;
;         const u32x2 gw = *(const u32x2*)(z + tokq * EIN + 1280 + col);
;         u32x2 w; w.x = pk2(o[mi][0] * bf_lo(gw.x), o[mi][1] * bf_hi(gw.x)); w.y = pk2(o[mi][2] * bf_lo(gw.y), o[mi][3] * bf_hi(gw.y));
;         *(u32x2*)(mix + tokq * 2048 + col) = w;
;     }
	v_add_f32_e32 v171, v171, v169
	ds_bpermute_b32 v169, v163, v171
	s_waitcnt lgkmcnt(0)
	v_add_f32_e32 v171, v171, v169
	v_add_f32_e32 v171, v171, v172
	v_div_scale_f32 v169, s[22:23], v171, v171, 1.0
	v_rcp_f32_e32 v170, v169
	s_nop 0
	v_fma_f32 v172, -v169, v170, 1.0
	v_fmac_f32_e32 v170, v172, v170
	v_div_scale_f32 v172, vcc, 1.0, v171, 1.0
	v_mul_f32_e32 v173, v172, v170
	v_fma_f32 v174, -v169, v173, v172
	v_fmac_f32_e32 v173, v174, v170
	v_fma_f32 v169, -v169, v173, v172
	v_div_fmas_f32 v169, v169, v170, v173
	v_div_fixup_f32 v174, v169, v171, 1.0
	v_pk_mul_f32 v[170:171], v[84:85], v[174:175] op_sel_hi:[1,0]
	v_cvt_pk_bf16_f32 v84, v170, v171
	v_pk_mul_f32 v[170:171], v[86:87], v[174:175] op_sel_hi:[1,0]
	v_cvt_pk_bf16_f32 v85, v170, v171
	v_pk_mul_f32 v[170:171], v[88:89], v[174:175] op_sel_hi:[1,0]
	v_cvt_pk_bf16_f32 v86, v170, v171
	v_pk_mul_f32 v[170:171], v[90:91], v[174:175] op_sel_hi:[1,0]
	v_cvt_pk_bf16_f32 v87, v170, v171
	v_pk_mul_f32 v[170:171], v[92:93], v[174:175] op_sel_hi:[1,0]
	v_cvt_pk_bf16_f32 v88, v170, v171
	v_pk_mul_f32 v[170:171], v[94:95], v[174:175] op_sel_hi:[1,0]
	v_cvt_pk_bf16_f32 v89, v170, v171
	v_pk_mul_f32 v[170:171], v[96:97], v[174:175] op_sel_hi:[1,0]
	v_cvt_pk_bf16_f32 v90, v170, v171
	v_pk_mul_f32 v[170:171], v[98:99], v[174:175] op_sel_hi:[1,0]
	v_cvt_pk_bf16_f32 v91, v170, v171
	v_pk_mul_f32 v[170:171], v[100:101], v[174:175] op_sel_hi:[1,0]
	v_cvt_pk_bf16_f32 v92, v170, v171
	v_pk_mul_f32 v[170:171], v[102:103], v[174:175] op_sel_hi:[1,0]
	v_cvt_pk_bf16_f32 v93, v170, v171
	v_pk_mul_f32 v[170:171], v[104:105], v[174:175] op_sel_hi:[1,0]
	v_cvt_pk_bf16_f32 v94, v170, v171
	v_pk_mul_f32 v[170:171], v[106:107], v[174:175] op_sel_hi:[1,0]
	v_cvt_pk_bf16_f32 v95, v170, v171
	v_pk_mul_f32 v[170:171], v[108:109], v[174:175] op_sel_hi:[1,0]
	v_cvt_pk_bf16_f32 v96, v170, v171
	v_pk_mul_f32 v[170:171], v[110:111], v[174:175] op_sel_hi:[1,0]
	v_cvt_pk_bf16_f32 v97, v170, v171
	v_pk_mul_f32 v[170:171], v[112:113], v[174:175] op_sel_hi:[1,0]
	v_cvt_pk_bf16_f32 v98, v170, v171
	v_pk_mul_f32 v[170:171], v[114:115], v[174:175] op_sel_hi:[1,0]
	v_cvt_pk_bf16_f32 v99, v170, v171
	v_pk_mul_f32 v[170:171], v[116:117], v[174:175] op_sel_hi:[1,0]
	v_cvt_pk_bf16_f32 v100, v170, v171
	v_pk_mul_f32 v[170:171], v[118:119], v[174:175] op_sel_hi:[1,0]
	v_cvt_pk_bf16_f32 v101, v170, v171
	v_mov_b32_e32 v102, 0
	v_mov_b32_e32 v103, 0
	s_nop 1
	s_waitcnt lgkmcnt(12)
	v_mfma_f32_16x16x32_bf16 v[4:7], v[20:23], v[84:87], 0
	ds_read_b64 v[20:21], v159 offset:25408
	ds_read_b64 v[22:23], v159 offset:25440
	s_waitcnt lgkmcnt(12)
	v_mfma_f32_16x16x32_bf16 v[8:11], v[24:27], v[84:87], 0
	ds_read_b64 v[24:25], v159 offset:128
	ds_read_b64 v[26:27], v159 offset:160
	s_waitcnt lgkmcnt(12)
	v_mfma_f32_16x16x32_bf16 v[12:15], v[28:31], v[84:87], 0
	ds_read_b64 v[28:29], v159 offset:8576
	ds_read_b64 v[30:31], v159 offset:8608
	s_waitcnt lgkmcnt(12)
	v_mfma_f32_16x16x32_bf16 v[16:19], v[32:35], v[84:87], 0
	ds_read_b64 v[32:33], v159 offset:17024
	ds_read_b64 v[34:35], v159 offset:17056
	s_waitcnt lgkmcnt(12)
	v_mfma_f32_16x16x32_bf16 v[4:7], v[36:39], v[88:91], v[4:7]
	ds_read_b64 v[36:37], v159 offset:25472
	ds_read_b64 v[38:39], v159 offset:25504
	s_waitcnt lgkmcnt(12)
	v_mfma_f32_16x16x32_bf16 v[8:11], v[72:75], v[88:91], v[8:11]
	ds_read_b64 v[72:73], v159 offset:192
	ds_read_b64 v[74:75], v159 offset:224
	s_waitcnt lgkmcnt(12)
	v_mfma_f32_16x16x32_bf16 v[12:15], v[76:79], v[88:91], v[12:15]
	ds_read_b64 v[76:77], v159 offset:8640
	ds_read_b64 v[78:79], v159 offset:8672
	s_waitcnt lgkmcnt(12)
	v_mfma_f32_16x16x32_bf16 v[16:19], v[20:23], v[88:91], v[16:19]
	ds_read_b64 v[20:21], v159 offset:17088
	ds_read_b64 v[22:23], v159 offset:17120
	s_waitcnt lgkmcnt(12)
	v_mfma_f32_16x16x32_bf16 v[4:7], v[24:27], v[92:95], v[4:7]
	ds_read_b64 v[24:25], v159 offset:25536
	ds_read_b64 v[26:27], v159 offset:25568
	s_waitcnt lgkmcnt(12)
	v_mfma_f32_16x16x32_bf16 v[8:11], v[28:31], v[92:95], v[8:11]
	ds_read_b64 v[28:29], v159 offset:256
	ds_read_b64 v[30:31], v159 offset:288
	s_waitcnt lgkmcnt(12)
	v_mfma_f32_16x16x32_bf16 v[12:15], v[32:35], v[92:95], v[12:15]
	ds_read_b64 v[32:33], v159 offset:8704
	ds_read_b64 v[34:35], v159 offset:8736
	s_waitcnt lgkmcnt(12)
	v_mfma_f32_16x16x32_bf16 v[16:19], v[36:39], v[92:95], v[16:19]
	ds_read_b64 v[36:37], v159 offset:17152
	ds_read_b64 v[38:39], v159 offset:17184
	s_waitcnt lgkmcnt(12)
	v_mfma_f32_16x16x32_bf16 v[4:7], v[72:75], v[96:99], v[4:7]
	ds_read_b64 v[72:73], v159 offset:25600
	ds_read_b64 v[74:75], v159 offset:25632
	s_waitcnt lgkmcnt(12)
	v_mfma_f32_16x16x32_bf16 v[8:11], v[76:79], v[96:99], v[8:11]
	s_waitcnt lgkmcnt(10)
	v_mfma_f32_16x16x32_bf16 v[12:15], v[20:23], v[96:99], v[12:15]
	s_waitcnt lgkmcnt(8)
	v_mfma_f32_16x16x32_bf16 v[16:19], v[24:27], v[96:99], v[16:19]
	s_waitcnt lgkmcnt(6)
	v_mfma_f32_16x16x32_bf16 v[4:7], v[28:31], v[100:103], v[4:7]
	s_waitcnt lgkmcnt(4)
	v_mfma_f32_16x16x32_bf16 v[8:11], v[32:35], v[100:103], v[8:11]
	s_waitcnt lgkmcnt(2)
	v_mfma_f32_16x16x32_bf16 v[12:15], v[36:39], v[100:103], v[12:15]
	s_waitcnt lgkmcnt(0)
	v_mfma_f32_16x16x32_bf16 v[16:19], v[72:75], v[100:103], v[16:19]
	s_nop 7
	s_waitcnt vmcnt(0)
	v_lshlrev_b32_e32 v172, 16, v130
	v_and_b32_e32 v173, 0xffff0000, v130
	v_lshlrev_b32_e32 v174, 16, v131
	v_and_b32_e32 v175, 0xffff0000, v131
	v_mul_f32_e32 v172, v4, v172
	v_mul_f32_e32 v173, v5, v173
	v_mul_f32_e32 v174, v6, v174
	v_mul_f32_e32 v175, v7, v175
	v_cvt_pk_bf16_f32 v170, v172, v173
	v_cvt_pk_bf16_f32 v171, v174, v175
	global_store_dwordx2 v157, v[170:171], s[14:15] offset:384
	v_lshlrev_b32_e32 v172, 16, v132
	v_and_b32_e32 v173, 0xffff0000, v132
	v_lshlrev_b32_e32 v174, 16, v133
	v_and_b32_e32 v175, 0xffff0000, v133
	v_mul_f32_e32 v172, v8, v172
	v_mul_f32_e32 v173, v9, v173
	v_mul_f32_e32 v174, v10, v174
	v_mul_f32_e32 v175, v11, v175
	v_cvt_pk_bf16_f32 v170, v172, v173
	v_cvt_pk_bf16_f32 v171, v174, v175
	global_store_dwordx2 v157, v[170:171], s[14:15] offset:416
	v_lshlrev_b32_e32 v172, 16, v134
	v_and_b32_e32 v173, 0xffff0000, v134
	v_lshlrev_b32_e32 v174, 16, v135
	v_and_b32_e32 v175, 0xffff0000, v135
	v_mul_f32_e32 v172, v12, v172
	v_mul_f32_e32 v173, v13, v173
	v_mul_f32_e32 v174, v14, v174
	v_mul_f32_e32 v175, v15, v175
	v_cvt_pk_bf16_f32 v170, v172, v173
	v_cvt_pk_bf16_f32 v171, v174, v175
	global_store_dwordx2 v157, v[170:171], s[14:15] offset:448
	v_lshlrev_b32_e32 v172, 16, v136
	v_and_b32_e32 v173, 0xffff0000, v136
	v_lshlrev_b32_e32 v174, 16, v137
	v_and_b32_e32 v175, 0xffff0000, v137
	v_mul_f32_e32 v172, v16, v172
	v_mul_f32_e32 v173, v17, v173
	v_mul_f32_e32 v174, v18, v174
	v_mul_f32_e32 v175, v19, v175
	v_cvt_pk_bf16_f32 v170, v172, v173
	v_cvt_pk_bf16_f32 v171, v174, v175
	global_store_dwordx2 v157, v[170:171], s[14:15] offset:480
	s_barrier
; #define LAS __attribute__((address_space(3)))
; __device__ __forceinline__ float bf_lo(unsigned w) { return __uint_as_float(w << 16); }
; __device__ __forceinline__ float bf_hi(unsigned w) { return __uint_as_float(w & 0xffff0000u); }
; __device__ __forceinline__ void attn_sample_item(LAS float* wl, const bf16_t* z, bf16_t* mix, const float* sinks, const float* ck, const float* cv, int it, int lane) {
;     const int h = it & 15, b = it >> 4, kv = h >> 3;
;     LAS float* qs = wl;
;     LAS float* pT = wl + 512;
;     const size_t tok0 = (size_t)T_P + b * 8;
; #pragma unroll
;     for (int t = 0; t < 8; ++t) qs[t * 64 + lane] = bf1(z[(tok0 + t) * EIN + h * 64 + lane]);
;     __builtin_amdgcn_wave_barrier();
;     asm volatile("s_waitcnt lgkmcnt(0)" ::: "memory");
;     const float slope = exp2f(-0.5f * (float)(h + 1)), sink = sinks[h];
;     float s[3][8];
; #pragma unroll
;     for (int ps = 0; ps < 3; ++ps) {
;         const int idx = lane + 64 * ps;
; #pragma unroll
;         for (int t = 0; t < 8; ++t) s[ps][t] = 0.f;
;         if (idx < 128) {
;             const f32x4* kp = (const f32x4*)(ck + (((size_t)b * 128 + idx) * 2 + kv) * 64);
; #pragma unroll 8
;             for (int d4 = 0; d4 < 16; ++d4) {
;                 const f32x4 k4 = kp[d4];
; #pragma unroll
;                 for (int t = 0; t < 8; ++t) { const f32x4 q4 = *(const LAS f32x4*)(qs + t * 64 + 4 * d4); s[ps][t] += (k4[0] * q4[0] + k4[1] * q4[1]) + (k4[2] * q4[2] + k4[3] * q4[3]); }
;             }
;         } else if (idx < 136) {
;             const bf16_t* kp = z + (tok0 + (idx - 128)) * EIN + 1024 + kv * 64;
; #pragma unroll 4
;             for (int d4 = 0; d4 < 16; ++d4) {
;                 const u32x2 kw = *(const u32x2*)(kp + 4 * d4);
;                 const float k0 = bf_lo(kw.x), k1 = bf_hi(kw.x), k2 = bf_lo(kw.y), k3 = bf_hi(kw.y);
; #pragma unroll
;                 for (int t = 0; t < 8; ++t) { const f32x4 q4 = *(const LAS f32x4*)(qs + t * 64 + 4 * d4); s[ps][t] += (k0 * q4[0] + k1 * q4[1]) + (k2 * q4[2] + k3 * q4[3]); }
;             }
;         }
; #pragma unroll
;         for (int t = 0; t < 8; ++t) {
;             const int dist = t + 128 - idx;
;             const bool valid = (idx < 136) && (dist >= 0) && (dist < 128);
;             s[ps][t] = valid ? s[ps][t] * 0.125f - slope * (float)dist : -1e30f;
;         }
.LBB0_1059:
.LBB0_1060:
	v_readlane_b32 s4, v254, 50
	v_readlane_b32 s5, v254, 51
	s_lshl_b64 s[42:43], s[4:5], 21
	s_cmpk_gt_i32 s54, 0x7ff
	s_cbranch_scc1 .LBB0_1095
	v_sub_u32_e32 v0, 0x80, v82
	v_cvt_f32_ubyte0_e32 v59, v0
	v_sub_u32_e32 v0, 0x81, v82
	v_cvt_f32_ubyte0_e32 v60, v0
	v_sub_u32_e32 v0, 0x82, v82
	v_cvt_f32_ubyte0_e32 v61, v0
	v_sub_u32_e32 v0, 0x83, v82
	v_cvt_f32_ubyte0_e32 v62, v0
	v_sub_u32_e32 v0, 0x84, v82
	v_cvt_f32_ubyte0_e32 v63, v0
	v_sub_u32_e32 v0, 0x85, v82
	v_cvt_f32_ubyte0_e32 v64, v0
	v_sub_u32_e32 v0, 0x86, v82
	v_cvt_f32_ubyte0_e32 v65, v0
	v_sub_u32_e32 v0, 0x87, v82
	v_cvt_f32_ubyte0_e32 v66, v0
	v_or_b32_e32 v0, 64, v82
	v_sub_u32_e32 v2, 0x80, v0
	v_cvt_f32_ubyte0_e32 v67, v2
	v_sub_u32_e32 v2, 0x81, v0
	v_cvt_f32_ubyte0_e32 v68, v2
	v_sub_u32_e32 v2, 0x82, v0
	v_cvt_f32_ubyte0_e32 v69, v2
	v_sub_u32_e32 v2, 0x83, v0
	v_cvt_f32_ubyte0_e32 v70, v2
	v_sub_u32_e32 v2, 0x84, v0
	v_cvt_f32_ubyte0_e32 v71, v2
	v_sub_u32_e32 v2, 0x85, v0
	v_cvt_f32_ubyte0_e32 v72, v2
	v_sub_u32_e32 v2, 0x86, v0
	v_sub_u32_e32 v0, 0x87, v0
	v_cvt_f32_ubyte0_e32 v74, v0
	v_or_b32_e32 v0, 0x80, v82
	v_cvt_f32_ubyte0_e32 v73, v2
	s_movk_i32 s20, 0x88
	v_sub_u32_e32 v2, 0x81, v0
	s_movk_i32 s36, 0x80
	v_cmp_gt_u32_e64 s[20:21], s20, v0
	v_cmp_gt_u32_e32 vcc, s36, v2
	v_cvt_f32_u32_e32 v75, v2
	v_sub_u32_e32 v2, 0x82, v0
	s_and_b64 s[22:23], s[20:21], vcc
	v_cmp_gt_u32_e32 vcc, s36, v2
	v_cvt_f32_u32_e32 v76, v2
	v_sub_u32_e32 v2, 0x83, v0
	s_and_b64 s[24:25], s[20:21], vcc
	v_cmp_gt_u32_e32 vcc, s36, v2
	v_cvt_f32_u32_e32 v77, v2
	v_sub_u32_e32 v2, 0x84, v0
	s_and_b64 s[26:27], s[20:21], vcc
	v_cmp_gt_u32_e32 vcc, s36, v2
	v_cvt_f32_u32_e32 v78, v2
	v_sub_u32_e32 v2, 0x85, v0
	s_and_b64 s[28:29], s[20:21], vcc
	v_cmp_gt_u32_e32 vcc, s36, v2
	v_cvt_f32_u32_e32 v79, v2
	v_sub_u32_e32 v2, 0x86, v0
	s_mulk_i32 s44, 0x3000
	s_and_b64 s[30:31], s[20:21], vcc
	v_cmp_gt_u32_e32 vcc, s36, v2
	v_sub_u32_e32 v0, 0x87, v0
	s_add_i32 s55, s44, 0
	s_and_b64 s[34:35], s[20:21], vcc
	v_cmp_gt_u32_e32 vcc, s36, v0
	v_readlane_b32 s44, v255, 0
	s_and_b64 s[36:37], s[20:21], vcc
	s_and_b32 s44, s44, 0xc0
	s_cmp_eq_u32 s44, 0
	v_readlane_b32 s46, v254, 58
	s_cselect_b64 s[44:45], -1, 0
	v_readlane_b32 s47, v254, 59
	s_add_u32 s46, s46, s42
	v_cvt_f32_u32_e32 v81, v0
	s_addc_u32 s47, s47, s43
	v_lshlrev_b32_e32 v0, 9, v82
	v_cvt_f32_u32_e32 v80, v2
	v_lshl_add_u64 v[2:3], s[46:47], 0, v[0:1]
	s_mov_b64 s[48:49], 0x8040
	v_lshl_add_u64 v[34:35], v[2:3], 0, s[48:49]
	v_readlane_b32 s48, v255, 3
	v_readlane_b32 s49, v255, 4
	s_add_u32 s56, s48, 0x19208810
	s_addc_u32 s57, s49, 0
	s_add_i32 s62, s55, 0x800
	v_readlane_b32 s48, v254, 60
	v_readlane_b32 s49, v254, 61
	s_add_u32 s48, s48, s42
	v_mov_b32_e32 v83, v1
	v_lshlrev_b32_e32 v0, 2, v82
	s_addc_u32 s49, s49, s43
	v_lshlrev_b64 v[28:29], 1, v[82:83]
	v_lshlrev_b32_e32 v4, 5, v82
	v_lshl_add_u64 v[2:3], s[48:49], 0, v[0:1]
	s_mov_b64 s[48:49], 0x1000
	v_lshl_add_u64 v[30:31], s[96:97], 0, v[28:29]
	v_lshl_add_u32 v58, v82, 2, s55
	v_lshlrev_b32_e32 v26, 1, v82
	v_mov_b32_e32 v27, v1
	v_cmp_eq_u32_e64 s[4:5], 0, v82
	v_cmp_lt_u32_e64 s[6:7], 1, v82
	v_cmp_lt_u32_e64 s[8:9], 2, v82
	v_cmp_lt_u32_e64 s[10:11], 3, v82
	v_cmp_lt_u32_e64 s[12:13], 4, v82
	v_cmp_lt_u32_e64 s[14:15], 5, v82
	v_cmp_lt_u32_e64 s[16:17], 6, v82
	v_cmp_lt_u32_e64 s[18:19], 7, v82
	v_cmp_gt_u32_e64 s[38:39], 8, v82
	v_lshl_add_u64 v[32:33], s[92:93], 0, v[28:29]
	v_lshl_add_u64 v[36:37], v[2:3], 0, s[48:49]
	v_add_u32_e32 v0, s55, v4
	s_mov_b32 s63, s54
	s_branch .LBB0_1063

; __device__ __forceinline__ float wave_sum(float v) {
; #pragma unroll
;     for (int o = 1; o < 64; o <<= 1) v += __shfl_xor(v, o);
;     return v;
; }
; __device__ __forceinline__ float wave_max(float v) {
; #pragma unroll
;     for (int o = 1; o < 64; o <<= 1) v = fmaxf(v, __shfl_xor(v, o));
;     return v;
; }
; __device__ __forceinline__ void attn_sample_item(LAS float* wl, const bf16_t* z, bf16_t* mix, const float* sinks, const float* ck, const float* cv, int it, int lane) {
;     ...
; #pragma unroll
;     for (int t = 0; t < 8; ++t) {
;         float m = fmaxf(fmaxf(s[0][t], s[1][t]), s[2][t]); m = fmaxf(wave_max(m), sink);
;         const float p0 = __expf(s[0][t] - m), p1 = __expf(s[1][t] - m), p2 = __expf(s[2][t] - m);
;         const float den = wave_sum(p0 + p1 + p2) + __expf(sink - m), inv = 1.0f / den;
;         pT[lane * 8 + t] = p0 * inv; pT[(lane + 64) * 8 + t] = p1 * inv; if (lane < 8) pT[(lane + 128) * 8 + t] = p2 * inv;
;     }
.LBB0_1072:
	s_or_b64 exec, exec, s[52:53]
	s_add_i32 s52, s69, 1
	v_cvt_f32_ubyte0_e32 v4, s52
	v_mul_f32_e32 v5, -0.5, v4
	s_mov_b32 s52, 0xc2fc0000
	v_cmp_gt_f32_e32 vcc, s52, v5
	s_and_b64 s[52:53], vcc, exec
	s_cselect_b32 s52, 0xffffffc0, 0
	v_cndmask_b32_e32 v5, 0, v216, vcc
	v_fmac_f32_e32 v5, -0.5, v4
	v_exp_f32_e32 v4, v5
	v_xor_b32_e32 v21, 32, v215
	v_ldexp_f32 v5, v4, s52
	v_mul_f32_e32 v4, v5, v59
	s_mov_b32 s52, 0x3e000000
	v_fma_f32 v4, v39, s52, -v4
	v_cndmask_b32_e64 v16, v4, v221, s[4:5]
	v_mul_f32_e32 v4, v5, v67
	v_fma_f32 v17, v47, s52, -v4
	v_and_b32_e32 v4, 64, v215
	v_add_u32_e32 v15, 64, v4
	v_xor_b32_e32 v4, 1, v215
	v_fmac_f32_e32 v11, 0x80000000, v5
	v_cmp_lt_i32_e32 vcc, v4, v15
	v_cndmask_b32_e64 v18, v221, v11, s[4:5]
	v_max3_f32 v12, v16, v17, v18
	v_cndmask_b32_e32 v4, v215, v4, vcc
	v_lshlrev_b32_e32 v4, 2, v4
	ds_bpermute_b32 v13, v4, v12
	v_xor_b32_e32 v11, 2, v215
	v_cmp_lt_i32_e32 vcc, v11, v15
	s_waitcnt lgkmcnt(0)
	v_max_f32_e32 v13, v13, v13
	v_cndmask_b32_e32 v11, v215, v11, vcc
	v_lshlrev_b32_e32 v11, 2, v11
	v_max_f32_e32 v13, v12, v13
	ds_bpermute_b32 v14, v11, v13
	v_xor_b32_e32 v12, 4, v215
	v_cmp_lt_i32_e32 vcc, v12, v15
	s_waitcnt lgkmcnt(0)
	v_max_f32_e32 v14, v14, v14
	v_cndmask_b32_e32 v12, v215, v12, vcc
	v_lshlrev_b32_e32 v12, 2, v12
	v_max_f32_e32 v14, v13, v14
	ds_bpermute_b32 v19, v12, v14
	v_xor_b32_e32 v13, 8, v215
	v_cmp_lt_i32_e32 vcc, v13, v15
	s_waitcnt lgkmcnt(0)
	v_max_f32_e32 v19, v19, v19
	v_cndmask_b32_e32 v13, v215, v13, vcc
	v_lshlrev_b32_e32 v13, 2, v13
	v_max_f32_e32 v19, v14, v19
	ds_bpermute_b32 v20, v13, v19
	v_xor_b32_e32 v14, 16, v215
	v_cmp_lt_i32_e32 vcc, v14, v15
	s_waitcnt lgkmcnt(0)
	v_max_f32_e32 v20, v20, v20
	v_cndmask_b32_e32 v14, v215, v14, vcc
	v_lshlrev_b32_e32 v14, 2, v14
	v_max_f32_e32 v19, v19, v20
	ds_bpermute_b32 v20, v14, v19
	v_cmp_lt_i32_e32 vcc, v21, v15
	s_waitcnt lgkmcnt(0)
	v_max_f32_e32 v20, v20, v20
	v_cndmask_b32_e32 v15, v215, v21, vcc
	v_lshlrev_b32_e32 v15, 2, v15
	v_max_f32_e32 v19, v19, v20
	ds_bpermute_b32 v20, v15, v19
	s_waitcnt lgkmcnt(0)
	v_max3_f32 v19, v19, v20, v83
	v_sub_f32_e32 v16, v16, v19
	v_mul_f32_e32 v16, 0x3fb8aa3b, v16
	v_exp_f32_e32 v20, v16
	v_sub_f32_e32 v16, v17, v19
	v_mul_f32_e32 v16, 0x3fb8aa3b, v16
	v_exp_f32_e32 v21, v16
	v_sub_f32_e32 v16, v18, v19
	v_mul_f32_e32 v16, 0x3fb8aa3b, v16
	v_exp_f32_e32 v16, v16
	v_add_f32_e32 v17, v20, v21
	v_sub_f32_e32 v19, v83, v19
	v_mul_f32_e32 v19, 0x3fb8aa3b, v19
	v_add_f32_e32 v17, v16, v17
	v_exp_f32_e32 v19, v19
	s_waitcnt lgkmcnt(0)
	s_nop 1
	v_add_f32_dpp v17, v17, v17 quad_perm:[1,0,3,2] row_mask:0xf bank_mask:0xf
	s_nop 1
	v_add_f32_dpp v17, v17, v17 quad_perm:[2,3,0,1] row_mask:0xf bank_mask:0xf
	s_nop 1
	v_add_f32_dpp v17, v17, v17 row_half_mirror row_mask:0xf bank_mask:0xf
	s_nop 1
	v_add_f32_dpp v17, v17, v17 row_mirror row_mask:0xf bank_mask:0xf
	s_nop 1
	v_add_f32_dpp v17, v17, v17 row_bcast:15 row_mask:0xa bank_mask:0xf
	s_nop 1
	v_add_f32_dpp v17, v17, v17 row_bcast:31 row_mask:0xc bank_mask:0xf
	s_nop 1
	v_readlane_b32 s100, v17, 63
	s_nop 1
	v_mov_b32_e32 v17, s100
	v_add_f32_e32 v17, v19, v17
	v_div_scale_f32 v18, s[52:53], v17, v17, 1.0
	v_rcp_f32_e32 v19, v18
	v_div_scale_f32 v22, vcc, 1.0, v17, 1.0
	v_fma_f32 v23, -v18, v19, 1.0
	v_fmac_f32_e32 v19, v23, v19
	v_mul_f32_e32 v23, v22, v19
	v_fma_f32 v24, -v18, v23, v22
	v_fmac_f32_e32 v23, v24, v19
	v_fma_f32 v18, -v18, v23, v22
	v_div_fmas_f32 v18, v18, v19, v23
	v_div_fixup_f32 v17, v18, v17, 1.0
	v_mul_f32_e32 v18, v20, v17
	v_mul_f32_e32 v19, v21, v17
	ds_write2st64_b32 v0, v18, v19 offset0:8 offset1:16
	s_and_saveexec_b64 s[52:53], s[38:39]
	v_mul_f32_e32 v16, v16, v17
	ds_write_b32 v0, v16 offset:6144
	s_or_b64 exec, exec, s[52:53]
	v_mul_f32_e32 v16, v5, v60
	s_mov_b32 s52, 0x3e000000
	v_fma_f32 v10, -v5, v75, v10
	v_fma_f32 v16, v38, s52, -v16
	v_mul_f32_e32 v17, v5, v68
	v_cndmask_b32_e64 v10, v221, v10, s[22:23]
	v_cndmask_b32_e64 v16, v221, v16, s[6:7]
	v_fma_f32 v17, v46, s52, -v17
	v_max3_f32 v18, v16, v17, v10
	ds_bpermute_b32 v19, v4, v18
	s_waitcnt lgkmcnt(0)
	v_max_f32_e32 v19, v19, v19
	v_max_f32_e32 v18, v18, v19
	ds_bpermute_b32 v19, v11, v18
	s_waitcnt lgkmcnt(0)
	v_max_f32_e32 v19, v19, v19
	v_max_f32_e32 v18, v18, v19
	ds_bpermute_b32 v19, v12, v18
	s_waitcnt lgkmcnt(0)
	v_max_f32_e32 v19, v19, v19
	v_max_f32_e32 v18, v18, v19
	ds_bpermute_b32 v19, v13, v18
	s_waitcnt lgkmcnt(0)
	v_max_f32_e32 v19, v19, v19
	v_max_f32_e32 v18, v18, v19
	ds_bpermute_b32 v19, v14, v18
	s_waitcnt lgkmcnt(0)
	v_max_f32_e32 v19, v19, v19
	v_max_f32_e32 v18, v18, v19
	ds_bpermute_b32 v19, v15, v18
	s_waitcnt lgkmcnt(0)
	v_max3_f32 v18, v18, v19, v83
	v_sub_f32_e32 v16, v16, v18
	v_sub_f32_e32 v17, v17, v18
	v_sub_f32_e32 v10, v10, v18
	v_mul_f32_e32 v16, 0x3fb8aa3b, v16
	v_mul_f32_e32 v17, 0x3fb8aa3b, v17
	v_mul_f32_e32 v10, 0x3fb8aa3b, v10
	v_exp_f32_e32 v19, v16
	v_exp_f32_e32 v17, v17
	v_exp_f32_e32 v10, v10
	v_sub_f32_e32 v18, v83, v18
	v_mul_f32_e32 v18, 0x3fb8aa3b, v18
	v_add_f32_e32 v16, v19, v17
	v_add_f32_e32 v16, v10, v16
	v_exp_f32_e32 v18, v18
	s_waitcnt lgkmcnt(0)
; __device__ __forceinline__ float wave_sum(float v) {
; #pragma unroll
;     for (int o = 1; o < 64; o <<= 1) v += __shfl_xor(v, o);
;     return v;
; }
; __device__ __forceinline__ float wave_max(float v) {
; #pragma unroll
;     for (int o = 1; o < 64; o <<= 1) v = fmaxf(v, __shfl_xor(v, o));
;     return v;
; }
; __device__ __forceinline__ void attn_sample_item(LAS float* wl, const bf16_t* z, bf16_t* mix, const float* sinks, const float* ck, const float* cv, int it, int lane) {
;     ...
; #pragma unroll
;     for (int t = 0; t < 8; ++t) {
;         float m = fmaxf(fmaxf(s[0][t], s[1][t]), s[2][t]); m = fmaxf(wave_max(m), sink);
;         const float p0 = __expf(s[0][t] - m), p1 = __expf(s[1][t] - m), p2 = __expf(s[2][t] - m);
;         const float den = wave_sum(p0 + p1 + p2) + __expf(sink - m), inv = 1.0f / den;
;         pT[lane * 8 + t] = p0 * inv; pT[(lane + 64) * 8 + t] = p1 * inv; if (lane < 8) pT[(lane + 128) * 8 + t] = p2 * inv;
;     }
	s_nop 1
	v_add_f32_dpp v16, v16, v16 quad_perm:[1,0,3,2] row_mask:0xf bank_mask:0xf
	s_nop 1
	v_add_f32_dpp v16, v16, v16 quad_perm:[2,3,0,1] row_mask:0xf bank_mask:0xf
	s_nop 1
	v_add_f32_dpp v16, v16, v16 row_half_mirror row_mask:0xf bank_mask:0xf
	s_nop 1
	v_add_f32_dpp v16, v16, v16 row_mirror row_mask:0xf bank_mask:0xf
	s_nop 1
	v_add_f32_dpp v16, v16, v16 row_bcast:15 row_mask:0xa bank_mask:0xf
	s_nop 1
	v_add_f32_dpp v16, v16, v16 row_bcast:31 row_mask:0xc bank_mask:0xf
	s_nop 1
	v_readlane_b32 s100, v16, 63
	s_nop 1
	v_mov_b32_e32 v16, s100
	v_add_f32_e32 v16, v18, v16
	v_div_scale_f32 v18, s[52:53], v16, v16, 1.0
	v_rcp_f32_e32 v20, v18
	v_div_scale_f32 v21, vcc, 1.0, v16, 1.0
	v_fma_f32 v22, -v18, v20, 1.0
	v_fmac_f32_e32 v20, v22, v20
	v_mul_f32_e32 v22, v21, v20
	v_fma_f32 v23, -v18, v22, v21
	v_fmac_f32_e32 v22, v23, v20
	v_fma_f32 v18, -v18, v22, v21
	v_div_fmas_f32 v18, v18, v20, v22
	v_div_fixup_f32 v16, v18, v16, 1.0
	v_mul_f32_e32 v18, v19, v16
	v_mul_f32_e32 v17, v17, v16
	v_add_u32_e32 v19, 4, v0
	ds_write2st64_b32 v19, v18, v17 offset0:8 offset1:16
	s_and_saveexec_b64 s[52:53], s[38:39]
	v_mul_f32_e32 v10, v10, v16
	ds_write_b32 v0, v10 offset:6148
	s_or_b64 exec, exec, s[52:53]
	v_mul_f32_e32 v10, v5, v61
	s_mov_b32 s52, 0x3e000000
	v_fma_f32 v9, -v5, v76, v9
	v_fma_f32 v10, v43, s52, -v10
	v_mul_f32_e32 v16, v5, v69
	v_cndmask_b32_e64 v9, v221, v9, s[24:25]
	v_cndmask_b32_e64 v10, v221, v10, s[8:9]
	v_fma_f32 v16, v51, s52, -v16
	v_max3_f32 v17, v10, v16, v9
	ds_bpermute_b32 v18, v4, v17
	s_waitcnt lgkmcnt(0)
	v_max_f32_e32 v18, v18, v18
	v_max_f32_e32 v17, v17, v18
	ds_bpermute_b32 v18, v11, v17
	s_waitcnt lgkmcnt(0)
	v_max_f32_e32 v18, v18, v18
	v_max_f32_e32 v17, v17, v18
	ds_bpermute_b32 v18, v12, v17
	s_waitcnt lgkmcnt(0)
	v_max_f32_e32 v18, v18, v18
	v_max_f32_e32 v17, v17, v18
	ds_bpermute_b32 v18, v13, v17
	s_waitcnt lgkmcnt(0)
	v_max_f32_e32 v18, v18, v18
	v_max_f32_e32 v17, v17, v18
	ds_bpermute_b32 v18, v14, v17
	s_waitcnt lgkmcnt(0)
	v_max_f32_e32 v18, v18, v18
	v_max_f32_e32 v17, v17, v18
	ds_bpermute_b32 v18, v15, v17
	s_waitcnt lgkmcnt(0)
	v_max3_f32 v17, v17, v18, v83
	v_sub_f32_e32 v10, v10, v17
	v_sub_f32_e32 v16, v16, v17
	v_sub_f32_e32 v9, v9, v17
	v_mul_f32_e32 v10, 0x3fb8aa3b, v10
	v_mul_f32_e32 v16, 0x3fb8aa3b, v16
	v_mul_f32_e32 v9, 0x3fb8aa3b, v9
	v_exp_f32_e32 v18, v10
	v_exp_f32_e32 v16, v16
	v_exp_f32_e32 v9, v9
	v_sub_f32_e32 v17, v83, v17
	v_mul_f32_e32 v17, 0x3fb8aa3b, v17
	v_add_f32_e32 v10, v18, v16
	v_add_f32_e32 v10, v9, v10
	v_exp_f32_e32 v17, v17
	s_waitcnt lgkmcnt(0)
	s_nop 1
	v_add_f32_dpp v10, v10, v10 quad_perm:[1,0,3,2] row_mask:0xf bank_mask:0xf
	s_nop 1
	v_add_f32_dpp v10, v10, v10 quad_perm:[2,3,0,1] row_mask:0xf bank_mask:0xf
	s_nop 1
	v_add_f32_dpp v10, v10, v10 row_half_mirror row_mask:0xf bank_mask:0xf
	s_nop 1
	v_add_f32_dpp v10, v10, v10 row_mirror row_mask:0xf bank_mask:0xf
	s_nop 1
	v_add_f32_dpp v10, v10, v10 row_bcast:15 row_mask:0xa bank_mask:0xf
	s_nop 1
	v_add_f32_dpp v10, v10, v10 row_bcast:31 row_mask:0xc bank_mask:0xf
	s_nop 1
	v_readlane_b32 s100, v10, 63
	s_nop 1
	v_mov_b32_e32 v10, s100
	v_add_f32_e32 v10, v17, v10
	v_div_scale_f32 v17, s[52:53], v10, v10, 1.0
	v_rcp_f32_e32 v19, v17
	v_div_scale_f32 v20, vcc, 1.0, v10, 1.0
	v_fma_f32 v21, -v17, v19, 1.0
	v_fmac_f32_e32 v19, v21, v19
	v_mul_f32_e32 v21, v20, v19
	v_fma_f32 v22, -v17, v21, v20
	v_fmac_f32_e32 v21, v22, v19
	v_fma_f32 v17, -v17, v21, v20
	v_div_fmas_f32 v17, v17, v19, v21
	v_div_fixup_f32 v10, v17, v10, 1.0
	v_mul_f32_e32 v17, v18, v10
	v_mul_f32_e32 v16, v16, v10
	v_add_u32_e32 v18, 8, v0
	ds_write2st64_b32 v18, v17, v16 offset0:8 offset1:16
	s_and_saveexec_b64 s[52:53], s[38:39]
	v_mul_f32_e32 v9, v9, v10
	ds_write_b32 v0, v9 offset:6152
	s_or_b64 exec, exec, s[52:53]
	v_mul_f32_e32 v9, v5, v62
	s_mov_b32 s52, 0x3e000000
	v_fma_f32 v8, -v5, v77, v8
	v_fma_f32 v9, v42, s52, -v9
	v_mul_f32_e32 v10, v5, v70
	v_cndmask_b32_e64 v8, v221, v8, s[26:27]
	v_cndmask_b32_e64 v9, v221, v9, s[10:11]
	v_fma_f32 v10, v50, s52, -v10
	v_max3_f32 v16, v9, v10, v8
	ds_bpermute_b32 v17, v4, v16
	s_waitcnt lgkmcnt(0)
	v_max_f32_e32 v17, v17, v17
	v_max_f32_e32 v16, v16, v17
	ds_bpermute_b32 v17, v11, v16
	s_waitcnt lgkmcnt(0)
	v_max_f32_e32 v17, v17, v17
	v_max_f32_e32 v16, v16, v17
	ds_bpermute_b32 v17, v12, v16
	s_waitcnt lgkmcnt(0)
	v_max_f32_e32 v17, v17, v17
	v_max_f32_e32 v16, v16, v17
	ds_bpermute_b32 v17, v13, v16
	s_waitcnt lgkmcnt(0)
	v_max_f32_e32 v17, v17, v17
	v_max_f32_e32 v16, v16, v17
	ds_bpermute_b32 v17, v14, v16
	s_waitcnt lgkmcnt(0)
	v_max_f32_e32 v17, v17, v17
	v_max_f32_e32 v16, v16, v17
	ds_bpermute_b32 v17, v15, v16
	s_waitcnt lgkmcnt(0)
	v_max3_f32 v16, v16, v17, v83
	v_sub_f32_e32 v9, v9, v16
	v_sub_f32_e32 v10, v10, v16
	v_sub_f32_e32 v8, v8, v16
	v_mul_f32_e32 v9, 0x3fb8aa3b, v9
	v_mul_f32_e32 v10, 0x3fb8aa3b, v10
	v_mul_f32_e32 v8, 0x3fb8aa3b, v8
	v_exp_f32_e32 v17, v9
	v_exp_f32_e32 v10, v10
	v_exp_f32_e32 v8, v8
	v_sub_f32_e32 v16, v83, v16
	v_mul_f32_e32 v16, 0x3fb8aa3b, v16
	v_add_f32_e32 v9, v17, v10
	v_add_f32_e32 v9, v8, v9
	v_exp_f32_e32 v16, v16
	s_waitcnt lgkmcnt(0)
; __device__ __forceinline__ void attn_sample_item(LAS float* wl, const bf16_t* z, bf16_t* mix, const float* sinks, const float* ck, const float* cv, int it, int lane) {
;     ...
;     for (int t = 0; t < 8; ++t) {
;         float m = fmaxf(fmaxf(s[0][t], s[1][t]), s[2][t]); m = fmaxf(wave_max(m), sink);
;         const float p0 = __expf(s[0][t] - m), p1 = __expf(s[1][t] - m), p2 = __expf(s[2][t] - m);
;         const float den = wave_sum(p0 + p1 + p2) + __expf(sink - m), inv = 1.0f / den;
;         pT[lane * 8 + t] = p0 * inv; pT[(lane + 64) * 8 + t] = p1 * inv; if (lane < 8) pT[(lane + 128) * 8 + t] = p2 * inv;
;     }
	s_nop 1
	v_add_f32_dpp v9, v9, v9 quad_perm:[1,0,3,2] row_mask:0xf bank_mask:0xf
	s_nop 1
	v_add_f32_dpp v9, v9, v9 quad_perm:[2,3,0,1] row_mask:0xf bank_mask:0xf
	s_nop 1
	v_add_f32_dpp v9, v9, v9 row_half_mirror row_mask:0xf bank_mask:0xf
	s_nop 1
	v_add_f32_dpp v9, v9, v9 row_mirror row_mask:0xf bank_mask:0xf
	s_nop 1
	v_add_f32_dpp v9, v9, v9 row_bcast:15 row_mask:0xa bank_mask:0xf
	s_nop 1
	v_add_f32_dpp v9, v9, v9 row_bcast:31 row_mask:0xc bank_mask:0xf
	s_nop 1
	v_readlane_b32 s100, v9, 63
	s_nop 1
	v_mov_b32_e32 v9, s100
	v_add_f32_e32 v9, v16, v9
	v_div_scale_f32 v16, s[52:53], v9, v9, 1.0
	v_rcp_f32_e32 v18, v16
	v_div_scale_f32 v19, vcc, 1.0, v9, 1.0
	v_fma_f32 v20, -v16, v18, 1.0
	v_fmac_f32_e32 v18, v20, v18
	v_mul_f32_e32 v20, v19, v18
	v_fma_f32 v21, -v16, v20, v19
	v_fmac_f32_e32 v20, v21, v18
	v_fma_f32 v16, -v16, v20, v19
	v_div_fmas_f32 v16, v16, v18, v20
	v_div_fixup_f32 v9, v16, v9, 1.0
	v_mul_f32_e32 v16, v17, v9
	v_mul_f32_e32 v10, v10, v9
	v_add_u32_e32 v17, 12, v0
	ds_write2st64_b32 v17, v16, v10 offset0:8 offset1:16
	s_and_saveexec_b64 s[52:53], s[38:39]
	v_mul_f32_e32 v8, v8, v9
	ds_write_b32 v0, v8 offset:6156
	s_or_b64 exec, exec, s[52:53]
	v_mul_f32_e32 v8, v5, v63
	s_mov_b32 s52, 0x3e000000
	v_fma_f32 v7, -v5, v78, v7
	v_fma_f32 v8, v41, s52, -v8
	v_mul_f32_e32 v9, v5, v71
	v_cndmask_b32_e64 v7, v221, v7, s[28:29]
	v_cndmask_b32_e64 v8, v221, v8, s[12:13]
	v_fma_f32 v9, v49, s52, -v9
	v_max3_f32 v10, v8, v9, v7
	ds_bpermute_b32 v16, v4, v10
	s_waitcnt lgkmcnt(0)
	v_max_f32_e32 v16, v16, v16
	v_max_f32_e32 v10, v10, v16
	ds_bpermute_b32 v16, v11, v10
	s_waitcnt lgkmcnt(0)
	v_max_f32_e32 v16, v16, v16
	v_max_f32_e32 v10, v10, v16
	ds_bpermute_b32 v16, v12, v10
	s_waitcnt lgkmcnt(0)
	v_max_f32_e32 v16, v16, v16
	v_max_f32_e32 v10, v10, v16
	ds_bpermute_b32 v16, v13, v10
	s_waitcnt lgkmcnt(0)
	v_max_f32_e32 v16, v16, v16
	v_max_f32_e32 v10, v10, v16
	ds_bpermute_b32 v16, v14, v10
	s_waitcnt lgkmcnt(0)
	v_max_f32_e32 v16, v16, v16
	v_max_f32_e32 v10, v10, v16
	ds_bpermute_b32 v16, v15, v10
	s_waitcnt lgkmcnt(0)
	v_max3_f32 v10, v10, v16, v83
	v_sub_f32_e32 v8, v8, v10
	v_sub_f32_e32 v9, v9, v10
	v_sub_f32_e32 v7, v7, v10
	v_mul_f32_e32 v8, 0x3fb8aa3b, v8
	v_mul_f32_e32 v9, 0x3fb8aa3b, v9
	v_mul_f32_e32 v7, 0x3fb8aa3b, v7
	v_exp_f32_e32 v16, v8
	v_exp_f32_e32 v9, v9
	v_exp_f32_e32 v7, v7
	v_sub_f32_e32 v10, v83, v10
	v_mul_f32_e32 v10, 0x3fb8aa3b, v10
	v_add_f32_e32 v8, v16, v9
	v_add_f32_e32 v8, v7, v8
	v_exp_f32_e32 v10, v10
	s_waitcnt lgkmcnt(0)
	s_nop 1
	v_add_f32_dpp v8, v8, v8 quad_perm:[1,0,3,2] row_mask:0xf bank_mask:0xf
	s_nop 1
	v_add_f32_dpp v8, v8, v8 quad_perm:[2,3,0,1] row_mask:0xf bank_mask:0xf
	s_nop 1
	v_add_f32_dpp v8, v8, v8 row_half_mirror row_mask:0xf bank_mask:0xf
	s_nop 1
	v_add_f32_dpp v8, v8, v8 row_mirror row_mask:0xf bank_mask:0xf
	s_nop 1
	v_add_f32_dpp v8, v8, v8 row_bcast:15 row_mask:0xa bank_mask:0xf
	s_nop 1
	v_add_f32_dpp v8, v8, v8 row_bcast:31 row_mask:0xc bank_mask:0xf
	s_nop 1
	v_readlane_b32 s100, v8, 63
	s_nop 1
	v_mov_b32_e32 v8, s100
	v_add_f32_e32 v8, v10, v8
	v_div_scale_f32 v10, s[52:53], v8, v8, 1.0
	v_rcp_f32_e32 v17, v10
	v_div_scale_f32 v18, vcc, 1.0, v8, 1.0
	v_fma_f32 v19, -v10, v17, 1.0
	v_fmac_f32_e32 v17, v19, v17
	v_mul_f32_e32 v19, v18, v17
	v_fma_f32 v20, -v10, v19, v18
	v_fmac_f32_e32 v19, v20, v17
	v_fma_f32 v10, -v10, v19, v18
	v_div_fmas_f32 v10, v10, v17, v19
	v_div_fixup_f32 v8, v10, v8, 1.0
	v_mul_f32_e32 v10, v16, v8
	v_mul_f32_e32 v9, v9, v8
	v_add_u32_e32 v16, 16, v0
	ds_write2st64_b32 v16, v10, v9 offset0:8 offset1:16
	s_and_saveexec_b64 s[52:53], s[38:39]
	v_mul_f32_e32 v7, v7, v8
	ds_write_b32 v0, v7 offset:6160
	s_or_b64 exec, exec, s[52:53]
	v_mul_f32_e32 v7, v5, v64
	s_mov_b32 s52, 0x3e000000
	v_fma_f32 v6, -v5, v79, v6
	v_fma_f32 v7, v40, s52, -v7
	v_mul_f32_e32 v8, v5, v72
	v_cndmask_b32_e64 v6, v221, v6, s[30:31]
	v_cndmask_b32_e64 v7, v221, v7, s[14:15]
	v_fma_f32 v8, v48, s52, -v8
	v_max3_f32 v9, v7, v8, v6
	ds_bpermute_b32 v10, v4, v9
	s_waitcnt lgkmcnt(0)
	v_max_f32_e32 v10, v10, v10
	v_max_f32_e32 v9, v9, v10
	ds_bpermute_b32 v10, v11, v9
	s_waitcnt lgkmcnt(0)
	v_max_f32_e32 v10, v10, v10
	v_max_f32_e32 v9, v9, v10
	ds_bpermute_b32 v10, v12, v9
	s_waitcnt lgkmcnt(0)
	v_max_f32_e32 v10, v10, v10
	v_max_f32_e32 v9, v9, v10
	ds_bpermute_b32 v10, v13, v9
	s_waitcnt lgkmcnt(0)
	v_max_f32_e32 v10, v10, v10
	v_max_f32_e32 v9, v9, v10
	ds_bpermute_b32 v10, v14, v9
	s_waitcnt lgkmcnt(0)
	v_max_f32_e32 v10, v10, v10
	v_max_f32_e32 v9, v9, v10
	ds_bpermute_b32 v10, v15, v9
	s_waitcnt lgkmcnt(0)
	v_max3_f32 v9, v9, v10, v83
	v_sub_f32_e32 v7, v7, v9
	v_sub_f32_e32 v8, v8, v9
	v_sub_f32_e32 v6, v6, v9
	v_mul_f32_e32 v7, 0x3fb8aa3b, v7
	v_mul_f32_e32 v8, 0x3fb8aa3b, v8
	v_mul_f32_e32 v6, 0x3fb8aa3b, v6
	v_exp_f32_e32 v10, v7
	v_exp_f32_e32 v8, v8
	v_exp_f32_e32 v6, v6
	v_sub_f32_e32 v9, v83, v9
	v_mul_f32_e32 v9, 0x3fb8aa3b, v9
	v_add_f32_e32 v7, v10, v8
	v_add_f32_e32 v7, v6, v7
	v_exp_f32_e32 v9, v9
	s_waitcnt lgkmcnt(0)
; __device__ __forceinline__ void attn_sample_item(LAS float* wl, const bf16_t* z, bf16_t* mix, const float* sinks, const float* ck, const float* cv, int it, int lane) {
;     ...
;     for (int t = 0; t < 8; ++t) {
;         float m = fmaxf(fmaxf(s[0][t], s[1][t]), s[2][t]); m = fmaxf(wave_max(m), sink);
;         const float p0 = __expf(s[0][t] - m), p1 = __expf(s[1][t] - m), p2 = __expf(s[2][t] - m);
;         const float den = wave_sum(p0 + p1 + p2) + __expf(sink - m), inv = 1.0f / den;
;         pT[lane * 8 + t] = p0 * inv; pT[(lane + 64) * 8 + t] = p1 * inv; if (lane < 8) pT[(lane + 128) * 8 + t] = p2 * inv;
;     }
;     __builtin_amdgcn_wave_barrier();
;     asm volatile("s_waitcnt lgkmcnt(0)" ::: "memory");
;     float o[8];
; #pragma unroll
;     for (int t = 0; t < 8; ++t) o[t] = 0.f;
	s_nop 1
	v_add_f32_dpp v7, v7, v7 quad_perm:[1,0,3,2] row_mask:0xf bank_mask:0xf
	s_nop 1
	v_add_f32_dpp v7, v7, v7 quad_perm:[2,3,0,1] row_mask:0xf bank_mask:0xf
	s_nop 1
	v_add_f32_dpp v7, v7, v7 row_half_mirror row_mask:0xf bank_mask:0xf
	s_nop 1
	v_add_f32_dpp v7, v7, v7 row_mirror row_mask:0xf bank_mask:0xf
	s_nop 1
	v_add_f32_dpp v7, v7, v7 row_bcast:15 row_mask:0xa bank_mask:0xf
	s_nop 1
	v_add_f32_dpp v7, v7, v7 row_bcast:31 row_mask:0xc bank_mask:0xf
	s_nop 1
	v_readlane_b32 s100, v7, 63
	s_nop 1
	v_mov_b32_e32 v7, s100
	v_add_f32_e32 v7, v9, v7
	v_div_scale_f32 v9, s[52:53], v7, v7, 1.0
	v_rcp_f32_e32 v16, v9
	v_div_scale_f32 v17, vcc, 1.0, v7, 1.0
	v_fma_f32 v18, -v9, v16, 1.0
	v_fmac_f32_e32 v16, v18, v16
	v_mul_f32_e32 v18, v17, v16
	v_fma_f32 v19, -v9, v18, v17
	v_fmac_f32_e32 v18, v19, v16
	v_fma_f32 v9, -v9, v18, v17
	v_div_fmas_f32 v9, v9, v16, v18
	v_div_fixup_f32 v7, v9, v7, 1.0
	v_mul_f32_e32 v9, v10, v7
	v_mul_f32_e32 v8, v8, v7
	v_add_u32_e32 v10, 20, v0
	ds_write2st64_b32 v10, v9, v8 offset0:8 offset1:16
	s_and_saveexec_b64 s[52:53], s[38:39]
	v_mul_f32_e32 v6, v6, v7
	ds_write_b32 v0, v6 offset:6164
	s_or_b64 exec, exec, s[52:53]
	v_mul_f32_e32 v6, v5, v65
	s_mov_b32 s52, 0x3e000000
	v_fma_f32 v2, -v5, v80, v2
	v_fma_f32 v6, v45, s52, -v6
	v_mul_f32_e32 v7, v5, v73
	v_cndmask_b32_e64 v2, v221, v2, s[34:35]
	v_cndmask_b32_e64 v6, v221, v6, s[16:17]
	v_fma_f32 v7, v55, s52, -v7
	v_max3_f32 v8, v6, v7, v2
	ds_bpermute_b32 v9, v4, v8
	s_waitcnt lgkmcnt(0)
	v_max_f32_e32 v9, v9, v9
	v_max_f32_e32 v8, v8, v9
	ds_bpermute_b32 v9, v11, v8
	s_waitcnt lgkmcnt(0)
	v_max_f32_e32 v9, v9, v9
	v_max_f32_e32 v8, v8, v9
	ds_bpermute_b32 v9, v12, v8
	s_waitcnt lgkmcnt(0)
	v_max_f32_e32 v9, v9, v9
	v_max_f32_e32 v8, v8, v9
	ds_bpermute_b32 v9, v13, v8
	s_waitcnt lgkmcnt(0)
	v_max_f32_e32 v9, v9, v9
	v_max_f32_e32 v8, v8, v9
	ds_bpermute_b32 v9, v14, v8
	s_waitcnt lgkmcnt(0)
	v_max_f32_e32 v9, v9, v9
	v_max_f32_e32 v8, v8, v9
	ds_bpermute_b32 v9, v15, v8
	s_waitcnt lgkmcnt(0)
	v_max3_f32 v8, v8, v9, v83
	v_sub_f32_e32 v6, v6, v8
	v_sub_f32_e32 v7, v7, v8
	v_sub_f32_e32 v2, v2, v8
	v_mul_f32_e32 v6, 0x3fb8aa3b, v6
	v_mul_f32_e32 v7, 0x3fb8aa3b, v7
	v_mul_f32_e32 v2, 0x3fb8aa3b, v2
	v_exp_f32_e32 v9, v6
	v_exp_f32_e32 v7, v7
	v_exp_f32_e32 v2, v2
	v_sub_f32_e32 v8, v83, v8
	v_mul_f32_e32 v8, 0x3fb8aa3b, v8
	v_add_f32_e32 v6, v9, v7
	v_add_f32_e32 v6, v2, v6
	v_exp_f32_e32 v8, v8
	s_waitcnt lgkmcnt(0)
	s_nop 1
	v_add_f32_dpp v6, v6, v6 quad_perm:[1,0,3,2] row_mask:0xf bank_mask:0xf
	s_nop 1
	v_add_f32_dpp v6, v6, v6 quad_perm:[2,3,0,1] row_mask:0xf bank_mask:0xf
	s_nop 1
	v_add_f32_dpp v6, v6, v6 row_half_mirror row_mask:0xf bank_mask:0xf
	s_nop 1
	v_add_f32_dpp v6, v6, v6 row_mirror row_mask:0xf bank_mask:0xf
	s_nop 1
	v_add_f32_dpp v6, v6, v6 row_bcast:15 row_mask:0xa bank_mask:0xf
	s_nop 1
	v_add_f32_dpp v6, v6, v6 row_bcast:31 row_mask:0xc bank_mask:0xf
	s_nop 1
	v_readlane_b32 s100, v6, 63
	s_nop 1
	v_mov_b32_e32 v6, s100
	v_add_f32_e32 v6, v8, v6
	v_div_scale_f32 v8, s[52:53], v6, v6, 1.0
	v_rcp_f32_e32 v10, v8
	v_div_scale_f32 v16, vcc, 1.0, v6, 1.0
	v_fma_f32 v17, -v8, v10, 1.0
	v_fmac_f32_e32 v10, v17, v10
	v_mul_f32_e32 v17, v16, v10
	v_fma_f32 v18, -v8, v17, v16
	v_fmac_f32_e32 v17, v18, v10
	v_fma_f32 v8, -v8, v17, v16
	v_div_fmas_f32 v8, v8, v10, v17
	v_div_fixup_f32 v6, v8, v6, 1.0
	v_mul_f32_e32 v8, v9, v6
	v_mul_f32_e32 v7, v7, v6
	v_add_u32_e32 v9, 24, v0
	ds_write2st64_b32 v9, v8, v7 offset0:8 offset1:16
	s_and_saveexec_b64 s[52:53], s[38:39]
	v_mul_f32_e32 v2, v2, v6
	ds_write_b32 v0, v2 offset:6168
	s_or_b64 exec, exec, s[52:53]
	v_fma_f32 v2, -v5, v81, v3
	v_mul_f32_e32 v3, v5, v66
	s_mov_b32 s52, 0x3e000000
	v_fma_f32 v3, v44, s52, -v3
	v_mul_f32_e32 v5, v5, v74
	v_cndmask_b32_e64 v2, v221, v2, s[36:37]
	v_cndmask_b32_e64 v3, v221, v3, s[18:19]
	v_fma_f32 v5, v54, s52, -v5
	v_max3_f32 v6, v3, v5, v2
	ds_bpermute_b32 v7, v4, v6
	s_waitcnt lgkmcnt(0)
	v_max_f32_e32 v7, v7, v7
	v_max_f32_e32 v6, v6, v7
	ds_bpermute_b32 v7, v11, v6
	s_waitcnt lgkmcnt(0)
	v_max_f32_e32 v7, v7, v7
	v_max_f32_e32 v6, v6, v7
	ds_bpermute_b32 v7, v12, v6
	s_waitcnt lgkmcnt(0)
	v_max_f32_e32 v7, v7, v7
	v_max_f32_e32 v6, v6, v7
	ds_bpermute_b32 v7, v13, v6
	s_waitcnt lgkmcnt(0)
	v_max_f32_e32 v7, v7, v7
	v_max_f32_e32 v6, v6, v7
	ds_bpermute_b32 v7, v14, v6
	s_waitcnt lgkmcnt(0)
	v_max_f32_e32 v7, v7, v7
	v_max_f32_e32 v6, v6, v7
	ds_bpermute_b32 v7, v15, v6
	s_waitcnt lgkmcnt(0)
	v_max3_f32 v6, v6, v7, v83
	v_sub_f32_e32 v3, v3, v6
	v_sub_f32_e32 v5, v5, v6
	v_sub_f32_e32 v2, v2, v6
	v_mul_f32_e32 v3, 0x3fb8aa3b, v3
	v_mul_f32_e32 v5, 0x3fb8aa3b, v5
	v_mul_f32_e32 v2, 0x3fb8aa3b, v2
	v_exp_f32_e32 v7, v3
	v_exp_f32_e32 v5, v5
	v_exp_f32_e32 v2, v2
	v_sub_f32_e32 v6, v83, v6
	v_mul_f32_e32 v6, 0x3fb8aa3b, v6
	v_add_f32_e32 v3, v7, v5
	v_add_f32_e32 v3, v2, v3
	v_exp_f32_e32 v6, v6
	s_waitcnt lgkmcnt(0)
	s_nop 1
	v_add_f32_dpp v3, v3, v3 quad_perm:[1,0,3,2] row_mask:0xf bank_mask:0xf
	s_nop 1
	v_add_f32_dpp v3, v3, v3 quad_perm:[2,3,0,1] row_mask:0xf bank_mask:0xf
	s_nop 1
	v_add_f32_dpp v3, v3, v3 row_half_mirror row_mask:0xf bank_mask:0xf
	s_nop 1
	v_add_f32_dpp v3, v3, v3 row_mirror row_mask:0xf bank_mask:0xf
	s_nop 1
	v_add_f32_dpp v3, v3, v3 row_bcast:15 row_mask:0xa bank_mask:0xf
	s_nop 1
	v_add_f32_dpp v3, v3, v3 row_bcast:31 row_mask:0xc bank_mask:0xf
	s_nop 1
	v_readlane_b32 s100, v3, 63
	s_nop 1
	v_mov_b32_e32 v3, s100
	v_add_f32_e32 v3, v6, v3
	v_div_scale_f32 v4, s[52:53], v3, v3, 1.0
	v_rcp_f32_e32 v6, v4
	v_div_scale_f32 v8, vcc, 1.0, v3, 1.0
	v_fma_f32 v9, -v4, v6, 1.0
	v_fmac_f32_e32 v6, v9, v6
	v_mul_f32_e32 v9, v8, v6
	v_fma_f32 v10, -v4, v9, v8
	v_fmac_f32_e32 v9, v10, v6
	v_fma_f32 v4, -v4, v9, v8
	v_div_fmas_f32 v4, v4, v6, v9
	v_div_fixup_f32 v3, v4, v3, 1.0
	v_mul_f32_e32 v4, v7, v3
	v_mul_f32_e32 v5, v5, v3
	v_add_u32_e32 v6, 28, v0
	ds_write2st64_b32 v6, v4, v5 offset0:8 offset1:16
	s_and_saveexec_b64 s[52:53], s[38:39]
	v_mul_f32_e32 v2, v2, v3
	ds_write_b32 v0, v2 offset:6172
	s_or_b64 exec, exec, s[52:53]
	s_waitcnt lgkmcnt(0)
	v_mov_b32_e32 v2, 0
	v_lshl_add_u64 v[10:11], v[36:37], 0, s[50:51]
	s_mov_b32 s50, -16
	s_mov_b32 s51, s62
	v_mov_b32_e32 v3, v2
	v_mov_b32_e32 v8, v2
	v_mov_b32_e32 v9, v2
	v_mov_b32_e32 v6, v2
	v_mov_b32_e32 v7, v2
	v_mov_b32_e32 v4, v2
	v_mov_b32_e32 v5, v2

; __global__ void __launch_bounds__(NTHREADS, 2) hybrid_fwd(Params P) {
;     ...
;                 if (PHS(15)) for (int it = gw; it < 2048; it += NGW) if ((it & 7) == 4) gate_sample_item(Z, MIX, out + OUT_CVS + (size_t)li * 262144, w_s, b_s, lg_, lb_, it >> 3, lane);
.LBB0_1091:
	v_readlane_b32 s4, v254, 52
	v_readlane_b32 s5, v254, 53
	s_lshl_b64 s[4:5], s[4:5], 20
	v_readlane_b32 s6, v255, 1
	v_readlane_b32 s7, v255, 2
	s_add_u32 s4, s6, s4
	s_addc_u32 s5, s7, s5
	s_add_u32 s12, s4, 0x16280000
	v_readlane_b32 s4, v255, 0
	s_addc_u32 s13, s5, 0
	s_and_b32 s4, s4, 0x1c0
	v_lshlrev_b32_e32 v0, 4, v82
	s_cmpk_eq_i32 s4, 0x80
	s_cselect_b64 s[4:5], -1, 0
	v_lshlrev_b32_e32 v27, 1, v0
	s_branch .LBB0_1093

; __device__ __forceinline__ float bf_lo(unsigned w) { return __uint_as_float(w << 16); }
; __device__ __forceinline__ float bf_hi(unsigned w) { return __uint_as_float(w & 0xffff0000u); }
; __device__ __forceinline__ void gate_sample_item(const bf16_t* z, bf16_t* mix, float* cvs  , const float* w_s, const float* b_s,
;                                                  const float* lnv_g, const float* lnv_b, int it, int lane) {
;     const int cq = it & 7, b = it >> 3, gr = cq >> 1;
;     const size_t tok0 = (size_t)T_P + b * 8;
;     const int c = cq * 128 + 2 * lane;
;     float vn0[8], vn1[8];
; #pragma unroll
;     for (int j = 0; j < 8; ++j) {
;         const bf16_t* vp = z + (tok0 + j) * EIN + 3328 + lane * 16;
;         const u32x4 a = *(const u32x4*)vp, cc = *(const u32x4*)(vp + 8);
;         float v[16] = {bf_lo(a.x), bf_hi(a.x), bf_lo(a.y), bf_hi(a.y), bf_lo(a.z), bf_hi(a.z), bf_lo(a.w), bf_hi(a.w),
;                        bf_lo(cc.x), bf_hi(cc.x), bf_lo(cc.y), bf_hi(cc.y), bf_lo(cc.z), bf_hi(cc.z), bf_lo(cc.w), bf_hi(cc.w)};
;         float s = 0.f;
; #pragma unroll
;         for (int e = 0; e < 16; ++e) s += v[e];
;         const float mean = wave_sum(s) * (1.0f / 1024.0f);
;         float q = 0.f;
; #pragma unroll
;         for (int e = 0; e < 16; ++e) { const float d = v[e] - mean; q += d * d; }
;         const float rstd = rsqrtf(wave_sum(q) * (1.0f / 1024.0f) + EPSN);
;         const unsigned xw = *(const unsigned*)(z + (tok0 + j) * EIN + 3328 + c);
;         vn0[j] = (bf_lo(xw) - mean) * rstd * lnv_g[c] + lnv_b[c];
;         vn1[j] = (bf_hi(xw) - mean) * rstd * lnv_g[c + 1] + lnv_b[c + 1];
;         *(f32x2*)(cvs + ((size_t)b * 8 + j) * 1024 + c) = (f32x2){vn0[j], vn1[j]};
.LBB0_1093:
	s_andn2_b64 vcc, exec, s[4:5]
	s_cbranch_vccnz .LBB0_1092
	v_and_b32_e32 v2, 64, v215
	v_add_u32_e32 v2, 64, v2
	v_xor_b32_e32 v3, 1, v215
	v_cmp_lt_i32_e32 vcc, v3, v2
	s_ashr_i32 s14, s54, 3
	s_and_b32 s11, s14, 7
	v_cndmask_b32_e32 v3, v215, v3, vcc
	v_lshlrev_b32_e32 v28, 2, v3
	v_xor_b32_e32 v3, 2, v215
	v_cmp_lt_i32_e32 vcc, v3, v2
	s_ashr_i32 s10, s54, 6
	s_and_b32 s8, s14, -8
	v_cndmask_b32_e32 v3, v215, v3, vcc
	v_lshlrev_b32_e32 v29, 2, v3
	v_xor_b32_e32 v3, 4, v215
	v_cmp_lt_i32_e32 vcc, v3, v2
	s_ashr_i32 s9, s8, 31
	v_lshl_or_b32 v0, s11, 7, v26
	v_cndmask_b32_e32 v3, v215, v3, vcc
	v_lshlrev_b32_e32 v30, 2, v3
	v_xor_b32_e32 v3, 8, v215
	v_cmp_lt_i32_e32 vcc, v3, v2
	s_ashr_i32 s11, s10, 31
	s_lshl_b64 s[6:7], s[8:9], 12
	v_cndmask_b32_e32 v3, v215, v3, vcc
	v_lshlrev_b32_e32 v31, 2, v3
	v_xor_b32_e32 v3, 16, v215
	v_cmp_lt_i32_e32 vcc, v3, v2
	s_lshl_b64 s[10:11], s[10:11], 15
	s_add_u32 s10, s12, s10
	v_cndmask_b32_e32 v3, v215, v3, vcc
	v_lshlrev_b32_e32 v32, 2, v3
	v_xor_b32_e32 v3, 32, v215
	s_addc_u32 s11, s13, s11
	s_mul_hi_i32 s9, s8, 0x2a00
	s_mulk_i32 s8, 0x2a00
	v_cmp_lt_i32_e32 vcc, v3, v2
	s_add_u32 s8, s96, s8
	v_lshlrev_b64 v[6:7], 2, v[0:1]
	v_cndmask_b32_e32 v2, v215, v3, vcc
	s_addc_u32 s9, s97, s9
	v_lshlrev_b32_e32 v33, 2, v2
	v_lshl_add_u64 v[2:3], s[76:77], 0, v[6:7]
	v_lshl_add_u64 v[4:5], s[78:79], 0, v[6:7]
	v_lshl_add_u64 v[6:7], s[10:11], 0, v[6:7]
	s_add_u32 s10, s8, 0x5401a00
	s_addc_u32 s11, s9, 0
	global_load_dwordx4 v[8:11], v27, s[10:11] offset:16
	global_load_dwordx4 v[12:15], v27, s[10:11]
	s_waitcnt vmcnt(1)
	v_lshlrev_b32_e32 v24, 16, v8
	s_waitcnt vmcnt(0)
	v_lshlrev_b32_e32 v16, 16, v12
	v_and_b32_e32 v17, 0xffff0000, v12
	v_and_b32_e32 v25, 0xffff0000, v8
	v_add_f32_e32 v8, 0, v16
	v_lshlrev_b32_e32 v18, 16, v13
	v_add_f32_e32 v8, v8, v17
	v_and_b32_e32 v19, 0xffff0000, v13
	v_add_f32_e32 v8, v8, v18
	v_lshlrev_b32_e32 v20, 16, v14
	v_add_f32_e32 v8, v8, v19
	v_and_b32_e32 v21, 0xffff0000, v14
	v_add_f32_e32 v8, v8, v20
	v_lshlrev_b32_e32 v22, 16, v15
	v_add_f32_e32 v8, v8, v21
	v_and_b32_e32 v23, 0xffff0000, v15
	v_add_f32_e32 v8, v8, v22
	v_add_f32_e32 v8, v8, v23
	v_add_f32_e32 v8, v8, v24
	v_lshlrev_b32_e32 v34, 16, v9
	v_add_f32_e32 v8, v8, v25
	v_and_b32_e32 v9, 0xffff0000, v9
	v_add_f32_e32 v8, v8, v34
	v_add_f32_e32 v8, v8, v9
	v_lshlrev_b32_e32 v15, 16, v10
	v_and_b32_e32 v14, 0xffff0000, v10
	v_add_f32_e32 v8, v8, v15
	v_lshlrev_b32_e32 v13, 16, v11
	v_add_f32_e32 v8, v8, v14
	v_and_b32_e32 v12, 0xffff0000, v11
	v_add_f32_e32 v8, v8, v13
	v_add_f32_e32 v8, v8, v12
	ds_bpermute_b32 v10, v28, v8
	s_waitcnt lgkmcnt(0)
	v_add_f32_e32 v8, v8, v10
	ds_bpermute_b32 v10, v29, v8
	s_waitcnt lgkmcnt(0)
	v_add_f32_e32 v8, v8, v10
	ds_bpermute_b32 v10, v30, v8
	s_waitcnt lgkmcnt(0)
	v_add_f32_e32 v8, v8, v10
	ds_bpermute_b32 v10, v31, v8
	s_waitcnt lgkmcnt(0)
	v_add_f32_e32 v8, v8, v10
	ds_bpermute_b32 v10, v32, v8
	s_waitcnt lgkmcnt(0)
	v_add_f32_e32 v8, v8, v10
	ds_bpermute_b32 v10, v33, v8
	s_waitcnt lgkmcnt(0)
	v_add_f32_e32 v10, v8, v10
	v_fmac_f32_e32 v17, 0xba800000, v10
	v_fmac_f32_e32 v16, 0xba800000, v10
	v_mul_f32_e32 v17, v17, v17
	v_fmac_f32_e32 v17, v16, v16
	v_fmac_f32_e32 v18, 0xba800000, v10
	v_fmac_f32_e32 v17, v18, v18
	v_fmac_f32_e32 v19, 0xba800000, v10
	v_fmac_f32_e32 v17, v19, v19
	v_fmac_f32_e32 v20, 0xba800000, v10
	v_fmac_f32_e32 v17, v20, v20
	v_fmac_f32_e32 v21, 0xba800000, v10
	v_fmac_f32_e32 v17, v21, v21
	v_fmac_f32_e32 v22, 0xba800000, v10
	v_fmac_f32_e32 v17, v22, v22
	v_fmac_f32_e32 v23, 0xba800000, v10
	v_fmac_f32_e32 v17, v23, v23
	v_fmac_f32_e32 v24, 0xba800000, v10
	v_fmac_f32_e32 v17, v24, v24
	v_fmac_f32_e32 v25, 0xba800000, v10
	v_mul_f32_e32 v8, 0x3a800000, v10
	v_fmac_f32_e32 v17, v25, v25
	v_fmac_f32_e32 v34, 0xba800000, v10
	v_fmac_f32_e32 v9, 0xba800000, v10
	v_fmac_f32_e32 v17, v34, v34
	v_pk_add_f32 v[10:11], v[14:15], v[8:9] op_sel_hi:[1,0] neg_lo:[0,1] neg_hi:[0,1]
	v_fmac_f32_e32 v17, v9, v9
	v_pk_mul_f32 v[10:11], v[10:11], v[10:11]
	s_nop 0
	v_add_f32_e32 v9, v11, v17
	v_add_f32_e32 v9, v10, v9
	v_pk_add_f32 v[10:11], v[12:13], v[8:9] op_sel_hi:[1,0] neg_lo:[0,1] neg_hi:[0,1]
	s_nop 0
	v_pk_mul_f32 v[10:11], v[10:11], v[10:11]
	s_nop 0
	v_add_f32_e32 v9, v11, v9
	v_add_f32_e32 v9, v10, v9
	s_waitcnt lgkmcnt(0)
	s_nop 1
	v_add_f32_dpp v9, v9, v9 quad_perm:[1,0,3,2] row_mask:0xf bank_mask:0xf
	s_nop 1
	v_add_f32_dpp v9, v9, v9 quad_perm:[2,3,0,1] row_mask:0xf bank_mask:0xf
	s_nop 1
	v_add_f32_dpp v9, v9, v9 row_half_mirror row_mask:0xf bank_mask:0xf
	s_nop 1
	v_add_f32_dpp v9, v9, v9 row_mirror row_mask:0xf bank_mask:0xf
	s_nop 1
	v_add_f32_dpp v9, v9, v9 row_bcast:15 row_mask:0xa bank_mask:0xf
	s_nop 1
	v_add_f32_dpp v9, v9, v9 row_bcast:31 row_mask:0xc bank_mask:0xf
	s_nop 1
	v_readlane_b32 s100, v9, 63
	s_nop 1
	v_mov_b32_e32 v9, s100
	v_fmamk_f32 v9, v9, 0x3a800000, v138
	v_cmp_gt_f32_e32 vcc, s59, v9
	v_mul_f32_e32 v10, 0x4b800000, v9
	s_nop 0
	v_cndmask_b32_e32 v9, v9, v10, vcc
	v_rsq_f32_e32 v9, v9
	s_nop 0
	v_mul_f32_e32 v10, 0x45800000, v9
	v_cndmask_b32_e32 v12, v9, v10, vcc
	v_lshlrev_b64 v[10:11], 1, v[0:1]
	v_lshl_add_u64 v[14:15], s[10:11], 0, v[10:11]
	global_load_dword v0, v[14:15], off
	s_add_u32 s10, s8, 0x5404400
	s_addc_u32 s11, s9, 0
	s_waitcnt vmcnt(0)
	v_lshlrev_b32_e32 v14, 16, v0
	v_and_b32_e32 v15, 0xffff0000, v0
	v_pk_add_f32 v[8:9], v[14:15], v[8:9] op_sel_hi:[1,0] neg_lo:[0,1] neg_hi:[0,1]
	s_nop 0
	v_pk_mul_f32 v[8:9], v[8:9], v[12:13] op_sel_hi:[1,0]
	global_load_dwordx2 v[12:13], v[2:3], off
	global_load_dwordx2 v[14:15], v[4:5], off
	s_waitcnt vmcnt(0)
; __device__ __forceinline__ float bf_lo(unsigned w) { return __uint_as_float(w << 16); }
; __device__ __forceinline__ float bf_hi(unsigned w) { return __uint_as_float(w & 0xffff0000u); }
; __device__ __forceinline__ void gate_sample_item(const bf16_t* z, bf16_t* mix, float* cvs  , const float* w_s, const float* b_s,
;                                                  const float* lnv_g, const float* lnv_b, int it, int lane) {
;     ...
;     for (int j = 0; j < 8; ++j) {
;         const bf16_t* vp = z + (tok0 + j) * EIN + 3328 + lane * 16;
;         const u32x4 a = *(const u32x4*)vp, cc = *(const u32x4*)(vp + 8);
;         float v[16] = {bf_lo(a.x), bf_hi(a.x), bf_lo(a.y), bf_hi(a.y), bf_lo(a.z), bf_hi(a.z), bf_lo(a.w), bf_hi(a.w),
;                        bf_lo(cc.x), bf_hi(cc.x), bf_lo(cc.y), bf_hi(cc.y), bf_lo(cc.z), bf_hi(cc.z), bf_lo(cc.w), bf_hi(cc.w)};
;         float s = 0.f;
; #pragma unroll
;         for (int e = 0; e < 16; ++e) s += v[e];
;         const float mean = wave_sum(s) * (1.0f / 1024.0f);
;         float q = 0.f;
; #pragma unroll
;         for (int e = 0; e < 16; ++e) { const float d = v[e] - mean; q += d * d; }
;         const float rstd = rsqrtf(wave_sum(q) * (1.0f / 1024.0f) + EPSN);
;         const unsigned xw = *(const unsigned*)(z + (tok0 + j) * EIN + 3328 + c);
;         vn0[j] = (bf_lo(xw) - mean) * rstd * lnv_g[c] + lnv_b[c];
;         vn1[j] = (bf_hi(xw) - mean) * rstd * lnv_g[c + 1] + lnv_b[c + 1];
;         *(f32x2*)(cvs + ((size_t)b * 8 + j) * 1024 + c) = (f32x2){vn0[j], vn1[j]};
	v_pk_fma_f32 v[12:13], v[12:13], v[8:9], v[14:15]
	global_store_dwordx2 v[6:7], v[12:13], off
	global_load_dwordx4 v[14:17], v27, s[10:11] offset:16
	global_load_dwordx4 v[18:21], v27, s[10:11]
	s_waitcnt vmcnt(1)
	v_lshlrev_b32_e32 v34, 16, v14
	s_waitcnt vmcnt(0)
	v_lshlrev_b32_e32 v22, 16, v18
	v_and_b32_e32 v18, 0xffff0000, v18
	v_add_f32_e32 v0, 0, v22
	v_lshlrev_b32_e32 v23, 16, v19
	v_add_f32_e32 v0, v0, v18
	v_and_b32_e32 v19, 0xffff0000, v19
	v_add_f32_e32 v0, v0, v23
	v_lshlrev_b32_e32 v24, 16, v20
	v_add_f32_e32 v0, v0, v19
	v_and_b32_e32 v20, 0xffff0000, v20
	v_add_f32_e32 v0, v0, v24
	v_lshlrev_b32_e32 v25, 16, v21
	v_add_f32_e32 v0, v0, v20
	v_and_b32_e32 v21, 0xffff0000, v21
	v_add_f32_e32 v0, v0, v25
	v_add_f32_e32 v0, v0, v21
	v_and_b32_e32 v35, 0xffff0000, v14
	v_add_f32_e32 v0, v0, v34
	v_lshlrev_b32_e32 v36, 16, v15
	v_add_f32_e32 v0, v0, v35
	v_and_b32_e32 v37, 0xffff0000, v15
	v_add_f32_e32 v0, v0, v36
	v_add_f32_e32 v0, v0, v37
	v_lshlrev_b32_e32 v15, 16, v16
	v_and_b32_e32 v14, 0xffff0000, v16
	v_add_f32_e32 v0, v0, v15
	v_lshlrev_b32_e32 v9, 16, v17
	v_add_f32_e32 v0, v0, v14
	v_and_b32_e32 v8, 0xffff0000, v17
	v_add_f32_e32 v0, v0, v9
	v_add_f32_e32 v0, v0, v8
	ds_bpermute_b32 v16, v28, v0
	s_waitcnt lgkmcnt(0)
	v_add_f32_e32 v0, v0, v16
	ds_bpermute_b32 v16, v29, v0
	s_waitcnt lgkmcnt(0)
	v_add_f32_e32 v0, v0, v16
	ds_bpermute_b32 v16, v30, v0
	s_waitcnt lgkmcnt(0)
	v_add_f32_e32 v0, v0, v16
	ds_bpermute_b32 v16, v31, v0
	s_waitcnt lgkmcnt(0)
	v_add_f32_e32 v0, v0, v16
	ds_bpermute_b32 v16, v32, v0
	s_waitcnt lgkmcnt(0)
	v_add_f32_e32 v0, v0, v16
	ds_bpermute_b32 v16, v33, v0
	s_waitcnt lgkmcnt(0)
	v_add_f32_e32 v16, v0, v16
	v_fmac_f32_e32 v18, 0xba800000, v16
	v_fmac_f32_e32 v22, 0xba800000, v16
	v_mul_f32_e32 v17, v18, v18
	v_fmac_f32_e32 v17, v22, v22
	v_fmac_f32_e32 v23, 0xba800000, v16
	v_fmac_f32_e32 v17, v23, v23
	v_fmac_f32_e32 v19, 0xba800000, v16
	v_fmac_f32_e32 v17, v19, v19
	v_fmac_f32_e32 v24, 0xba800000, v16
	v_fmac_f32_e32 v17, v24, v24
	v_fmac_f32_e32 v20, 0xba800000, v16
	v_fmac_f32_e32 v17, v20, v20
	v_fmac_f32_e32 v25, 0xba800000, v16
	v_fmac_f32_e32 v17, v25, v25
	v_fmac_f32_e32 v21, 0xba800000, v16
	v_fmac_f32_e32 v17, v21, v21
	v_fmac_f32_e32 v34, 0xba800000, v16
	v_fmac_f32_e32 v17, v34, v34
	v_fmac_f32_e32 v35, 0xba800000, v16
	v_mul_f32_e32 v0, 0x3a800000, v16
	v_fmac_f32_e32 v17, v35, v35
	v_fmac_f32_e32 v36, 0xba800000, v16
	v_fmac_f32_e32 v17, v36, v36
	v_fmac_f32_e32 v37, 0xba800000, v16
	v_pk_add_f32 v[14:15], v[14:15], v[0:1] op_sel_hi:[1,0] neg_lo:[0,1] neg_hi:[0,1]
	v_fmac_f32_e32 v17, v37, v37
	v_pk_mul_f32 v[14:15], v[14:15], v[14:15]
	v_pk_add_f32 v[8:9], v[8:9], v[0:1] op_sel_hi:[1,0] neg_lo:[0,1] neg_hi:[0,1]
	v_add_f32_e32 v15, v15, v17
	v_add_f32_e32 v14, v14, v15
	v_pk_mul_f32 v[8:9], v[8:9], v[8:9]
	s_nop 0
	v_add_f32_e32 v9, v9, v14
	v_add_f32_e32 v8, v8, v9
	v_lshl_add_u64 v[14:15], s[10:11], 0, v[10:11]
	s_add_u32 s10, s8, 0x5406e00
	s_addc_u32 s11, s9, 0
	s_waitcnt lgkmcnt(0)
	s_nop 1
	v_add_f32_dpp v8, v8, v8 quad_perm:[1,0,3,2] row_mask:0xf bank_mask:0xf
	s_nop 1
	v_add_f32_dpp v8, v8, v8 quad_perm:[2,3,0,1] row_mask:0xf bank_mask:0xf
	s_nop 1
	v_add_f32_dpp v8, v8, v8 row_half_mirror row_mask:0xf bank_mask:0xf
	s_nop 1
	v_add_f32_dpp v8, v8, v8 row_mirror row_mask:0xf bank_mask:0xf
	s_nop 1
	v_add_f32_dpp v8, v8, v8 row_bcast:15 row_mask:0xa bank_mask:0xf
	s_nop 1
	v_add_f32_dpp v8, v8, v8 row_bcast:31 row_mask:0xc bank_mask:0xf
	s_nop 1
	v_readlane_b32 s100, v8, 63
	s_nop 1
	v_mov_b32_e32 v8, s100
	v_fmamk_f32 v8, v8, 0x3a800000, v138
	v_cmp_gt_f32_e32 vcc, s59, v8
	v_mul_f32_e32 v9, 0x4b800000, v8
	s_nop 0
	v_cndmask_b32_e32 v8, v8, v9, vcc
	v_rsq_f32_e32 v8, v8
	s_nop 0
	v_mul_f32_e32 v9, 0x45800000, v8
	v_cndmask_b32_e32 v8, v8, v9, vcc
	global_load_dword v9, v[14:15], off
	s_waitcnt vmcnt(0)
	v_lshlrev_b32_e32 v14, 16, v9
	v_and_b32_e32 v15, 0xffff0000, v9
	v_pk_add_f32 v[14:15], v[14:15], v[0:1] op_sel_hi:[1,0] neg_lo:[0,1] neg_hi:[0,1]
	s_nop 0
	v_pk_mul_f32 v[8:9], v[14:15], v[8:9] op_sel_hi:[1,0]
	global_load_dwordx2 v[14:15], v[2:3], off
	global_load_dwordx2 v[16:17], v[4:5], off
	s_waitcnt vmcnt(0)
	v_pk_fma_f32 v[14:15], v[14:15], v[8:9], v[16:17]
	v_add_co_u32_e32 v8, vcc, s33, v6
	s_nop 1
	v_addc_co_u32_e32 v9, vcc, 0, v7, vcc
	global_store_dwordx2 v[8:9], v[14:15], off offset:-4096
	global_load_dwordx4 v[16:19], v27, s[10:11] offset:16
	global_load_dwordx4 v[20:23], v27, s[10:11]
	s_waitcnt vmcnt(1)
	v_lshlrev_b32_e32 v38, 16, v16
	s_waitcnt vmcnt(0)
	v_lshlrev_b32_e32 v24, 16, v20
	v_and_b32_e32 v25, 0xffff0000, v20
	v_add_f32_e32 v0, 0, v24
	v_lshlrev_b32_e32 v34, 16, v21
	v_add_f32_e32 v0, v0, v25
	v_and_b32_e32 v35, 0xffff0000, v21
	v_add_f32_e32 v0, v0, v34
	v_lshlrev_b32_e32 v36, 16, v22
	v_add_f32_e32 v0, v0, v35
	v_and_b32_e32 v22, 0xffff0000, v22
	v_add_f32_e32 v0, v0, v36
	v_lshlrev_b32_e32 v37, 16, v23
	v_add_f32_e32 v0, v0, v22
	v_and_b32_e32 v23, 0xffff0000, v23
	v_add_f32_e32 v0, v0, v37
	v_add_f32_e32 v0, v0, v23
	v_and_b32_e32 v39, 0xffff0000, v16
	v_add_f32_e32 v0, v0, v38
	v_lshlrev_b32_e32 v40, 16, v17
	v_add_f32_e32 v0, v0, v39
	v_and_b32_e32 v41, 0xffff0000, v17
	v_add_f32_e32 v0, v0, v40
	v_add_f32_e32 v0, v0, v41
	v_lshlrev_b32_e32 v21, 16, v18
	v_and_b32_e32 v20, 0xffff0000, v18
	v_add_f32_e32 v0, v0, v21
	v_lshlrev_b32_e32 v17, 16, v19
	v_add_f32_e32 v0, v0, v20
	v_and_b32_e32 v16, 0xffff0000, v19
	v_add_f32_e32 v0, v0, v17
	v_add_f32_e32 v0, v0, v16
	ds_bpermute_b32 v18, v28, v0
	s_waitcnt lgkmcnt(0)
	v_add_f32_e32 v0, v0, v18
	ds_bpermute_b32 v18, v29, v0
	s_waitcnt lgkmcnt(0)
	v_add_f32_e32 v0, v0, v18
	ds_bpermute_b32 v18, v30, v0
	s_waitcnt lgkmcnt(0)
; __device__ __forceinline__ float bf_lo(unsigned w) { return __uint_as_float(w << 16); }
; __device__ __forceinline__ float bf_hi(unsigned w) { return __uint_as_float(w & 0xffff0000u); }
; __device__ __forceinline__ void gate_sample_item(const bf16_t* z, bf16_t* mix, float* cvs  , const float* w_s, const float* b_s,
;                                                  const float* lnv_g, const float* lnv_b, int it, int lane) {
;     ...
;     for (int j = 0; j < 8; ++j) {
;         const bf16_t* vp = z + (tok0 + j) * EIN + 3328 + lane * 16;
;         const u32x4 a = *(const u32x4*)vp, cc = *(const u32x4*)(vp + 8);
;         float v[16] = {bf_lo(a.x), bf_hi(a.x), bf_lo(a.y), bf_hi(a.y), bf_lo(a.z), bf_hi(a.z), bf_lo(a.w), bf_hi(a.w),
;                        bf_lo(cc.x), bf_hi(cc.x), bf_lo(cc.y), bf_hi(cc.y), bf_lo(cc.z), bf_hi(cc.z), bf_lo(cc.w), bf_hi(cc.w)};
;         float s = 0.f;
; #pragma unroll
;         for (int e = 0; e < 16; ++e) s += v[e];
;         const float mean = wave_sum(s) * (1.0f / 1024.0f);
;         float q = 0.f;
; #pragma unroll
;         for (int e = 0; e < 16; ++e) { const float d = v[e] - mean; q += d * d; }
;         const float rstd = rsqrtf(wave_sum(q) * (1.0f / 1024.0f) + EPSN);
;         const unsigned xw = *(const unsigned*)(z + (tok0 + j) * EIN + 3328 + c);
;         vn0[j] = (bf_lo(xw) - mean) * rstd * lnv_g[c] + lnv_b[c];
;         vn1[j] = (bf_hi(xw) - mean) * rstd * lnv_g[c + 1] + lnv_b[c + 1];
;         *(f32x2*)(cvs + ((size_t)b * 8 + j) * 1024 + c) = (f32x2){vn0[j], vn1[j]};
	v_add_f32_e32 v0, v0, v18
	ds_bpermute_b32 v18, v31, v0
	s_waitcnt lgkmcnt(0)
	v_add_f32_e32 v0, v0, v18
	ds_bpermute_b32 v18, v32, v0
	s_waitcnt lgkmcnt(0)
	v_add_f32_e32 v0, v0, v18
	ds_bpermute_b32 v18, v33, v0
	s_waitcnt lgkmcnt(0)
	v_add_f32_e32 v18, v0, v18
	v_fmac_f32_e32 v25, 0xba800000, v18
	v_fmac_f32_e32 v24, 0xba800000, v18
	v_mul_f32_e32 v25, v25, v25
	v_fmac_f32_e32 v25, v24, v24
	v_fmac_f32_e32 v34, 0xba800000, v18
	v_fmac_f32_e32 v25, v34, v34
	v_fmac_f32_e32 v35, 0xba800000, v18
	v_fmac_f32_e32 v25, v35, v35
	v_fmac_f32_e32 v36, 0xba800000, v18
	v_fmac_f32_e32 v25, v36, v36
	v_fmac_f32_e32 v22, 0xba800000, v18
	v_fmac_f32_e32 v25, v22, v22
	v_fmac_f32_e32 v37, 0xba800000, v18
	v_fmac_f32_e32 v25, v37, v37
	v_fmac_f32_e32 v23, 0xba800000, v18
	v_fmac_f32_e32 v25, v23, v23
	v_fmac_f32_e32 v38, 0xba800000, v18
	v_fmac_f32_e32 v25, v38, v38
	v_fmac_f32_e32 v39, 0xba800000, v18
	v_mul_f32_e32 v0, 0x3a800000, v18
	v_fmac_f32_e32 v25, v39, v39
	v_fmac_f32_e32 v40, 0xba800000, v18
	v_fmac_f32_e32 v25, v40, v40
	v_fmac_f32_e32 v41, 0xba800000, v18
	v_pk_add_f32 v[18:19], v[20:21], v[0:1] op_sel_hi:[1,0] neg_lo:[0,1] neg_hi:[0,1]
	v_fmac_f32_e32 v25, v41, v41
	v_pk_mul_f32 v[18:19], v[18:19], v[18:19]
	v_pk_add_f32 v[16:17], v[16:17], v[0:1] op_sel_hi:[1,0] neg_lo:[0,1] neg_hi:[0,1]
	v_add_f32_e32 v19, v19, v25
	v_add_f32_e32 v18, v18, v19
	v_pk_mul_f32 v[16:17], v[16:17], v[16:17]
	s_nop 0
	v_add_f32_e32 v17, v17, v18
	v_add_f32_e32 v16, v16, v17
	v_lshl_add_u64 v[18:19], s[10:11], 0, v[10:11]
	s_add_u32 s10, s8, 0x5409800
	s_addc_u32 s11, s9, 0
	s_waitcnt lgkmcnt(0)
	s_nop 1
	v_add_f32_dpp v16, v16, v16 quad_perm:[1,0,3,2] row_mask:0xf bank_mask:0xf
	s_nop 1
	v_add_f32_dpp v16, v16, v16 quad_perm:[2,3,0,1] row_mask:0xf bank_mask:0xf
	s_nop 1
	v_add_f32_dpp v16, v16, v16 row_half_mirror row_mask:0xf bank_mask:0xf
	s_nop 1
	v_add_f32_dpp v16, v16, v16 row_mirror row_mask:0xf bank_mask:0xf
	s_nop 1
	v_add_f32_dpp v16, v16, v16 row_bcast:15 row_mask:0xa bank_mask:0xf
	s_nop 1
	v_add_f32_dpp v16, v16, v16 row_bcast:31 row_mask:0xc bank_mask:0xf
	s_nop 1
	v_readlane_b32 s100, v16, 63
	s_nop 1
	v_mov_b32_e32 v16, s100
	v_fmamk_f32 v16, v16, 0x3a800000, v138
	v_cmp_gt_f32_e32 vcc, s59, v16
	v_mul_f32_e32 v17, 0x4b800000, v16
	s_nop 0
	v_cndmask_b32_e32 v16, v16, v17, vcc
	v_rsq_f32_e32 v16, v16
	s_nop 0
	v_mul_f32_e32 v17, 0x45800000, v16
	v_cndmask_b32_e32 v16, v16, v17, vcc
	global_load_dword v17, v[18:19], off
	s_waitcnt vmcnt(0)
	v_lshlrev_b32_e32 v18, 16, v17
	v_and_b32_e32 v19, 0xffff0000, v17
	v_pk_add_f32 v[18:19], v[18:19], v[0:1] op_sel_hi:[1,0] neg_lo:[0,1] neg_hi:[0,1]
	s_nop 0
	v_pk_mul_f32 v[16:17], v[18:19], v[16:17] op_sel_hi:[1,0]
	global_load_dwordx2 v[18:19], v[2:3], off
	global_load_dwordx2 v[20:21], v[4:5], off
	s_waitcnt vmcnt(0)
	v_pk_fma_f32 v[16:17], v[18:19], v[16:17], v[20:21]
	global_store_dwordx2 v[8:9], v[16:17], off
	global_load_dwordx4 v[18:21], v27, s[10:11] offset:16
	global_load_dwordx4 v[22:25], v27, s[10:11]
	s_waitcnt vmcnt(1)
	v_lshlrev_b32_e32 v38, 16, v18
	s_waitcnt vmcnt(0)
	v_lshlrev_b32_e32 v34, 16, v22
	v_and_b32_e32 v22, 0xffff0000, v22
	v_add_f32_e32 v0, 0, v34
	v_lshlrev_b32_e32 v35, 16, v23
	v_add_f32_e32 v0, v0, v22
	v_and_b32_e32 v23, 0xffff0000, v23
	v_add_f32_e32 v0, v0, v35
	v_lshlrev_b32_e32 v36, 16, v24
	v_add_f32_e32 v0, v0, v23
	v_and_b32_e32 v24, 0xffff0000, v24
	v_add_f32_e32 v0, v0, v36
	v_lshlrev_b32_e32 v37, 16, v25
	v_add_f32_e32 v0, v0, v24
	v_and_b32_e32 v25, 0xffff0000, v25
	v_add_f32_e32 v0, v0, v37
	v_add_f32_e32 v0, v0, v25
	v_and_b32_e32 v39, 0xffff0000, v18
	v_add_f32_e32 v0, v0, v38
	v_lshlrev_b32_e32 v40, 16, v19
	v_add_f32_e32 v0, v0, v39
	v_and_b32_e32 v41, 0xffff0000, v19
	v_add_f32_e32 v0, v0, v40
	v_add_f32_e32 v0, v0, v41
	v_lshlrev_b32_e32 v19, 16, v20
	v_and_b32_e32 v18, 0xffff0000, v20
	v_add_f32_e32 v0, v0, v19
	v_lshlrev_b32_e32 v9, 16, v21
	v_add_f32_e32 v0, v0, v18
	v_and_b32_e32 v8, 0xffff0000, v21
	v_add_f32_e32 v0, v0, v9
	v_add_f32_e32 v0, v0, v8
	ds_bpermute_b32 v20, v28, v0
	s_waitcnt lgkmcnt(0)
	v_add_f32_e32 v0, v0, v20
	ds_bpermute_b32 v20, v29, v0
	s_waitcnt lgkmcnt(0)
	v_add_f32_e32 v0, v0, v20
	ds_bpermute_b32 v20, v30, v0
	s_waitcnt lgkmcnt(0)
	v_add_f32_e32 v0, v0, v20
	ds_bpermute_b32 v20, v31, v0
	s_waitcnt lgkmcnt(0)
	v_add_f32_e32 v0, v0, v20
	ds_bpermute_b32 v20, v32, v0
	s_waitcnt lgkmcnt(0)
	v_add_f32_e32 v0, v0, v20
	ds_bpermute_b32 v20, v33, v0
	s_waitcnt lgkmcnt(0)
	v_add_f32_e32 v20, v0, v20
	v_fmac_f32_e32 v22, 0xba800000, v20
	v_fmac_f32_e32 v34, 0xba800000, v20
	v_mul_f32_e32 v21, v22, v22
	v_fmac_f32_e32 v21, v34, v34
	v_fmac_f32_e32 v35, 0xba800000, v20
	v_fmac_f32_e32 v21, v35, v35
	v_fmac_f32_e32 v23, 0xba800000, v20
	v_fmac_f32_e32 v21, v23, v23
	v_fmac_f32_e32 v36, 0xba800000, v20
	v_fmac_f32_e32 v21, v36, v36
	v_fmac_f32_e32 v24, 0xba800000, v20
	v_fmac_f32_e32 v21, v24, v24
	v_fmac_f32_e32 v37, 0xba800000, v20
	v_fmac_f32_e32 v21, v37, v37
	v_fmac_f32_e32 v25, 0xba800000, v20
	v_fmac_f32_e32 v21, v25, v25
	v_fmac_f32_e32 v38, 0xba800000, v20
	v_fmac_f32_e32 v21, v38, v38
	v_fmac_f32_e32 v39, 0xba800000, v20
	v_mul_f32_e32 v0, 0x3a800000, v20
	v_fmac_f32_e32 v21, v39, v39
	v_fmac_f32_e32 v40, 0xba800000, v20
	v_fmac_f32_e32 v21, v40, v40
	v_fmac_f32_e32 v41, 0xba800000, v20
	v_pk_add_f32 v[18:19], v[18:19], v[0:1] op_sel_hi:[1,0] neg_lo:[0,1] neg_hi:[0,1]
	v_fmac_f32_e32 v21, v41, v41
	v_pk_mul_f32 v[18:19], v[18:19], v[18:19]
	v_pk_add_f32 v[8:9], v[8:9], v[0:1] op_sel_hi:[1,0] neg_lo:[0,1] neg_hi:[0,1]
	v_add_f32_e32 v19, v19, v21
	v_add_f32_e32 v18, v18, v19
	v_pk_mul_f32 v[8:9], v[8:9], v[8:9]
	s_nop 0
	v_add_f32_e32 v9, v9, v18
	v_add_f32_e32 v8, v8, v9
	v_lshl_add_u64 v[18:19], s[10:11], 0, v[10:11]
	s_add_u32 s10, s8, 0x540c200
	s_addc_u32 s11, s9, 0
	s_waitcnt lgkmcnt(0)
; __device__ __forceinline__ float bf_lo(unsigned w) { return __uint_as_float(w << 16); }
; __device__ __forceinline__ float bf_hi(unsigned w) { return __uint_as_float(w & 0xffff0000u); }
; __device__ __forceinline__ void gate_sample_item(const bf16_t* z, bf16_t* mix, float* cvs  , const float* w_s, const float* b_s,
;                                                  const float* lnv_g, const float* lnv_b, int it, int lane) {
;     ...
;     for (int j = 0; j < 8; ++j) {
;         const bf16_t* vp = z + (tok0 + j) * EIN + 3328 + lane * 16;
;         const u32x4 a = *(const u32x4*)vp, cc = *(const u32x4*)(vp + 8);
;         float v[16] = {bf_lo(a.x), bf_hi(a.x), bf_lo(a.y), bf_hi(a.y), bf_lo(a.z), bf_hi(a.z), bf_lo(a.w), bf_hi(a.w),
;                        bf_lo(cc.x), bf_hi(cc.x), bf_lo(cc.y), bf_hi(cc.y), bf_lo(cc.z), bf_hi(cc.z), bf_lo(cc.w), bf_hi(cc.w)};
;         float s = 0.f;
; #pragma unroll
;         for (int e = 0; e < 16; ++e) s += v[e];
;         const float mean = wave_sum(s) * (1.0f / 1024.0f);
;         float q = 0.f;
; #pragma unroll
;         for (int e = 0; e < 16; ++e) { const float d = v[e] - mean; q += d * d; }
;         const float rstd = rsqrtf(wave_sum(q) * (1.0f / 1024.0f) + EPSN);
;         const unsigned xw = *(const unsigned*)(z + (tok0 + j) * EIN + 3328 + c);
;         vn0[j] = (bf_lo(xw) - mean) * rstd * lnv_g[c] + lnv_b[c];
;         vn1[j] = (bf_hi(xw) - mean) * rstd * lnv_g[c + 1] + lnv_b[c + 1];
;         *(f32x2*)(cvs + ((size_t)b * 8 + j) * 1024 + c) = (f32x2){vn0[j], vn1[j]};
	s_nop 1
	v_add_f32_dpp v8, v8, v8 quad_perm:[1,0,3,2] row_mask:0xf bank_mask:0xf
	s_nop 1
	v_add_f32_dpp v8, v8, v8 quad_perm:[2,3,0,1] row_mask:0xf bank_mask:0xf
	s_nop 1
	v_add_f32_dpp v8, v8, v8 row_half_mirror row_mask:0xf bank_mask:0xf
	s_nop 1
	v_add_f32_dpp v8, v8, v8 row_mirror row_mask:0xf bank_mask:0xf
	s_nop 1
	v_add_f32_dpp v8, v8, v8 row_bcast:15 row_mask:0xa bank_mask:0xf
	s_nop 1
	v_add_f32_dpp v8, v8, v8 row_bcast:31 row_mask:0xc bank_mask:0xf
	s_nop 1
	v_readlane_b32 s100, v8, 63
	s_nop 1
	v_mov_b32_e32 v8, s100
	v_fmamk_f32 v8, v8, 0x3a800000, v138
	v_cmp_gt_f32_e32 vcc, s59, v8
	v_mul_f32_e32 v9, 0x4b800000, v8
	s_nop 0
	v_cndmask_b32_e32 v8, v8, v9, vcc
	v_rsq_f32_e32 v8, v8
	s_nop 0
	v_mul_f32_e32 v9, 0x45800000, v8
	v_cndmask_b32_e32 v8, v8, v9, vcc
	global_load_dword v9, v[18:19], off
	s_waitcnt vmcnt(0)
	v_lshlrev_b32_e32 v18, 16, v9
	v_and_b32_e32 v19, 0xffff0000, v9
	v_pk_add_f32 v[18:19], v[18:19], v[0:1] op_sel_hi:[1,0] neg_lo:[0,1] neg_hi:[0,1]
	s_nop 0
	v_pk_mul_f32 v[8:9], v[18:19], v[8:9] op_sel_hi:[1,0]
	global_load_dwordx2 v[18:19], v[2:3], off
	global_load_dwordx2 v[20:21], v[4:5], off
	s_waitcnt vmcnt(0)
	v_pk_fma_f32 v[18:19], v[18:19], v[8:9], v[20:21]
	v_add_co_u32_e32 v8, vcc, s89, v6
	s_nop 1
	v_addc_co_u32_e32 v9, vcc, 0, v7, vcc
	global_store_dwordx2 v[8:9], v[18:19], off offset:-4096
	global_load_dwordx4 v[20:23], v27, s[10:11] offset:16
	global_load_dwordx4 v[34:37], v27, s[10:11]
	s_waitcnt vmcnt(1)
	v_lshlrev_b32_e32 v42, 16, v20
	s_waitcnt vmcnt(0)
	v_lshlrev_b32_e32 v38, 16, v34
	v_and_b32_e32 v34, 0xffff0000, v34
	v_add_f32_e32 v0, 0, v38
	v_lshlrev_b32_e32 v39, 16, v35
	v_add_f32_e32 v0, v0, v34
	v_and_b32_e32 v35, 0xffff0000, v35
	v_add_f32_e32 v0, v0, v39
	v_lshlrev_b32_e32 v40, 16, v36
	v_add_f32_e32 v0, v0, v35
	v_and_b32_e32 v36, 0xffff0000, v36
	v_add_f32_e32 v0, v0, v40
	v_lshlrev_b32_e32 v41, 16, v37
	v_add_f32_e32 v0, v0, v36
	v_and_b32_e32 v37, 0xffff0000, v37
	v_add_f32_e32 v0, v0, v41
	v_add_f32_e32 v0, v0, v37
	v_and_b32_e32 v43, 0xffff0000, v20
	v_add_f32_e32 v0, v0, v42
	v_lshlrev_b32_e32 v44, 16, v21
	v_add_f32_e32 v0, v0, v43
	v_and_b32_e32 v45, 0xffff0000, v21
	v_add_f32_e32 v0, v0, v44
	v_add_f32_e32 v0, v0, v45
	v_lshlrev_b32_e32 v25, 16, v22
	v_and_b32_e32 v24, 0xffff0000, v22
	v_add_f32_e32 v0, v0, v25
	v_lshlrev_b32_e32 v21, 16, v23
	v_add_f32_e32 v0, v0, v24
	v_and_b32_e32 v20, 0xffff0000, v23
	v_add_f32_e32 v0, v0, v21
	v_add_f32_e32 v0, v0, v20
	ds_bpermute_b32 v22, v28, v0
	s_waitcnt lgkmcnt(0)
	v_add_f32_e32 v0, v0, v22
	ds_bpermute_b32 v22, v29, v0
	s_waitcnt lgkmcnt(0)
	v_add_f32_e32 v0, v0, v22
	ds_bpermute_b32 v22, v30, v0
	s_waitcnt lgkmcnt(0)
	v_add_f32_e32 v0, v0, v22
	ds_bpermute_b32 v22, v31, v0
	s_waitcnt lgkmcnt(0)
	v_add_f32_e32 v0, v0, v22
	ds_bpermute_b32 v22, v32, v0
	s_waitcnt lgkmcnt(0)
	v_add_f32_e32 v0, v0, v22
	ds_bpermute_b32 v22, v33, v0
	s_waitcnt lgkmcnt(0)
	v_add_f32_e32 v22, v0, v22
	v_fmac_f32_e32 v34, 0xba800000, v22
	v_fmac_f32_e32 v38, 0xba800000, v22
	v_mul_f32_e32 v34, v34, v34
	v_fmac_f32_e32 v34, v38, v38
	v_fmac_f32_e32 v39, 0xba800000, v22
	v_fmac_f32_e32 v34, v39, v39
	v_fmac_f32_e32 v35, 0xba800000, v22
	v_fmac_f32_e32 v34, v35, v35
	v_fmac_f32_e32 v40, 0xba800000, v22
	v_fmac_f32_e32 v34, v40, v40
	v_fmac_f32_e32 v36, 0xba800000, v22
	v_fmac_f32_e32 v34, v36, v36
	v_fmac_f32_e32 v41, 0xba800000, v22
	v_fmac_f32_e32 v34, v41, v41
	v_fmac_f32_e32 v37, 0xba800000, v22
	v_fmac_f32_e32 v34, v37, v37
	v_fmac_f32_e32 v42, 0xba800000, v22
	v_fmac_f32_e32 v34, v42, v42
	v_fmac_f32_e32 v43, 0xba800000, v22
	v_mul_f32_e32 v0, 0x3a800000, v22
	v_fmac_f32_e32 v34, v43, v43
	v_fmac_f32_e32 v44, 0xba800000, v22
	v_fmac_f32_e32 v34, v44, v44
	v_fmac_f32_e32 v45, 0xba800000, v22
	v_pk_add_f32 v[22:23], v[24:25], v[0:1] op_sel_hi:[1,0] neg_lo:[0,1] neg_hi:[0,1]
	v_fmac_f32_e32 v34, v45, v45
	v_pk_mul_f32 v[22:23], v[22:23], v[22:23]
	v_pk_add_f32 v[20:21], v[20:21], v[0:1] op_sel_hi:[1,0] neg_lo:[0,1] neg_hi:[0,1]
	v_add_f32_e32 v23, v23, v34
	v_add_f32_e32 v22, v22, v23
	v_pk_mul_f32 v[20:21], v[20:21], v[20:21]
	s_nop 0
	v_add_f32_e32 v21, v21, v22
	v_add_f32_e32 v20, v20, v21
	v_lshl_add_u64 v[22:23], s[10:11], 0, v[10:11]
	s_add_u32 s10, s8, 0x540ec00
	s_addc_u32 s11, s9, 0
	s_waitcnt lgkmcnt(0)
	s_nop 1
	v_add_f32_dpp v20, v20, v20 quad_perm:[1,0,3,2] row_mask:0xf bank_mask:0xf
	s_nop 1
	v_add_f32_dpp v20, v20, v20 quad_perm:[2,3,0,1] row_mask:0xf bank_mask:0xf
	s_nop 1
	v_add_f32_dpp v20, v20, v20 row_half_mirror row_mask:0xf bank_mask:0xf
	s_nop 1
	v_add_f32_dpp v20, v20, v20 row_mirror row_mask:0xf bank_mask:0xf
	s_nop 1
	v_add_f32_dpp v20, v20, v20 row_bcast:15 row_mask:0xa bank_mask:0xf
	s_nop 1
	v_add_f32_dpp v20, v20, v20 row_bcast:31 row_mask:0xc bank_mask:0xf
	s_nop 1
	v_readlane_b32 s100, v20, 63
	s_nop 1
	v_mov_b32_e32 v20, s100
	v_fmamk_f32 v20, v20, 0x3a800000, v138
	v_cmp_gt_f32_e32 vcc, s59, v20
	v_mul_f32_e32 v21, 0x4b800000, v20
	s_nop 0
	v_cndmask_b32_e32 v20, v20, v21, vcc
	v_rsq_f32_e32 v20, v20
	s_nop 0
	v_mul_f32_e32 v21, 0x45800000, v20
	v_cndmask_b32_e32 v20, v20, v21, vcc
	global_load_dword v21, v[22:23], off
	s_waitcnt vmcnt(0)
	v_lshlrev_b32_e32 v22, 16, v21
	v_and_b32_e32 v23, 0xffff0000, v21
	v_pk_add_f32 v[22:23], v[22:23], v[0:1] op_sel_hi:[1,0] neg_lo:[0,1] neg_hi:[0,1]
	s_nop 0
	v_pk_mul_f32 v[20:21], v[22:23], v[20:21] op_sel_hi:[1,0]
	global_load_dwordx2 v[22:23], v[2:3], off
	global_load_dwordx2 v[24:25], v[4:5], off
	s_waitcnt vmcnt(0)
	v_pk_fma_f32 v[20:21], v[22:23], v[20:21], v[24:25]
	global_store_dwordx2 v[8:9], v[20:21], off
	global_load_dwordx4 v[22:25], v27, s[10:11] offset:16
	global_load_dwordx4 v[34:37], v27, s[10:11]
	s_waitcnt vmcnt(1)
; __device__ __forceinline__ float bf_lo(unsigned w) { return __uint_as_float(w << 16); }
; __device__ __forceinline__ float bf_hi(unsigned w) { return __uint_as_float(w & 0xffff0000u); }
; __device__ __forceinline__ void gate_sample_item(const bf16_t* z, bf16_t* mix, float* cvs  , const float* w_s, const float* b_s,
;                                                  const float* lnv_g, const float* lnv_b, int it, int lane) {
;     ...
;     for (int j = 0; j < 8; ++j) {
;         const bf16_t* vp = z + (tok0 + j) * EIN + 3328 + lane * 16;
;         const u32x4 a = *(const u32x4*)vp, cc = *(const u32x4*)(vp + 8);
;         float v[16] = {bf_lo(a.x), bf_hi(a.x), bf_lo(a.y), bf_hi(a.y), bf_lo(a.z), bf_hi(a.z), bf_lo(a.w), bf_hi(a.w),
;                        bf_lo(cc.x), bf_hi(cc.x), bf_lo(cc.y), bf_hi(cc.y), bf_lo(cc.z), bf_hi(cc.z), bf_lo(cc.w), bf_hi(cc.w)};
;         float s = 0.f;
; #pragma unroll
;         for (int e = 0; e < 16; ++e) s += v[e];
;         const float mean = wave_sum(s) * (1.0f / 1024.0f);
;         float q = 0.f;
; #pragma unroll
;         for (int e = 0; e < 16; ++e) { const float d = v[e] - mean; q += d * d; }
;         const float rstd = rsqrtf(wave_sum(q) * (1.0f / 1024.0f) + EPSN);
;         const unsigned xw = *(const unsigned*)(z + (tok0 + j) * EIN + 3328 + c);
;         vn0[j] = (bf_lo(xw) - mean) * rstd * lnv_g[c] + lnv_b[c];
;         vn1[j] = (bf_hi(xw) - mean) * rstd * lnv_g[c + 1] + lnv_b[c + 1];
;         *(f32x2*)(cvs + ((size_t)b * 8 + j) * 1024 + c) = (f32x2){vn0[j], vn1[j]};
	v_lshlrev_b32_e32 v42, 16, v22
	s_waitcnt vmcnt(0)
	v_lshlrev_b32_e32 v38, 16, v34
	v_and_b32_e32 v34, 0xffff0000, v34
	v_add_f32_e32 v0, 0, v38
	v_lshlrev_b32_e32 v39, 16, v35
	v_add_f32_e32 v0, v0, v34
	v_and_b32_e32 v35, 0xffff0000, v35
	v_add_f32_e32 v0, v0, v39
	v_lshlrev_b32_e32 v40, 16, v36
	v_add_f32_e32 v0, v0, v35
	v_and_b32_e32 v36, 0xffff0000, v36
	v_add_f32_e32 v0, v0, v40
	v_lshlrev_b32_e32 v41, 16, v37
	v_add_f32_e32 v0, v0, v36
	v_and_b32_e32 v37, 0xffff0000, v37
	v_add_f32_e32 v0, v0, v41
	v_add_f32_e32 v0, v0, v37
	v_and_b32_e32 v43, 0xffff0000, v22
	v_add_f32_e32 v0, v0, v42
	v_lshlrev_b32_e32 v44, 16, v23
	v_add_f32_e32 v0, v0, v43
	v_and_b32_e32 v45, 0xffff0000, v23
	v_add_f32_e32 v0, v0, v44
	v_add_f32_e32 v0, v0, v45
	v_lshlrev_b32_e32 v23, 16, v24
	v_and_b32_e32 v22, 0xffff0000, v24
	v_add_f32_e32 v0, v0, v23
	v_lshlrev_b32_e32 v9, 16, v25
	v_add_f32_e32 v0, v0, v22
	v_and_b32_e32 v8, 0xffff0000, v25
	v_add_f32_e32 v0, v0, v9
	v_add_f32_e32 v0, v0, v8
	ds_bpermute_b32 v24, v28, v0
	s_waitcnt lgkmcnt(0)
	v_add_f32_e32 v0, v0, v24
	ds_bpermute_b32 v24, v29, v0
	s_waitcnt lgkmcnt(0)
	v_add_f32_e32 v0, v0, v24
	ds_bpermute_b32 v24, v30, v0
	s_waitcnt lgkmcnt(0)
	v_add_f32_e32 v0, v0, v24
	ds_bpermute_b32 v24, v31, v0
	s_waitcnt lgkmcnt(0)
	v_add_f32_e32 v0, v0, v24
	ds_bpermute_b32 v24, v32, v0
	s_waitcnt lgkmcnt(0)
	v_add_f32_e32 v0, v0, v24
	ds_bpermute_b32 v24, v33, v0
	s_waitcnt lgkmcnt(0)
	v_add_f32_e32 v24, v0, v24
	v_fmac_f32_e32 v34, 0xba800000, v24
	v_fmac_f32_e32 v38, 0xba800000, v24
	v_mul_f32_e32 v25, v34, v34
	v_fmac_f32_e32 v25, v38, v38
	v_fmac_f32_e32 v39, 0xba800000, v24
	v_fmac_f32_e32 v25, v39, v39
	v_fmac_f32_e32 v35, 0xba800000, v24
	v_fmac_f32_e32 v25, v35, v35
	v_fmac_f32_e32 v40, 0xba800000, v24
	v_fmac_f32_e32 v25, v40, v40
	v_fmac_f32_e32 v36, 0xba800000, v24
	v_fmac_f32_e32 v25, v36, v36
	v_fmac_f32_e32 v41, 0xba800000, v24
	v_fmac_f32_e32 v25, v41, v41
	v_fmac_f32_e32 v37, 0xba800000, v24
	v_fmac_f32_e32 v25, v37, v37
	v_fmac_f32_e32 v42, 0xba800000, v24
	v_fmac_f32_e32 v25, v42, v42
	v_fmac_f32_e32 v43, 0xba800000, v24
	v_mul_f32_e32 v0, 0x3a800000, v24
	v_fmac_f32_e32 v25, v43, v43
	v_fmac_f32_e32 v44, 0xba800000, v24
	v_fmac_f32_e32 v25, v44, v44
	v_fmac_f32_e32 v45, 0xba800000, v24
	v_pk_add_f32 v[22:23], v[22:23], v[0:1] op_sel_hi:[1,0] neg_lo:[0,1] neg_hi:[0,1]
	v_fmac_f32_e32 v25, v45, v45
	v_pk_mul_f32 v[22:23], v[22:23], v[22:23]
	v_pk_add_f32 v[8:9], v[8:9], v[0:1] op_sel_hi:[1,0] neg_lo:[0,1] neg_hi:[0,1]
	v_add_f32_e32 v23, v23, v25
	v_add_f32_e32 v22, v22, v23
	v_pk_mul_f32 v[8:9], v[8:9], v[8:9]
	s_nop 0
	v_add_f32_e32 v9, v9, v22
	v_add_f32_e32 v8, v8, v9
	v_lshl_add_u64 v[22:23], s[10:11], 0, v[10:11]
	s_add_u32 s10, s8, 0x5411600
	s_addc_u32 s11, s9, 0
	s_waitcnt lgkmcnt(0)
	s_nop 1
	v_add_f32_dpp v8, v8, v8 quad_perm:[1,0,3,2] row_mask:0xf bank_mask:0xf
	s_nop 1
	v_add_f32_dpp v8, v8, v8 quad_perm:[2,3,0,1] row_mask:0xf bank_mask:0xf
	s_nop 1
	v_add_f32_dpp v8, v8, v8 row_half_mirror row_mask:0xf bank_mask:0xf
	s_nop 1
	v_add_f32_dpp v8, v8, v8 row_mirror row_mask:0xf bank_mask:0xf
	s_nop 1
	v_add_f32_dpp v8, v8, v8 row_bcast:15 row_mask:0xa bank_mask:0xf
	s_nop 1
	v_add_f32_dpp v8, v8, v8 row_bcast:31 row_mask:0xc bank_mask:0xf
	s_nop 1
	v_readlane_b32 s100, v8, 63
	s_nop 1
	v_mov_b32_e32 v8, s100
	v_fmamk_f32 v8, v8, 0x3a800000, v138
	v_cmp_gt_f32_e32 vcc, s59, v8
	v_mul_f32_e32 v9, 0x4b800000, v8
	s_nop 0
	v_cndmask_b32_e32 v8, v8, v9, vcc
	v_rsq_f32_e32 v8, v8
	s_nop 0
	v_mul_f32_e32 v9, 0x45800000, v8
	v_cndmask_b32_e32 v8, v8, v9, vcc
	global_load_dword v9, v[22:23], off
	s_waitcnt vmcnt(0)
	v_lshlrev_b32_e32 v22, 16, v9
	v_and_b32_e32 v23, 0xffff0000, v9
	v_pk_add_f32 v[22:23], v[22:23], v[0:1] op_sel_hi:[1,0] neg_lo:[0,1] neg_hi:[0,1]
	s_nop 0
	v_pk_mul_f32 v[8:9], v[22:23], v[8:9] op_sel_hi:[1,0]
	global_load_dwordx2 v[22:23], v[2:3], off
	global_load_dwordx2 v[24:25], v[4:5], off
	s_waitcnt vmcnt(0)
	v_pk_fma_f32 v[22:23], v[22:23], v[8:9], v[24:25]
	v_add_co_u32_e32 v8, vcc, s58, v6
	s_nop 1
	v_addc_co_u32_e32 v9, vcc, 0, v7, vcc
	global_store_dwordx2 v[8:9], v[22:23], off offset:-4096
	global_load_dwordx4 v[34:37], v27, s[10:11] offset:16
	global_load_dwordx4 v[38:41], v27, s[10:11]
	s_waitcnt vmcnt(1)
	v_lshlrev_b32_e32 v46, 16, v34
	s_waitcnt vmcnt(0)
	v_lshlrev_b32_e32 v42, 16, v38
	v_and_b32_e32 v38, 0xffff0000, v38
	v_add_f32_e32 v0, 0, v42
	v_lshlrev_b32_e32 v43, 16, v39
	v_add_f32_e32 v0, v0, v38
	v_and_b32_e32 v39, 0xffff0000, v39
	v_add_f32_e32 v0, v0, v43
	v_lshlrev_b32_e32 v44, 16, v40
	v_add_f32_e32 v0, v0, v39
	v_and_b32_e32 v40, 0xffff0000, v40
	v_add_f32_e32 v0, v0, v44
	v_lshlrev_b32_e32 v45, 16, v41
	v_add_f32_e32 v0, v0, v40
	v_and_b32_e32 v41, 0xffff0000, v41
	v_add_f32_e32 v0, v0, v45
	v_add_f32_e32 v0, v0, v41
	v_and_b32_e32 v47, 0xffff0000, v34
	v_add_f32_e32 v0, v0, v46
	v_lshlrev_b32_e32 v48, 16, v35
	v_add_f32_e32 v0, v0, v47
	v_and_b32_e32 v49, 0xffff0000, v35
	v_add_f32_e32 v0, v0, v48
	v_add_f32_e32 v0, v0, v49
	v_lshlrev_b32_e32 v35, 16, v36
	v_and_b32_e32 v34, 0xffff0000, v36
	v_add_f32_e32 v0, v0, v35
	v_lshlrev_b32_e32 v25, 16, v37
	v_add_f32_e32 v0, v0, v34
	v_and_b32_e32 v24, 0xffff0000, v37
	v_add_f32_e32 v0, v0, v25
	v_add_f32_e32 v0, v0, v24
	ds_bpermute_b32 v36, v28, v0
	s_waitcnt lgkmcnt(0)
	v_add_f32_e32 v0, v0, v36
	ds_bpermute_b32 v36, v29, v0
	s_waitcnt lgkmcnt(0)
	v_add_f32_e32 v0, v0, v36
	ds_bpermute_b32 v36, v30, v0
	s_waitcnt lgkmcnt(0)
	v_add_f32_e32 v0, v0, v36
	ds_bpermute_b32 v36, v31, v0
	s_waitcnt lgkmcnt(0)
	v_add_f32_e32 v0, v0, v36
	ds_bpermute_b32 v36, v32, v0
	s_waitcnt lgkmcnt(0)
; __device__ __forceinline__ float bf_lo(unsigned w) { return __uint_as_float(w << 16); }
; __device__ __forceinline__ float bf_hi(unsigned w) { return __uint_as_float(w & 0xffff0000u); }
; __device__ __forceinline__ void gate_sample_item(const bf16_t* z, bf16_t* mix, float* cvs  , const float* w_s, const float* b_s,
;                                                  const float* lnv_g, const float* lnv_b, int it, int lane) {
;     ...
;     for (int j = 0; j < 8; ++j) {
;         const bf16_t* vp = z + (tok0 + j) * EIN + 3328 + lane * 16;
;         const u32x4 a = *(const u32x4*)vp, cc = *(const u32x4*)(vp + 8);
;         float v[16] = {bf_lo(a.x), bf_hi(a.x), bf_lo(a.y), bf_hi(a.y), bf_lo(a.z), bf_hi(a.z), bf_lo(a.w), bf_hi(a.w),
;                        bf_lo(cc.x), bf_hi(cc.x), bf_lo(cc.y), bf_hi(cc.y), bf_lo(cc.z), bf_hi(cc.z), bf_lo(cc.w), bf_hi(cc.w)};
;         float s = 0.f;
; #pragma unroll
;         for (int e = 0; e < 16; ++e) s += v[e];
;         const float mean = wave_sum(s) * (1.0f / 1024.0f);
;         float q = 0.f;
; #pragma unroll
;         for (int e = 0; e < 16; ++e) { const float d = v[e] - mean; q += d * d; }
;         const float rstd = rsqrtf(wave_sum(q) * (1.0f / 1024.0f) + EPSN);
;         const unsigned xw = *(const unsigned*)(z + (tok0 + j) * EIN + 3328 + c);
;         vn0[j] = (bf_lo(xw) - mean) * rstd * lnv_g[c] + lnv_b[c];
;         vn1[j] = (bf_hi(xw) - mean) * rstd * lnv_g[c + 1] + lnv_b[c + 1];
;         *(f32x2*)(cvs + ((size_t)b * 8 + j) * 1024 + c) = (f32x2){vn0[j], vn1[j]};
	v_add_f32_e32 v0, v0, v36
	ds_bpermute_b32 v36, v33, v0
	s_waitcnt lgkmcnt(0)
	v_add_f32_e32 v36, v0, v36
	v_fmac_f32_e32 v38, 0xba800000, v36
	v_fmac_f32_e32 v42, 0xba800000, v36
	v_mul_f32_e32 v37, v38, v38
	v_fmac_f32_e32 v37, v42, v42
	v_fmac_f32_e32 v43, 0xba800000, v36
	v_fmac_f32_e32 v37, v43, v43
	v_fmac_f32_e32 v39, 0xba800000, v36
	v_fmac_f32_e32 v37, v39, v39
	v_fmac_f32_e32 v44, 0xba800000, v36
	v_fmac_f32_e32 v37, v44, v44
	v_fmac_f32_e32 v40, 0xba800000, v36
	v_fmac_f32_e32 v37, v40, v40
	v_fmac_f32_e32 v45, 0xba800000, v36
	v_fmac_f32_e32 v37, v45, v45
	v_fmac_f32_e32 v41, 0xba800000, v36
	v_fmac_f32_e32 v37, v41, v41
	v_fmac_f32_e32 v46, 0xba800000, v36
	v_fmac_f32_e32 v37, v46, v46
	v_fmac_f32_e32 v47, 0xba800000, v36
	v_mul_f32_e32 v0, 0x3a800000, v36
	v_fmac_f32_e32 v37, v47, v47
	v_fmac_f32_e32 v48, 0xba800000, v36
	v_fmac_f32_e32 v37, v48, v48
	v_fmac_f32_e32 v49, 0xba800000, v36
	v_pk_add_f32 v[34:35], v[34:35], v[0:1] op_sel_hi:[1,0] neg_lo:[0,1] neg_hi:[0,1]
	v_fmac_f32_e32 v37, v49, v49
	v_pk_mul_f32 v[34:35], v[34:35], v[34:35]
	v_pk_add_f32 v[24:25], v[24:25], v[0:1] op_sel_hi:[1,0] neg_lo:[0,1] neg_hi:[0,1]
	v_add_f32_e32 v35, v35, v37
	v_add_f32_e32 v34, v34, v35
	v_pk_mul_f32 v[24:25], v[24:25], v[24:25]
	s_nop 0
	v_add_f32_e32 v25, v25, v34
	v_add_f32_e32 v24, v24, v25
	v_lshl_add_u64 v[34:35], s[10:11], 0, v[10:11]
	s_add_u32 s10, s8, 0x5414000
	s_addc_u32 s11, s9, 0
	s_waitcnt lgkmcnt(0)
	s_nop 1
	v_add_f32_dpp v24, v24, v24 quad_perm:[1,0,3,2] row_mask:0xf bank_mask:0xf
	s_nop 1
	v_add_f32_dpp v24, v24, v24 quad_perm:[2,3,0,1] row_mask:0xf bank_mask:0xf
	s_nop 1
	v_add_f32_dpp v24, v24, v24 row_half_mirror row_mask:0xf bank_mask:0xf
	s_nop 1
	v_add_f32_dpp v24, v24, v24 row_mirror row_mask:0xf bank_mask:0xf
	s_nop 1
	v_add_f32_dpp v24, v24, v24 row_bcast:15 row_mask:0xa bank_mask:0xf
	s_nop 1
	v_add_f32_dpp v24, v24, v24 row_bcast:31 row_mask:0xc bank_mask:0xf
	s_nop 1
	v_readlane_b32 s100, v24, 63
	s_nop 1
	v_mov_b32_e32 v24, s100
	v_fmamk_f32 v24, v24, 0x3a800000, v138
	v_cmp_gt_f32_e32 vcc, s59, v24
	v_mul_f32_e32 v25, 0x4b800000, v24
	s_nop 0
	v_cndmask_b32_e32 v24, v24, v25, vcc
	v_rsq_f32_e32 v24, v24
	s_nop 0
	v_mul_f32_e32 v25, 0x45800000, v24
	v_cndmask_b32_e32 v24, v24, v25, vcc
	global_load_dword v25, v[34:35], off
	s_waitcnt vmcnt(0)
	v_lshlrev_b32_e32 v34, 16, v25
	v_and_b32_e32 v35, 0xffff0000, v25
	v_pk_add_f32 v[34:35], v[34:35], v[0:1] op_sel_hi:[1,0] neg_lo:[0,1] neg_hi:[0,1]
	s_nop 0
	v_pk_mul_f32 v[24:25], v[34:35], v[24:25] op_sel_hi:[1,0]
	global_load_dwordx2 v[34:35], v[2:3], off
	global_load_dwordx2 v[36:37], v[4:5], off
	s_waitcnt vmcnt(0)
	v_pk_fma_f32 v[24:25], v[34:35], v[24:25], v[36:37]
	global_store_dwordx2 v[8:9], v[24:25], off
	global_load_dwordx4 v[34:37], v27, s[10:11] offset:16
	global_load_dwordx4 v[38:41], v27, s[10:11]
	s_waitcnt vmcnt(1)
	v_lshlrev_b32_e32 v46, 16, v34
	s_waitcnt vmcnt(0)
	v_lshlrev_b32_e32 v42, 16, v38
	v_and_b32_e32 v38, 0xffff0000, v38
	v_add_f32_e32 v0, 0, v42
	v_lshlrev_b32_e32 v43, 16, v39
	v_add_f32_e32 v0, v0, v38
	v_and_b32_e32 v39, 0xffff0000, v39
	v_add_f32_e32 v0, v0, v43
	v_lshlrev_b32_e32 v44, 16, v40
	v_add_f32_e32 v0, v0, v39
	v_and_b32_e32 v40, 0xffff0000, v40
	v_add_f32_e32 v0, v0, v44
	v_lshlrev_b32_e32 v45, 16, v41
	v_add_f32_e32 v0, v0, v40
	v_and_b32_e32 v41, 0xffff0000, v41
	v_add_f32_e32 v0, v0, v45
	v_add_f32_e32 v0, v0, v41
	v_and_b32_e32 v47, 0xffff0000, v34
	v_add_f32_e32 v0, v0, v46
	v_lshlrev_b32_e32 v48, 16, v35
	v_add_f32_e32 v0, v0, v47
	v_and_b32_e32 v49, 0xffff0000, v35
	v_add_f32_e32 v0, v0, v48
	v_add_f32_e32 v0, v0, v49
	v_lshlrev_b32_e32 v35, 16, v36
	v_and_b32_e32 v34, 0xffff0000, v36
	v_add_f32_e32 v0, v0, v35
	v_lshlrev_b32_e32 v9, 16, v37
	v_add_f32_e32 v0, v0, v34
	v_and_b32_e32 v8, 0xffff0000, v37
	v_add_f32_e32 v0, v0, v9
	v_add_f32_e32 v0, v0, v8
	ds_bpermute_b32 v36, v28, v0
	s_waitcnt lgkmcnt(0)
	v_add_f32_e32 v0, v0, v36
	ds_bpermute_b32 v36, v29, v0
	s_waitcnt lgkmcnt(0)
	v_add_f32_e32 v0, v0, v36
	ds_bpermute_b32 v36, v30, v0
	s_waitcnt lgkmcnt(0)
	v_add_f32_e32 v0, v0, v36
	ds_bpermute_b32 v36, v31, v0
	s_waitcnt lgkmcnt(0)
	v_add_f32_e32 v0, v0, v36
	ds_bpermute_b32 v36, v32, v0
	s_waitcnt lgkmcnt(0)
	v_add_f32_e32 v0, v0, v36
	ds_bpermute_b32 v36, v33, v0
	s_waitcnt lgkmcnt(0)
	v_add_f32_e32 v36, v0, v36
	v_fmac_f32_e32 v38, 0xba800000, v36
	v_fmac_f32_e32 v42, 0xba800000, v36
	v_mul_f32_e32 v37, v38, v38
	v_fmac_f32_e32 v37, v42, v42
	v_fmac_f32_e32 v43, 0xba800000, v36
	v_fmac_f32_e32 v37, v43, v43
	v_fmac_f32_e32 v39, 0xba800000, v36
	v_fmac_f32_e32 v37, v39, v39
	v_fmac_f32_e32 v44, 0xba800000, v36
	v_fmac_f32_e32 v37, v44, v44
	v_fmac_f32_e32 v40, 0xba800000, v36
	v_fmac_f32_e32 v37, v40, v40
	v_fmac_f32_e32 v45, 0xba800000, v36
	v_fmac_f32_e32 v37, v45, v45
	v_fmac_f32_e32 v41, 0xba800000, v36
	v_fmac_f32_e32 v37, v41, v41
	v_fmac_f32_e32 v46, 0xba800000, v36
	v_fmac_f32_e32 v37, v46, v46
	v_fmac_f32_e32 v47, 0xba800000, v36
	v_mul_f32_e32 v0, 0x3a800000, v36
	v_fmac_f32_e32 v37, v47, v47
	v_fmac_f32_e32 v48, 0xba800000, v36
	v_fmac_f32_e32 v37, v48, v48
	v_fmac_f32_e32 v49, 0xba800000, v36
	v_pk_add_f32 v[34:35], v[34:35], v[0:1] op_sel_hi:[1,0] neg_lo:[0,1] neg_hi:[0,1]
	v_fmac_f32_e32 v37, v49, v49
	v_pk_mul_f32 v[34:35], v[34:35], v[34:35]
	v_pk_add_f32 v[8:9], v[8:9], v[0:1] op_sel_hi:[1,0] neg_lo:[0,1] neg_hi:[0,1]
	v_add_f32_e32 v35, v35, v37
	v_add_f32_e32 v34, v34, v35
	v_pk_mul_f32 v[8:9], v[8:9], v[8:9]
	s_nop 0
	v_add_f32_e32 v9, v9, v34
	v_add_f32_e32 v8, v8, v9
	ds_bpermute_b32 v9, v28, v8
	s_waitcnt lgkmcnt(0)
; __device__ __forceinline__ float bf_lo(unsigned w) { return __uint_as_float(w << 16); }
; __device__ __forceinline__ float bf_hi(unsigned w) { return __uint_as_float(w & 0xffff0000u); }
; __device__ __forceinline__ unsigned pk2(float lo, float hi) { return pg8::cvt_pk_bf16(lo, hi); }
; __device__ __forceinline__ void gate_sample_item(const bf16_t* z, bf16_t* mix, float* cvs  , const float* w_s, const float* b_s,
;                                                  const float* lnv_g, const float* lnv_b, int it, int lane) {
;     ...
;         const float rstd = rsqrtf(wave_sum(q) * (1.0f / 1024.0f) + EPSN);
;         const unsigned xw = *(const unsigned*)(z + (tok0 + j) * EIN + 3328 + c);
;         vn0[j] = (bf_lo(xw) - mean) * rstd * lnv_g[c] + lnv_b[c];
;         vn1[j] = (bf_hi(xw) - mean) * rstd * lnv_g[c + 1] + lnv_b[c + 1];
;         *(f32x2*)(cvs + ((size_t)b * 8 + j) * 1024 + c) = (f32x2){vn0[j], vn1[j]};
;     }
; #pragma unroll
;     for (int t = 0; t < 8; ++t) {
;         float m0 = b_s[gr * 128 + t], m1 = m0;
; #pragma unroll
;         for (int j = 0; j < 8; ++j)
;             if (j <= t) { const float w = w_s[((size_t)gr * 128 + t) * 128 + j]; m0 += w * vn0[j]; m1 += w * vn1[j]; }
;         const unsigned uw = *(const unsigned*)(z + (tok0 + t) * EIN + 2304 + c), gw = *(const unsigned*)(z + (tok0 + t) * EIN + 4352 + c);
;         *(unsigned*)(mix + (tok0 + t) * 2048 + 1024 + c) = pk2(bf_lo(gw) * bf_lo(uw) * m0, bf_hi(gw) * bf_hi(uw) * m1);
	v_add_f32_e32 v8, v8, v9
	ds_bpermute_b32 v9, v29, v8
	v_lshl_add_u64 v[28:29], s[10:11], 0, v[10:11]
	s_bfe_u32 s10, s14, 0x20001
	s_lshl_b32 s11, s10, 9
	v_readlane_b32 s14, v255, 7
	s_waitcnt lgkmcnt(0)
	v_add_f32_e32 v8, v8, v9
	ds_bpermute_b32 v9, v30, v8
	v_readlane_b32 s15, v255, 8
	s_lshl_b32 s10, s10, 16
	s_waitcnt lgkmcnt(0)
	v_add_f32_e32 v8, v8, v9
	ds_bpermute_b32 v9, v31, v8
	v_lshl_add_u64 v[30:31], s[8:9], 0, v[10:11]
	s_mov_b32 s8, 0x5401000
	s_add_u32 s9, s6, 0x2000000
	s_waitcnt lgkmcnt(0)
	v_add_f32_e32 v8, v8, v9
	ds_bpermute_b32 v9, v32, v8
	v_mov_b32_e32 v32, s10
	s_waitcnt lgkmcnt(0)
	v_add_f32_e32 v8, v8, v9
	ds_bpermute_b32 v9, v33, v8
	s_waitcnt lgkmcnt(0)
	v_add_f32_e32 v8, v8, v9
	v_fmamk_f32 v8, v8, 0x3a800000, v138
	v_cmp_gt_f32_e32 vcc, s59, v8
	v_mul_f32_e32 v9, 0x4b800000, v8
	s_nop 0
	v_cndmask_b32_e32 v8, v8, v9, vcc
	v_rsq_f32_e32 v8, v8
	s_nop 0
	v_mul_f32_e32 v9, 0x45800000, v8
	v_cndmask_b32_e32 v8, v8, v9, vcc
	global_load_dword v9, v[28:29], off
	s_nop 0
	global_load_dwordx2 v[2:3], v[2:3], off
	s_nop 0
	global_load_dwordx2 v[4:5], v[4:5], off
	s_waitcnt vmcnt(2)
	v_lshlrev_b32_e32 v28, 16, v9
	v_and_b32_e32 v29, 0xffff0000, v9
	v_pk_add_f32 v[28:29], v[28:29], v[0:1] op_sel_hi:[1,0] neg_lo:[0,1] neg_hi:[0,1]
	v_mov_b32_e32 v0, s11
	v_pk_mul_f32 v[8:9], v[28:29], v[8:9] op_sel_hi:[1,0]
	s_waitcnt vmcnt(0)
	v_pk_fma_f32 v[28:29], v[2:3], v[8:9], v[4:5]
	v_add_co_u32_e32 v2, vcc, s65, v6
	s_nop 1
	v_addc_co_u32_e32 v3, vcc, 0, v7, vcc
	v_add_co_u32_e32 v34, vcc, s8, v30
	global_store_dwordx2 v[2:3], v[28:29], off
	s_nop 0
	v_addc_co_u32_e32 v35, vcc, 0, v31, vcc
	s_mov_b32 s8, 0x5402000
	global_load_dwordx4 v[2:5], v0, s[14:15] offset:16
	global_load_dwordx4 v[6:9], v0, s[14:15]
	global_load_dword v33, v[34:35], off offset:512
	v_add_co_u32_e32 v34, vcc, s8, v30
	global_load_dword v0, v32, s[90:91]
	s_nop 0
	v_addc_co_u32_e32 v35, vcc, 0, v31, vcc
	global_load_dword v35, v[34:35], off offset:512
	s_addc_u32 s8, s7, 0
	s_add_u32 s10, s92, s9
	s_addc_u32 s11, s93, s8
	s_add_u32 s6, s92, s6
	s_addc_u32 s7, s93, s7
	s_waitcnt vmcnt(2)
	v_lshlrev_b32_e32 v36, 16, v33
	v_and_b32_e32 v37, 0xffff0000, v33
	s_waitcnt vmcnt(1)
	v_pk_fma_f32 v[38:39], v[12:13], v[0:1], v[6:7] op_sel_hi:[1,0,0]
	s_waitcnt vmcnt(0)
	v_lshlrev_b32_e32 v34, 16, v35
	v_and_b32_e32 v35, 0xffff0000, v35
	v_pk_mul_f32 v[34:35], v[36:37], v[34:35]
	s_nop 0
	v_pk_mul_f32 v[34:35], v[38:39], v[34:35]
	s_nop 0
	v_cvt_pk_bf16_f32 v0, v34, v35
	v_lshl_add_u64 v[34:35], s[10:11], 0, v[10:11]
	s_mov_b32 s10, 0x5403000
	v_add_co_u32_e32 v36, vcc, s10, v30
	global_store_dword v[34:35], v0, off offset:2048
	s_nop 0
	v_addc_co_u32_e32 v37, vcc, 0, v31, vcc
	s_mov_b32 s10, 0x5404000
	global_load_dword v0, v[36:37], off offset:3072
	v_add_co_u32_e32 v36, vcc, s10, v30
	global_load_dwordx2 v[34:35], v32, s[90:91] offset:512
	s_nop 0
	v_addc_co_u32_e32 v37, vcc, 0, v31, vcc
	global_load_dword v33, v[36:37], off offset:3072
	s_waitcnt vmcnt(2)
	v_lshlrev_b32_e32 v38, 16, v0
	v_and_b32_e32 v39, 0xffff0000, v0
	s_waitcnt vmcnt(1)
	v_pk_fma_f32 v[6:7], v[12:13], v[34:35], v[6:7] op_sel:[0,0,1] op_sel_hi:[1,0,1]
	s_nop 0
	v_pk_fma_f32 v[6:7], v[14:15], v[34:35], v[6:7] op_sel:[0,1,0]
	s_waitcnt vmcnt(0)
	v_lshlrev_b32_e32 v36, 16, v33
	v_and_b32_e32 v37, 0xffff0000, v33
	v_pk_mul_f32 v[34:35], v[38:39], v[36:37]
	s_nop 0
	v_pk_mul_f32 v[6:7], v[6:7], v[34:35]
	global_load_dwordx3 v[34:36], v32, s[90:91] offset:1024
	v_cvt_pk_bf16_f32 v0, v6, v7
	v_lshl_add_u64 v[6:7], s[6:7], 0, v[10:11]
	s_mov_b32 s6, 0x2001000
	v_add_co_u32_e32 v6, vcc, s6, v6
	s_mov_b32 s6, 0x5406000
	s_nop 0
	v_addc_co_u32_e32 v7, vcc, 0, v7, vcc
	global_store_dword v[6:7], v0, off offset:2048
	v_add_co_u32_e32 v6, vcc, s6, v30
	s_mov_b32 s6, 0x5407000
	s_nop 0
	v_addc_co_u32_e32 v7, vcc, 0, v31, vcc
	global_load_dword v0, v[6:7], off offset:1536
	v_add_co_u32_e32 v6, vcc, s6, v30
	s_or_b32 s6, s9, 0x2000
	s_nop 0
	v_addc_co_u32_e32 v7, vcc, 0, v31, vcc
	global_load_dword v7, v[6:7], off offset:1536
	s_add_u32 s6, s92, s6
	s_addc_u32 s7, s93, s8
	s_waitcnt vmcnt(3)
	v_pk_fma_f32 v[40:41], v[12:13], v[34:35], v[8:9] op_sel_hi:[1,0,0]
	s_nop 0
	v_pk_fma_f32 v[34:35], v[14:15], v[34:35], v[40:41] op_sel:[0,1,0]
	s_waitcnt vmcnt(1)
	v_lshlrev_b32_e32 v38, 16, v0
	v_and_b32_e32 v39, 0xffff0000, v0
	v_mov_b32_e32 v0, v36
	v_pk_fma_f32 v[34:35], v[16:17], v[0:1], v[34:35] op_sel_hi:[1,0,1]
	s_waitcnt vmcnt(0)
	v_lshlrev_b32_e32 v6, 16, v7
	v_and_b32_e32 v7, 0xffff0000, v7
	v_pk_mul_f32 v[6:7], v[38:39], v[6:7]
	s_nop 0
	v_pk_mul_f32 v[6:7], v[34:35], v[6:7]
	global_load_dwordx4 v[34:37], v32, s[90:91] offset:1536
	v_cvt_pk_bf16_f32 v0, v6, v7
	v_lshl_add_u64 v[6:7], s[6:7], 0, v[10:11]
	s_mov_b32 s6, 0x540a000
	global_store_dword v[6:7], v0, off offset:2048
	v_add_co_u32_e32 v6, vcc, s6, v30
	s_or_b32 s6, s9, 0x3000
	s_nop 0
	v_addc_co_u32_e32 v7, vcc, 0, v31, vcc
	global_load_dword v0, v[6:7], off offset:-4096
	s_nop 0
	global_load_dword v7, v[6:7], off
	s_add_u32 s6, s92, s6
	s_addc_u32 s7, s93, s8
	s_waitcnt vmcnt(1)
	v_lshlrev_b32_e32 v38, 16, v0
	v_and_b32_e32 v39, 0xffff0000, v0
	v_mov_b32_e32 v0, v9
	v_pk_fma_f32 v[8:9], v[12:13], v[34:35], v[0:1] op_sel_hi:[1,0,0]
	s_waitcnt vmcnt(0)
; __device__ __forceinline__ float bf_lo(unsigned w) { return __uint_as_float(w << 16); }
; __device__ __forceinline__ float bf_hi(unsigned w) { return __uint_as_float(w & 0xffff0000u); }
; __device__ __forceinline__ unsigned pk2(float lo, float hi) { return pg8::cvt_pk_bf16(lo, hi); }
; __device__ __forceinline__ void gate_sample_item(const bf16_t* z, bf16_t* mix, float* cvs  , const float* w_s, const float* b_s,
;                                                  const float* lnv_g, const float* lnv_b, int it, int lane) {
;     ...
; #pragma unroll
;     for (int t = 0; t < 8; ++t) {
;         float m0 = b_s[gr * 128 + t], m1 = m0;
; #pragma unroll
;         for (int j = 0; j < 8; ++j)
;             if (j <= t) { const float w = w_s[((size_t)gr * 128 + t) * 128 + j]; m0 += w * vn0[j]; m1 += w * vn1[j]; }
;         const unsigned uw = *(const unsigned*)(z + (tok0 + t) * EIN + 2304 + c), gw = *(const unsigned*)(z + (tok0 + t) * EIN + 4352 + c);
;         *(unsigned*)(mix + (tok0 + t) * 2048 + 1024 + c) = pk2(bf_lo(gw) * bf_lo(uw) * m0, bf_hi(gw) * bf_hi(uw) * m1);
;     }
	v_lshlrev_b32_e32 v6, 16, v7
	v_pk_fma_f32 v[8:9], v[14:15], v[34:35], v[8:9] op_sel:[0,1,0]
	v_and_b32_e32 v7, 0xffff0000, v7
	v_pk_fma_f32 v[8:9], v[16:17], v[36:37], v[8:9] op_sel_hi:[1,0,1]
	v_mov_b32_e32 v0, v37
	v_pk_fma_f32 v[8:9], v[18:19], v[0:1], v[8:9] op_sel_hi:[1,0,1]
	v_pk_mul_f32 v[6:7], v[38:39], v[6:7]
	s_nop 0
	v_pk_mul_f32 v[6:7], v[8:9], v[6:7]
	s_nop 0
	v_cvt_pk_bf16_f32 v0, v6, v7
	v_lshl_add_u64 v[6:7], s[6:7], 0, v[10:11]
	s_mov_b32 s6, 0x540b000
	global_store_dword v[6:7], v0, off offset:2048
	v_add_co_u32_e32 v34, vcc, s6, v30
	global_load_dword v0, v32, s[90:91] offset:2064
	global_load_dwordx4 v[6:9], v32, s[90:91] offset:2048
	v_addc_co_u32_e32 v35, vcc, 0, v31, vcc
	s_mov_b32 s6, 0x540c000
	global_load_dword v33, v[34:35], off offset:2560
	v_add_co_u32_e32 v34, vcc, s6, v30
	s_or_b32 s6, s9, 0x4000
	s_nop 0
	v_addc_co_u32_e32 v35, vcc, 0, v31, vcc
	global_load_dword v35, v[34:35], off offset:2560
	s_add_u32 s6, s92, s6
	s_addc_u32 s7, s93, s8
	s_waitcnt vmcnt(2)
	v_pk_fma_f32 v[38:39], v[12:13], v[6:7], v[2:3] op_sel_hi:[1,0,0]
	s_nop 0
	v_pk_fma_f32 v[6:7], v[14:15], v[6:7], v[38:39] op_sel:[0,1,0]
	s_waitcnt vmcnt(1)
	v_lshlrev_b32_e32 v36, 16, v33
	v_pk_fma_f32 v[6:7], v[16:17], v[8:9], v[6:7] op_sel_hi:[1,0,1]
	v_mov_b32_e32 v8, v9
	v_and_b32_e32 v37, 0xffff0000, v33
	v_pk_fma_f32 v[6:7], v[18:19], v[8:9], v[6:7] op_sel_hi:[1,0,1]
	s_waitcnt vmcnt(0)
	v_lshlrev_b32_e32 v34, 16, v35
	v_and_b32_e32 v35, 0xffff0000, v35
	v_pk_fma_f32 v[6:7], v[20:21], v[0:1], v[6:7] op_sel_hi:[1,0,1]
	v_pk_mul_f32 v[8:9], v[36:37], v[34:35]
	s_nop 0
	v_pk_mul_f32 v[6:7], v[6:7], v[8:9]
	s_nop 0
	v_cvt_pk_bf16_f32 v0, v6, v7
	v_lshl_add_u64 v[6:7], s[6:7], 0, v[10:11]
	global_store_dword v[6:7], v0, off offset:2048
	s_mov_b32 s6, 0x540e000
	global_load_dwordx2 v[34:35], v32, s[90:91] offset:2576
	global_load_dwordx4 v[6:9], v32, s[90:91] offset:2560
	v_add_co_u32_e32 v36, vcc, s6, v30
	s_mov_b32 s6, 0x540f000
	s_nop 0
	v_addc_co_u32_e32 v37, vcc, 0, v31, vcc
	global_load_dword v0, v[36:37], off offset:1024
	v_add_co_u32_e32 v36, vcc, s6, v30
	s_or_b32 s6, s9, 0x5000
	s_nop 0
	v_addc_co_u32_e32 v37, vcc, 0, v31, vcc
	global_load_dword v33, v[36:37], off offset:1024
	s_add_u32 s6, s92, s6
	s_addc_u32 s7, s93, s8
	s_waitcnt vmcnt(2)
	v_pk_fma_f32 v[2:3], v[12:13], v[6:7], v[2:3] op_sel:[0,0,1] op_sel_hi:[1,0,1]
	s_nop 0
	v_pk_fma_f32 v[2:3], v[14:15], v[6:7], v[2:3] op_sel:[0,1,0]
	s_waitcnt vmcnt(1)
	v_lshlrev_b32_e32 v38, 16, v0
	v_and_b32_e32 v39, 0xffff0000, v0
	v_pk_fma_f32 v[2:3], v[16:17], v[8:9], v[2:3] op_sel_hi:[1,0,1]
	v_mov_b32_e32 v0, v9
	v_pk_fma_f32 v[2:3], v[18:19], v[0:1], v[2:3] op_sel_hi:[1,0,1]
	s_waitcnt vmcnt(0)
	v_lshlrev_b32_e32 v36, 16, v33
	v_and_b32_e32 v37, 0xffff0000, v33
	v_pk_fma_f32 v[2:3], v[20:21], v[34:35], v[2:3] op_sel_hi:[1,0,1]
	v_pk_mul_f32 v[6:7], v[38:39], v[36:37]
	v_pk_fma_f32 v[2:3], v[22:23], v[34:35], v[2:3] op_sel:[0,1,0]
	s_nop 0
	v_pk_mul_f32 v[2:3], v[2:3], v[6:7]
	s_nop 0
	v_cvt_pk_bf16_f32 v0, v2, v3
	v_lshl_add_u64 v[2:3], s[6:7], 0, v[10:11]
	global_store_dword v[2:3], v0, off offset:2048
	s_mov_b32 s6, 0x5410000
	global_load_dwordx3 v[34:36], v32, s[90:91] offset:3088
	global_load_dwordx4 v[6:9], v32, s[90:91] offset:3072
	v_add_co_u32_e32 v2, vcc, s6, v30
	s_mov_b32 s6, 0x5411000
	s_nop 0
	v_addc_co_u32_e32 v3, vcc, 0, v31, vcc
	global_load_dword v0, v[2:3], off offset:3584
	v_add_co_u32_e32 v2, vcc, s6, v30
	s_or_b32 s6, s9, 0x6000
	s_nop 0
	v_addc_co_u32_e32 v3, vcc, 0, v31, vcc
	global_load_dword v3, v[2:3], off offset:3584
	s_add_u32 s6, s92, s6
	s_addc_u32 s7, s93, s8
	s_waitcnt vmcnt(2)
	v_pk_fma_f32 v[40:41], v[12:13], v[6:7], v[4:5] op_sel_hi:[1,0,0]
	s_nop 0
	v_pk_fma_f32 v[6:7], v[14:15], v[6:7], v[40:41] op_sel:[0,1,0]
	s_waitcnt vmcnt(1)
	v_lshlrev_b32_e32 v38, 16, v0
	v_and_b32_e32 v39, 0xffff0000, v0
	v_pk_fma_f32 v[6:7], v[16:17], v[8:9], v[6:7] op_sel_hi:[1,0,1]
	v_mov_b32_e32 v0, v9
	v_pk_fma_f32 v[6:7], v[18:19], v[0:1], v[6:7] op_sel_hi:[1,0,1]
	v_mov_b32_e32 v0, v36
	v_pk_fma_f32 v[6:7], v[20:21], v[34:35], v[6:7] op_sel_hi:[1,0,1]
	s_waitcnt vmcnt(0)
	v_lshlrev_b32_e32 v2, 16, v3
	v_and_b32_e32 v3, 0xffff0000, v3
	v_pk_fma_f32 v[6:7], v[22:23], v[34:35], v[6:7] op_sel:[0,1,0]
	v_pk_mul_f32 v[2:3], v[38:39], v[2:3]
	v_pk_fma_f32 v[6:7], v[24:25], v[0:1], v[6:7] op_sel_hi:[1,0,1]
	s_nop 0
	v_pk_mul_f32 v[2:3], v[6:7], v[2:3]
	s_nop 0
	v_cvt_pk_bf16_f32 v0, v2, v3
	v_lshl_add_u64 v[2:3], s[6:7], 0, v[10:11]
	s_mov_b32 s6, 0x5413000
	global_store_dword v[2:3], v0, off offset:2048
	v_add_co_u32_e32 v2, vcc, s6, v30
	global_load_dwordx4 v[6:9], v32, s[90:91] offset:3600
	s_nop 0
	global_load_dwordx4 v[32:35], v32, s[90:91] offset:3584
	v_addc_co_u32_e32 v3, vcc, 0, v31, vcc
	global_load_dword v0, v[2:3], off offset:2048
	s_mov_b32 s6, 0x5414000
	v_add_co_u32_e32 v2, vcc, s6, v30
	s_or_b32 s6, s9, 0x7000
	s_nop 0
	v_addc_co_u32_e32 v3, vcc, 0, v31, vcc
	global_load_dword v3, v[2:3], off offset:2048
	s_add_u32 s6, s92, s6
	s_addc_u32 s7, s93, s8
	s_waitcnt vmcnt(1)
	v_lshlrev_b32_e32 v30, 16, v0
	v_and_b32_e32 v31, 0xffff0000, v0
	v_mov_b32_e32 v0, v5
	v_pk_fma_f32 v[4:5], v[12:13], v[32:33], v[0:1] op_sel_hi:[1,0,0]
	v_mov_b32_e32 v0, v35
	v_pk_fma_f32 v[4:5], v[14:15], v[32:33], v[4:5] op_sel:[0,1,0]
	s_waitcnt vmcnt(0)
	v_lshlrev_b32_e32 v2, 16, v3
	v_pk_fma_f32 v[4:5], v[16:17], v[34:35], v[4:5] op_sel_hi:[1,0,1]
	v_and_b32_e32 v3, 0xffff0000, v3
	v_pk_fma_f32 v[4:5], v[18:19], v[0:1], v[4:5] op_sel_hi:[1,0,1]
	v_mov_b32_e32 v0, v9
	v_pk_fma_f32 v[4:5], v[20:21], v[6:7], v[4:5] op_sel_hi:[1,0,1]
	v_pk_mul_f32 v[2:3], v[30:31], v[2:3]
	v_pk_fma_f32 v[4:5], v[22:23], v[6:7], v[4:5] op_sel:[0,1,0]
	s_nop 0
	v_pk_fma_f32 v[4:5], v[24:25], v[8:9], v[4:5] op_sel_hi:[1,0,1]
	s_nop 0
	v_pk_fma_f32 v[4:5], v[28:29], v[0:1], v[4:5] op_sel_hi:[1,0,1]
	s_nop 0
	v_pk_mul_f32 v[2:3], v[4:5], v[2:3]
	s_nop 0
	v_cvt_pk_bf16_f32 v0, v2, v3
	v_lshl_add_u64 v[2:3], s[6:7], 0, v[10:11]
	global_store_dword v[2:3], v0, off offset:2048
	s_branch .LBB0_1092

; #define INP(name, idx) const float* name; { int ii_ = (idx); asm volatile("" : "+s"(ii_)); { const GAS float* g_ = (const GAS float*)P.in[ii_]; asm volatile("" : "+s"(g_)); name = (const float*)g_; } }
; #define WSB(name, type, off) type* name; { GAS unsigned char* w_ = (GAS unsigned char*)P.ws; OPQ64(w_); name = (type*)(w_ + (off)); }
; #define OUTP(name) float* name; { GAS float* o_ = (GAS float*)P.out; OPQ64(o_); name = (float*)o_; }
; __global__ void __launch_bounds__(NTHREADS, 2) hybrid_fwd(Params P) {
;     ...
;     if (PH(11)) {
;                 PHASE_IDS
;         INP(norm_final, 24) OUTP(out) WSB(X, float, WS_X) WSB(SS, float, WS_SS)
;         WSB(XBf, bf16_t, WS_XB)
;         for (int m = gw; m < T_ALL; m += NGW) {
;             const float sp = (lane < 32) ? SS[(size_t)m * 32 + lane] : 0.f;
;             const float rstd = rsqrtf(wave_sum(sp) * (1.0f / 2048.0f) + EPSN);
;             const u32x2* xr = (const u32x2*)(XBf + (size_t)m * 2048) + lane; const f32x4* gr_ = (const f32x4*)norm_final + lane;
;             f32x4* yr = (f32x4*)(out + OUT_YP + (size_t)m * 2048) + lane;
.LBB0_1566:
	v_readlane_b32 s0, v254, 0
	v_readlane_b32 s1, v254, 1
	v_readlane_b32 s1, v254, 9
	s_cmp_ge_i32 s1, s0
	s_cselect_b64 s[0:1], -1, 0
	s_and_b64 s[0:1], s[0:1], s[4:5]
	s_and_b64 vcc, exec, s[0:1]
	s_cbranch_vccz .LBB0_1572
	s_lshl_b32 s1, s90, 3
	v_readfirstlane_b32 s0, v139
	s_ashr_i32 s0, s0, 6
	s_add_i32 s8, s1, s0
	s_mov_b32 s0, 24
	s_ashr_i32 s1, s0, 31
	s_lshl_b64 s[0:1], s[0:1], 3
	s_add_u32 s0, s96, s0
	s_addc_u32 s1, s97, s1
	s_load_dwordx2 s[10:11], s[0:1], 0x0
	s_waitcnt lgkmcnt(0)
	s_load_dwordx4 s[4:7], s[96:97], 0xc8
	s_cmpk_gt_i32 s8, 0x20ff
	s_waitcnt lgkmcnt(0)
	s_mov_b64 s[0:1], s[6:7]
	s_mov_b64 s[2:3], s[6:7]
	s_cbranch_scc1 .LBB0_1572
	v_and_b32_e32 v0, 64, v215
	v_add_u32_e32 v0, 64, v0
	v_xor_b32_e32 v1, 1, v215
	v_cmp_lt_i32_e64 s[0:1], v1, v0
	v_and_b32_e32 v22, 63, v139
	v_lshlrev_b32_e32 v14, 4, v22
	v_cndmask_b32_e64 v1, v215, v1, s[0:1]
	v_lshlrev_b32_e32 v16, 2, v1
	v_xor_b32_e32 v1, 2, v215
	v_cmp_lt_i32_e64 s[0:1], v1, v0
	v_mov_b32_e32 v15, 0
	s_ashr_i32 s9, s8, 31
	v_cndmask_b32_e64 v1, v215, v1, s[0:1]
	v_lshlrev_b32_e32 v17, 2, v1
	v_xor_b32_e32 v1, 4, v215
	v_cmp_lt_i32_e64 s[0:1], v1, v0
	v_cmp_gt_u32_e32 vcc, 32, v22
	s_movk_i32 s12, 0xf000
	v_cndmask_b32_e64 v1, v215, v1, s[0:1]
	v_lshlrev_b32_e32 v18, 2, v1
	v_xor_b32_e32 v1, 8, v215
	v_cmp_lt_i32_e64 s[0:1], v1, v0
	s_nop 1
	v_cndmask_b32_e64 v1, v215, v1, s[0:1]
	v_lshlrev_b32_e32 v19, 2, v1
	v_xor_b32_e32 v1, 16, v215
	v_cmp_lt_i32_e64 s[0:1], v1, v0
	s_nop 1
	v_cndmask_b32_e64 v1, v215, v1, s[0:1]
	v_lshlrev_b32_e32 v20, 2, v1
	v_xor_b32_e32 v1, 32, v215
	v_cmp_lt_i32_e64 s[0:1], v1, v0
	s_nop 1
	v_cndmask_b32_e64 v0, v215, v1, s[0:1]
	v_lshlrev_b32_e32 v21, 2, v0
	v_lshl_add_u64 v[0:1], s[10:11], 0, v[14:15]
	s_mov_b64 s[0:1], 0x1000
	s_lshl_b64 s[10:11], s[8:9], 13
	v_lshl_add_u64 v[2:3], v[0:1], 0, s[0:1]
	s_mov_b64 s[0:1], 0x1400
	s_add_u32 s4, s4, s10
	v_lshl_add_u64 v[4:5], v[0:1], 0, s[0:1]
	s_mov_b64 s[0:1], 0x1800
	s_addc_u32 s5, s5, s11
	v_lshl_add_u64 v[6:7], v[0:1], 0, s[0:1]
	s_mov_b64 s[0:1], 0x1c00
	v_lshl_add_u64 v[10:11], s[4:5], 0, v[14:15]
	s_ashr_i32 s93, s92, 31
	v_lshl_add_u64 v[8:9], v[0:1], 0, s[0:1]
	v_lshl_add_u64 v[10:11], v[10:11], 0, s[0:1]
	s_lshl_b64 s[4:5], s[92:93], 13
	s_lshl_b64 s[0:1], s[8:9], 7
	s_add_u32 s0, s2, s0
	v_lshlrev_b32_e32 v14, 2, v22
	s_addc_u32 s1, s3, s1
	v_lshl_add_u64 v[12:13], s[0:1], 0, v[14:15]
	s_mov_b64 s[0:1], 0x13d00000
	v_lshl_add_u64 v[12:13], v[12:13], 0, s[0:1]
	s_lshl_b64 s[10:11], s[92:93], 7
	s_lshl_b64 s[0:1], s[8:9], 12
	s_add_u32 s0, s6, s0
	v_lshlrev_b32_e32 v14, 3, v22
	s_addc_u32 s1, s7, s1
	v_lshl_add_u64 v[14:15], s[0:1], 0, v[14:15]
	s_mov_b64 s[0:1], 0x11c00e00
	v_lshl_add_u64 v[14:15], v[14:15], 0, s[0:1]
	s_lshl_b64 s[6:7], s[92:93], 12
	v_mov_b32_e32 v22, 0x358637bd
	s_mov_b32 s9, 0x800000
	global_load_dwordx4 v[40:43], v[0:1], off
	global_load_dwordx4 v[44:47], v[0:1], off offset:1024
	global_load_dwordx4 v[48:51], v[0:1], off offset:2048
	global_load_dwordx4 v[52:55], v[0:1], off offset:3072
	global_load_dwordx4 v[56:59], v[2:3], off
	global_load_dwordx4 v[60:63], v[4:5], off
	global_load_dwordx4 v[64:67], v[6:7], off
	global_load_dwordx4 v[68:71], v[8:9], off
	s_branch .LBB0_1570
; __device__ __forceinline__ float bf_lo(unsigned w) { return __uint_as_float(w << 16); }
; __device__ __forceinline__ float bf_hi(unsigned w) { return __uint_as_float(w & 0xffff0000u); }
; __global__ void __launch_bounds__(NTHREADS, 2) hybrid_fwd(Params P) {
;     ...
;         for (int m = gw; m < T_ALL; m += NGW) {
;             const float sp = (lane < 32) ? SS[(size_t)m * 32 + lane] : 0.f;
;             const float rstd = rsqrtf(wave_sum(sp) * (1.0f / 2048.0f) + EPSN);
;             const u32x2* xr = (const u32x2*)(XBf + (size_t)m * 2048) + lane; const f32x4* gr_ = (const f32x4*)norm_final + lane;
;             f32x4* yr = (f32x4*)(out + OUT_YP + (size_t)m * 2048) + lane;
; #pragma unroll
;             for (int j = 0; j < 8; ++j) { const u32x2 w = xr[64 * j]; const f32x4 xv = {bf_lo(w.x), bf_hi(w.x), bf_lo(w.y), bf_hi(w.y)}; yr[64 * j] = xv * rstd * gr_[64 * j]; }
;         }
.LBB0_1569:
	s_or_b64 exec, exec, s[0:1]
	global_load_dwordx2 v[72:73], v[14:15], off offset:-3584
	global_load_dwordx2 v[74:75], v[14:15], off offset:-3072
	global_load_dwordx2 v[76:77], v[14:15], off offset:-2560
	global_load_dwordx2 v[78:79], v[14:15], off offset:-2048
	global_load_dwordx2 v[80:81], v[14:15], off offset:-1536
	global_load_dwordx2 v[82:83], v[14:15], off offset:-1024
	global_load_dwordx2 v[84:85], v[14:15], off offset:-512
	global_load_dwordx2 v[86:87], v[14:15], off
	v_lshl_add_u64 v[14:15], v[14:15], 0, s[6:7]
	s_waitcnt vmcnt(8)
	s_waitcnt lgkmcnt(0)
	s_nop 1
	v_add_f32_dpp v23, v23, v23 quad_perm:[1,0,3,2] row_mask:0xf bank_mask:0xf
	s_nop 1
	v_add_f32_dpp v23, v23, v23 quad_perm:[2,3,0,1] row_mask:0xf bank_mask:0xf
	s_nop 1
	v_add_f32_dpp v23, v23, v23 row_half_mirror row_mask:0xf bank_mask:0xf
	s_nop 1
	v_add_f32_dpp v23, v23, v23 row_mirror row_mask:0xf bank_mask:0xf
	s_nop 1
	v_add_f32_dpp v23, v23, v23 row_bcast:15 row_mask:0xa bank_mask:0xf
	s_nop 1
	v_add_f32_dpp v23, v23, v23 row_bcast:31 row_mask:0xc bank_mask:0xf
	s_nop 1
	v_readlane_b32 s100, v23, 63
	s_nop 1
	v_mov_b32_e32 v23, s100
	v_fmamk_f32 v23, v23, 0x3a000000, v22
	v_mul_f32_e32 v30, 0x4b800000, v23
	v_cmp_gt_f32_e64 s[0:1], s9, v23
	s_nop 1
	v_cndmask_b32_e64 v23, v23, v30, s[0:1]
	v_rsq_f32_e32 v23, v23
	v_add_co_u32_e64 v30, s[2:3], s12, v10
	s_nop 1
	v_addc_co_u32_e64 v31, s[2:3], -1, v11, s[2:3]
	v_mul_f32_e32 v32, 0x45800000, v23
	v_cndmask_b32_e64 v32, v23, v32, s[0:1]
	s_add_i32 s8, s8, s92
	v_lshl_add_u64 v[12:13], v[12:13], 0, s[10:11]
	s_cmpk_lt_i32 s8, 0x2100
	s_waitcnt vmcnt(7)
	v_lshlrev_b32_e32 v34, 16, v72
	v_and_b32_e32 v35, 0xffff0000, v72
	v_lshlrev_b32_e32 v28, 16, v73
	v_and_b32_e32 v29, 0xffff0000, v73
	v_pk_mul_f32 v[34:35], v[32:33], v[34:35] op_sel_hi:[0,1]
	v_pk_mul_f32 v[28:29], v[32:33], v[28:29] op_sel_hi:[0,1]
	v_pk_mul_f32 v[26:27], v[42:43], v[28:29]
	v_pk_mul_f32 v[24:25], v[40:41], v[34:35]
	global_store_dwordx4 v[30:31], v[24:27], off offset:-3072
	s_waitcnt vmcnt(7)
	v_lshlrev_b32_e32 v34, 16, v74
	v_and_b32_e32 v35, 0xffff0000, v74
	v_lshlrev_b32_e32 v28, 16, v75
	v_and_b32_e32 v29, 0xffff0000, v75
	v_pk_mul_f32 v[34:35], v[32:33], v[34:35] op_sel_hi:[0,1]
	v_pk_mul_f32 v[28:29], v[32:33], v[28:29] op_sel_hi:[0,1]
	v_pk_mul_f32 v[38:39], v[46:47], v[28:29]
	v_pk_mul_f32 v[36:37], v[44:45], v[34:35]
	global_store_dwordx4 v[30:31], v[36:39], off offset:-2048
	s_waitcnt vmcnt(7)
	v_lshlrev_b32_e32 v34, 16, v76
	v_and_b32_e32 v35, 0xffff0000, v76
	v_lshlrev_b32_e32 v28, 16, v77
	v_and_b32_e32 v29, 0xffff0000, v77
	v_pk_mul_f32 v[34:35], v[32:33], v[34:35] op_sel_hi:[0,1]
	v_pk_mul_f32 v[28:29], v[32:33], v[28:29] op_sel_hi:[0,1]
	v_pk_mul_f32 v[26:27], v[50:51], v[28:29]
	v_pk_mul_f32 v[24:25], v[48:49], v[34:35]
	global_store_dwordx4 v[30:31], v[24:27], off offset:-1024
	s_waitcnt vmcnt(7)
	v_lshlrev_b32_e32 v34, 16, v78
	v_and_b32_e32 v35, 0xffff0000, v78
	v_lshlrev_b32_e32 v28, 16, v79
	v_and_b32_e32 v29, 0xffff0000, v79
	v_pk_mul_f32 v[34:35], v[32:33], v[34:35] op_sel_hi:[0,1]
	v_pk_mul_f32 v[28:29], v[32:33], v[28:29] op_sel_hi:[0,1]
	v_pk_mul_f32 v[38:39], v[54:55], v[28:29]
	v_pk_mul_f32 v[36:37], v[52:53], v[34:35]
	global_store_dwordx4 v[10:11], v[36:39], off offset:-4096
	s_waitcnt vmcnt(7)
	v_lshlrev_b32_e32 v34, 16, v80
	v_and_b32_e32 v35, 0xffff0000, v80
	v_lshlrev_b32_e32 v28, 16, v81
	v_and_b32_e32 v29, 0xffff0000, v81
	v_pk_mul_f32 v[34:35], v[32:33], v[34:35] op_sel_hi:[0,1]
	v_pk_mul_f32 v[28:29], v[32:33], v[28:29] op_sel_hi:[0,1]
	v_pk_mul_f32 v[26:27], v[58:59], v[28:29]
	v_pk_mul_f32 v[24:25], v[56:57], v[34:35]
	global_store_dwordx4 v[10:11], v[24:27], off offset:-3072
	s_waitcnt vmcnt(7)
	v_lshlrev_b32_e32 v34, 16, v82
	v_and_b32_e32 v35, 0xffff0000, v82
	v_lshlrev_b32_e32 v28, 16, v83
	v_and_b32_e32 v29, 0xffff0000, v83
	v_pk_mul_f32 v[34:35], v[32:33], v[34:35] op_sel_hi:[0,1]
	v_pk_mul_f32 v[28:29], v[32:33], v[28:29] op_sel_hi:[0,1]
	v_pk_mul_f32 v[38:39], v[62:63], v[28:29]
	v_pk_mul_f32 v[36:37], v[60:61], v[34:35]
	global_store_dwordx4 v[10:11], v[36:39], off offset:-2048
	s_waitcnt vmcnt(7)
	v_lshlrev_b32_e32 v34, 16, v84
	v_and_b32_e32 v35, 0xffff0000, v84
	v_lshlrev_b32_e32 v28, 16, v85
	v_and_b32_e32 v29, 0xffff0000, v85
	v_pk_mul_f32 v[34:35], v[32:33], v[34:35] op_sel_hi:[0,1]
	v_pk_mul_f32 v[28:29], v[32:33], v[28:29] op_sel_hi:[0,1]
	v_pk_mul_f32 v[26:27], v[66:67], v[28:29]
	v_pk_mul_f32 v[24:25], v[64:65], v[34:35]
	global_store_dwordx4 v[10:11], v[24:27], off offset:-1024
	s_waitcnt vmcnt(7)
	v_lshlrev_b32_e32 v34, 16, v86
	v_and_b32_e32 v35, 0xffff0000, v86
	v_lshlrev_b32_e32 v28, 16, v87
	v_and_b32_e32 v29, 0xffff0000, v87
	v_pk_mul_f32 v[34:35], v[32:33], v[34:35] op_sel_hi:[0,1]
	v_pk_mul_f32 v[28:29], v[32:33], v[28:29] op_sel_hi:[0,1]
	v_pk_mul_f32 v[38:39], v[70:71], v[28:29]
	v_pk_mul_f32 v[36:37], v[68:69], v[34:35]
	global_store_dwordx4 v[10:11], v[36:39], off
	v_lshl_add_u64 v[10:11], v[10:11], 0, s[4:5]
	s_cbranch_scc0 .LBB0_1572

; __global__ void __launch_bounds__(NTHREADS, 2) hybrid_fwd(Params P) {
	.amdhsa_kernel _Z10hybrid_fwd6Params
		.amdhsa_group_segment_fixed_size 0
		.amdhsa_private_segment_fixed_size 0
		.amdhsa_kernarg_size 480
		.amdhsa_user_sgpr_count 2
		.amdhsa_user_sgpr_dispatch_ptr 0
		.amdhsa_user_sgpr_queue_ptr 0
		.amdhsa_user_sgpr_kernarg_segment_ptr 1
		.amdhsa_user_sgpr_dispatch_id 0
		.amdhsa_user_sgpr_kernarg_preload_length 0
		.amdhsa_user_sgpr_kernarg_preload_offset 0
		.amdhsa_user_sgpr_private_segment_size 0
		.amdhsa_uses_dynamic_stack 0
		.amdhsa_enable_private_segment 0
		.amdhsa_system_sgpr_workgroup_id_x 1
		.amdhsa_system_sgpr_workgroup_id_y 0
		.amdhsa_system_sgpr_workgroup_id_z 0
		.amdhsa_system_sgpr_workgroup_info 0
		.amdhsa_system_vgpr_workitem_id 2
		.amdhsa_next_free_vgpr 256
		.amdhsa_next_free_sgpr 102
		.amdhsa_accum_offset 256
		.amdhsa_reserve_vcc 1
		.amdhsa_float_round_mode_32 0
		.amdhsa_float_round_mode_16_64 0
		.amdhsa_float_denorm_mode_32 3
		.amdhsa_float_denorm_mode_16_64 3
		.amdhsa_dx10_clamp 1
		.amdhsa_ieee_mode 1
		.amdhsa_fp16_overflow 0
		.amdhsa_tg_split 0
		.amdhsa_exception_fp_ieee_invalid_op 0
		.amdhsa_exception_fp_denorm_src 0
		.amdhsa_exception_fp_ieee_div_zero 0
		.amdhsa_exception_fp_ieee_overflow 0
		.amdhsa_exception_fp_ieee_underflow 0
		.amdhsa_exception_fp_ieee_inexact 0
		.amdhsa_exception_int_div_zero 0
	.end_amdhsa_kernel

; __global__ void __launch_bounds__(NTHREADS, 2) hybrid_fwd(Params P) {
amdhsa.kernels:
  - .agpr_count:     0
    .args:
      - .offset:         0
        .size:           224
        .value_kind:     by_value
      - .offset:         224
        .size:           4
        .value_kind:     hidden_block_count_x
      - .offset:         228
        .size:           4
        .value_kind:     hidden_block_count_y
      - .offset:         232
        .size:           4
        .value_kind:     hidden_block_count_z
      - .offset:         236
        .size:           2
        .value_kind:     hidden_group_size_x
      - .offset:         238
        .size:           2
        .value_kind:     hidden_group_size_y
      - .offset:         240
        .size:           2
        .value_kind:     hidden_group_size_z
      - .offset:         242
        .size:           2
        .value_kind:     hidden_remainder_x
      - .offset:         244
        .size:           2
        .value_kind:     hidden_remainder_y
      - .offset:         246
        .size:           2
        .value_kind:     hidden_remainder_z
      - .offset:         264
        .size:           8
        .value_kind:     hidden_global_offset_x
      - .offset:         272
        .size:           8
        .value_kind:     hidden_global_offset_y
      - .offset:         280
        .size:           8
        .value_kind:     hidden_global_offset_z
      - .offset:         288
        .size:           2
        .value_kind:     hidden_grid_dims
      - .offset:         312
        .size:           8
        .value_kind:     hidden_multigrid_sync_arg
      - .offset:         344
        .size:           4
        .value_kind:     hidden_dynamic_lds_size
    .group_segment_fixed_size: 0
    .kernarg_segment_align: 8
    .kernarg_segment_size: 480
    .language:       OpenCL C
    .language_version:
      - 2
      - 0
    .max_flat_workgroup_size: 512
    .name:           _Z10hybrid_fwd6Params
    .private_segment_fixed_size: 0
    .sgpr_count:     108
    .sgpr_spill_count: 103
    .symbol:         _Z10hybrid_fwd6Params.kd
    .uniform_work_group_size: 1
    .uses_dynamic_stack: false
    .vgpr_count:     256
    .vgpr_spill_count: 0
    .wavefront_size: 64
